# GEMM loops: dropped duplicate lgkmcnt(0) waits and the s_nop before each LDS-DMA (m0 write now separated by the address add)
# speedup vs baseline: 1.0022x; 1.0022x over previous
; #define PG8_STAGE(bufoff, gbase, voff) do { _Pragma("unroll") for (int _i = 0; _i < 2; ++_i) \
;         __builtin_amdgcn_global_load_lds((const unsigned*)((const char*)(gbase) + (voff)[_i]), (LAS unsigned*)(lds + (bufoff) + ldsw + _i * 8192), 16, 0, 0); } while (0)
; #define PG8_LDA(dst, b, h) do { _Pragma("unroll") for (int m = 0; m < 4; ++m) _Pragma("unroll") for (int k = 0; k < 2; ++k) dst[m][k] = *(const LAS bf16x8*)(lds + PG8_SA(b, h) + aoff + m * 2048 + k * 1024); } while (0)
; #define PG8_LDB(dst, b, h) do { _Pragma("unroll") for (int n = 0; n < 2; ++n) _Pragma("unroll") for (int k = 0; k < 2; ++k) dst[n][k] = *(const LAS bf16x8*)(lds + PG8_SB(b, h) + boff + n * 2048 + k * 1024); } while (0)
; #define PG8_MMA(ai, bj, At, Bt) do { __builtin_amdgcn_s_setprio(1); _Pragma("unroll") for (int m = 0; m < 4; ++m) _Pragma("unroll") for (int n = 0; n < 2; ++n) _Pragma("unroll") for (int k = 0; k < 2; ++k) \
;         acc[ai][bj][m][n] = __builtin_amdgcn_mfma_f32_16x16x32_bf16(Bt[n][k], At[m][k], acc[ai][bj][m][n], 0, 0, 0); __builtin_amdgcn_s_setprio(0); } while (0)
; template <class Epi>
; __device__ __forceinline__ void gemm_phase(LAS unsigned char* lds, const Gemm g, const StaticOrder& S, const Epi& E) {
;     ...
;         const bool has_next = S.next(ui + 1, nxt);
;         const char* nA = has_next ? g.arow(nxt.pm) : cA; const char* nB = has_next ? (const char*)g.Bt + (size_t)nxt.pn * tB : cB;
;         for (int t = 0; t < nt; t += 2) {
;             const bool last = (t == nt - 2);
;             const char* a1 = cA + (size_t)(t + 1) * kstep;
;             const char* a2 = last ? nA : cA + (size_t)(t + 2) * kstep; const char* b2 = last ? nB : cB + (size_t)(t + 2) * kstep;
;             const char* a3 = a2 + kstep; const char* b3 = b2 + kstep;
;             PG8_LDB(B0, 0, 0); PG8_SCHED; PG8_LDA(At, 0, 0); PG8_STAGE(PG8_SA(1, 1), a1 + hA, voffA);
;             PG8_WAIT_L(8); PG8_BAR; PG8_WAIT_L(0); PG8_MMA(0, 0, At, B0); PG8_BAR; PG8_SCHED;
;             PG8_LDB(B1, 0, 1); PG8_STAGE(PG8_SB(0, 0), b2, voffB);
;             PG8_BAR; PG8_WAIT_L(0); PG8_MMA(0, 1, At, B1); PG8_BAR;
;             PG8_LDA(At, 0, 1); PG8_STAGE(PG8_SA(0, 0), a2, voffA);
;             PG8_BAR; PG8_WAIT_L(0); PG8_MMA(1, 0, At, B0); PG8_BAR; PG8_SCHED;
;             PG8_STAGE(PG8_SB(0, 1), b2 + hB, voffB);
;             PG8_WAIT_V(6); PG8_BAR; PG8_MMA(1, 1, At, B1); PG8_BAR;
.LBB0_281:
	s_add_u32 s16, s12, 0xfffc0080
	s_addc_u32 s17, s13, -1
	s_add_i32 s26, 0, 0x10000
	v_add_u32_e32 v139, s26, v137
	ds_read_b128 v[140:143], v139
	ds_read_b128 v[146:149], v139 offset:1024
	ds_read_b128 v[150:153], v139 offset:2048
	ds_read_b128 v[154:157], v139 offset:3072
	s_cmp_eq_u32 s78, 12
	s_cselect_b32 s21, s72, s17
	s_cselect_b32 s20, s76, s16
	s_cselect_b32 s17, s7, s77
	s_cselect_b32 s16, s24, s25
	v_lshl_add_u64 v[186:187], s[12:13], 0, v[132:133]
	s_add_i32 m0, s61, 0xc000
	ds_read_b128 v[158:161], v138
	ds_read_b128 v[162:165], v138 offset:1024
	ds_read_b128 v[166:169], v138 offset:2048
	ds_read_b128 v[170:173], v138 offset:3072
	ds_read_b128 v[174:177], v138 offset:4096
	ds_read_b128 v[178:181], v138 offset:5120
	ds_read_b128 v[182:185], v138 offset:6144
	ds_read_b128 v[196:199], v138 offset:7168
	global_load_lds_dwordx4 v[186:187], off
	s_add_i32 m0, s61, 0xe000
	v_lshl_add_u64 v[186:187], s[12:13], 0, v[134:135]
	global_load_lds_dwordx4 v[186:187], off
	s_waitcnt lgkmcnt(8)
	s_barrier
	s_waitcnt lgkmcnt(0)
	s_setprio 1
	v_mfma_f32_16x16x32_bf16 v[120:123], v[140:143], v[158:161], v[120:123]
	v_mfma_f32_16x16x32_bf16 v[124:127], v[150:153], v[158:161], v[124:127]
	v_mfma_f32_16x16x32_bf16 v[104:107], v[140:143], v[166:169], v[104:107]
	v_mfma_f32_16x16x32_bf16 v[108:111], v[150:153], v[166:169], v[108:111]
	v_mfma_f32_16x16x32_bf16 v[88:91], v[140:143], v[174:177], v[88:91]
	v_mfma_f32_16x16x32_bf16 v[92:95], v[150:153], v[174:177], v[92:95]
	v_mfma_f32_16x16x32_bf16 v[72:75], v[140:143], v[182:185], v[72:75]
	v_mfma_f32_16x16x32_bf16 v[76:79], v[150:153], v[182:185], v[76:79]
	v_mfma_f32_16x16x32_bf16 v[120:123], v[146:149], v[162:165], v[120:123]
	v_mfma_f32_16x16x32_bf16 v[124:127], v[154:157], v[162:165], v[124:127]
	v_mfma_f32_16x16x32_bf16 v[104:107], v[146:149], v[170:173], v[104:107]
	v_mfma_f32_16x16x32_bf16 v[108:111], v[154:157], v[170:173], v[108:111]
	v_mfma_f32_16x16x32_bf16 v[88:91], v[146:149], v[178:181], v[88:91]
	v_mfma_f32_16x16x32_bf16 v[92:95], v[154:157], v[178:181], v[92:95]
	v_mfma_f32_16x16x32_bf16 v[72:75], v[146:149], v[196:199], v[72:75]
	v_mfma_f32_16x16x32_bf16 v[76:79], v[154:157], v[196:199], v[76:79]
	s_setprio 0
	s_barrier
	s_add_i32 s28, 0, 0x14000
	s_add_i32 s26, s26, s35
	v_add_u32_e32 v139, s28, v137
	v_lshl_add_u64 v[186:187], s[16:17], 0, v[130:131]
	s_mov_b32 m0, s26
	ds_read_b128 v[200:203], v139
	ds_read_b128 v[204:207], v139 offset:1024
	ds_read_b128 v[214:217], v139 offset:2048
	ds_read_b128 v[218:221], v139 offset:3072
	global_load_lds_dwordx4 v[186:187], off
	s_add_i32 m0, s26, 0x2000
	v_lshl_add_u64 v[188:189], s[16:17], 0, v[128:129]
	global_load_lds_dwordx4 v[188:189], off
	s_barrier
	s_waitcnt lgkmcnt(0)
	s_setprio 1
	v_mfma_f32_16x16x32_bf16 v[112:115], v[200:203], v[158:161], v[112:115]
	v_mfma_f32_16x16x32_bf16 v[116:119], v[214:217], v[158:161], v[116:119]
	v_mfma_f32_16x16x32_bf16 v[96:99], v[200:203], v[166:169], v[96:99]
	v_mfma_f32_16x16x32_bf16 v[100:103], v[214:217], v[166:169], v[100:103]
	v_mfma_f32_16x16x32_bf16 v[80:83], v[200:203], v[174:177], v[80:83]
	v_mfma_f32_16x16x32_bf16 v[84:87], v[214:217], v[174:177], v[84:87]
	v_mfma_f32_16x16x32_bf16 v[64:67], v[200:203], v[182:185], v[64:67]
	v_mfma_f32_16x16x32_bf16 v[68:71], v[214:217], v[182:185], v[68:71]
	v_mfma_f32_16x16x32_bf16 v[112:115], v[204:207], v[162:165], v[112:115]
	v_mfma_f32_16x16x32_bf16 v[116:119], v[218:221], v[162:165], v[116:119]
	v_mfma_f32_16x16x32_bf16 v[96:99], v[204:207], v[170:173], v[96:99]
	v_mfma_f32_16x16x32_bf16 v[100:103], v[218:221], v[170:173], v[100:103]
	v_mfma_f32_16x16x32_bf16 v[80:83], v[204:207], v[178:181], v[80:83]
	v_mfma_f32_16x16x32_bf16 v[84:87], v[218:221], v[178:181], v[84:87]
	v_mfma_f32_16x16x32_bf16 v[64:67], v[204:207], v[196:199], v[64:67]
	v_mfma_f32_16x16x32_bf16 v[68:71], v[218:221], v[196:199], v[68:71]
	s_setprio 0
	s_mov_b32 m0, s61
	v_lshl_add_u64 v[192:193], s[20:21], 0, v[130:131]
	s_barrier
	ds_read_b128 v[158:161], v138 offset:16384
	ds_read_b128 v[162:165], v138 offset:17408
	ds_read_b128 v[166:169], v138 offset:18432
	ds_read_b128 v[170:173], v138 offset:19456
	ds_read_b128 v[174:177], v138 offset:20480
	ds_read_b128 v[178:181], v138 offset:21504
	ds_read_b128 v[182:185], v138 offset:22528
	ds_read_b128 v[196:199], v138 offset:23552
	global_load_lds_dwordx4 v[192:193], off
	s_mov_b32 m0, s62
	v_lshl_add_u64 v[222:223], s[20:21], 0, v[128:129]
	global_load_lds_dwordx4 v[222:223], off
	s_barrier
	s_waitcnt lgkmcnt(0)
	s_setprio 1
	v_mfma_f32_16x16x32_bf16 v[56:59], v[140:143], v[158:161], v[56:59]
	v_mfma_f32_16x16x32_bf16 v[60:63], v[150:153], v[158:161], v[60:63]
	v_mfma_f32_16x16x32_bf16 v[40:43], v[140:143], v[166:169], v[40:43]
	v_mfma_f32_16x16x32_bf16 v[44:47], v[150:153], v[166:169], v[44:47]
	v_mfma_f32_16x16x32_bf16 v[24:27], v[140:143], v[174:177], v[24:27]
	v_mfma_f32_16x16x32_bf16 v[28:31], v[150:153], v[174:177], v[28:31]
	v_mfma_f32_16x16x32_bf16 v[8:11], v[140:143], v[182:185], v[8:11]
	v_mfma_f32_16x16x32_bf16 v[12:15], v[150:153], v[182:185], v[12:15]
	v_mfma_f32_16x16x32_bf16 v[56:59], v[146:149], v[162:165], v[56:59]
	v_mfma_f32_16x16x32_bf16 v[60:63], v[154:157], v[162:165], v[60:63]
	v_mfma_f32_16x16x32_bf16 v[40:43], v[146:149], v[170:173], v[40:43]
	v_mfma_f32_16x16x32_bf16 v[44:47], v[154:157], v[170:173], v[44:47]
	v_mfma_f32_16x16x32_bf16 v[24:27], v[146:149], v[178:181], v[24:27]
	v_mfma_f32_16x16x32_bf16 v[28:31], v[154:157], v[178:181], v[28:31]
	v_mfma_f32_16x16x32_bf16 v[8:11], v[146:149], v[196:199], v[8:11]
	v_mfma_f32_16x16x32_bf16 v[12:15], v[154:157], v[196:199], v[12:15]
	s_setprio 0
	s_barrier
; #define PG8_STAGE(bufoff, gbase, voff) do { _Pragma("unroll") for (int _i = 0; _i < 2; ++_i) \
;         __builtin_amdgcn_global_load_lds((const unsigned*)((const char*)(gbase) + (voff)[_i]), (LAS unsigned*)(lds + (bufoff) + ldsw + _i * 8192), 16, 0, 0); } while (0)
; #define PG8_LDA(dst, b, h) do { _Pragma("unroll") for (int m = 0; m < 4; ++m) _Pragma("unroll") for (int k = 0; k < 2; ++k) dst[m][k] = *(const LAS bf16x8*)(lds + PG8_SA(b, h) + aoff + m * 2048 + k * 1024); } while (0)
; #define PG8_LDB(dst, b, h) do { _Pragma("unroll") for (int n = 0; n < 2; ++n) _Pragma("unroll") for (int k = 0; k < 2; ++k) dst[n][k] = *(const LAS bf16x8*)(lds + PG8_SB(b, h) + boff + n * 2048 + k * 1024); } while (0)
; #define PG8_MMA(ai, bj, At, Bt) do { __builtin_amdgcn_s_setprio(1); _Pragma("unroll") for (int m = 0; m < 4; ++m) _Pragma("unroll") for (int n = 0; n < 2; ++n) _Pragma("unroll") for (int k = 0; k < 2; ++k) \
;         acc[ai][bj][m][n] = __builtin_amdgcn_mfma_f32_16x16x32_bf16(Bt[n][k], At[m][k], acc[ai][bj][m][n], 0, 0, 0); __builtin_amdgcn_s_setprio(0); } while (0)
; #define PG8_WAIT_V(n) asm volatile("s_waitcnt vmcnt(" #n ")" ::: "memory")
; #define PG8_WAIT_L(n) asm volatile("s_waitcnt lgkmcnt(" #n ")" ::: "memory")
; #define PG8_BAR __builtin_amdgcn_s_barrier()
; #define PG8_SCHED __builtin_amdgcn_sched_barrier(0)
; template <class Epi>
; __device__ __forceinline__ void gemm_phase(LAS unsigned char* lds, const Gemm g, const StaticOrder& S, const Epi& E) {
;     ...
;             PG8_WAIT_V(6); PG8_BAR; PG8_MMA(1, 1, At, B1); PG8_BAR;
;             PG8_LDB(B0, 1, 0); PG8_SCHED; PG8_LDA(At, 1, 0); PG8_STAGE(PG8_SA(0, 1), a2 + hA, voffA);
;             PG8_WAIT_L(8); PG8_BAR; PG8_WAIT_L(0); PG8_MMA(0, 0, At, B0); PG8_BAR; PG8_SCHED;
;             PG8_LDB(B1, 1, 1); PG8_STAGE(PG8_SB(1, 0), b3, voffB);
;             PG8_BAR; PG8_WAIT_L(0); PG8_MMA(0, 1, At, B1); PG8_BAR;
;             PG8_LDA(At, 1, 1); PG8_STAGE(PG8_SA(1, 0), a3, voffA);
;             PG8_BAR; PG8_WAIT_L(0); PG8_MMA(1, 0, At, B0); PG8_BAR; PG8_SCHED;
;             PG8_STAGE(PG8_SB(1, 1), b3 + hB, voffB);
;             PG8_WAIT_V(6); PG8_BAR; PG8_MMA(1, 1, At, B1); PG8_BAR;
	s_add_u32 s26, s16, 0x40000
	s_addc_u32 s27, s17, 0
	s_add_i32 s28, s28, s35
	s_mov_b32 m0, s28
	v_lshl_add_u64 v[140:141], s[26:27], 0, v[130:131]
	global_load_lds_dwordx4 v[140:141], off
	s_add_i32 m0, s28, 0x2000
	v_lshl_add_u64 v[140:141], s[26:27], 0, v[128:129]
	global_load_lds_dwordx4 v[140:141], off
	s_waitcnt vmcnt(6)
	s_barrier
	s_setprio 1
	v_mfma_f32_16x16x32_bf16 v[48:51], v[200:203], v[158:161], v[48:51]
	v_mfma_f32_16x16x32_bf16 v[52:55], v[214:217], v[158:161], v[52:55]
	v_mfma_f32_16x16x32_bf16 v[32:35], v[200:203], v[166:169], v[32:35]
	v_mfma_f32_16x16x32_bf16 v[36:39], v[214:217], v[166:169], v[36:39]
	v_mfma_f32_16x16x32_bf16 v[16:19], v[200:203], v[174:177], v[16:19]
	v_mfma_f32_16x16x32_bf16 v[20:23], v[214:217], v[174:177], v[20:23]
	v_mfma_f32_16x16x32_bf16 v[0:3], v[200:203], v[182:185], v[0:3]
	v_mfma_f32_16x16x32_bf16 v[4:7], v[214:217], v[182:185], v[4:7]
	v_mfma_f32_16x16x32_bf16 v[48:51], v[204:207], v[162:165], v[48:51]
	v_mfma_f32_16x16x32_bf16 v[52:55], v[218:221], v[162:165], v[52:55]
	v_mfma_f32_16x16x32_bf16 v[32:35], v[204:207], v[170:173], v[32:35]
	v_mfma_f32_16x16x32_bf16 v[36:39], v[218:221], v[170:173], v[36:39]
	v_mfma_f32_16x16x32_bf16 v[16:19], v[204:207], v[178:181], v[16:19]
	v_mfma_f32_16x16x32_bf16 v[20:23], v[218:221], v[178:181], v[20:23]
	v_mfma_f32_16x16x32_bf16 v[0:3], v[204:207], v[196:199], v[0:3]
	v_mfma_f32_16x16x32_bf16 v[4:7], v[218:221], v[196:199], v[4:7]
	s_setprio 0
	s_add_i32 s26, 0, 0x18000
	v_add_u32_e32 v139, s26, v137
	s_barrier
	ds_read_b128 v[140:143], v139
	ds_read_b128 v[146:149], v139 offset:1024
	ds_read_b128 v[150:153], v139 offset:2048
	ds_read_b128 v[154:157], v139 offset:3072
	s_add_u32 s20, s20, 0x40000
	s_addc_u32 s21, s21, 0
	s_mov_b32 m0, s63
	v_lshl_add_u64 v[200:201], s[20:21], 0, v[130:131]
	ds_read_b128 v[158:161], v138 offset:32768
	ds_read_b128 v[162:165], v138 offset:33792
	ds_read_b128 v[166:169], v138 offset:34816
	ds_read_b128 v[170:173], v138 offset:35840
	ds_read_b128 v[174:177], v138 offset:36864
	ds_read_b128 v[178:181], v138 offset:37888
	ds_read_b128 v[182:185], v138 offset:38912
	ds_read_b128 v[196:199], v138 offset:39936
	global_load_lds_dwordx4 v[200:201], off
	s_mov_b32 m0, s64
	v_lshl_add_u64 v[200:201], s[20:21], 0, v[128:129]
	global_load_lds_dwordx4 v[200:201], off
	s_waitcnt lgkmcnt(8)
	s_barrier
	s_waitcnt lgkmcnt(0)
	s_setprio 1
	v_mfma_f32_16x16x32_bf16 v[120:123], v[140:143], v[158:161], v[120:123]
	v_mfma_f32_16x16x32_bf16 v[124:127], v[150:153], v[158:161], v[124:127]
	v_mfma_f32_16x16x32_bf16 v[104:107], v[140:143], v[166:169], v[104:107]
	v_mfma_f32_16x16x32_bf16 v[108:111], v[150:153], v[166:169], v[108:111]
	v_mfma_f32_16x16x32_bf16 v[88:91], v[140:143], v[174:177], v[88:91]
	v_mfma_f32_16x16x32_bf16 v[92:95], v[150:153], v[174:177], v[92:95]
	v_mfma_f32_16x16x32_bf16 v[72:75], v[140:143], v[182:185], v[72:75]
	v_mfma_f32_16x16x32_bf16 v[76:79], v[150:153], v[182:185], v[76:79]
	v_mfma_f32_16x16x32_bf16 v[120:123], v[146:149], v[162:165], v[120:123]
	v_mfma_f32_16x16x32_bf16 v[124:127], v[154:157], v[162:165], v[124:127]
	v_mfma_f32_16x16x32_bf16 v[104:107], v[146:149], v[170:173], v[104:107]
	v_mfma_f32_16x16x32_bf16 v[108:111], v[154:157], v[170:173], v[108:111]
	v_mfma_f32_16x16x32_bf16 v[88:91], v[146:149], v[178:181], v[88:91]
	v_mfma_f32_16x16x32_bf16 v[92:95], v[154:157], v[178:181], v[92:95]
	v_mfma_f32_16x16x32_bf16 v[72:75], v[146:149], v[196:199], v[72:75]
	v_mfma_f32_16x16x32_bf16 v[76:79], v[154:157], v[196:199], v[76:79]
	s_setprio 0
	s_barrier
	s_add_i32 s20, 0, 0x1c000
	s_add_i32 s21, s26, s35
	v_add_u32_e32 v139, s20, v137
	v_lshl_add_u64 v[186:187], v[186:187], 0, s[88:89]
	s_mov_b32 m0, s21
	ds_read_b128 v[200:203], v139
	ds_read_b128 v[204:207], v139 offset:1024
	ds_read_b128 v[214:217], v139 offset:2048
	ds_read_b128 v[218:221], v139 offset:3072
	global_load_lds_dwordx4 v[186:187], off
	s_add_i32 m0, s21, 0x2000
	v_lshl_add_u64 v[186:187], v[188:189], 0, s[88:89]
	global_load_lds_dwordx4 v[186:187], off
	s_barrier
	s_waitcnt lgkmcnt(0)
	s_setprio 1
	v_mfma_f32_16x16x32_bf16 v[112:115], v[200:203], v[158:161], v[112:115]
	v_mfma_f32_16x16x32_bf16 v[116:119], v[214:217], v[158:161], v[116:119]
	v_mfma_f32_16x16x32_bf16 v[96:99], v[200:203], v[166:169], v[96:99]
	v_mfma_f32_16x16x32_bf16 v[100:103], v[214:217], v[166:169], v[100:103]
	v_mfma_f32_16x16x32_bf16 v[80:83], v[200:203], v[174:177], v[80:83]
	v_mfma_f32_16x16x32_bf16 v[84:87], v[214:217], v[174:177], v[84:87]
	v_mfma_f32_16x16x32_bf16 v[64:67], v[200:203], v[182:185], v[64:67]
	v_mfma_f32_16x16x32_bf16 v[68:71], v[214:217], v[182:185], v[68:71]
	v_mfma_f32_16x16x32_bf16 v[112:115], v[204:207], v[162:165], v[112:115]
	v_mfma_f32_16x16x32_bf16 v[116:119], v[218:221], v[162:165], v[116:119]
	v_mfma_f32_16x16x32_bf16 v[96:99], v[204:207], v[170:173], v[96:99]
	v_mfma_f32_16x16x32_bf16 v[100:103], v[218:221], v[170:173], v[100:103]
	v_mfma_f32_16x16x32_bf16 v[80:83], v[204:207], v[178:181], v[80:83]
	v_mfma_f32_16x16x32_bf16 v[84:87], v[218:221], v[178:181], v[84:87]
	v_mfma_f32_16x16x32_bf16 v[64:67], v[204:207], v[196:199], v[64:67]
	v_mfma_f32_16x16x32_bf16 v[68:71], v[218:221], v[196:199], v[68:71]
	s_setprio 0
	s_mov_b32 m0, s65
	v_lshl_add_u64 v[186:187], v[192:193], 0, s[88:89]
	s_barrier
	ds_read_b128 v[158:161], v138 offset:49152
	ds_read_b128 v[162:165], v138 offset:50176
	ds_read_b128 v[166:169], v138 offset:51200
	ds_read_b128 v[170:173], v138 offset:52224
	ds_read_b128 v[174:177], v138 offset:53248
	ds_read_b128 v[178:181], v138 offset:54272
	ds_read_b128 v[182:185], v138 offset:55296
	ds_read_b128 v[196:199], v138 offset:56320
	global_load_lds_dwordx4 v[186:187], off
	s_mov_b32 m0, s68
	v_lshl_add_u64 v[186:187], v[222:223], 0, s[88:89]
	global_load_lds_dwordx4 v[186:187], off
	s_barrier
; __device__ __forceinline__ unsigned pk2(float lo, float hi) { unsigned r; asm("v_cvt_pk_bf16_f32 %0, %1, %2" : "=v"(r) : "v"(lo), "v"(hi)); return r; }
; #define PG8_STAGE(bufoff, gbase, voff) do { _Pragma("unroll") for (int _i = 0; _i < 2; ++_i) \
;         __builtin_amdgcn_global_load_lds((const unsigned*)((const char*)(gbase) + (voff)[_i]), (LAS unsigned*)(lds + (bufoff) + ldsw + _i * 8192), 16, 0, 0); } while (0)
; #define PG8_MMA(ai, bj, At, Bt) do { __builtin_amdgcn_s_setprio(1); _Pragma("unroll") for (int m = 0; m < 4; ++m) _Pragma("unroll") for (int n = 0; n < 2; ++n) _Pragma("unroll") for (int k = 0; k < 2; ++k) \
;         acc[ai][bj][m][n] = __builtin_amdgcn_mfma_f32_16x16x32_bf16(Bt[n][k], At[m][k], acc[ai][bj][m][n], 0, 0, 0); __builtin_amdgcn_s_setprio(0); } while (0)
; #define PG8_WAIT_V(n) asm volatile("s_waitcnt vmcnt(" #n ")" ::: "memory")
; #define PG8_WAIT_L(n) asm volatile("s_waitcnt lgkmcnt(" #n ")" ::: "memory")
; #define PG8_BAR __builtin_amdgcn_s_barrier()
; #define PG8_SCHED __builtin_amdgcn_sched_barrier(0)
; template <class Epi>
; __device__ __forceinline__ void gemm_phase(LAS unsigned char* lds, const Gemm g, const StaticOrder& S, const Epi& E) {
;     ...
;             PG8_BAR; PG8_WAIT_L(0); PG8_MMA(1, 0, At, B0); PG8_BAR; PG8_SCHED;
;             PG8_STAGE(PG8_SB(1, 1), b3 + hB, voffB);
;             PG8_WAIT_V(6); PG8_BAR; PG8_MMA(1, 1, At, B1); PG8_BAR;
;     static __device__ __forceinline__ float sg(float g, float u) { return (g * u) * __builtin_amdgcn_rcpf(1.f + __builtin_amdgcn_exp2f(-g)); }
;     __device__ __forceinline__ void operator()(const f32x4 (&acc)[2][2][4][2], const Unit& u, int wr, int wc, int fr, int fq) const {
; #pragma unroll
;         for (int ai = 0; ai < 2; ++ai)
; #pragma unroll
;             for (int m = 0; m < 4; ++m) {
;                 const int row = u.pm * BM + ai * HALF + wr * 64 + m * 16 + fr;
;                 const f32x4 g0 = acc[ai][0][m][0], u0 = acc[ai][0][m][1], g1 = acc[ai][1][m][0], u1 = acc[ai][1][m][1];
;                 u32x4 o; o.x = pk2(sg(g0[0], u0[0]), sg(g0[1], u0[1])); o.y = pk2(sg(g0[2], u0[2]), sg(g0[3], u0[3]));
;                 o.z = pk2(sg(g1[0], u1[0]), sg(g1[1], u1[1])); o.w = pk2(sg(g1[2], u1[2]), sg(g1[3], u1[3]));
;                 *(u32x4*)(O + (size_t)row * DFF + u.pn * 128 + wc * 32 + fq * 8) = o;
	s_waitcnt lgkmcnt(0)
	s_setprio 1
	v_mfma_f32_16x16x32_bf16 v[56:59], v[140:143], v[158:161], v[56:59]
	v_mfma_f32_16x16x32_bf16 v[60:63], v[150:153], v[158:161], v[60:63]
	v_mfma_f32_16x16x32_bf16 v[40:43], v[140:143], v[166:169], v[40:43]
	v_mfma_f32_16x16x32_bf16 v[44:47], v[150:153], v[166:169], v[44:47]
	v_mfma_f32_16x16x32_bf16 v[24:27], v[140:143], v[174:177], v[24:27]
	v_mfma_f32_16x16x32_bf16 v[28:31], v[150:153], v[174:177], v[28:31]
	v_mfma_f32_16x16x32_bf16 v[8:11], v[140:143], v[182:185], v[8:11]
	v_mfma_f32_16x16x32_bf16 v[12:15], v[150:153], v[182:185], v[12:15]
	v_mfma_f32_16x16x32_bf16 v[56:59], v[146:149], v[162:165], v[56:59]
	v_mfma_f32_16x16x32_bf16 v[60:63], v[154:157], v[162:165], v[60:63]
	v_mfma_f32_16x16x32_bf16 v[40:43], v[146:149], v[170:173], v[40:43]
	v_mfma_f32_16x16x32_bf16 v[44:47], v[154:157], v[170:173], v[44:47]
	v_mfma_f32_16x16x32_bf16 v[24:27], v[146:149], v[178:181], v[24:27]
	v_mfma_f32_16x16x32_bf16 v[28:31], v[154:157], v[178:181], v[28:31]
	v_mfma_f32_16x16x32_bf16 v[8:11], v[146:149], v[196:199], v[8:11]
	v_mfma_f32_16x16x32_bf16 v[12:15], v[154:157], v[196:199], v[12:15]
	s_setprio 0
	s_barrier
	s_add_u32 s16, s16, 0x40080
	s_addc_u32 s17, s17, 0
	s_add_i32 s20, s20, s35
	s_mov_b32 m0, s20
	v_lshl_add_u64 v[140:141], s[16:17], 0, v[130:131]
	global_load_lds_dwordx4 v[140:141], off
	s_add_i32 m0, s20, 0x2000
	v_lshl_add_u64 v[140:141], s[16:17], 0, v[128:129]
	global_load_lds_dwordx4 v[140:141], off
	s_waitcnt vmcnt(6)
	s_barrier
	s_setprio 1
	v_mfma_f32_16x16x32_bf16 v[48:51], v[200:203], v[158:161], v[48:51]
	v_mfma_f32_16x16x32_bf16 v[52:55], v[214:217], v[158:161], v[52:55]
	v_mfma_f32_16x16x32_bf16 v[32:35], v[200:203], v[166:169], v[32:35]
	v_mfma_f32_16x16x32_bf16 v[36:39], v[214:217], v[166:169], v[36:39]
	v_mfma_f32_16x16x32_bf16 v[16:19], v[200:203], v[174:177], v[16:19]
	v_mfma_f32_16x16x32_bf16 v[20:23], v[214:217], v[174:177], v[20:23]
	v_mfma_f32_16x16x32_bf16 v[0:3], v[200:203], v[182:185], v[0:3]
	v_mfma_f32_16x16x32_bf16 v[4:7], v[214:217], v[182:185], v[4:7]
	v_mfma_f32_16x16x32_bf16 v[48:51], v[204:207], v[162:165], v[48:51]
	v_mfma_f32_16x16x32_bf16 v[52:55], v[218:221], v[162:165], v[52:55]
	v_mfma_f32_16x16x32_bf16 v[32:35], v[204:207], v[170:173], v[32:35]
	v_mfma_f32_16x16x32_bf16 v[36:39], v[218:221], v[170:173], v[36:39]
	v_mfma_f32_16x16x32_bf16 v[16:19], v[204:207], v[178:181], v[16:19]
	v_mfma_f32_16x16x32_bf16 v[20:23], v[218:221], v[178:181], v[20:23]
	v_mfma_f32_16x16x32_bf16 v[0:3], v[204:207], v[196:199], v[0:3]
	v_mfma_f32_16x16x32_bf16 v[4:7], v[218:221], v[196:199], v[4:7]
	s_setprio 0
	s_add_i32 s78, s78, 2
	s_add_u32 s12, s12, 0x100
	s_addc_u32 s13, s13, 0
	s_add_u32 s25, s25, 0x100
	s_addc_u32 s77, s77, 0
	s_cmp_gt_u32 s78, 13
	s_barrier
	s_cbranch_scc0 .LBB0_281
	v_mul_f32_e32 v124, v120, v124
	v_exp_f32_e64 v120, -v120
	v_mul_f32_e32 v108, v104, v108
	v_exp_f32_e64 v104, -v104
	v_mul_f32_e32 v92, v88, v92
	v_add_f32_e32 v120, 1.0, v120
	v_rcp_f32_e32 v120, v120
	v_add_f32_e32 v104, 1.0, v104
	v_rcp_f32_e32 v104, v104
	v_exp_f32_e64 v88, -v88
	v_mul_f32_e32 v120, v124, v120
	v_mul_f32_e32 v124, v121, v125
	v_exp_f32_e64 v121, -v121
	v_mul_f32_e32 v104, v108, v104
	v_mul_f32_e32 v108, v105, v109
	v_exp_f32_e64 v105, -v105
	v_add_f32_e32 v121, 1.0, v121
	v_rcp_f32_e32 v121, v121
	v_add_f32_e32 v88, 1.0, v88
	v_rcp_f32_e32 v88, v88
	v_mul_f32_e32 v76, v72, v76
	v_exp_f32_e64 v72, -v72
	v_mul_f32_e32 v121, v124, v121
	v_cvt_pk_bf16_f32 v120, v120, v121
	v_mul_f32_e32 v121, v122, v126
	v_exp_f32_e64 v122, -v122
	v_mul_f32_e32 v116, v112, v116
	v_exp_f32_e64 v112, -v112
	v_add_f32_e32 v105, 1.0, v105
	v_rcp_f32_e32 v105, v105
	v_mul_f32_e32 v88, v92, v88
	v_mul_f32_e32 v92, v89, v93
	v_exp_f32_e64 v89, -v89
	v_add_f32_e32 v72, 1.0, v72
	v_rcp_f32_e32 v72, v72
	v_mul_f32_e32 v60, v56, v60
	v_exp_f32_e64 v56, -v56
	v_add_f32_e32 v122, 1.0, v122
	v_add_f32_e32 v112, 1.0, v112
	v_rcp_f32_e32 v122, v122
	v_rcp_f32_e32 v112, v112
	v_mul_f32_e32 v105, v108, v105
	v_add_f32_e32 v89, 1.0, v89
	v_cvt_pk_bf16_f32 v104, v104, v105
	v_mul_f32_e32 v105, v106, v110
	v_exp_f32_e64 v106, -v106
	v_mul_f32_e32 v100, v96, v100
	v_exp_f32_e64 v96, -v96
	v_rcp_f32_e32 v89, v89
	v_mul_f32_e32 v72, v76, v72
	v_mul_f32_e32 v76, v73, v77
	v_exp_f32_e64 v73, -v73
	v_add_f32_e32 v56, 1.0, v56
	v_rcp_f32_e32 v56, v56
	v_mul_f32_e32 v44, v40, v44
	v_exp_f32_e64 v40, -v40
	v_mul_f32_e32 v121, v121, v122
	v_mul_f32_e32 v122, v123, v127
	v_exp_f32_e64 v123, -v123
	v_mul_f32_e32 v112, v116, v112
	v_mul_f32_e32 v116, v113, v117
	v_exp_f32_e64 v113, -v113
	v_add_f32_e32 v106, 1.0, v106
	v_add_f32_e32 v96, 1.0, v96
	v_mul_f32_e32 v89, v92, v89
	v_add_f32_e32 v73, 1.0, v73
	v_rcp_f32_e32 v106, v106
	v_rcp_f32_e32 v96, v96
	v_cvt_pk_bf16_f32 v88, v88, v89
	v_mul_f32_e32 v89, v90, v94
	v_exp_f32_e64 v90, -v90
	v_mul_f32_e32 v84, v80, v84
	v_exp_f32_e64 v80, -v80
	v_rcp_f32_e32 v73, v73
	v_mul_f32_e32 v56, v60, v56
	v_mul_f32_e32 v60, v57, v61
	v_exp_f32_e64 v57, -v57
	v_add_f32_e32 v40, 1.0, v40
	v_rcp_f32_e32 v40, v40
	v_mul_f32_e32 v28, v24, v28
	v_exp_f32_e64 v24, -v24
	v_add_f32_e32 v123, 1.0, v123
	v_add_f32_e32 v113, 1.0, v113
	v_rcp_f32_e32 v123, v123
	v_rcp_f32_e32 v113, v113
	v_mul_f32_e32 v105, v105, v106
	v_mul_f32_e32 v106, v107, v111
	v_exp_f32_e64 v107, -v107
	v_mul_f32_e32 v96, v100, v96
	v_mul_f32_e32 v100, v97, v101
	v_exp_f32_e64 v97, -v97
	v_add_f32_e32 v90, 1.0, v90
	v_add_f32_e32 v80, 1.0, v80
	v_mul_f32_e32 v73, v76, v73
	v_add_f32_e32 v57, 1.0, v57
	v_rcp_f32_e32 v90, v90
	v_rcp_f32_e32 v80, v80
	v_cvt_pk_bf16_f32 v72, v72, v73
	v_mul_f32_e32 v73, v74, v78
	v_exp_f32_e64 v74, -v74
; __device__ __forceinline__ unsigned pk2(float lo, float hi) { unsigned r; asm("v_cvt_pk_bf16_f32 %0, %1, %2" : "=v"(r) : "v"(lo), "v"(hi)); return r; }
;     static __device__ __forceinline__ float sg(float g, float u) { return (g * u) * __builtin_amdgcn_rcpf(1.f + __builtin_amdgcn_exp2f(-g)); }
;     __device__ __forceinline__ void operator()(const f32x4 (&acc)[2][2][4][2], const Unit& u, int wr, int wc, int fr, int fq) const {
; #pragma unroll
;         for (int ai = 0; ai < 2; ++ai)
; #pragma unroll
;             for (int m = 0; m < 4; ++m) {
;                 const int row = u.pm * BM + ai * HALF + wr * 64 + m * 16 + fr;
;                 const f32x4 g0 = acc[ai][0][m][0], u0 = acc[ai][0][m][1], g1 = acc[ai][1][m][0], u1 = acc[ai][1][m][1];
;                 u32x4 o; o.x = pk2(sg(g0[0], u0[0]), sg(g0[1], u0[1])); o.y = pk2(sg(g0[2], u0[2]), sg(g0[3], u0[3]));
;                 o.z = pk2(sg(g1[0], u1[0]), sg(g1[1], u1[1])); o.w = pk2(sg(g1[2], u1[2]), sg(g1[3], u1[3]));
;                 *(u32x4*)(O + (size_t)row * DFF + u.pn * 128 + wc * 32 + fq * 8) = o;
;             }
	v_mul_f32_e32 v68, v64, v68
	v_exp_f32_e64 v64, -v64
	v_rcp_f32_e32 v57, v57
	v_mul_f32_e32 v40, v44, v40
	v_mul_f32_e32 v44, v41, v45
	v_exp_f32_e64 v41, -v41
	v_add_f32_e32 v24, 1.0, v24
	v_rcp_f32_e32 v24, v24
	v_mul_f32_e32 v12, v8, v12
	v_exp_f32_e64 v8, -v8
	v_mul_f32_e32 v122, v122, v123
	v_mul_f32_e32 v113, v116, v113
	v_cvt_pk_bf16_f32 v121, v121, v122
	v_cvt_pk_bf16_f32 v122, v112, v113
	v_exp_f32_e64 v113, -v114
	v_add_f32_e32 v107, 1.0, v107
	v_add_f32_e32 v97, 1.0, v97
	v_mul_f32_e32 v112, v114, v118
	v_exp_f32_e64 v114, -v115
	v_rcp_f32_e32 v107, v107
	v_rcp_f32_e32 v97, v97
	v_mul_f32_e32 v89, v89, v90
	v_mul_f32_e32 v90, v91, v95
	v_exp_f32_e64 v91, -v91
	v_mul_f32_e32 v80, v84, v80
	v_mul_f32_e32 v84, v81, v85
	v_exp_f32_e64 v81, -v81
	v_add_f32_e32 v74, 1.0, v74
	v_add_f32_e32 v64, 1.0, v64
	v_mul_f32_e32 v57, v60, v57
	v_add_f32_e32 v41, 1.0, v41
	v_rcp_f32_e32 v74, v74
	v_rcp_f32_e32 v64, v64
	v_cvt_pk_bf16_f32 v56, v56, v57
	v_mul_f32_e32 v57, v58, v62
	v_exp_f32_e64 v58, -v58
	v_mul_f32_e32 v52, v48, v52
	v_exp_f32_e64 v48, -v48
	v_rcp_f32_e32 v41, v41
	v_mul_f32_e32 v24, v28, v24
	v_mul_f32_e32 v28, v25, v29
	v_exp_f32_e64 v25, -v25
	v_add_f32_e32 v8, 1.0, v8
	v_rcp_f32_e32 v8, v8
	v_add_f32_e32 v113, 1.0, v113
	v_rcp_f32_e32 v113, v113
	v_add_f32_e32 v114, 1.0, v114
	v_mul_f32_e32 v106, v106, v107
	v_mul_f32_e32 v97, v100, v97
	v_add_f32_e32 v91, 1.0, v91
	v_add_f32_e32 v81, 1.0, v81
	v_rcp_f32_e32 v114, v114
	v_cvt_pk_bf16_f32 v105, v105, v106
	v_cvt_pk_bf16_f32 v106, v96, v97
	v_exp_f32_e64 v97, -v98
	v_rcp_f32_e32 v91, v91
	v_rcp_f32_e32 v81, v81
	v_mul_f32_e32 v73, v73, v74
	v_mul_f32_e32 v74, v75, v79
	v_exp_f32_e64 v75, -v75
	v_mul_f32_e32 v64, v68, v64
	v_mul_f32_e32 v68, v65, v69
	v_exp_f32_e64 v65, -v65
	v_add_f32_e32 v58, 1.0, v58
	v_add_f32_e32 v48, 1.0, v48
	v_mul_f32_e32 v41, v44, v41
	v_add_f32_e32 v25, 1.0, v25
	v_mul_f32_e32 v96, v98, v102
	v_exp_f32_e64 v98, -v99
	v_rcp_f32_e32 v58, v58
	v_rcp_f32_e32 v48, v48
	v_cvt_pk_bf16_f32 v40, v40, v41
	v_mul_f32_e32 v41, v42, v46
	v_exp_f32_e64 v42, -v42
	v_mul_f32_e32 v36, v32, v36
	v_exp_f32_e64 v32, -v32
	v_rcp_f32_e32 v25, v25
	v_mul_f32_e32 v8, v12, v8
	v_mul_f32_e32 v12, v9, v13
	v_exp_f32_e64 v9, -v9
	v_mul_f32_e32 v112, v112, v113
	v_mul_f32_e32 v113, v115, v119
	s_lshl_b32 s12, s15, 7
	v_mul_f32_e32 v113, v113, v114
	v_add_f32_e32 v97, 1.0, v97
	v_mul_f32_e32 v90, v90, v91
	v_mul_f32_e32 v81, v84, v81
	v_add_f32_e32 v75, 1.0, v75
	v_add_f32_e32 v65, 1.0, v65
	v_lshl_add_u32 v139, s71, 8, v136
	s_ashr_i32 s13, s12, 31
	v_cvt_pk_bf16_f32 v123, v112, v113
	v_mov_b64_e32 v[112:113], s[4:5]
	v_rcp_f32_e32 v97, v97
	v_add_f32_e32 v98, 1.0, v98
	v_cvt_pk_bf16_f32 v89, v89, v90
	v_cvt_pk_bf16_f32 v90, v80, v81
	v_exp_f32_e64 v81, -v82
	v_rcp_f32_e32 v75, v75
	v_rcp_f32_e32 v65, v65
	v_mul_f32_e32 v57, v57, v58
	v_mul_f32_e32 v58, v59, v63
	v_exp_f32_e64 v59, -v59
	v_mul_f32_e32 v48, v52, v48
	v_mul_f32_e32 v52, v49, v53
	v_exp_f32_e64 v49, -v49
	v_add_f32_e32 v42, 1.0, v42
	v_add_f32_e32 v32, 1.0, v32
	v_mul_f32_e32 v25, v28, v25
	v_add_f32_e32 v9, 1.0, v9
	v_mad_i64_i32 v[114:115], s[16:17], v139, s33, v[112:113]
	s_lshl_b64 s[12:13], s[12:13], 1
	v_rcp_f32_e32 v98, v98
	v_mul_f32_e32 v80, v82, v86
	v_exp_f32_e64 v82, -v83
	v_rcp_f32_e32 v42, v42
	v_rcp_f32_e32 v32, v32
	v_cvt_pk_bf16_f32 v24, v24, v25
	v_mul_f32_e32 v25, v26, v30
	v_exp_f32_e64 v26, -v26
	v_mul_f32_e32 v20, v16, v20
	v_exp_f32_e64 v16, -v16
	v_rcp_f32_e32 v9, v9
	v_lshl_add_u64 v[114:115], v[114:115], 0, s[12:13]
	v_lshl_add_u64 v[114:115], v[114:115], 0, s[66:67]
	v_lshl_add_u64 v[114:115], v[114:115], 0, v[144:145]
	v_mul_f32_e32 v96, v96, v97
	v_mul_f32_e32 v97, v99, v103
	v_add_f32_e32 v81, 1.0, v81
	v_mul_f32_e32 v74, v74, v75
	v_mul_f32_e32 v65, v68, v65
	v_add_f32_e32 v59, 1.0, v59
	v_add_f32_e32 v49, 1.0, v49
	global_store_dwordx4 v[114:115], v[120:123], off
	v_or_b32_e32 v114, 16, v139
	v_mul_f32_e32 v97, v97, v98
	v_rcp_f32_e32 v81, v81
	v_add_f32_e32 v82, 1.0, v82
	v_cvt_pk_bf16_f32 v73, v73, v74
	v_cvt_pk_bf16_f32 v74, v64, v65
	v_exp_f32_e64 v65, -v66
	v_rcp_f32_e32 v59, v59
	v_rcp_f32_e32 v49, v49
	v_mul_f32_e32 v41, v41, v42
	v_mul_f32_e32 v42, v43, v47
	v_exp_f32_e64 v43, -v43
	v_mul_f32_e32 v32, v36, v32
	v_mul_f32_e32 v36, v33, v37
	v_exp_f32_e64 v33, -v33
	v_add_f32_e32 v26, 1.0, v26
	v_add_f32_e32 v16, 1.0, v16
	v_mul_f32_e32 v9, v12, v9
	v_cvt_pk_bf16_f32 v107, v96, v97
	v_mad_i64_i32 v[96:97], s[16:17], v114, s33, v[112:113]
	v_rcp_f32_e32 v82, v82
	v_mul_f32_e32 v64, v66, v70
	v_exp_f32_e64 v66, -v67
	v_rcp_f32_e32 v26, v26
	v_rcp_f32_e32 v16, v16
	v_cvt_pk_bf16_f32 v8, v8, v9
	v_mul_f32_e32 v9, v10, v14
	v_exp_f32_e64 v10, -v10
	v_mul_f32_e32 v4, v0, v4
	v_exp_f32_e64 v0, -v0
	v_lshl_add_u64 v[96:97], v[96:97], 0, s[12:13]
; __device__ __forceinline__ unsigned pk2(float lo, float hi) { unsigned r; asm("v_cvt_pk_bf16_f32 %0, %1, %2" : "=v"(r) : "v"(lo), "v"(hi)); return r; }
; #define PG8_WAIT_V(n) asm volatile("s_waitcnt vmcnt(" #n ")" ::: "memory")
; #define PG8_BAR __builtin_amdgcn_s_barrier()
;     static __device__ __forceinline__ float sg(float g, float u) { return (g * u) * __builtin_amdgcn_rcpf(1.f + __builtin_amdgcn_exp2f(-g)); }
; template <class Epi>
; __device__ __forceinline__ void gemm_phase(LAS unsigned char* lds, const Gemm g, const StaticOrder& S, const Epi& E) {
;     ...
;         E(acc, cur, wr, wc, fr, fq);
;         if (!has_next) break;
; #pragma unroll
;         for (int a = 0; a < 2; ++a)
; #pragma unroll
;             for (int b = 0; b < 2; ++b)
; #pragma unroll
;                 for (int m = 0; m < 4; ++m)
; #pragma unroll
;                     for (int n = 0; n < 2; ++n) acc[a][b][m][n] = (f32x4){0.f, 0.f, 0.f, 0.f};
;         cur = nxt; cA = nA; cB = nB; ++ui;
;     }
;     PG8_WAIT_V(0);
;     if (wr == 0) PG8_BAR;
;     PG8_BAR;
;     __device__ __forceinline__ void operator()(const f32x4 (&acc)[2][2][4][2], const Unit& u, int wr, int wc, int fr, int fq) const {
; #pragma unroll
;         for (int ai = 0; ai < 2; ++ai)
; #pragma unroll
;             for (int m = 0; m < 4; ++m) {
;                 const int row = u.pm * BM + ai * HALF + wr * 64 + m * 16 + fr;
;                 const f32x4 g0 = acc[ai][0][m][0], u0 = acc[ai][0][m][1], g1 = acc[ai][1][m][0], u1 = acc[ai][1][m][1];
;                 u32x4 o; o.x = pk2(sg(g0[0], u0[0]), sg(g0[1], u0[1])); o.y = pk2(sg(g0[2], u0[2]), sg(g0[3], u0[3]));
;                 o.z = pk2(sg(g1[0], u1[0]), sg(g1[1], u1[1])); o.w = pk2(sg(g1[2], u1[2]), sg(g1[3], u1[3]));
;                 *(u32x4*)(O + (size_t)row * DFF + u.pn * 128 + wc * 32 + fq * 8) = o;
;             }
	v_lshl_add_u64 v[96:97], v[96:97], 0, s[66:67]
	v_lshl_add_u64 v[96:97], v[96:97], 0, v[144:145]
	v_mul_f32_e32 v80, v80, v81
	v_mul_f32_e32 v81, v83, v87
	v_add_f32_e32 v65, 1.0, v65
	v_mul_f32_e32 v58, v58, v59
	v_mul_f32_e32 v49, v52, v49
	v_add_f32_e32 v43, 1.0, v43
	v_add_f32_e32 v33, 1.0, v33
	global_store_dwordx4 v[96:97], v[104:107], off
	v_or_b32_e32 v96, 32, v139
	v_mul_f32_e32 v81, v81, v82
	v_rcp_f32_e32 v65, v65
	v_add_f32_e32 v66, 1.0, v66
	v_cvt_pk_bf16_f32 v57, v57, v58
	v_cvt_pk_bf16_f32 v58, v48, v49
	v_exp_f32_e64 v49, -v50
	v_rcp_f32_e32 v43, v43
	v_rcp_f32_e32 v33, v33
	v_mul_f32_e32 v25, v25, v26
	v_mul_f32_e32 v26, v27, v31
	v_exp_f32_e64 v27, -v27
	v_mul_f32_e32 v16, v20, v16
	v_mul_f32_e32 v20, v17, v21
	v_exp_f32_e64 v17, -v17
	v_add_f32_e32 v10, 1.0, v10
	v_add_f32_e32 v0, 1.0, v0
	v_cvt_pk_bf16_f32 v91, v80, v81
	v_mad_i64_i32 v[80:81], s[16:17], v96, s33, v[112:113]
	v_rcp_f32_e32 v66, v66
	v_mul_f32_e32 v48, v50, v54
	v_exp_f32_e64 v50, -v51
	v_rcp_f32_e32 v10, v10
	v_rcp_f32_e32 v0, v0
	v_lshl_add_u64 v[80:81], v[80:81], 0, s[12:13]
	v_lshl_add_u64 v[80:81], v[80:81], 0, s[66:67]
	v_lshl_add_u64 v[80:81], v[80:81], 0, v[144:145]
	v_mul_f32_e32 v64, v64, v65
	v_mul_f32_e32 v65, v67, v71
	v_add_f32_e32 v49, 1.0, v49
	v_mul_f32_e32 v42, v42, v43
	v_mul_f32_e32 v33, v36, v33
	v_add_f32_e32 v27, 1.0, v27
	v_add_f32_e32 v17, 1.0, v17
	global_store_dwordx4 v[80:81], v[88:91], off
	v_or_b32_e32 v80, 48, v139
	v_mul_f32_e32 v65, v65, v66
	v_rcp_f32_e32 v49, v49
	v_add_f32_e32 v50, 1.0, v50
	v_cvt_pk_bf16_f32 v41, v41, v42
	v_cvt_pk_bf16_f32 v42, v32, v33
	v_exp_f32_e64 v33, -v34
	v_rcp_f32_e32 v27, v27
	v_rcp_f32_e32 v17, v17
	v_mul_f32_e32 v9, v9, v10
	v_mul_f32_e32 v10, v11, v15
	v_exp_f32_e64 v11, -v11
	v_mul_f32_e32 v0, v4, v0
	v_mul_f32_e32 v4, v1, v5
	v_exp_f32_e64 v1, -v1
	v_cvt_pk_bf16_f32 v75, v64, v65
	v_mad_i64_i32 v[64:65], s[16:17], v80, s33, v[112:113]
	v_rcp_f32_e32 v50, v50
	v_mul_f32_e32 v32, v34, v38
	v_exp_f32_e64 v34, -v35
	v_lshl_add_u64 v[64:65], v[64:65], 0, s[12:13]
	v_lshl_add_u64 v[64:65], v[64:65], 0, s[66:67]
	v_lshl_add_u64 v[64:65], v[64:65], 0, v[144:145]
	v_mul_f32_e32 v48, v48, v49
	v_mul_f32_e32 v49, v51, v55
	v_add_f32_e32 v33, 1.0, v33
	v_mul_f32_e32 v26, v26, v27
	v_mul_f32_e32 v17, v20, v17
	v_add_f32_e32 v11, 1.0, v11
	v_add_f32_e32 v1, 1.0, v1
	global_store_dwordx4 v[64:65], v[72:75], off
	v_add_u32_e32 v64, 0x80, v139
	v_mul_f32_e32 v49, v49, v50
	v_rcp_f32_e32 v33, v33
	v_add_f32_e32 v34, 1.0, v34
	v_cvt_pk_bf16_f32 v25, v25, v26
	v_cvt_pk_bf16_f32 v26, v16, v17
	v_exp_f32_e64 v17, -v18
	v_rcp_f32_e32 v11, v11
	v_rcp_f32_e32 v1, v1
	v_cvt_pk_bf16_f32 v59, v48, v49
	v_mad_i64_i32 v[48:49], s[16:17], v64, s33, v[112:113]
	v_rcp_f32_e32 v34, v34
	v_mul_f32_e32 v16, v18, v22
	v_exp_f32_e64 v18, -v19
	v_lshl_add_u64 v[48:49], v[48:49], 0, s[12:13]
	v_lshl_add_u64 v[48:49], v[48:49], 0, s[66:67]
	v_lshl_add_u64 v[48:49], v[48:49], 0, v[144:145]
	v_mul_f32_e32 v32, v32, v33
	v_mul_f32_e32 v33, v35, v39
	v_add_f32_e32 v17, 1.0, v17
	v_mul_f32_e32 v10, v10, v11
	v_mul_f32_e32 v1, v4, v1
	global_store_dwordx4 v[48:49], v[56:59], off
	v_add_u32_e32 v48, 0x90, v139
	v_mul_f32_e32 v33, v33, v34
	v_rcp_f32_e32 v17, v17
	v_add_f32_e32 v18, 1.0, v18
	v_cvt_pk_bf16_f32 v9, v9, v10
	v_cvt_pk_bf16_f32 v10, v0, v1
	v_exp_f32_e64 v1, -v2
	v_cvt_pk_bf16_f32 v43, v32, v33
	v_mad_i64_i32 v[32:33], s[16:17], v48, s33, v[112:113]
	v_rcp_f32_e32 v18, v18
	v_mul_f32_e32 v0, v2, v6
	v_exp_f32_e64 v2, -v3
	v_lshl_add_u64 v[32:33], v[32:33], 0, s[12:13]
	v_lshl_add_u64 v[32:33], v[32:33], 0, s[66:67]
	v_lshl_add_u64 v[32:33], v[32:33], 0, v[144:145]
	v_mul_f32_e32 v16, v16, v17
	v_mul_f32_e32 v17, v19, v23
	v_add_f32_e32 v1, 1.0, v1
	global_store_dwordx4 v[32:33], v[40:43], off
	v_add_u32_e32 v32, 0xa0, v139
	v_mul_f32_e32 v17, v17, v18
	v_rcp_f32_e32 v1, v1
	v_add_f32_e32 v2, 1.0, v2
	v_cvt_pk_bf16_f32 v27, v16, v17
	v_mad_i64_i32 v[16:17], s[16:17], v32, s33, v[112:113]
	v_rcp_f32_e32 v2, v2
	v_lshl_add_u64 v[16:17], v[16:17], 0, s[12:13]
	v_lshl_add_u64 v[16:17], v[16:17], 0, s[66:67]
	v_lshl_add_u64 v[16:17], v[16:17], 0, v[144:145]
	v_mul_f32_e32 v0, v0, v1
	v_mul_f32_e32 v1, v3, v7
	global_store_dwordx4 v[16:17], v[24:27], off
	v_add_u32_e32 v16, 0xb0, v139
	v_mul_f32_e32 v1, v1, v2
	v_cvt_pk_bf16_f32 v11, v0, v1
	v_mad_i64_i32 v[0:1], s[16:17], v16, s33, v[112:113]
	v_lshl_add_u64 v[0:1], v[0:1], 0, s[12:13]
	v_lshl_add_u64 v[0:1], v[0:1], 0, s[66:67]
	v_lshl_add_u64 v[0:1], v[0:1], 0, v[144:145]
	s_and_b64 vcc, exec, s[0:1]
	s_mov_b32 s15, s6
	s_mov_b32 s71, s70
	s_mov_b64 s[16:17], s[10:11]
	s_mov_b64 s[12:13], s[8:9]
	global_store_dwordx4 v[0:1], v[8:11], off
	s_cbranch_vccz .LBB0_278
	s_waitcnt vmcnt(0)
	s_cmpk_gt_u32 s3, 0xff
	s_cbranch_scc1 .LBB0_285
	s_barrier

; #define PG8_STAGE(bufoff, gbase, voff) do { _Pragma("unroll") for (int _i = 0; _i < 2; ++_i) \
;         __builtin_amdgcn_global_load_lds((const unsigned*)((const char*)(gbase) + (voff)[_i]), (LAS unsigned*)(lds + (bufoff) + ldsw + _i * 8192), 16, 0, 0); } while (0)
; #define PG8_LDA(dst, b, h) do { _Pragma("unroll") for (int m = 0; m < 4; ++m) _Pragma("unroll") for (int k = 0; k < 2; ++k) dst[m][k] = *(const LAS bf16x8*)(lds + PG8_SA(b, h) + aoff + m * 2048 + k * 1024); } while (0)
; #define PG8_LDB(dst, b, h) do { _Pragma("unroll") for (int n = 0; n < 2; ++n) _Pragma("unroll") for (int k = 0; k < 2; ++k) dst[n][k] = *(const LAS bf16x8*)(lds + PG8_SB(b, h) + boff + n * 2048 + k * 1024); } while (0)
; #define PG8_MMA(ai, bj, At, Bt) do { __builtin_amdgcn_s_setprio(1); _Pragma("unroll") for (int m = 0; m < 4; ++m) _Pragma("unroll") for (int n = 0; n < 2; ++n) _Pragma("unroll") for (int k = 0; k < 2; ++k) \
;         acc[ai][bj][m][n] = __builtin_amdgcn_mfma_f32_16x16x32_bf16(Bt[n][k], At[m][k], acc[ai][bj][m][n], 0, 0, 0); __builtin_amdgcn_s_setprio(0); } while (0)
; template <class Epi>
; __device__ __forceinline__ void gemm_phase(LAS unsigned char* lds, const Gemm g, const StaticOrder& S, const Epi& E) {
;     ...
;         const bool has_next = S.next(ui + 1, nxt);
;         const char* nA = has_next ? g.arow(nxt.pm) : cA; const char* nB = has_next ? (const char*)g.Bt + (size_t)nxt.pn * tB : cB;
;         for (int t = 0; t < nt; t += 2) {
;             const bool last = (t == nt - 2);
;             const char* a1 = cA + (size_t)(t + 1) * kstep;
;             const char* a2 = last ? nA : cA + (size_t)(t + 2) * kstep; const char* b2 = last ? nB : cB + (size_t)(t + 2) * kstep;
;             const char* a3 = a2 + kstep; const char* b3 = b2 + kstep;
;             PG8_LDB(B0, 0, 0); PG8_SCHED; PG8_LDA(At, 0, 0); PG8_STAGE(PG8_SA(1, 1), a1 + hA, voffA);
;             PG8_WAIT_L(8); PG8_BAR; PG8_WAIT_L(0); PG8_MMA(0, 0, At, B0); PG8_BAR; PG8_SCHED;
;             PG8_LDB(B1, 0, 1); PG8_STAGE(PG8_SB(0, 0), b2, voffB);
;             PG8_BAR; PG8_WAIT_L(0); PG8_MMA(0, 1, At, B1); PG8_BAR;
;             PG8_LDA(At, 0, 1); PG8_STAGE(PG8_SA(0, 0), a2, voffA);
;             PG8_BAR; PG8_WAIT_L(0); PG8_MMA(1, 0, At, B0); PG8_BAR; PG8_SCHED;
;             PG8_STAGE(PG8_SB(0, 1), b2 + hB, voffB);
;             PG8_WAIT_V(6); PG8_BAR; PG8_MMA(1, 1, At, B1); PG8_BAR;
.LBB0_349:
	s_add_u32 s12, s10, 0x100
	s_addc_u32 s13, s11, 0
	s_add_i32 s26, 0, 0x10000
	v_add_u32_e32 v142, s26, v139
	ds_read_b128 v[134:137], v142
	ds_read_b128 v[146:149], v142 offset:1024
	ds_read_b128 v[150:153], v142 offset:2048
	ds_read_b128 v[154:157], v142 offset:3072
	s_cmp_eq_u32 s72, 40
	s_cselect_b32 s21, s5, s13
	s_cselect_b32 s20, s4, s12
	s_cselect_b32 s17, s7, s25
	s_cselect_b32 s16, s6, s24
	v_lshl_add_u64 v[142:143], s[10:11], 0, v[130:131]
	s_add_i32 m0, s61, 0xc000
	ds_read_b128 v[158:161], v141
	ds_read_b128 v[162:165], v141 offset:1024
	ds_read_b128 v[166:169], v141 offset:2048
	ds_read_b128 v[170:173], v141 offset:3072
	ds_read_b128 v[174:177], v141 offset:4096
	ds_read_b128 v[178:181], v141 offset:5120
	ds_read_b128 v[182:185], v141 offset:6144
	ds_read_b128 v[196:199], v141 offset:7168
	global_load_lds_dwordx4 v[142:143], off
	s_add_i32 m0, s61, 0xe000
	v_lshl_add_u64 v[142:143], s[10:11], 0, v[132:133]
	global_load_lds_dwordx4 v[142:143], off
	s_waitcnt lgkmcnt(8)
	s_barrier
	s_waitcnt lgkmcnt(0)
	s_setprio 1
	v_mfma_f32_16x16x32_bf16 v[124:127], v[134:137], v[158:161], v[124:127]
	v_mfma_f32_16x16x32_bf16 v[120:123], v[150:153], v[158:161], v[120:123]
	v_mfma_f32_16x16x32_bf16 v[116:119], v[134:137], v[166:169], v[116:119]
	v_mfma_f32_16x16x32_bf16 v[108:111], v[150:153], v[166:169], v[108:111]
	v_mfma_f32_16x16x32_bf16 v[100:103], v[134:137], v[174:177], v[100:103]
	v_mfma_f32_16x16x32_bf16 v[92:95], v[150:153], v[174:177], v[92:95]
	v_mfma_f32_16x16x32_bf16 v[84:87], v[134:137], v[182:185], v[84:87]
	v_mfma_f32_16x16x32_bf16 v[76:79], v[150:153], v[182:185], v[76:79]
	v_mfma_f32_16x16x32_bf16 v[124:127], v[146:149], v[162:165], v[124:127]
	v_mfma_f32_16x16x32_bf16 v[120:123], v[154:157], v[162:165], v[120:123]
	v_mfma_f32_16x16x32_bf16 v[116:119], v[146:149], v[170:173], v[116:119]
	v_mfma_f32_16x16x32_bf16 v[108:111], v[154:157], v[170:173], v[108:111]
	v_mfma_f32_16x16x32_bf16 v[100:103], v[146:149], v[178:181], v[100:103]
	v_mfma_f32_16x16x32_bf16 v[92:95], v[154:157], v[178:181], v[92:95]
	v_mfma_f32_16x16x32_bf16 v[84:87], v[146:149], v[196:199], v[84:87]
	v_mfma_f32_16x16x32_bf16 v[76:79], v[154:157], v[196:199], v[76:79]
	s_setprio 0
	s_barrier
	s_add_i32 s27, 0, 0x14000
	v_add_u32_e32 v142, s27, v139
	s_add_i32 s10, s26, s35
	ds_read_b128 v[200:203], v142
	ds_read_b128 v[204:207], v142 offset:1024
	ds_read_b128 v[214:217], v142 offset:2048
	ds_read_b128 v[218:221], v142 offset:3072
	v_lshl_add_u64 v[142:143], s[16:17], 0, v[144:145]
	s_mov_b32 m0, s10
	v_lshl_add_u64 v[186:187], s[16:17], 0, v[128:129]
	global_load_lds_dwordx4 v[142:143], off
	s_add_i32 m0, s10, 0x2000
	s_nop 0
	global_load_lds_dwordx4 v[186:187], off
	s_barrier
	s_waitcnt lgkmcnt(0)
	s_setprio 1
	v_mfma_f32_16x16x32_bf16 v[112:115], v[200:203], v[158:161], v[112:115]
	v_mfma_f32_16x16x32_bf16 v[104:107], v[214:217], v[158:161], v[104:107]
	v_mfma_f32_16x16x32_bf16 v[96:99], v[200:203], v[166:169], v[96:99]
	v_mfma_f32_16x16x32_bf16 v[88:91], v[214:217], v[166:169], v[88:91]
	v_mfma_f32_16x16x32_bf16 v[80:83], v[200:203], v[174:177], v[80:83]
	v_mfma_f32_16x16x32_bf16 v[72:75], v[214:217], v[174:177], v[72:75]
	v_mfma_f32_16x16x32_bf16 v[68:71], v[200:203], v[182:185], v[68:71]
	v_mfma_f32_16x16x32_bf16 v[64:67], v[214:217], v[182:185], v[64:67]
	v_mfma_f32_16x16x32_bf16 v[112:115], v[204:207], v[162:165], v[112:115]
	v_mfma_f32_16x16x32_bf16 v[104:107], v[218:221], v[162:165], v[104:107]
	v_mfma_f32_16x16x32_bf16 v[96:99], v[204:207], v[170:173], v[96:99]
	v_mfma_f32_16x16x32_bf16 v[88:91], v[218:221], v[170:173], v[88:91]
	v_mfma_f32_16x16x32_bf16 v[80:83], v[204:207], v[178:181], v[80:83]
	v_mfma_f32_16x16x32_bf16 v[72:75], v[218:221], v[178:181], v[72:75]
	v_mfma_f32_16x16x32_bf16 v[68:71], v[204:207], v[196:199], v[68:71]
	v_mfma_f32_16x16x32_bf16 v[64:67], v[218:221], v[196:199], v[64:67]
	s_setprio 0
	s_mov_b32 m0, s61
	v_lshl_add_u64 v[188:189], s[20:21], 0, v[144:145]
	s_barrier
	ds_read_b128 v[158:161], v141 offset:16384
	ds_read_b128 v[162:165], v141 offset:17408
	ds_read_b128 v[166:169], v141 offset:18432
	ds_read_b128 v[170:173], v141 offset:19456
	ds_read_b128 v[174:177], v141 offset:20480
	ds_read_b128 v[178:181], v141 offset:21504
	ds_read_b128 v[182:185], v141 offset:22528
	ds_read_b128 v[196:199], v141 offset:23552
	global_load_lds_dwordx4 v[188:189], off
	s_mov_b32 m0, s62
	v_lshl_add_u64 v[192:193], s[20:21], 0, v[128:129]
	global_load_lds_dwordx4 v[192:193], off
	s_barrier
	s_waitcnt lgkmcnt(0)
	s_setprio 1
	v_mfma_f32_16x16x32_bf16 v[60:63], v[134:137], v[158:161], v[60:63]
	v_mfma_f32_16x16x32_bf16 v[56:59], v[150:153], v[158:161], v[56:59]
	v_mfma_f32_16x16x32_bf16 v[52:55], v[134:137], v[166:169], v[52:55]
	v_mfma_f32_16x16x32_bf16 v[44:47], v[150:153], v[166:169], v[44:47]
	v_mfma_f32_16x16x32_bf16 v[36:39], v[134:137], v[174:177], v[36:39]
	v_mfma_f32_16x16x32_bf16 v[28:31], v[150:153], v[174:177], v[28:31]
	v_mfma_f32_16x16x32_bf16 v[20:23], v[134:137], v[182:185], v[20:23]
	v_mfma_f32_16x16x32_bf16 v[12:15], v[150:153], v[182:185], v[12:15]
	v_mfma_f32_16x16x32_bf16 v[60:63], v[146:149], v[162:165], v[60:63]
	v_mfma_f32_16x16x32_bf16 v[56:59], v[154:157], v[162:165], v[56:59]
	v_mfma_f32_16x16x32_bf16 v[52:55], v[146:149], v[170:173], v[52:55]
	v_mfma_f32_16x16x32_bf16 v[44:47], v[154:157], v[170:173], v[44:47]
	v_mfma_f32_16x16x32_bf16 v[36:39], v[146:149], v[178:181], v[36:39]
	v_mfma_f32_16x16x32_bf16 v[28:31], v[154:157], v[178:181], v[28:31]
	v_mfma_f32_16x16x32_bf16 v[20:23], v[146:149], v[196:199], v[20:23]
	v_mfma_f32_16x16x32_bf16 v[12:15], v[154:157], v[196:199], v[12:15]
	s_setprio 0
	s_barrier
; #define PG8_STAGE(bufoff, gbase, voff) do { _Pragma("unroll") for (int _i = 0; _i < 2; ++_i) \
;         __builtin_amdgcn_global_load_lds((const unsigned*)((const char*)(gbase) + (voff)[_i]), (LAS unsigned*)(lds + (bufoff) + ldsw + _i * 8192), 16, 0, 0); } while (0)
; #define PG8_LDA(dst, b, h) do { _Pragma("unroll") for (int m = 0; m < 4; ++m) _Pragma("unroll") for (int k = 0; k < 2; ++k) dst[m][k] = *(const LAS bf16x8*)(lds + PG8_SA(b, h) + aoff + m * 2048 + k * 1024); } while (0)
; #define PG8_LDB(dst, b, h) do { _Pragma("unroll") for (int n = 0; n < 2; ++n) _Pragma("unroll") for (int k = 0; k < 2; ++k) dst[n][k] = *(const LAS bf16x8*)(lds + PG8_SB(b, h) + boff + n * 2048 + k * 1024); } while (0)
; #define PG8_MMA(ai, bj, At, Bt) do { __builtin_amdgcn_s_setprio(1); _Pragma("unroll") for (int m = 0; m < 4; ++m) _Pragma("unroll") for (int n = 0; n < 2; ++n) _Pragma("unroll") for (int k = 0; k < 2; ++k) \
;         acc[ai][bj][m][n] = __builtin_amdgcn_mfma_f32_16x16x32_bf16(Bt[n][k], At[m][k], acc[ai][bj][m][n], 0, 0, 0); __builtin_amdgcn_s_setprio(0); } while (0)
; #define PG8_WAIT_V(n) asm volatile("s_waitcnt vmcnt(" #n ")" ::: "memory")
; #define PG8_WAIT_L(n) asm volatile("s_waitcnt lgkmcnt(" #n ")" ::: "memory")
; #define PG8_BAR __builtin_amdgcn_s_barrier()
; #define PG8_SCHED __builtin_amdgcn_sched_barrier(0)
; template <class Epi>
; __device__ __forceinline__ void gemm_phase(LAS unsigned char* lds, const Gemm g, const StaticOrder& S, const Epi& E) {
;     ...
;             PG8_WAIT_V(6); PG8_BAR; PG8_MMA(1, 1, At, B1); PG8_BAR;
;             PG8_LDB(B0, 1, 0); PG8_SCHED; PG8_LDA(At, 1, 0); PG8_STAGE(PG8_SA(0, 1), a2 + hA, voffA);
;             PG8_WAIT_L(8); PG8_BAR; PG8_WAIT_L(0); PG8_MMA(0, 0, At, B0); PG8_BAR; PG8_SCHED;
;             PG8_LDB(B1, 1, 1); PG8_STAGE(PG8_SB(1, 0), b3, voffB);
;             PG8_BAR; PG8_WAIT_L(0); PG8_MMA(0, 1, At, B1); PG8_BAR;
;             PG8_LDA(At, 1, 1); PG8_STAGE(PG8_SA(1, 0), a3, voffA);
;             PG8_BAR; PG8_WAIT_L(0); PG8_MMA(1, 0, At, B0); PG8_BAR; PG8_SCHED;
;             PG8_STAGE(PG8_SB(1, 1), b3 + hB, voffB);
;             PG8_WAIT_V(6); PG8_BAR; PG8_MMA(1, 1, At, B1); PG8_BAR;
	s_add_u32 s10, s16, 0xb0000
	s_addc_u32 s11, s17, 0
	s_add_i32 s26, s27, s35
	s_mov_b32 m0, s26
	v_lshl_add_u64 v[134:135], s[10:11], 0, v[144:145]
	global_load_lds_dwordx4 v[134:135], off
	s_add_i32 m0, s26, 0x2000
	v_lshl_add_u64 v[134:135], s[10:11], 0, v[128:129]
	global_load_lds_dwordx4 v[134:135], off
	s_waitcnt vmcnt(6)
	s_barrier
	s_setprio 1
	v_mfma_f32_16x16x32_bf16 v[48:51], v[200:203], v[158:161], v[48:51]
	v_mfma_f32_16x16x32_bf16 v[40:43], v[214:217], v[158:161], v[40:43]
	v_mfma_f32_16x16x32_bf16 v[32:35], v[200:203], v[166:169], v[32:35]
	v_mfma_f32_16x16x32_bf16 v[24:27], v[214:217], v[166:169], v[24:27]
	v_mfma_f32_16x16x32_bf16 v[16:19], v[200:203], v[174:177], v[16:19]
	v_mfma_f32_16x16x32_bf16 v[8:11], v[214:217], v[174:177], v[8:11]
	v_mfma_f32_16x16x32_bf16 v[4:7], v[200:203], v[182:185], v[4:7]
	v_mfma_f32_16x16x32_bf16 v[0:3], v[214:217], v[182:185], v[0:3]
	v_mfma_f32_16x16x32_bf16 v[48:51], v[204:207], v[162:165], v[48:51]
	v_mfma_f32_16x16x32_bf16 v[40:43], v[218:221], v[162:165], v[40:43]
	v_mfma_f32_16x16x32_bf16 v[32:35], v[204:207], v[170:173], v[32:35]
	v_mfma_f32_16x16x32_bf16 v[24:27], v[218:221], v[170:173], v[24:27]
	v_mfma_f32_16x16x32_bf16 v[16:19], v[204:207], v[178:181], v[16:19]
	v_mfma_f32_16x16x32_bf16 v[8:11], v[218:221], v[178:181], v[8:11]
	v_mfma_f32_16x16x32_bf16 v[4:7], v[204:207], v[196:199], v[4:7]
	v_mfma_f32_16x16x32_bf16 v[0:3], v[218:221], v[196:199], v[0:3]
	s_setprio 0
	s_add_i32 s26, 0, 0x18000
	v_add_u32_e32 v154, s26, v139
	s_barrier
	ds_read_b128 v[134:137], v154
	ds_read_b128 v[146:149], v154 offset:1024
	ds_read_b128 v[150:153], v154 offset:2048
	ds_read_b128 v[154:157], v154 offset:3072
	s_add_u32 s10, s20, 0xb0000
	s_addc_u32 s11, s21, 0
	s_mov_b32 m0, s63
	v_lshl_add_u64 v[200:201], s[10:11], 0, v[144:145]
	ds_read_b128 v[158:161], v141 offset:32768
	ds_read_b128 v[162:165], v141 offset:33792
	ds_read_b128 v[166:169], v141 offset:34816
	ds_read_b128 v[170:173], v141 offset:35840
	ds_read_b128 v[174:177], v141 offset:36864
	ds_read_b128 v[178:181], v141 offset:37888
	ds_read_b128 v[182:185], v141 offset:38912
	ds_read_b128 v[196:199], v141 offset:39936
	global_load_lds_dwordx4 v[200:201], off
	s_mov_b32 m0, s64
	v_lshl_add_u64 v[200:201], s[10:11], 0, v[128:129]
	global_load_lds_dwordx4 v[200:201], off
	s_waitcnt lgkmcnt(8)
	s_barrier
	s_waitcnt lgkmcnt(0)
	s_setprio 1
	v_mfma_f32_16x16x32_bf16 v[124:127], v[134:137], v[158:161], v[124:127]
	v_mfma_f32_16x16x32_bf16 v[120:123], v[150:153], v[158:161], v[120:123]
	v_mfma_f32_16x16x32_bf16 v[116:119], v[134:137], v[166:169], v[116:119]
	v_mfma_f32_16x16x32_bf16 v[108:111], v[150:153], v[166:169], v[108:111]
	v_mfma_f32_16x16x32_bf16 v[100:103], v[134:137], v[174:177], v[100:103]
	v_mfma_f32_16x16x32_bf16 v[92:95], v[150:153], v[174:177], v[92:95]
	v_mfma_f32_16x16x32_bf16 v[84:87], v[134:137], v[182:185], v[84:87]
	v_mfma_f32_16x16x32_bf16 v[76:79], v[150:153], v[182:185], v[76:79]
	v_mfma_f32_16x16x32_bf16 v[124:127], v[146:149], v[162:165], v[124:127]
	v_mfma_f32_16x16x32_bf16 v[120:123], v[154:157], v[162:165], v[120:123]
	v_mfma_f32_16x16x32_bf16 v[116:119], v[146:149], v[170:173], v[116:119]
	v_mfma_f32_16x16x32_bf16 v[108:111], v[154:157], v[170:173], v[108:111]
	v_mfma_f32_16x16x32_bf16 v[100:103], v[146:149], v[178:181], v[100:103]
	v_mfma_f32_16x16x32_bf16 v[92:95], v[154:157], v[178:181], v[92:95]
	v_mfma_f32_16x16x32_bf16 v[84:87], v[146:149], v[196:199], v[84:87]
	v_mfma_f32_16x16x32_bf16 v[76:79], v[154:157], v[196:199], v[76:79]
	s_setprio 0
	s_barrier
	s_add_i32 s20, 0, 0x1c000
	s_add_i32 s10, s26, s35
	v_add_u32_e32 v190, s20, v139
	v_lshl_add_u64 v[142:143], v[142:143], 0, s[88:89]
	s_mov_b32 m0, s10
	ds_read_b128 v[200:203], v190
	ds_read_b128 v[204:207], v190 offset:1024
	ds_read_b128 v[214:217], v190 offset:2048
	ds_read_b128 v[218:221], v190 offset:3072
	global_load_lds_dwordx4 v[142:143], off
	s_add_i32 m0, s10, 0x2000
	v_lshl_add_u64 v[142:143], v[186:187], 0, s[88:89]
	global_load_lds_dwordx4 v[142:143], off
	s_barrier
	s_waitcnt lgkmcnt(0)
	s_setprio 1
	v_mfma_f32_16x16x32_bf16 v[112:115], v[200:203], v[158:161], v[112:115]
	v_mfma_f32_16x16x32_bf16 v[104:107], v[214:217], v[158:161], v[104:107]
	v_mfma_f32_16x16x32_bf16 v[96:99], v[200:203], v[166:169], v[96:99]
	v_mfma_f32_16x16x32_bf16 v[88:91], v[214:217], v[166:169], v[88:91]
	v_mfma_f32_16x16x32_bf16 v[80:83], v[200:203], v[174:177], v[80:83]
	v_mfma_f32_16x16x32_bf16 v[72:75], v[214:217], v[174:177], v[72:75]
	v_mfma_f32_16x16x32_bf16 v[68:71], v[200:203], v[182:185], v[68:71]
	v_mfma_f32_16x16x32_bf16 v[64:67], v[214:217], v[182:185], v[64:67]
	v_mfma_f32_16x16x32_bf16 v[112:115], v[204:207], v[162:165], v[112:115]
	v_mfma_f32_16x16x32_bf16 v[104:107], v[218:221], v[162:165], v[104:107]
	v_mfma_f32_16x16x32_bf16 v[96:99], v[204:207], v[170:173], v[96:99]
	v_mfma_f32_16x16x32_bf16 v[88:91], v[218:221], v[170:173], v[88:91]
	v_mfma_f32_16x16x32_bf16 v[80:83], v[204:207], v[178:181], v[80:83]
	v_mfma_f32_16x16x32_bf16 v[72:75], v[218:221], v[178:181], v[72:75]
	v_mfma_f32_16x16x32_bf16 v[68:71], v[204:207], v[196:199], v[68:71]
	v_mfma_f32_16x16x32_bf16 v[64:67], v[218:221], v[196:199], v[64:67]
	s_setprio 0
	s_mov_b32 m0, s65
	v_lshl_add_u64 v[142:143], v[188:189], 0, s[88:89]
	s_barrier
	ds_read_b128 v[158:161], v141 offset:49152
	ds_read_b128 v[162:165], v141 offset:50176
	ds_read_b128 v[166:169], v141 offset:51200
	ds_read_b128 v[170:173], v141 offset:52224
	ds_read_b128 v[174:177], v141 offset:53248
	ds_read_b128 v[178:181], v141 offset:54272
	ds_read_b128 v[182:185], v141 offset:55296
	ds_read_b128 v[196:199], v141 offset:56320
	global_load_lds_dwordx4 v[142:143], off
	s_mov_b32 m0, s66
	v_lshl_add_u64 v[142:143], v[192:193], 0, s[88:89]
	global_load_lds_dwordx4 v[142:143], off
	s_barrier
; #define PG8_STAGE(bufoff, gbase, voff) do { _Pragma("unroll") for (int _i = 0; _i < 2; ++_i) \
;         __builtin_amdgcn_global_load_lds((const unsigned*)((const char*)(gbase) + (voff)[_i]), (LAS unsigned*)(lds + (bufoff) + ldsw + _i * 8192), 16, 0, 0); } while (0)
; #define PG8_MMA(ai, bj, At, Bt) do { __builtin_amdgcn_s_setprio(1); _Pragma("unroll") for (int m = 0; m < 4; ++m) _Pragma("unroll") for (int n = 0; n < 2; ++n) _Pragma("unroll") for (int k = 0; k < 2; ++k) \
;         acc[ai][bj][m][n] = __builtin_amdgcn_mfma_f32_16x16x32_bf16(Bt[n][k], At[m][k], acc[ai][bj][m][n], 0, 0, 0); __builtin_amdgcn_s_setprio(0); } while (0)
; #define PG8_WAIT_V(n) asm volatile("s_waitcnt vmcnt(" #n ")" ::: "memory")
; #define PG8_WAIT_L(n) asm volatile("s_waitcnt lgkmcnt(" #n ")" ::: "memory")
; #define PG8_BAR __builtin_amdgcn_s_barrier()
; #define PG8_SCHED __builtin_amdgcn_sched_barrier(0)
; template <class Epi>
; __device__ __forceinline__ void gemm_phase(LAS unsigned char* lds, const Gemm g, const StaticOrder& S, const Epi& E) {
;     ...
;             PG8_BAR; PG8_WAIT_L(0); PG8_MMA(1, 0, At, B0); PG8_BAR; PG8_SCHED;
;             PG8_STAGE(PG8_SB(1, 1), b3 + hB, voffB);
;             PG8_WAIT_V(6); PG8_BAR; PG8_MMA(1, 1, At, B1); PG8_BAR;
	s_waitcnt lgkmcnt(0)
	s_setprio 1
	v_mfma_f32_16x16x32_bf16 v[60:63], v[134:137], v[158:161], v[60:63]
	v_mfma_f32_16x16x32_bf16 v[56:59], v[150:153], v[158:161], v[56:59]
	v_mfma_f32_16x16x32_bf16 v[52:55], v[134:137], v[166:169], v[52:55]
	v_mfma_f32_16x16x32_bf16 v[44:47], v[150:153], v[166:169], v[44:47]
	v_mfma_f32_16x16x32_bf16 v[36:39], v[134:137], v[174:177], v[36:39]
	v_mfma_f32_16x16x32_bf16 v[28:31], v[150:153], v[174:177], v[28:31]
	v_mfma_f32_16x16x32_bf16 v[20:23], v[134:137], v[182:185], v[20:23]
	v_mfma_f32_16x16x32_bf16 v[12:15], v[150:153], v[182:185], v[12:15]
	v_mfma_f32_16x16x32_bf16 v[60:63], v[146:149], v[162:165], v[60:63]
	v_mfma_f32_16x16x32_bf16 v[56:59], v[154:157], v[162:165], v[56:59]
	v_mfma_f32_16x16x32_bf16 v[52:55], v[146:149], v[170:173], v[52:55]
	v_mfma_f32_16x16x32_bf16 v[44:47], v[154:157], v[170:173], v[44:47]
	v_mfma_f32_16x16x32_bf16 v[36:39], v[146:149], v[178:181], v[36:39]
	v_mfma_f32_16x16x32_bf16 v[28:31], v[154:157], v[178:181], v[28:31]
	v_mfma_f32_16x16x32_bf16 v[20:23], v[146:149], v[196:199], v[20:23]
	v_mfma_f32_16x16x32_bf16 v[12:15], v[154:157], v[196:199], v[12:15]
	s_setprio 0
	s_barrier
	s_add_u32 s10, s16, 0xb0080
	s_addc_u32 s11, s17, 0
	s_add_i32 s16, s20, s35
	s_mov_b32 m0, s16
	v_lshl_add_u64 v[134:135], s[10:11], 0, v[144:145]
	global_load_lds_dwordx4 v[134:135], off
	s_add_i32 m0, s16, 0x2000
	v_lshl_add_u64 v[134:135], s[10:11], 0, v[128:129]
	global_load_lds_dwordx4 v[134:135], off
	s_waitcnt vmcnt(6)
	s_barrier
	s_setprio 1
	v_mfma_f32_16x16x32_bf16 v[48:51], v[200:203], v[158:161], v[48:51]
	v_mfma_f32_16x16x32_bf16 v[40:43], v[214:217], v[158:161], v[40:43]
	v_mfma_f32_16x16x32_bf16 v[32:35], v[200:203], v[166:169], v[32:35]
	v_mfma_f32_16x16x32_bf16 v[24:27], v[214:217], v[166:169], v[24:27]
	v_mfma_f32_16x16x32_bf16 v[16:19], v[200:203], v[174:177], v[16:19]
	v_mfma_f32_16x16x32_bf16 v[8:11], v[214:217], v[174:177], v[8:11]
	v_mfma_f32_16x16x32_bf16 v[4:7], v[200:203], v[182:185], v[4:7]
	v_mfma_f32_16x16x32_bf16 v[0:3], v[214:217], v[182:185], v[0:3]
	v_mfma_f32_16x16x32_bf16 v[48:51], v[204:207], v[162:165], v[48:51]
	v_mfma_f32_16x16x32_bf16 v[40:43], v[218:221], v[162:165], v[40:43]
	v_mfma_f32_16x16x32_bf16 v[32:35], v[204:207], v[170:173], v[32:35]
	v_mfma_f32_16x16x32_bf16 v[24:27], v[218:221], v[170:173], v[24:27]
	v_mfma_f32_16x16x32_bf16 v[16:19], v[204:207], v[178:181], v[16:19]
	v_mfma_f32_16x16x32_bf16 v[8:11], v[218:221], v[178:181], v[8:11]
	v_mfma_f32_16x16x32_bf16 v[4:7], v[204:207], v[196:199], v[4:7]
	v_mfma_f32_16x16x32_bf16 v[0:3], v[218:221], v[196:199], v[0:3]
	s_setprio 0
	s_add_i32 s72, s72, 2
	s_add_u32 s24, s24, 0x100
	s_addc_u32 s25, s25, 0
	s_cmp_gt_u32 s72, 41
	s_mov_b64 s[10:11], s[12:13]
	s_barrier
	s_cbranch_scc0 .LBB0_349
; __device__ __forceinline__ unsigned pk2(float lo, float hi) { unsigned r; asm("v_cvt_pk_bf16_f32 %0, %1, %2" : "=v"(r) : "v"(lo), "v"(hi)); return r; }
;     __device__ __forceinline__ void operator()(const f32x4 (&acc)[2][2][4][2], const Unit& u, int wr, int wc, int fr, int fq) const {
;     ...
;         const int row_t = rmap == 1 ? odd_phys_row0(u.pm, grp) : (rmap == 2 ? odd_phys_row0(u.pm % (BG * TPB), u.pm / (BG * TPB)) : u.pm * BM);
;         int c = col_t + 64 * wc + 16 * fq;
;         if (mode == 2) c = (c >> 6) * 96 + (c & 63);
; #pragma unroll
;         for (int ai = 0; ai < 2; ++ai)
; #pragma unroll
;             for (int m = 0; m < 4; ++m) {
;                 const int row = row_t + ai * HALF + wr * 64 + m * 16 + fr;
;                 bf16_t* rp = O + (size_t)row * ldc + c;
; #pragma unroll
;                 for (int bj = 0; bj < 2; ++bj) {
;                     const f32x4 v0 = acc[ai][bj][m][0], v1 = acc[ai][bj][m][1];
;                     u32x4 o; o.x = pk2(v0[0], v0[1]); o.y = pk2(v0[2], v0[3]); o.z = pk2(v1[0], v1[1]); o.w = pk2(v1[2], v1[3]);
;                     *(u32x4*)(rp + 8 * bj) = o;
;                 }
;             }
	v_lshl_add_u32 v134, s71, 8, v138
	v_cvt_pk_bf16_f32 v68, v68, v69
	v_cvt_pk_bf16_f32 v69, v70, v71
	v_cvt_pk_bf16_f32 v70, v64, v65
	v_add_u32_e32 v64, 0x80, v134
	v_lshl_or_b32 v136, s15, 8, v140
	v_ashrrev_i32_e32 v135, 31, v134
	v_cvt_pk_bf16_f32 v112, v112, v113
	v_cvt_pk_bf16_f32 v113, v114, v115
	v_cvt_pk_bf16_f32 v114, v104, v105
	v_or_b32_e32 v104, 16, v134
	v_ashrrev_i32_e32 v65, 31, v64
	v_cvt_pk_bf16_f32 v48, v48, v49
	v_cvt_pk_bf16_f32 v49, v50, v51
	v_cvt_pk_bf16_f32 v50, v40, v41
	v_add_u32_e32 v40, 0x90, v134
	v_ashrrev_i32_e32 v137, 31, v136
	v_lshlrev_b64 v[142:143], 11, v[134:135]
	v_ashrrev_i32_e32 v105, 31, v104
	v_cvt_pk_bf16_f32 v96, v96, v97
	v_cvt_pk_bf16_f32 v97, v98, v99
	v_cvt_pk_bf16_f32 v98, v88, v89
	v_or_b32_e32 v88, 32, v134
	v_lshlrev_b64 v[64:65], 11, v[64:65]
	v_ashrrev_i32_e32 v41, 31, v40
	v_cvt_pk_bf16_f32 v32, v32, v33
	v_cvt_pk_bf16_f32 v33, v34, v35
	v_cvt_pk_bf16_f32 v34, v24, v25
	v_add_u32_e32 v24, 0xa0, v134
	v_lshl_add_u64 v[142:143], s[8:9], 0, v[142:143]
	v_lshlrev_b64 v[136:137], 1, v[136:137]
	v_lshlrev_b64 v[104:105], 11, v[104:105]
	v_ashrrev_i32_e32 v89, 31, v88
	v_cvt_pk_bf16_f32 v80, v80, v81
	v_cvt_pk_bf16_f32 v81, v82, v83
	v_cvt_pk_bf16_f32 v82, v72, v73
	v_or_b32_e32 v72, 48, v134
	v_lshl_add_u64 v[64:65], s[8:9], 0, v[64:65]
	v_lshlrev_b64 v[40:41], 11, v[40:41]
	v_ashrrev_i32_e32 v25, 31, v24
	v_cvt_pk_bf16_f32 v16, v16, v17
	v_cvt_pk_bf16_f32 v17, v18, v19
	v_cvt_pk_bf16_f32 v18, v8, v9
	v_add_u32_e32 v8, 0xb0, v134
	v_lshl_add_u64 v[142:143], v[142:143], 0, v[136:137]
	v_lshl_add_u64 v[104:105], s[8:9], 0, v[104:105]
	v_lshlrev_b64 v[88:89], 11, v[88:89]
	v_ashrrev_i32_e32 v73, 31, v72
	v_lshl_add_u64 v[64:65], v[64:65], 0, v[136:137]
	v_lshl_add_u64 v[40:41], s[8:9], 0, v[40:41]
	v_lshlrev_b64 v[24:25], 11, v[24:25]
	v_ashrrev_i32_e32 v9, 31, v8
	v_cvt_pk_bf16_f32 v115, v106, v107
	global_store_dwordx4 v[142:143], v[112:115], off offset:16
	v_lshl_add_u64 v[88:89], s[8:9], 0, v[88:89]
	v_lshlrev_b64 v[72:73], 11, v[72:73]
	v_lshl_add_u64 v[112:113], v[104:105], 0, v[136:137]
	v_cvt_pk_bf16_f32 v51, v42, v43
	global_store_dwordx4 v[64:65], v[48:51], off offset:16
	v_lshl_add_u64 v[24:25], s[8:9], 0, v[24:25]
	v_lshlrev_b64 v[8:9], 11, v[8:9]
	v_lshl_add_u64 v[48:49], v[40:41], 0, v[136:137]
	v_cvt_pk_bf16_f32 v99, v90, v91
	global_store_dwordx4 v[112:113], v[96:99], off offset:16
	v_lshl_add_u64 v[72:73], s[8:9], 0, v[72:73]
	v_cvt_pk_bf16_f32 v35, v26, v27
	global_store_dwordx4 v[48:49], v[32:35], off offset:16
	v_lshl_add_u64 v[96:97], v[88:89], 0, v[136:137]
	v_lshl_add_u64 v[8:9], s[8:9], 0, v[8:9]
	v_lshl_add_u64 v[32:33], v[24:25], 0, v[136:137]
	v_cvt_pk_bf16_f32 v83, v74, v75
	global_store_dwordx4 v[96:97], v[80:83], off offset:16
	v_cvt_pk_bf16_f32 v19, v10, v11
	global_store_dwordx4 v[32:33], v[16:19], off offset:16
	s_and_b64 vcc, exec, s[0:1]
	v_lshl_add_u64 v[80:81], v[72:73], 0, v[136:137]
	v_lshl_add_u64 v[16:17], v[8:9], 0, v[136:137]
	s_mov_b32 s15, s69
	s_mov_b32 s71, s70
	s_mov_b64 s[12:13], s[6:7]
	s_mov_b64 s[10:11], s[4:5]
	v_cvt_pk_bf16_f32 v124, v124, v125
	v_cvt_pk_bf16_f32 v125, v126, v127
	v_cvt_pk_bf16_f32 v126, v120, v121
	v_cvt_pk_bf16_f32 v127, v122, v123
	global_store_dwordx4 v[142:143], v[124:127], off
	v_cvt_pk_bf16_f32 v104, v116, v117
	v_cvt_pk_bf16_f32 v105, v118, v119
	v_cvt_pk_bf16_f32 v106, v108, v109
	v_cvt_pk_bf16_f32 v107, v110, v111
	global_store_dwordx4 v[112:113], v[104:107], off
	v_cvt_pk_bf16_f32 v88, v100, v101
	v_cvt_pk_bf16_f32 v89, v102, v103
	v_cvt_pk_bf16_f32 v90, v92, v93
	v_cvt_pk_bf16_f32 v91, v94, v95
	global_store_dwordx4 v[96:97], v[88:91], off
	v_cvt_pk_bf16_f32 v72, v84, v85
	v_cvt_pk_bf16_f32 v73, v86, v87
	v_cvt_pk_bf16_f32 v74, v76, v77
	v_cvt_pk_bf16_f32 v75, v78, v79
	global_store_dwordx4 v[80:81], v[72:75], off
	v_cvt_pk_bf16_f32 v71, v66, v67
	global_store_dwordx4 v[80:81], v[68:71], off offset:16
	v_cvt_pk_bf16_f32 v60, v60, v61
	v_cvt_pk_bf16_f32 v61, v62, v63
	v_cvt_pk_bf16_f32 v62, v56, v57
	v_cvt_pk_bf16_f32 v63, v58, v59
	global_store_dwordx4 v[64:65], v[60:63], off
	v_cvt_pk_bf16_f32 v40, v52, v53
	v_cvt_pk_bf16_f32 v41, v54, v55
	v_cvt_pk_bf16_f32 v42, v44, v45
	v_cvt_pk_bf16_f32 v43, v46, v47
	global_store_dwordx4 v[48:49], v[40:43], off
	v_cvt_pk_bf16_f32 v24, v36, v37
	v_cvt_pk_bf16_f32 v25, v38, v39
	v_cvt_pk_bf16_f32 v26, v28, v29
	v_cvt_pk_bf16_f32 v27, v30, v31
	global_store_dwordx4 v[32:33], v[24:27], off
	v_cvt_pk_bf16_f32 v8, v20, v21
	v_cvt_pk_bf16_f32 v9, v22, v23
	v_cvt_pk_bf16_f32 v10, v12, v13
	v_cvt_pk_bf16_f32 v11, v14, v15
	global_store_dwordx4 v[16:17], v[8:11], off
	v_cvt_pk_bf16_f32 v4, v4, v5
	v_cvt_pk_bf16_f32 v5, v6, v7
	v_cvt_pk_bf16_f32 v6, v0, v1
	v_cvt_pk_bf16_f32 v7, v2, v3
	global_store_dwordx4 v[16:17], v[4:7], off offset:16
	s_cbranch_vccz .LBB0_342
	s_waitcnt vmcnt(0)
	s_cmpk_gt_u32 s3, 0xff
	s_cbranch_scc1 .LBB0_353
	s_barrier

; #define PG8_STAGE(bufoff, gbase, voff) do { _Pragma("unroll") for (int _i = 0; _i < 2; ++_i) \
;         __builtin_amdgcn_global_load_lds((const unsigned*)((const char*)(gbase) + (voff)[_i]), (LAS unsigned*)(lds + (bufoff) + ldsw + _i * 8192), 16, 0, 0); } while (0)
; #define PG8_LDA(dst, b, h) do { _Pragma("unroll") for (int m = 0; m < 4; ++m) _Pragma("unroll") for (int k = 0; k < 2; ++k) dst[m][k] = *(const LAS bf16x8*)(lds + PG8_SA(b, h) + aoff + m * 2048 + k * 1024); } while (0)
; #define PG8_LDB(dst, b, h) do { _Pragma("unroll") for (int n = 0; n < 2; ++n) _Pragma("unroll") for (int k = 0; k < 2; ++k) dst[n][k] = *(const LAS bf16x8*)(lds + PG8_SB(b, h) + boff + n * 2048 + k * 1024); } while (0)
; #define PG8_MMA(ai, bj, At, Bt) do { __builtin_amdgcn_s_setprio(1); _Pragma("unroll") for (int m = 0; m < 4; ++m) _Pragma("unroll") for (int n = 0; n < 2; ++n) _Pragma("unroll") for (int k = 0; k < 2; ++k) \
;         acc[ai][bj][m][n] = __builtin_amdgcn_mfma_f32_16x16x32_bf16(Bt[n][k], At[m][k], acc[ai][bj][m][n], 0, 0, 0); __builtin_amdgcn_s_setprio(0); } while (0)
; template <class Epi>
; __device__ __forceinline__ void gemm_phase(LAS unsigned char* lds, const Gemm g, const StaticOrder& S, const Epi& E) {
;     ...
;         const bool has_next = S.next(ui + 1, nxt);
;         const char* nA = has_next ? g.arow(nxt.pm) : cA; const char* nB = has_next ? (const char*)g.Bt + (size_t)nxt.pn * tB : cB;
;         for (int t = 0; t < nt; t += 2) {
;             const bool last = (t == nt - 2);
;             const char* a1 = cA + (size_t)(t + 1) * kstep;
;             const char* a2 = last ? nA : cA + (size_t)(t + 2) * kstep; const char* b2 = last ? nB : cB + (size_t)(t + 2) * kstep;
;             const char* a3 = a2 + kstep; const char* b3 = b2 + kstep;
;             PG8_LDB(B0, 0, 0); PG8_SCHED; PG8_LDA(At, 0, 0); PG8_STAGE(PG8_SA(1, 1), a1 + hA, voffA);
;             PG8_WAIT_L(8); PG8_BAR; PG8_WAIT_L(0); PG8_MMA(0, 0, At, B0); PG8_BAR; PG8_SCHED;
;             PG8_LDB(B1, 0, 1); PG8_STAGE(PG8_SB(0, 0), b2, voffB);
;             PG8_BAR; PG8_WAIT_L(0); PG8_MMA(0, 1, At, B1); PG8_BAR;
;             PG8_LDA(At, 0, 1); PG8_STAGE(PG8_SA(0, 0), a2, voffA);
;             PG8_BAR; PG8_WAIT_L(0); PG8_MMA(1, 0, At, B0); PG8_BAR; PG8_SCHED;
;             PG8_STAGE(PG8_SB(0, 1), b2 + hB, voffB);
;             PG8_WAIT_V(6); PG8_BAR; PG8_MMA(1, 1, At, B1); PG8_BAR;
.LBB0_499:
	s_add_u32 s26, s4, 0xfffc0080
	s_addc_u32 s27, s5, -1
	s_add_i32 s28, 0, 0x10000
	v_add_u32_e32 v146, s28, v149
	ds_read_b128 v[136:139], v146
	ds_read_b128 v[140:143], v146 offset:1024
	ds_read_b128 v[158:161], v146 offset:2048
	ds_read_b128 v[162:165], v146 offset:3072
	s_cmp_eq_u32 s84, 12
	s_cselect_b32 s65, s21, s27
	s_cselect_b32 s64, s20, s26
	s_cselect_b32 s35, s15, s25
	s_cselect_b32 s34, s17, s24
	v_lshl_add_u64 v[146:147], s[4:5], 0, v[132:133]
	s_add_i32 m0, s66, 0xc000
	ds_read_b128 v[166:169], v154
	ds_read_b128 v[170:173], v154 offset:1024
	ds_read_b128 v[174:177], v154 offset:2048
	ds_read_b128 v[178:181], v154 offset:3072
	ds_read_b128 v[182:185], v154 offset:4096
	ds_read_b128 v[196:199], v154 offset:5120
	ds_read_b128 v[200:203], v154 offset:6144
	ds_read_b128 v[204:207], v154 offset:7168
	global_load_lds_dwordx4 v[146:147], off
	s_add_i32 m0, s66, 0xe000
	v_lshl_add_u64 v[146:147], s[4:5], 0, v[134:135]
	global_load_lds_dwordx4 v[146:147], off
	s_waitcnt lgkmcnt(8)
	s_barrier
	s_waitcnt lgkmcnt(0)
	s_setprio 1
	v_mfma_f32_16x16x32_bf16 v[124:127], v[136:139], v[166:169], v[124:127]
	v_mfma_f32_16x16x32_bf16 v[120:123], v[158:161], v[166:169], v[120:123]
	v_mfma_f32_16x16x32_bf16 v[116:119], v[136:139], v[174:177], v[116:119]
	v_mfma_f32_16x16x32_bf16 v[108:111], v[158:161], v[174:177], v[108:111]
	v_mfma_f32_16x16x32_bf16 v[100:103], v[136:139], v[182:185], v[100:103]
	v_mfma_f32_16x16x32_bf16 v[92:95], v[158:161], v[182:185], v[92:95]
	v_mfma_f32_16x16x32_bf16 v[84:87], v[136:139], v[200:203], v[84:87]
	v_mfma_f32_16x16x32_bf16 v[76:79], v[158:161], v[200:203], v[76:79]
	v_mfma_f32_16x16x32_bf16 v[124:127], v[140:143], v[170:173], v[124:127]
	v_mfma_f32_16x16x32_bf16 v[120:123], v[162:165], v[170:173], v[120:123]
	v_mfma_f32_16x16x32_bf16 v[116:119], v[140:143], v[178:181], v[116:119]
	v_mfma_f32_16x16x32_bf16 v[108:111], v[162:165], v[178:181], v[108:111]
	v_mfma_f32_16x16x32_bf16 v[100:103], v[140:143], v[196:199], v[100:103]
	v_mfma_f32_16x16x32_bf16 v[92:95], v[162:165], v[196:199], v[92:95]
	v_mfma_f32_16x16x32_bf16 v[84:87], v[140:143], v[204:207], v[84:87]
	v_mfma_f32_16x16x32_bf16 v[76:79], v[162:165], v[204:207], v[76:79]
	s_setprio 0
	s_barrier
	s_add_i32 s29, 0, 0x14000
	v_add_u32_e32 v146, s29, v149
	s_add_i32 s26, s28, s71
	ds_read_b128 v[216:219], v146
	ds_read_b128 v[220:223], v146 offset:1024
	ds_read_b128 v[224:227], v146 offset:2048
	ds_read_b128 v[228:231], v146 offset:3072
	v_lshl_add_u64 v[146:147], s[34:35], 0, v[128:129]
	s_mov_b32 m0, s26
	v_lshl_add_u64 v[186:187], s[34:35], 0, v[130:131]
	global_load_lds_dwordx4 v[146:147], off
	s_add_i32 m0, s26, 0x2000
	s_nop 0
	global_load_lds_dwordx4 v[186:187], off
	s_barrier
	s_waitcnt lgkmcnt(0)
	s_setprio 1
	v_mfma_f32_16x16x32_bf16 v[112:115], v[216:219], v[166:169], v[112:115]
	v_mfma_f32_16x16x32_bf16 v[104:107], v[224:227], v[166:169], v[104:107]
	v_mfma_f32_16x16x32_bf16 v[96:99], v[216:219], v[174:177], v[96:99]
	v_mfma_f32_16x16x32_bf16 v[88:91], v[224:227], v[174:177], v[88:91]
	v_mfma_f32_16x16x32_bf16 v[80:83], v[216:219], v[182:185], v[80:83]
	v_mfma_f32_16x16x32_bf16 v[72:75], v[224:227], v[182:185], v[72:75]
	v_mfma_f32_16x16x32_bf16 v[68:71], v[216:219], v[200:203], v[68:71]
	v_mfma_f32_16x16x32_bf16 v[64:67], v[224:227], v[200:203], v[64:67]
	v_mfma_f32_16x16x32_bf16 v[112:115], v[220:223], v[170:173], v[112:115]
	v_mfma_f32_16x16x32_bf16 v[104:107], v[228:231], v[170:173], v[104:107]
	v_mfma_f32_16x16x32_bf16 v[96:99], v[220:223], v[178:181], v[96:99]
	v_mfma_f32_16x16x32_bf16 v[88:91], v[228:231], v[178:181], v[88:91]
	v_mfma_f32_16x16x32_bf16 v[80:83], v[220:223], v[196:199], v[80:83]
	v_mfma_f32_16x16x32_bf16 v[72:75], v[228:231], v[196:199], v[72:75]
	v_mfma_f32_16x16x32_bf16 v[68:71], v[220:223], v[204:207], v[68:71]
	v_mfma_f32_16x16x32_bf16 v[64:67], v[228:231], v[204:207], v[64:67]
	s_setprio 0
	s_mov_b32 m0, s66
	v_lshl_add_u64 v[188:189], s[64:65], 0, v[128:129]
	s_barrier
	ds_read_b128 v[166:169], v154 offset:16384
	ds_read_b128 v[170:173], v154 offset:17408
	ds_read_b128 v[174:177], v154 offset:18432
	ds_read_b128 v[178:181], v154 offset:19456
	ds_read_b128 v[182:185], v154 offset:20480
	ds_read_b128 v[196:199], v154 offset:21504
	ds_read_b128 v[200:203], v154 offset:22528
	ds_read_b128 v[204:207], v154 offset:23552
	global_load_lds_dwordx4 v[188:189], off
	s_mov_b32 m0, s72
	v_lshl_add_u64 v[192:193], s[64:65], 0, v[130:131]
	global_load_lds_dwordx4 v[192:193], off
	s_barrier
	s_waitcnt lgkmcnt(0)
	s_setprio 1
	v_mfma_f32_16x16x32_bf16 v[60:63], v[136:139], v[166:169], v[60:63]
	v_mfma_f32_16x16x32_bf16 v[56:59], v[158:161], v[166:169], v[56:59]
	v_mfma_f32_16x16x32_bf16 v[52:55], v[136:139], v[174:177], v[52:55]
	v_mfma_f32_16x16x32_bf16 v[44:47], v[158:161], v[174:177], v[44:47]
	v_mfma_f32_16x16x32_bf16 v[36:39], v[136:139], v[182:185], v[36:39]
	v_mfma_f32_16x16x32_bf16 v[28:31], v[158:161], v[182:185], v[28:31]
	v_mfma_f32_16x16x32_bf16 v[20:23], v[136:139], v[200:203], v[20:23]
	v_mfma_f32_16x16x32_bf16 v[12:15], v[158:161], v[200:203], v[12:15]
	v_mfma_f32_16x16x32_bf16 v[60:63], v[140:143], v[170:173], v[60:63]
	v_mfma_f32_16x16x32_bf16 v[56:59], v[162:165], v[170:173], v[56:59]
	v_mfma_f32_16x16x32_bf16 v[52:55], v[140:143], v[178:181], v[52:55]
	v_mfma_f32_16x16x32_bf16 v[44:47], v[162:165], v[178:181], v[44:47]
	v_mfma_f32_16x16x32_bf16 v[36:39], v[140:143], v[196:199], v[36:39]
	v_mfma_f32_16x16x32_bf16 v[28:31], v[162:165], v[196:199], v[28:31]
	v_mfma_f32_16x16x32_bf16 v[20:23], v[140:143], v[204:207], v[20:23]
	v_mfma_f32_16x16x32_bf16 v[12:15], v[162:165], v[204:207], v[12:15]
	s_setprio 0
	s_barrier
; #define PG8_STAGE(bufoff, gbase, voff) do { _Pragma("unroll") for (int _i = 0; _i < 2; ++_i) \
;         __builtin_amdgcn_global_load_lds((const unsigned*)((const char*)(gbase) + (voff)[_i]), (LAS unsigned*)(lds + (bufoff) + ldsw + _i * 8192), 16, 0, 0); } while (0)
; #define PG8_LDA(dst, b, h) do { _Pragma("unroll") for (int m = 0; m < 4; ++m) _Pragma("unroll") for (int k = 0; k < 2; ++k) dst[m][k] = *(const LAS bf16x8*)(lds + PG8_SA(b, h) + aoff + m * 2048 + k * 1024); } while (0)
; #define PG8_LDB(dst, b, h) do { _Pragma("unroll") for (int n = 0; n < 2; ++n) _Pragma("unroll") for (int k = 0; k < 2; ++k) dst[n][k] = *(const LAS bf16x8*)(lds + PG8_SB(b, h) + boff + n * 2048 + k * 1024); } while (0)
; #define PG8_MMA(ai, bj, At, Bt) do { __builtin_amdgcn_s_setprio(1); _Pragma("unroll") for (int m = 0; m < 4; ++m) _Pragma("unroll") for (int n = 0; n < 2; ++n) _Pragma("unroll") for (int k = 0; k < 2; ++k) \
;         acc[ai][bj][m][n] = __builtin_amdgcn_mfma_f32_16x16x32_bf16(Bt[n][k], At[m][k], acc[ai][bj][m][n], 0, 0, 0); __builtin_amdgcn_s_setprio(0); } while (0)
; #define PG8_WAIT_V(n) asm volatile("s_waitcnt vmcnt(" #n ")" ::: "memory")
; #define PG8_WAIT_L(n) asm volatile("s_waitcnt lgkmcnt(" #n ")" ::: "memory")
; #define PG8_BAR __builtin_amdgcn_s_barrier()
; #define PG8_SCHED __builtin_amdgcn_sched_barrier(0)
; template <class Epi>
; __device__ __forceinline__ void gemm_phase(LAS unsigned char* lds, const Gemm g, const StaticOrder& S, const Epi& E) {
;     ...
;             PG8_WAIT_V(6); PG8_BAR; PG8_MMA(1, 1, At, B1); PG8_BAR;
;             PG8_LDB(B0, 1, 0); PG8_SCHED; PG8_LDA(At, 1, 0); PG8_STAGE(PG8_SA(0, 1), a2 + hA, voffA);
;             PG8_WAIT_L(8); PG8_BAR; PG8_WAIT_L(0); PG8_MMA(0, 0, At, B0); PG8_BAR; PG8_SCHED;
;             PG8_LDB(B1, 1, 1); PG8_STAGE(PG8_SB(1, 0), b3, voffB);
;             PG8_BAR; PG8_WAIT_L(0); PG8_MMA(0, 1, At, B1); PG8_BAR;
;             PG8_LDA(At, 1, 1); PG8_STAGE(PG8_SA(1, 0), a3, voffA);
;             PG8_BAR; PG8_WAIT_L(0); PG8_MMA(1, 0, At, B0); PG8_BAR; PG8_SCHED;
;             PG8_STAGE(PG8_SB(1, 1), b3 + hB, voffB);
;             PG8_WAIT_V(6); PG8_BAR; PG8_MMA(1, 1, At, B1); PG8_BAR;
	s_add_u32 s26, s34, 0x40000
	s_addc_u32 s27, s35, 0
	s_add_i32 s28, s29, s71
	s_mov_b32 m0, s28
	v_lshl_add_u64 v[136:137], s[26:27], 0, v[128:129]
	global_load_lds_dwordx4 v[136:137], off
	s_add_i32 m0, s28, 0x2000
	v_lshl_add_u64 v[136:137], s[26:27], 0, v[130:131]
	global_load_lds_dwordx4 v[136:137], off
	s_waitcnt vmcnt(6)
	s_barrier
	s_setprio 1
	v_mfma_f32_16x16x32_bf16 v[48:51], v[216:219], v[166:169], v[48:51]
	v_mfma_f32_16x16x32_bf16 v[40:43], v[224:227], v[166:169], v[40:43]
	v_mfma_f32_16x16x32_bf16 v[32:35], v[216:219], v[174:177], v[32:35]
	v_mfma_f32_16x16x32_bf16 v[24:27], v[224:227], v[174:177], v[24:27]
	v_mfma_f32_16x16x32_bf16 v[16:19], v[216:219], v[182:185], v[16:19]
	v_mfma_f32_16x16x32_bf16 v[8:11], v[224:227], v[182:185], v[8:11]
	v_mfma_f32_16x16x32_bf16 v[4:7], v[216:219], v[200:203], v[4:7]
	v_mfma_f32_16x16x32_bf16 v[0:3], v[224:227], v[200:203], v[0:3]
	v_mfma_f32_16x16x32_bf16 v[48:51], v[220:223], v[170:173], v[48:51]
	v_mfma_f32_16x16x32_bf16 v[40:43], v[228:231], v[170:173], v[40:43]
	v_mfma_f32_16x16x32_bf16 v[32:35], v[220:223], v[178:181], v[32:35]
	v_mfma_f32_16x16x32_bf16 v[24:27], v[228:231], v[178:181], v[24:27]
	v_mfma_f32_16x16x32_bf16 v[16:19], v[220:223], v[196:199], v[16:19]
	v_mfma_f32_16x16x32_bf16 v[8:11], v[228:231], v[196:199], v[8:11]
	v_mfma_f32_16x16x32_bf16 v[4:7], v[220:223], v[204:207], v[4:7]
	v_mfma_f32_16x16x32_bf16 v[0:3], v[228:231], v[204:207], v[0:3]
	s_setprio 0
	s_add_i32 s28, 0, 0x18000
	v_add_u32_e32 v157, s28, v149
	s_barrier
	ds_read_b128 v[136:139], v157
	ds_read_b128 v[140:143], v157 offset:1024
	ds_read_b128 v[158:161], v157 offset:2048
	ds_read_b128 v[162:165], v157 offset:3072
	s_add_u32 s26, s64, 0x40000
	s_addc_u32 s27, s65, 0
	s_mov_b32 m0, s76
	v_lshl_add_u64 v[216:217], s[26:27], 0, v[128:129]
	ds_read_b128 v[166:169], v154 offset:32768
	ds_read_b128 v[170:173], v154 offset:33792
	ds_read_b128 v[174:177], v154 offset:34816
	ds_read_b128 v[178:181], v154 offset:35840
	ds_read_b128 v[182:185], v154 offset:36864
	ds_read_b128 v[196:199], v154 offset:37888
	ds_read_b128 v[200:203], v154 offset:38912
	ds_read_b128 v[204:207], v154 offset:39936
	global_load_lds_dwordx4 v[216:217], off
	s_mov_b32 m0, s77
	v_lshl_add_u64 v[216:217], s[26:27], 0, v[130:131]
	global_load_lds_dwordx4 v[216:217], off
	s_waitcnt lgkmcnt(8)
	s_barrier
	s_waitcnt lgkmcnt(0)
	s_setprio 1
	v_mfma_f32_16x16x32_bf16 v[124:127], v[136:139], v[166:169], v[124:127]
	v_mfma_f32_16x16x32_bf16 v[120:123], v[158:161], v[166:169], v[120:123]
	v_mfma_f32_16x16x32_bf16 v[116:119], v[136:139], v[174:177], v[116:119]
	v_mfma_f32_16x16x32_bf16 v[108:111], v[158:161], v[174:177], v[108:111]
	v_mfma_f32_16x16x32_bf16 v[100:103], v[136:139], v[182:185], v[100:103]
	v_mfma_f32_16x16x32_bf16 v[92:95], v[158:161], v[182:185], v[92:95]
	v_mfma_f32_16x16x32_bf16 v[84:87], v[136:139], v[200:203], v[84:87]
	v_mfma_f32_16x16x32_bf16 v[76:79], v[158:161], v[200:203], v[76:79]
	v_mfma_f32_16x16x32_bf16 v[124:127], v[140:143], v[170:173], v[124:127]
	v_mfma_f32_16x16x32_bf16 v[120:123], v[162:165], v[170:173], v[120:123]
	v_mfma_f32_16x16x32_bf16 v[116:119], v[140:143], v[178:181], v[116:119]
	v_mfma_f32_16x16x32_bf16 v[108:111], v[162:165], v[178:181], v[108:111]
	v_mfma_f32_16x16x32_bf16 v[100:103], v[140:143], v[196:199], v[100:103]
	v_mfma_f32_16x16x32_bf16 v[92:95], v[162:165], v[196:199], v[92:95]
	v_mfma_f32_16x16x32_bf16 v[84:87], v[140:143], v[204:207], v[84:87]
	v_mfma_f32_16x16x32_bf16 v[76:79], v[162:165], v[204:207], v[76:79]
	s_setprio 0
	s_barrier
	s_add_i32 s29, 0, 0x1c000
	s_add_i32 s26, s28, s71
	v_add_u32_e32 v157, s29, v149
	v_lshl_add_u64 v[146:147], v[146:147], 0, s[88:89]
	s_mov_b32 m0, s26
	ds_read_b128 v[216:219], v157
	ds_read_b128 v[220:223], v157 offset:1024
	ds_read_b128 v[224:227], v157 offset:2048
	ds_read_b128 v[228:231], v157 offset:3072
	global_load_lds_dwordx4 v[146:147], off
	s_add_i32 m0, s26, 0x2000
	v_lshl_add_u64 v[146:147], v[186:187], 0, s[88:89]
	global_load_lds_dwordx4 v[146:147], off
	s_barrier
	s_waitcnt lgkmcnt(0)
	s_setprio 1
	v_mfma_f32_16x16x32_bf16 v[112:115], v[216:219], v[166:169], v[112:115]
	v_mfma_f32_16x16x32_bf16 v[104:107], v[224:227], v[166:169], v[104:107]
	v_mfma_f32_16x16x32_bf16 v[96:99], v[216:219], v[174:177], v[96:99]
	v_mfma_f32_16x16x32_bf16 v[88:91], v[224:227], v[174:177], v[88:91]
	v_mfma_f32_16x16x32_bf16 v[80:83], v[216:219], v[182:185], v[80:83]
	v_mfma_f32_16x16x32_bf16 v[72:75], v[224:227], v[182:185], v[72:75]
	v_mfma_f32_16x16x32_bf16 v[68:71], v[216:219], v[200:203], v[68:71]
	v_mfma_f32_16x16x32_bf16 v[64:67], v[224:227], v[200:203], v[64:67]
	v_mfma_f32_16x16x32_bf16 v[112:115], v[220:223], v[170:173], v[112:115]
	v_mfma_f32_16x16x32_bf16 v[104:107], v[228:231], v[170:173], v[104:107]
	v_mfma_f32_16x16x32_bf16 v[96:99], v[220:223], v[178:181], v[96:99]
	v_mfma_f32_16x16x32_bf16 v[88:91], v[228:231], v[178:181], v[88:91]
	v_mfma_f32_16x16x32_bf16 v[80:83], v[220:223], v[196:199], v[80:83]
	v_mfma_f32_16x16x32_bf16 v[72:75], v[228:231], v[196:199], v[72:75]
	v_mfma_f32_16x16x32_bf16 v[68:71], v[220:223], v[204:207], v[68:71]
	v_mfma_f32_16x16x32_bf16 v[64:67], v[228:231], v[204:207], v[64:67]
	s_setprio 0
	s_mov_b32 m0, s78
	v_lshl_add_u64 v[146:147], v[188:189], 0, s[88:89]
	s_barrier
	ds_read_b128 v[166:169], v154 offset:49152
	ds_read_b128 v[170:173], v154 offset:50176
	ds_read_b128 v[174:177], v154 offset:51200
	ds_read_b128 v[178:181], v154 offset:52224
	ds_read_b128 v[182:185], v154 offset:53248
	ds_read_b128 v[196:199], v154 offset:54272
	ds_read_b128 v[200:203], v154 offset:55296
	ds_read_b128 v[204:207], v154 offset:56320
	global_load_lds_dwordx4 v[146:147], off
	s_mov_b32 m0, s79
	v_lshl_add_u64 v[146:147], v[192:193], 0, s[88:89]
	global_load_lds_dwordx4 v[146:147], off
	s_barrier
; #define LAS __attribute__((address_space(3)))
; __device__ __forceinline__ unsigned pk2(float lo, float hi) { unsigned r; asm("v_cvt_pk_bf16_f32 %0, %1, %2" : "=v"(r) : "v"(lo), "v"(hi)); return r; }
; #define PG8_STAGE(bufoff, gbase, voff) do { _Pragma("unroll") for (int _i = 0; _i < 2; ++_i) \
;         __builtin_amdgcn_global_load_lds((const unsigned*)((const char*)(gbase) + (voff)[_i]), (LAS unsigned*)(lds + (bufoff) + ldsw + _i * 8192), 16, 0, 0); } while (0)
; template <class Epi>
; __device__ __forceinline__ void gemm_phase(LAS unsigned char* lds, const Gemm g, const StaticOrder& S, const Epi& E) {
;     ...
;             PG8_BAR; PG8_WAIT_L(0); PG8_MMA(1, 0, At, B0); PG8_BAR; PG8_SCHED;
;             PG8_STAGE(PG8_SB(1, 1), b3 + hB, voffB);
;             PG8_WAIT_V(6); PG8_BAR; PG8_MMA(1, 1, At, B1); PG8_BAR;
;     __device__ __forceinline__ void operator()(const f32x4 (&acc)[2][2][4][2], const Unit& u, int wr, int wc, int fr, int fq) const {
;         const int col_t = u.pn * BM;
;         if (mode != 0 && col_t >= vt0) {
;             const int bl = u.pm / TPB, key0 = (u.pm - bl * TPB) * 256;
;             LAS bf16_t* sc = (LAS bf16_t*)(trs + (wr * 4 + wc) * 2304);
;             const int lane = fq * 16 + fr;
; #pragma unroll
;             for (int ai = 0; ai < 2; ++ai)
; #pragma unroll
;                 for (int bj = 0; bj < 2; ++bj)
; #pragma unroll
;                     for (int n = 0; n < 2; ++n) {
; #pragma unroll
;                         for (int m = 0; m < 4; ++m) {
;                             const f32x4 v = acc[ai][bj][m][n];
;                             const unsigned p0 = pk2(v[0], v[1]), p1 = pk2(v[2], v[3]);
;                             LAS bf16_t* w = sc + (4 * fq) * 72 + 16 * m + fr;
;                             w[0] = (bf16_t)(p0 & 0xffffu); w[72] = (bf16_t)(p0 >> 16); w[144] = (bf16_t)(p1 & 0xffffu); w[216] = (bf16_t)(p1 >> 16);
;                         }
; #pragma unroll
;                         for (int j = 0; j < 2; ++j) {
;                             const int ch = lane + 64 * j, fi = ch >> 3, seg = ch & 7;
;                             const u32x4 o = *(const LAS u32x4*)(sc + fi * 72 + 8 * seg);
;                             const int f = col_t - vt0 + 64 * wc + 16 * (fi >> 2) + 8 * bj + 4 * n + (fi & 3);
;                             *(u32x4*)(Vt + ((size_t)bl * vtnf + f) * KEYS + key0 + ai * HALF + wr * 64 + 8 * seg) = o;
	s_waitcnt lgkmcnt(0)
	s_setprio 1
	v_mfma_f32_16x16x32_bf16 v[60:63], v[136:139], v[166:169], v[60:63]
	v_mfma_f32_16x16x32_bf16 v[56:59], v[158:161], v[166:169], v[56:59]
	v_mfma_f32_16x16x32_bf16 v[52:55], v[136:139], v[174:177], v[52:55]
	v_mfma_f32_16x16x32_bf16 v[44:47], v[158:161], v[174:177], v[44:47]
	v_mfma_f32_16x16x32_bf16 v[36:39], v[136:139], v[182:185], v[36:39]
	v_mfma_f32_16x16x32_bf16 v[28:31], v[158:161], v[182:185], v[28:31]
	v_mfma_f32_16x16x32_bf16 v[20:23], v[136:139], v[200:203], v[20:23]
	v_mfma_f32_16x16x32_bf16 v[12:15], v[158:161], v[200:203], v[12:15]
	v_mfma_f32_16x16x32_bf16 v[60:63], v[140:143], v[170:173], v[60:63]
	v_mfma_f32_16x16x32_bf16 v[56:59], v[162:165], v[170:173], v[56:59]
	v_mfma_f32_16x16x32_bf16 v[52:55], v[140:143], v[178:181], v[52:55]
	v_mfma_f32_16x16x32_bf16 v[44:47], v[162:165], v[178:181], v[44:47]
	v_mfma_f32_16x16x32_bf16 v[36:39], v[140:143], v[196:199], v[36:39]
	v_mfma_f32_16x16x32_bf16 v[28:31], v[162:165], v[196:199], v[28:31]
	v_mfma_f32_16x16x32_bf16 v[20:23], v[140:143], v[204:207], v[20:23]
	v_mfma_f32_16x16x32_bf16 v[12:15], v[162:165], v[204:207], v[12:15]
	s_setprio 0
	s_barrier
	s_add_u32 s26, s34, 0x40080
	s_addc_u32 s27, s35, 0
	s_add_i32 s28, s29, s71
	s_mov_b32 m0, s28
	v_lshl_add_u64 v[136:137], s[26:27], 0, v[128:129]
	global_load_lds_dwordx4 v[136:137], off
	s_add_i32 m0, s28, 0x2000
	v_lshl_add_u64 v[136:137], s[26:27], 0, v[130:131]
	global_load_lds_dwordx4 v[136:137], off
	s_waitcnt vmcnt(6)
	s_barrier
	s_setprio 1
	v_mfma_f32_16x16x32_bf16 v[48:51], v[216:219], v[166:169], v[48:51]
	v_mfma_f32_16x16x32_bf16 v[40:43], v[224:227], v[166:169], v[40:43]
	v_mfma_f32_16x16x32_bf16 v[32:35], v[216:219], v[174:177], v[32:35]
	v_mfma_f32_16x16x32_bf16 v[24:27], v[224:227], v[174:177], v[24:27]
	v_mfma_f32_16x16x32_bf16 v[16:19], v[216:219], v[182:185], v[16:19]
	v_mfma_f32_16x16x32_bf16 v[8:11], v[224:227], v[182:185], v[8:11]
	v_mfma_f32_16x16x32_bf16 v[4:7], v[216:219], v[200:203], v[4:7]
	v_mfma_f32_16x16x32_bf16 v[0:3], v[224:227], v[200:203], v[0:3]
	v_mfma_f32_16x16x32_bf16 v[48:51], v[220:223], v[170:173], v[48:51]
	v_mfma_f32_16x16x32_bf16 v[40:43], v[228:231], v[170:173], v[40:43]
	v_mfma_f32_16x16x32_bf16 v[32:35], v[220:223], v[178:181], v[32:35]
	v_mfma_f32_16x16x32_bf16 v[24:27], v[228:231], v[178:181], v[24:27]
	v_mfma_f32_16x16x32_bf16 v[16:19], v[220:223], v[196:199], v[16:19]
	v_mfma_f32_16x16x32_bf16 v[8:11], v[228:231], v[196:199], v[8:11]
	v_mfma_f32_16x16x32_bf16 v[4:7], v[220:223], v[204:207], v[4:7]
	v_mfma_f32_16x16x32_bf16 v[0:3], v[228:231], v[204:207], v[0:3]
	s_setprio 0
	s_add_i32 s84, s84, 2
	s_add_u32 s4, s4, 0x100
	s_addc_u32 s5, s5, 0
	s_add_u32 s24, s24, 0x100
	s_addc_u32 s25, s25, 0
	s_cmp_gt_u32 s84, 13
	s_barrier
	s_cbranch_scc0 .LBB0_499
	s_lshl_b32 s15, s3, 8
	s_cmp_lt_i32 s3, 11
	s_mov_b64 s[4:5], -1
	s_cbranch_scc1 .LBB0_502
	s_mul_hi_i32 s3, s80, 0x3e0f83e1
	s_lshr_b32 s4, s3, 31
	s_ashr_i32 s3, s3, 3
	s_add_i32 s4, s3, s4
	v_cvt_pk_bf16_f32 v136, v124, v125
	s_mul_i32 s3, s4, 0xffffffdf
	v_cvt_pk_bf16_f32 v137, v126, v127
	ds_write_b16 v151, v136
	ds_write_b16_d16_hi v151, v136 offset:144
	ds_write_b16 v151, v137 offset:288
	ds_write_b16_d16_hi v151, v137 offset:432
	v_cvt_pk_bf16_f32 v136, v116, v117
	s_add_i32 s3, s3, s80
	v_cvt_pk_bf16_f32 v137, v118, v119
	ds_write_b16 v151, v136 offset:32
	ds_write_b16_d16_hi v151, v136 offset:176
	ds_write_b16 v151, v137 offset:320
	ds_write_b16_d16_hi v151, v137 offset:464
	v_cvt_pk_bf16_f32 v136, v100, v101
	s_lshl_b32 s24, s3, 8
	s_or_b32 s3, s15, s81
	v_cvt_pk_bf16_f32 v137, v102, v103
	ds_write_b16 v151, v136 offset:64
	ds_write_b16_d16_hi v151, v136 offset:208
	ds_write_b16 v151, v137 offset:352
	ds_write_b16_d16_hi v151, v137 offset:496
	v_cvt_pk_bf16_f32 v136, v84, v85
	s_ashr_i32 s5, s4, 31
	v_cvt_pk_bf16_f32 v137, v86, v87
	ds_write_b16 v151, v136 offset:96
	ds_write_b16_d16_hi v151, v136 offset:240
	ds_write_b16 v151, v137 offset:384
	ds_write_b16_d16_hi v151, v137 offset:528
	v_add_u32_e32 v136, s3, v152
	s_lshl_b64 s[4:5], s[4:5], 10
	v_ashrrev_i32_e32 v137, 31, v136
	v_lshl_add_u64 v[136:137], s[4:5], 0, v[136:137]
	v_mov_b64_e32 v[162:163], s[10:11]
	s_ashr_i32 s25, s24, 31
	ds_read_b128 v[138:141], v155
	v_mad_u64_u32 v[142:143], s[26:27], v136, s91, v[162:163]
	v_mad_i32_i24 v143, v137, s91, v143
	s_lshl_b64 s[34:35], s[24:25], 1
	v_lshl_add_u64 v[136:137], v[142:143], 0, s[34:35]
	v_lshl_add_u64 v[136:137], v[136:137], 0, s[12:13]
	v_lshl_add_u64 v[136:137], v[136:137], 0, v[144:145]
	s_waitcnt lgkmcnt(0)
	global_store_dwordx4 v[136:137], v[138:141], off
	ds_read_b128 v[140:143], v156
	s_or_b32 s17, s3, 4
	v_add_u32_e32 v138, s3, v153
	v_ashrrev_i32_e32 v139, 31, v138
	v_lshl_add_u64 v[138:139], s[4:5], 0, v[138:139]
	v_mad_u64_u32 v[146:147], s[24:25], v138, s91, v[162:163]
	v_mad_i32_i24 v147, v139, s91, v147
	v_lshl_add_u64 v[138:139], v[146:147], 0, s[34:35]
	v_lshl_add_u64 v[138:139], v[138:139], 0, s[12:13]
	v_lshl_add_u64 v[138:139], v[138:139], 0, v[144:145]
	s_waitcnt lgkmcnt(0)
; #define LAS __attribute__((address_space(3)))
; __device__ __forceinline__ unsigned pk2(float lo, float hi) { unsigned r; asm("v_cvt_pk_bf16_f32 %0, %1, %2" : "=v"(r) : "v"(lo), "v"(hi)); return r; }
;     __device__ __forceinline__ void operator()(const f32x4 (&acc)[2][2][4][2], const Unit& u, int wr, int wc, int fr, int fq) const {
;     ...
; #pragma unroll
;             for (int ai = 0; ai < 2; ++ai)
; #pragma unroll
;                 for (int bj = 0; bj < 2; ++bj)
; #pragma unroll
;                     for (int n = 0; n < 2; ++n) {
; #pragma unroll
;                         for (int m = 0; m < 4; ++m) {
;                             const f32x4 v = acc[ai][bj][m][n];
;                             const unsigned p0 = pk2(v[0], v[1]), p1 = pk2(v[2], v[3]);
;                             LAS bf16_t* w = sc + (4 * fq) * 72 + 16 * m + fr;
;                             w[0] = (bf16_t)(p0 & 0xffffu); w[72] = (bf16_t)(p0 >> 16); w[144] = (bf16_t)(p1 & 0xffffu); w[216] = (bf16_t)(p1 >> 16);
;                         }
; #pragma unroll
;                         for (int j = 0; j < 2; ++j) {
;                             const int ch = lane + 64 * j, fi = ch >> 3, seg = ch & 7;
;                             const u32x4 o = *(const LAS u32x4*)(sc + fi * 72 + 8 * seg);
;                             const int f = col_t - vt0 + 64 * wc + 16 * (fi >> 2) + 8 * bj + 4 * n + (fi & 3);
;                             *(u32x4*)(Vt + ((size_t)bl * vtnf + f) * KEYS + key0 + ai * HALF + wr * 64 + 8 * seg) = o;
;                         }
;                     }
	global_store_dwordx4 v[138:139], v[140:143], off
	v_cvt_pk_bf16_f32 v157, v104, v105
	s_nop 1
	v_cvt_pk_bf16_f32 v140, v120, v121
	v_cvt_pk_bf16_f32 v141, v122, v123
	ds_write_b16 v151, v140
	ds_write_b16_d16_hi v151, v140 offset:144
	ds_write_b16 v151, v141 offset:288
	ds_write_b16_d16_hi v151, v141 offset:432
	v_cvt_pk_bf16_f32 v140, v108, v109
	v_cvt_pk_bf16_f32 v141, v110, v111
	ds_write_b16 v151, v140 offset:32
	ds_write_b16_d16_hi v151, v140 offset:176
	ds_write_b16 v151, v141 offset:320
	ds_write_b16_d16_hi v151, v141 offset:464
	v_cvt_pk_bf16_f32 v140, v92, v93
	v_cvt_pk_bf16_f32 v141, v94, v95
	ds_write_b16 v151, v140 offset:64
	ds_write_b16_d16_hi v151, v140 offset:208
	ds_write_b16 v151, v141 offset:352
	ds_write_b16_d16_hi v151, v141 offset:496
	v_cvt_pk_bf16_f32 v140, v76, v77
	v_cvt_pk_bf16_f32 v141, v78, v79
	ds_write_b16 v151, v140 offset:96
	ds_write_b16_d16_hi v151, v140 offset:240
	ds_write_b16 v151, v141 offset:384
	ds_write_b16_d16_hi v151, v141 offset:528
	v_add_u32_e32 v140, s17, v152
	v_ashrrev_i32_e32 v141, 31, v140
	v_lshl_add_u64 v[140:141], s[4:5], 0, v[140:141]
	ds_read_b128 v[158:161], v155
	v_mad_u64_u32 v[142:143], s[24:25], v140, s91, v[162:163]
	v_mad_i32_i24 v143, v141, s91, v143
	v_lshl_add_u64 v[140:141], v[142:143], 0, s[34:35]
	v_add_u32_e32 v142, s17, v153
	v_lshl_add_u64 v[140:141], v[140:141], 0, s[12:13]
	v_ashrrev_i32_e32 v143, 31, v142
	v_lshl_add_u64 v[140:141], v[140:141], 0, v[144:145]
	v_lshl_add_u64 v[142:143], s[4:5], 0, v[142:143]
	s_waitcnt lgkmcnt(0)
	global_store_dwordx4 v[140:141], v[158:161], off
	ds_read_b128 v[158:161], v156
	v_mad_u64_u32 v[146:147], s[24:25], v142, s91, v[162:163]
	v_mad_i32_i24 v147, v143, s91, v147
	v_lshl_add_u64 v[142:143], v[146:147], 0, s[34:35]
	v_lshl_add_u64 v[142:143], v[142:143], 0, s[12:13]
	v_lshl_add_u64 v[142:143], v[142:143], 0, v[144:145]
	v_cvt_pk_bf16_f32 v146, v112, v113
	s_waitcnt lgkmcnt(0)
	global_store_dwordx4 v[142:143], v[158:161], off
	v_cvt_pk_bf16_f32 v147, v114, v115
	ds_write_b16 v151, v146
	ds_write_b16_d16_hi v151, v146 offset:144
	ds_write_b16 v151, v147 offset:288
	ds_write_b16_d16_hi v151, v147 offset:432
	v_cvt_pk_bf16_f32 v146, v96, v97
	v_cvt_pk_bf16_f32 v147, v98, v99
	ds_write_b16 v151, v146 offset:32
	ds_write_b16_d16_hi v151, v146 offset:176
	ds_write_b16 v151, v147 offset:320
	ds_write_b16_d16_hi v151, v147 offset:464
	v_cvt_pk_bf16_f32 v146, v80, v81
	s_or_b32 s17, s3, 8
	v_cvt_pk_bf16_f32 v147, v82, v83
	ds_write_b16 v151, v146 offset:64
	ds_write_b16_d16_hi v151, v146 offset:208
	ds_write_b16 v151, v147 offset:352
	ds_write_b16_d16_hi v151, v147 offset:496
	v_cvt_pk_bf16_f32 v146, v68, v69
	v_cvt_pk_bf16_f32 v147, v70, v71
	ds_write_b16 v151, v146 offset:96
	ds_write_b16_d16_hi v151, v146 offset:240
	ds_write_b16 v151, v147 offset:384
	ds_write_b16_d16_hi v151, v147 offset:528
	v_add_u32_e32 v146, s17, v152
	v_ashrrev_i32_e32 v147, 31, v146
	v_lshl_add_u64 v[146:147], s[4:5], 0, v[146:147]
	ds_read_b128 v[158:161], v155
	v_mad_u64_u32 v[164:165], s[24:25], v146, s91, v[162:163]
	v_mad_i32_i24 v165, v147, s91, v165
	v_lshl_add_u64 v[146:147], v[164:165], 0, s[34:35]
	v_add_u32_e32 v164, s17, v153
	v_lshl_add_u64 v[146:147], v[146:147], 0, s[12:13]
	v_ashrrev_i32_e32 v165, 31, v164
	v_lshl_add_u64 v[146:147], v[146:147], 0, v[144:145]
	v_lshl_add_u64 v[164:165], s[4:5], 0, v[164:165]
	s_waitcnt lgkmcnt(0)
	global_store_dwordx4 v[146:147], v[158:161], off
	ds_read_b128 v[158:161], v156
	v_mad_u64_u32 v[166:167], s[24:25], v164, s91, v[162:163]
	v_mad_i32_i24 v167, v165, s91, v167
	v_lshl_add_u64 v[164:165], v[166:167], 0, s[34:35]
	v_lshl_add_u64 v[164:165], v[164:165], 0, s[12:13]
	v_lshl_add_u64 v[164:165], v[164:165], 0, v[144:145]
	s_waitcnt lgkmcnt(0)
	global_store_dwordx4 v[164:165], v[158:161], off
	s_or_b32 s3, s3, 12
	v_add_u32_e32 v166, s3, v152
	v_cvt_pk_bf16_f32 v158, v106, v107
	ds_write_b16 v151, v157
	ds_write_b16_d16_hi v151, v157 offset:144
	ds_write_b16 v151, v158 offset:288
	ds_write_b16_d16_hi v151, v158 offset:432
	v_cvt_pk_bf16_f32 v157, v88, v89
	v_cvt_pk_bf16_f32 v158, v90, v91
	ds_write_b16 v151, v157 offset:32
	ds_write_b16_d16_hi v151, v157 offset:176
	ds_write_b16 v151, v158 offset:320
	ds_write_b16_d16_hi v151, v158 offset:464
	v_cvt_pk_bf16_f32 v157, v72, v73
	v_cvt_pk_bf16_f32 v158, v74, v75
	ds_write_b16 v151, v157 offset:64
	ds_write_b16_d16_hi v151, v157 offset:208
	ds_write_b16 v151, v158 offset:352
	ds_write_b16_d16_hi v151, v158 offset:496
	v_cvt_pk_bf16_f32 v157, v64, v65
	v_ashrrev_i32_e32 v167, 31, v166
	v_cvt_pk_bf16_f32 v158, v66, v67
	ds_write_b16 v151, v157 offset:96
	ds_write_b16_d16_hi v151, v157 offset:240
	ds_write_b16 v151, v158 offset:384
	ds_write_b16_d16_hi v151, v158 offset:528
	v_lshl_add_u64 v[166:167], s[4:5], 0, v[166:167]
	ds_read_b128 v[158:161], v155
	v_mad_u64_u32 v[168:169], s[24:25], v166, s91, v[162:163]
	v_mad_i32_i24 v169, v167, s91, v169
	v_lshl_add_u64 v[166:167], v[168:169], 0, s[34:35]
	v_add_u32_e32 v168, s3, v153
	v_lshl_add_u64 v[166:167], v[166:167], 0, s[12:13]
	v_ashrrev_i32_e32 v169, 31, v168
	v_lshl_add_u64 v[166:167], v[166:167], 0, v[144:145]
	v_lshl_add_u64 v[168:169], s[4:5], 0, v[168:169]
	s_waitcnt lgkmcnt(0)
; #define LAS __attribute__((address_space(3)))
; __device__ __forceinline__ unsigned pk2(float lo, float hi) { unsigned r; asm("v_cvt_pk_bf16_f32 %0, %1, %2" : "=v"(r) : "v"(lo), "v"(hi)); return r; }
;     __device__ __forceinline__ void operator()(const f32x4 (&acc)[2][2][4][2], const Unit& u, int wr, int wc, int fr, int fq) const {
;     ...
; #pragma unroll
;             for (int ai = 0; ai < 2; ++ai)
; #pragma unroll
;                 for (int bj = 0; bj < 2; ++bj)
; #pragma unroll
;                     for (int n = 0; n < 2; ++n) {
; #pragma unroll
;                         for (int m = 0; m < 4; ++m) {
;                             const f32x4 v = acc[ai][bj][m][n];
;                             const unsigned p0 = pk2(v[0], v[1]), p1 = pk2(v[2], v[3]);
;                             LAS bf16_t* w = sc + (4 * fq) * 72 + 16 * m + fr;
;                             w[0] = (bf16_t)(p0 & 0xffffu); w[72] = (bf16_t)(p0 >> 16); w[144] = (bf16_t)(p1 & 0xffffu); w[216] = (bf16_t)(p1 >> 16);
;                         }
; #pragma unroll
;                         for (int j = 0; j < 2; ++j) {
;                             const int ch = lane + 64 * j, fi = ch >> 3, seg = ch & 7;
;                             const u32x4 o = *(const LAS u32x4*)(sc + fi * 72 + 8 * seg);
;                             const int f = col_t - vt0 + 64 * wc + 16 * (fi >> 2) + 8 * bj + 4 * n + (fi & 3);
;                             *(u32x4*)(Vt + ((size_t)bl * vtnf + f) * KEYS + key0 + ai * HALF + wr * 64 + 8 * seg) = o;
;                         }
;                     }
	global_store_dwordx4 v[166:167], v[158:161], off
	ds_read_b128 v[158:161], v156
	v_mad_u64_u32 v[162:163], s[4:5], v168, s91, v[162:163]
	v_mad_i32_i24 v163, v169, s91, v163
	v_lshl_add_u64 v[162:163], v[162:163], 0, s[34:35]
	v_lshl_add_u64 v[162:163], v[162:163], 0, s[12:13]
	v_lshl_add_u64 v[162:163], v[162:163], 0, v[144:145]
	v_cvt_pk_bf16_f32 v157, v60, v61
	s_waitcnt lgkmcnt(0)
	global_store_dwordx4 v[162:163], v[158:161], off
	s_mov_b64 s[4:5], 0
	s_nop 0
	v_cvt_pk_bf16_f32 v158, v62, v63
	ds_write_b16 v151, v157
	ds_write_b16_d16_hi v151, v157 offset:144
	ds_write_b16 v151, v158 offset:288
	ds_write_b16_d16_hi v151, v158 offset:432
	v_cvt_pk_bf16_f32 v157, v52, v53
	v_cvt_pk_bf16_f32 v158, v54, v55
	ds_write_b16 v151, v157 offset:32
	ds_write_b16_d16_hi v151, v157 offset:176
	ds_write_b16 v151, v158 offset:320
	ds_write_b16_d16_hi v151, v158 offset:464
	v_cvt_pk_bf16_f32 v157, v36, v37
	v_cvt_pk_bf16_f32 v158, v38, v39
	ds_write_b16 v151, v157 offset:64
	ds_write_b16_d16_hi v151, v157 offset:208
	ds_write_b16 v151, v158 offset:352
	ds_write_b16_d16_hi v151, v158 offset:496
	v_cvt_pk_bf16_f32 v157, v20, v21
	v_cvt_pk_bf16_f32 v158, v22, v23
	ds_write_b16 v151, v157 offset:96
	ds_write_b16_d16_hi v151, v157 offset:240
	ds_write_b16 v151, v158 offset:384
	ds_write_b16_d16_hi v151, v158 offset:528
	ds_read_b128 v[158:161], v155
	s_waitcnt lgkmcnt(0)
	global_store_dwordx4 v[136:137], v[158:161], off offset:256
	ds_read_b128 v[158:161], v156
	v_cvt_pk_bf16_f32 v136, v56, v57
	v_cvt_pk_bf16_f32 v137, v58, v59
	s_waitcnt lgkmcnt(0)
	global_store_dwordx4 v[138:139], v[158:161], off offset:256
	ds_write_b16 v151, v136
	ds_write_b16_d16_hi v151, v136 offset:144
	ds_write_b16 v151, v137 offset:288
	ds_write_b16_d16_hi v151, v137 offset:432
	v_cvt_pk_bf16_f32 v136, v44, v45
	v_cvt_pk_bf16_f32 v137, v46, v47
	ds_write_b16 v151, v136 offset:32
	ds_write_b16_d16_hi v151, v136 offset:176
	ds_write_b16 v151, v137 offset:320
	ds_write_b16_d16_hi v151, v137 offset:464
	v_cvt_pk_bf16_f32 v136, v28, v29
	v_cvt_pk_bf16_f32 v137, v30, v31
	ds_write_b16 v151, v136 offset:64
	ds_write_b16_d16_hi v151, v136 offset:208
	ds_write_b16 v151, v137 offset:352
	ds_write_b16_d16_hi v151, v137 offset:496
	v_cvt_pk_bf16_f32 v136, v12, v13
	v_cvt_pk_bf16_f32 v137, v14, v15
	ds_write_b16 v151, v136 offset:96
	ds_write_b16_d16_hi v151, v136 offset:240
	ds_write_b16 v151, v137 offset:384
	ds_write_b16_d16_hi v151, v137 offset:528
	ds_read_b128 v[136:139], v155
	s_waitcnt lgkmcnt(0)
	global_store_dwordx4 v[140:141], v[136:139], off offset:256
	ds_read_b128 v[136:139], v156
	s_waitcnt lgkmcnt(0)
	global_store_dwordx4 v[142:143], v[136:139], off offset:256
	s_nop 1
	v_cvt_pk_bf16_f32 v136, v48, v49
	v_cvt_pk_bf16_f32 v137, v50, v51
	ds_write_b16 v151, v136
	ds_write_b16_d16_hi v151, v136 offset:144
	ds_write_b16 v151, v137 offset:288
	ds_write_b16_d16_hi v151, v137 offset:432
	v_cvt_pk_bf16_f32 v136, v32, v33
	v_cvt_pk_bf16_f32 v137, v34, v35
	ds_write_b16 v151, v136 offset:32
	ds_write_b16_d16_hi v151, v136 offset:176
	ds_write_b16 v151, v137 offset:320
	ds_write_b16_d16_hi v151, v137 offset:464
	v_cvt_pk_bf16_f32 v136, v16, v17
	v_cvt_pk_bf16_f32 v137, v18, v19
	ds_write_b16 v151, v136 offset:64
	ds_write_b16_d16_hi v151, v136 offset:208
	ds_write_b16 v151, v137 offset:352
	ds_write_b16_d16_hi v151, v137 offset:496
	v_cvt_pk_bf16_f32 v136, v4, v5
	v_cvt_pk_bf16_f32 v137, v6, v7
	ds_write_b16 v151, v136 offset:96
	ds_write_b16_d16_hi v151, v136 offset:240
	ds_write_b16 v151, v137 offset:384
	ds_write_b16_d16_hi v151, v137 offset:528
	ds_read_b128 v[136:139], v155
	s_waitcnt lgkmcnt(0)
	global_store_dwordx4 v[146:147], v[136:139], off offset:256
	ds_read_b128 v[136:139], v156
	s_waitcnt lgkmcnt(0)
	global_store_dwordx4 v[164:165], v[136:139], off offset:256
	s_nop 1
	v_cvt_pk_bf16_f32 v136, v40, v41
	v_cvt_pk_bf16_f32 v137, v42, v43
	ds_write_b16 v151, v136
	ds_write_b16_d16_hi v151, v136 offset:144
	ds_write_b16 v151, v137 offset:288
	ds_write_b16_d16_hi v151, v137 offset:432
	v_cvt_pk_bf16_f32 v136, v24, v25
	v_cvt_pk_bf16_f32 v137, v26, v27
	ds_write_b16 v151, v136 offset:32
	ds_write_b16_d16_hi v151, v136 offset:176
	ds_write_b16 v151, v137 offset:320
	ds_write_b16_d16_hi v151, v137 offset:464
	v_cvt_pk_bf16_f32 v136, v8, v9
	v_cvt_pk_bf16_f32 v137, v10, v11
	ds_write_b16 v151, v136 offset:64
	ds_write_b16_d16_hi v151, v136 offset:208
	ds_write_b16 v151, v137 offset:352
	ds_write_b16_d16_hi v151, v137 offset:496
	v_cvt_pk_bf16_f32 v136, v0, v1
	v_cvt_pk_bf16_f32 v137, v2, v3
	ds_write_b16 v151, v136 offset:96
	ds_write_b16_d16_hi v151, v136 offset:240
	ds_write_b16 v151, v137 offset:384
	ds_write_b16_d16_hi v151, v137 offset:528
	ds_read_b128 v[136:139], v155
	s_waitcnt lgkmcnt(0)
	global_store_dwordx4 v[166:167], v[136:139], off offset:256
	ds_read_b128 v[136:139], v156
	s_waitcnt lgkmcnt(0)
	global_store_dwordx4 v[162:163], v[136:139], off offset:256

; #define PG8_STAGE(bufoff, gbase, voff) do { _Pragma("unroll") for (int _i = 0; _i < 2; ++_i) \
;         __builtin_amdgcn_global_load_lds((const unsigned*)((const char*)(gbase) + (voff)[_i]), (LAS unsigned*)(lds + (bufoff) + ldsw + _i * 8192), 16, 0, 0); } while (0)
; #define PG8_LDA(dst, b, h) do { _Pragma("unroll") for (int m = 0; m < 4; ++m) _Pragma("unroll") for (int k = 0; k < 2; ++k) dst[m][k] = *(const LAS bf16x8*)(lds + PG8_SA(b, h) + aoff + m * 2048 + k * 1024); } while (0)
; #define PG8_LDB(dst, b, h) do { _Pragma("unroll") for (int n = 0; n < 2; ++n) _Pragma("unroll") for (int k = 0; k < 2; ++k) dst[n][k] = *(const LAS bf16x8*)(lds + PG8_SB(b, h) + boff + n * 2048 + k * 1024); } while (0)
; #define PG8_MMA(ai, bj, At, Bt) do { __builtin_amdgcn_s_setprio(1); _Pragma("unroll") for (int m = 0; m < 4; ++m) _Pragma("unroll") for (int n = 0; n < 2; ++n) _Pragma("unroll") for (int k = 0; k < 2; ++k) \
;         acc[ai][bj][m][n] = __builtin_amdgcn_mfma_f32_16x16x32_bf16(Bt[n][k], At[m][k], acc[ai][bj][m][n], 0, 0, 0); __builtin_amdgcn_s_setprio(0); } while (0)
; template <class Epi>
; __device__ __forceinline__ void gemm_phase(LAS unsigned char* lds, const Gemm g, const StaticOrder& S, const Epi& E) {
;     ...
;         const bool has_next = S.next(ui + 1, nxt);
;         const char* nA = has_next ? g.arow(nxt.pm) : cA; const char* nB = has_next ? (const char*)g.Bt + (size_t)nxt.pn * tB : cB;
;         for (int t = 0; t < nt; t += 2) {
;             const bool last = (t == nt - 2);
;             const char* a1 = cA + (size_t)(t + 1) * kstep;
;             const char* a2 = last ? nA : cA + (size_t)(t + 2) * kstep; const char* b2 = last ? nB : cB + (size_t)(t + 2) * kstep;
;             const char* a3 = a2 + kstep; const char* b3 = b2 + kstep;
;             PG8_LDB(B0, 0, 0); PG8_SCHED; PG8_LDA(At, 0, 0); PG8_STAGE(PG8_SA(1, 1), a1 + hA, voffA);
;             PG8_WAIT_L(8); PG8_BAR; PG8_WAIT_L(0); PG8_MMA(0, 0, At, B0); PG8_BAR; PG8_SCHED;
;             PG8_LDB(B1, 0, 1); PG8_STAGE(PG8_SB(0, 0), b2, voffB);
;             PG8_BAR; PG8_WAIT_L(0); PG8_MMA(0, 1, At, B1); PG8_BAR;
;             PG8_LDA(At, 0, 1); PG8_STAGE(PG8_SA(0, 0), a2, voffA);
;             PG8_BAR; PG8_WAIT_L(0); PG8_MMA(1, 0, At, B0); PG8_BAR; PG8_SCHED;
;             PG8_STAGE(PG8_SB(0, 1), b2 + hB, voffB);
;             PG8_WAIT_V(6); PG8_BAR; PG8_MMA(1, 1, At, B1); PG8_BAR;
.LBB0_655:
	s_add_u32 s12, s10, 0x100
	s_addc_u32 s13, s11, 0
	s_add_i32 s26, 0, 0x10000
	v_add_u32_e32 v156, s26, v143
	ds_read_b128 v[138:141], v156
	ds_read_b128 v[148:151], v156 offset:1024
	ds_read_b128 v[152:155], v156 offset:2048
	ds_read_b128 v[156:159], v156 offset:3072
	s_cmp_eq_u32 s78, 2
	s_cselect_b32 s21, s5, s13
	s_cselect_b32 s20, s4, s12
	s_cselect_b32 s17, s7, s25
	s_cselect_b32 s16, s6, s24
	v_lshl_add_u64 v[184:185], s[10:11], 0, v[134:135]
	s_add_i32 m0, s64, 0xc000
	ds_read_b128 v[160:163], v147
	ds_read_b128 v[164:167], v147 offset:1024
	ds_read_b128 v[168:171], v147 offset:2048
	ds_read_b128 v[172:175], v147 offset:3072
	ds_read_b128 v[176:179], v147 offset:4096
	ds_read_b128 v[180:183], v147 offset:5120
	ds_read_b128 v[196:199], v147 offset:6144
	ds_read_b128 v[200:203], v147 offset:7168
	global_load_lds_dwordx4 v[184:185], off
	s_add_i32 m0, s64, 0xe000
	v_lshl_add_u64 v[184:185], s[10:11], 0, v[136:137]
	global_load_lds_dwordx4 v[184:185], off
	s_waitcnt lgkmcnt(8)
	s_barrier
	s_waitcnt lgkmcnt(0)
	s_setprio 1
	v_mfma_f32_16x16x32_bf16 v[124:127], v[138:141], v[160:163], v[124:127]
	v_mfma_f32_16x16x32_bf16 v[120:123], v[152:155], v[160:163], v[120:123]
	v_mfma_f32_16x16x32_bf16 v[116:119], v[138:141], v[168:171], v[116:119]
	v_mfma_f32_16x16x32_bf16 v[108:111], v[152:155], v[168:171], v[108:111]
	v_mfma_f32_16x16x32_bf16 v[100:103], v[138:141], v[176:179], v[100:103]
	v_mfma_f32_16x16x32_bf16 v[92:95], v[152:155], v[176:179], v[92:95]
	v_mfma_f32_16x16x32_bf16 v[84:87], v[138:141], v[196:199], v[84:87]
	v_mfma_f32_16x16x32_bf16 v[76:79], v[152:155], v[196:199], v[76:79]
	v_mfma_f32_16x16x32_bf16 v[124:127], v[148:151], v[164:167], v[124:127]
	v_mfma_f32_16x16x32_bf16 v[120:123], v[156:159], v[164:167], v[120:123]
	v_mfma_f32_16x16x32_bf16 v[116:119], v[148:151], v[172:175], v[116:119]
	v_mfma_f32_16x16x32_bf16 v[108:111], v[156:159], v[172:175], v[108:111]
	v_mfma_f32_16x16x32_bf16 v[100:103], v[148:151], v[180:183], v[100:103]
	v_mfma_f32_16x16x32_bf16 v[92:95], v[156:159], v[180:183], v[92:95]
	v_mfma_f32_16x16x32_bf16 v[84:87], v[148:151], v[200:203], v[84:87]
	v_mfma_f32_16x16x32_bf16 v[76:79], v[156:159], v[200:203], v[76:79]
	s_setprio 0
	s_barrier
	s_add_i32 s27, 0, 0x14000
	v_add_u32_e32 v184, s27, v143
	s_add_i32 s10, s26, s63
	ds_read_b128 v[204:207], v184
	ds_read_b128 v[216:219], v184 offset:1024
	ds_read_b128 v[220:223], v184 offset:2048
	ds_read_b128 v[224:227], v184 offset:3072
	v_lshl_add_u64 v[184:185], s[16:17], 0, v[144:145]
	s_mov_b32 m0, s10
	v_lshl_add_u64 v[186:187], s[16:17], 0, v[132:133]
	global_load_lds_dwordx4 v[184:185], off
	s_add_i32 m0, s10, 0x2000
	s_nop 0
	global_load_lds_dwordx4 v[186:187], off
	s_barrier
	s_waitcnt lgkmcnt(0)
	s_setprio 1
	v_mfma_f32_16x16x32_bf16 v[112:115], v[204:207], v[160:163], v[112:115]
	v_mfma_f32_16x16x32_bf16 v[104:107], v[220:223], v[160:163], v[104:107]
	v_mfma_f32_16x16x32_bf16 v[96:99], v[204:207], v[168:171], v[96:99]
	v_mfma_f32_16x16x32_bf16 v[88:91], v[220:223], v[168:171], v[88:91]
	v_mfma_f32_16x16x32_bf16 v[80:83], v[204:207], v[176:179], v[80:83]
	v_mfma_f32_16x16x32_bf16 v[72:75], v[220:223], v[176:179], v[72:75]
	v_mfma_f32_16x16x32_bf16 v[68:71], v[204:207], v[196:199], v[68:71]
	v_mfma_f32_16x16x32_bf16 v[64:67], v[220:223], v[196:199], v[64:67]
	v_mfma_f32_16x16x32_bf16 v[112:115], v[216:219], v[164:167], v[112:115]
	v_mfma_f32_16x16x32_bf16 v[104:107], v[224:227], v[164:167], v[104:107]
	v_mfma_f32_16x16x32_bf16 v[96:99], v[216:219], v[172:175], v[96:99]
	v_mfma_f32_16x16x32_bf16 v[88:91], v[224:227], v[172:175], v[88:91]
	v_mfma_f32_16x16x32_bf16 v[80:83], v[216:219], v[180:183], v[80:83]
	v_mfma_f32_16x16x32_bf16 v[72:75], v[224:227], v[180:183], v[72:75]
	v_mfma_f32_16x16x32_bf16 v[68:71], v[216:219], v[200:203], v[68:71]
	v_mfma_f32_16x16x32_bf16 v[64:67], v[224:227], v[200:203], v[64:67]
	s_setprio 0
	s_mov_b32 m0, s64
	v_lshl_add_u64 v[188:189], s[20:21], 0, v[128:129]
	s_barrier
	ds_read_b128 v[160:163], v147 offset:16384
	ds_read_b128 v[164:167], v147 offset:17408
	ds_read_b128 v[168:171], v147 offset:18432
	ds_read_b128 v[172:175], v147 offset:19456
	ds_read_b128 v[176:179], v147 offset:20480
	ds_read_b128 v[180:183], v147 offset:21504
	ds_read_b128 v[196:199], v147 offset:22528
	ds_read_b128 v[200:203], v147 offset:23552
	global_load_lds_dwordx4 v[188:189], off
	s_mov_b32 m0, s65
	v_lshl_add_u64 v[192:193], s[20:21], 0, v[130:131]
	global_load_lds_dwordx4 v[192:193], off
	s_barrier
	s_waitcnt lgkmcnt(0)
	s_setprio 1
	v_mfma_f32_16x16x32_bf16 v[60:63], v[138:141], v[160:163], v[60:63]
	v_mfma_f32_16x16x32_bf16 v[56:59], v[152:155], v[160:163], v[56:59]
	v_mfma_f32_16x16x32_bf16 v[52:55], v[138:141], v[168:171], v[52:55]
	v_mfma_f32_16x16x32_bf16 v[44:47], v[152:155], v[168:171], v[44:47]
	v_mfma_f32_16x16x32_bf16 v[36:39], v[138:141], v[176:179], v[36:39]
	v_mfma_f32_16x16x32_bf16 v[28:31], v[152:155], v[176:179], v[28:31]
	v_mfma_f32_16x16x32_bf16 v[20:23], v[138:141], v[196:199], v[20:23]
	v_mfma_f32_16x16x32_bf16 v[12:15], v[152:155], v[196:199], v[12:15]
	v_mfma_f32_16x16x32_bf16 v[60:63], v[148:151], v[164:167], v[60:63]
	v_mfma_f32_16x16x32_bf16 v[56:59], v[156:159], v[164:167], v[56:59]
	v_mfma_f32_16x16x32_bf16 v[52:55], v[148:151], v[172:175], v[52:55]
	v_mfma_f32_16x16x32_bf16 v[44:47], v[156:159], v[172:175], v[44:47]
	v_mfma_f32_16x16x32_bf16 v[36:39], v[148:151], v[180:183], v[36:39]
	v_mfma_f32_16x16x32_bf16 v[28:31], v[156:159], v[180:183], v[28:31]
	v_mfma_f32_16x16x32_bf16 v[20:23], v[148:151], v[200:203], v[20:23]
	v_mfma_f32_16x16x32_bf16 v[12:15], v[156:159], v[200:203], v[12:15]
	s_setprio 0
	s_barrier
; #define PG8_STAGE(bufoff, gbase, voff) do { _Pragma("unroll") for (int _i = 0; _i < 2; ++_i) \
;         __builtin_amdgcn_global_load_lds((const unsigned*)((const char*)(gbase) + (voff)[_i]), (LAS unsigned*)(lds + (bufoff) + ldsw + _i * 8192), 16, 0, 0); } while (0)
; #define PG8_LDA(dst, b, h) do { _Pragma("unroll") for (int m = 0; m < 4; ++m) _Pragma("unroll") for (int k = 0; k < 2; ++k) dst[m][k] = *(const LAS bf16x8*)(lds + PG8_SA(b, h) + aoff + m * 2048 + k * 1024); } while (0)
; #define PG8_LDB(dst, b, h) do { _Pragma("unroll") for (int n = 0; n < 2; ++n) _Pragma("unroll") for (int k = 0; k < 2; ++k) dst[n][k] = *(const LAS bf16x8*)(lds + PG8_SB(b, h) + boff + n * 2048 + k * 1024); } while (0)
; #define PG8_MMA(ai, bj, At, Bt) do { __builtin_amdgcn_s_setprio(1); _Pragma("unroll") for (int m = 0; m < 4; ++m) _Pragma("unroll") for (int n = 0; n < 2; ++n) _Pragma("unroll") for (int k = 0; k < 2; ++k) \
;         acc[ai][bj][m][n] = __builtin_amdgcn_mfma_f32_16x16x32_bf16(Bt[n][k], At[m][k], acc[ai][bj][m][n], 0, 0, 0); __builtin_amdgcn_s_setprio(0); } while (0)
; #define PG8_WAIT_V(n) asm volatile("s_waitcnt vmcnt(" #n ")" ::: "memory")
; #define PG8_WAIT_L(n) asm volatile("s_waitcnt lgkmcnt(" #n ")" ::: "memory")
; #define PG8_BAR __builtin_amdgcn_s_barrier()
; #define PG8_SCHED __builtin_amdgcn_sched_barrier(0)
; template <class Epi>
; __device__ __forceinline__ void gemm_phase(LAS unsigned char* lds, const Gemm g, const StaticOrder& S, const Epi& E) {
;     ...
;             PG8_WAIT_V(6); PG8_BAR; PG8_MMA(1, 1, At, B1); PG8_BAR;
;             PG8_LDB(B0, 1, 0); PG8_SCHED; PG8_LDA(At, 1, 0); PG8_STAGE(PG8_SA(0, 1), a2 + hA, voffA);
;             PG8_WAIT_L(8); PG8_BAR; PG8_WAIT_L(0); PG8_MMA(0, 0, At, B0); PG8_BAR; PG8_SCHED;
;             PG8_LDB(B1, 1, 1); PG8_STAGE(PG8_SB(1, 0), b3, voffB);
;             PG8_BAR; PG8_WAIT_L(0); PG8_MMA(0, 1, At, B1); PG8_BAR;
;             PG8_LDA(At, 1, 1); PG8_STAGE(PG8_SA(1, 0), a3, voffA);
;             PG8_BAR; PG8_WAIT_L(0); PG8_MMA(1, 0, At, B0); PG8_BAR; PG8_SCHED;
;             PG8_STAGE(PG8_SB(1, 1), b3 + hB, voffB);
;             PG8_WAIT_V(6); PG8_BAR; PG8_MMA(1, 1, At, B1); PG8_BAR;
	s_add_u32 s10, s16, 0x18000
	s_addc_u32 s11, s17, 0
	s_add_i32 s26, s27, s63
	s_mov_b32 m0, s26
	v_lshl_add_u64 v[138:139], s[10:11], 0, v[144:145]
	global_load_lds_dwordx4 v[138:139], off
	s_add_i32 m0, s26, 0x2000
	v_lshl_add_u64 v[138:139], s[10:11], 0, v[132:133]
	global_load_lds_dwordx4 v[138:139], off
	s_waitcnt vmcnt(6)
	s_barrier
	s_setprio 1
	v_mfma_f32_16x16x32_bf16 v[48:51], v[204:207], v[160:163], v[48:51]
	v_mfma_f32_16x16x32_bf16 v[40:43], v[220:223], v[160:163], v[40:43]
	v_mfma_f32_16x16x32_bf16 v[32:35], v[204:207], v[168:171], v[32:35]
	v_mfma_f32_16x16x32_bf16 v[24:27], v[220:223], v[168:171], v[24:27]
	v_mfma_f32_16x16x32_bf16 v[16:19], v[204:207], v[176:179], v[16:19]
	v_mfma_f32_16x16x32_bf16 v[8:11], v[220:223], v[176:179], v[8:11]
	v_mfma_f32_16x16x32_bf16 v[4:7], v[204:207], v[196:199], v[4:7]
	v_mfma_f32_16x16x32_bf16 v[0:3], v[220:223], v[196:199], v[0:3]
	v_mfma_f32_16x16x32_bf16 v[48:51], v[216:219], v[164:167], v[48:51]
	v_mfma_f32_16x16x32_bf16 v[40:43], v[224:227], v[164:167], v[40:43]
	v_mfma_f32_16x16x32_bf16 v[32:35], v[216:219], v[172:175], v[32:35]
	v_mfma_f32_16x16x32_bf16 v[24:27], v[224:227], v[172:175], v[24:27]
	v_mfma_f32_16x16x32_bf16 v[16:19], v[216:219], v[180:183], v[16:19]
	v_mfma_f32_16x16x32_bf16 v[8:11], v[224:227], v[180:183], v[8:11]
	v_mfma_f32_16x16x32_bf16 v[4:7], v[216:219], v[200:203], v[4:7]
	v_mfma_f32_16x16x32_bf16 v[0:3], v[224:227], v[200:203], v[0:3]
	s_setprio 0
	s_add_i32 s26, 0, 0x18000
	v_add_u32_e32 v156, s26, v143
	s_barrier
	ds_read_b128 v[138:141], v156
	ds_read_b128 v[148:151], v156 offset:1024
	ds_read_b128 v[152:155], v156 offset:2048
	ds_read_b128 v[156:159], v156 offset:3072
	s_add_u32 s10, s20, 0xb0000
	s_addc_u32 s11, s21, 0
	s_mov_b32 m0, s66
	v_lshl_add_u64 v[204:205], s[10:11], 0, v[128:129]
	ds_read_b128 v[160:163], v147 offset:32768
	ds_read_b128 v[164:167], v147 offset:33792
	ds_read_b128 v[168:171], v147 offset:34816
	ds_read_b128 v[172:175], v147 offset:35840
	ds_read_b128 v[176:179], v147 offset:36864
	ds_read_b128 v[180:183], v147 offset:37888
	ds_read_b128 v[196:199], v147 offset:38912
	ds_read_b128 v[200:203], v147 offset:39936
	global_load_lds_dwordx4 v[204:205], off
	s_mov_b32 m0, s68
	v_lshl_add_u64 v[204:205], s[10:11], 0, v[130:131]
	global_load_lds_dwordx4 v[204:205], off
	s_waitcnt lgkmcnt(8)
	s_barrier
	s_waitcnt lgkmcnt(0)
	s_setprio 1
	v_mfma_f32_16x16x32_bf16 v[124:127], v[138:141], v[160:163], v[124:127]
	v_mfma_f32_16x16x32_bf16 v[120:123], v[152:155], v[160:163], v[120:123]
	v_mfma_f32_16x16x32_bf16 v[116:119], v[138:141], v[168:171], v[116:119]
	v_mfma_f32_16x16x32_bf16 v[108:111], v[152:155], v[168:171], v[108:111]
	v_mfma_f32_16x16x32_bf16 v[100:103], v[138:141], v[176:179], v[100:103]
	v_mfma_f32_16x16x32_bf16 v[92:95], v[152:155], v[176:179], v[92:95]
	v_mfma_f32_16x16x32_bf16 v[84:87], v[138:141], v[196:199], v[84:87]
	v_mfma_f32_16x16x32_bf16 v[76:79], v[152:155], v[196:199], v[76:79]
	v_mfma_f32_16x16x32_bf16 v[124:127], v[148:151], v[164:167], v[124:127]
	v_mfma_f32_16x16x32_bf16 v[120:123], v[156:159], v[164:167], v[120:123]
	v_mfma_f32_16x16x32_bf16 v[116:119], v[148:151], v[172:175], v[116:119]
	v_mfma_f32_16x16x32_bf16 v[108:111], v[156:159], v[172:175], v[108:111]
	v_mfma_f32_16x16x32_bf16 v[100:103], v[148:151], v[180:183], v[100:103]
	v_mfma_f32_16x16x32_bf16 v[92:95], v[156:159], v[180:183], v[92:95]
	v_mfma_f32_16x16x32_bf16 v[84:87], v[148:151], v[200:203], v[84:87]
	v_mfma_f32_16x16x32_bf16 v[76:79], v[156:159], v[200:203], v[76:79]
	s_setprio 0
	s_barrier
	s_add_i32 s20, 0, 0x1c000
	s_add_i32 s10, s26, s63
	v_add_u32_e32 v190, s20, v143
	v_lshl_add_u64 v[184:185], v[184:185], 0, s[88:89]
	s_mov_b32 m0, s10
	ds_read_b128 v[204:207], v190
	ds_read_b128 v[216:219], v190 offset:1024
	ds_read_b128 v[220:223], v190 offset:2048
	ds_read_b128 v[224:227], v190 offset:3072
	global_load_lds_dwordx4 v[184:185], off
	s_add_i32 m0, s10, 0x2000
	v_lshl_add_u64 v[184:185], v[186:187], 0, s[88:89]
	global_load_lds_dwordx4 v[184:185], off
	s_barrier
	s_waitcnt lgkmcnt(0)
	s_setprio 1
	v_mfma_f32_16x16x32_bf16 v[112:115], v[204:207], v[160:163], v[112:115]
	v_mfma_f32_16x16x32_bf16 v[104:107], v[220:223], v[160:163], v[104:107]
	v_mfma_f32_16x16x32_bf16 v[96:99], v[204:207], v[168:171], v[96:99]
	v_mfma_f32_16x16x32_bf16 v[88:91], v[220:223], v[168:171], v[88:91]
	v_mfma_f32_16x16x32_bf16 v[80:83], v[204:207], v[176:179], v[80:83]
	v_mfma_f32_16x16x32_bf16 v[72:75], v[220:223], v[176:179], v[72:75]
	v_mfma_f32_16x16x32_bf16 v[68:71], v[204:207], v[196:199], v[68:71]
	v_mfma_f32_16x16x32_bf16 v[64:67], v[220:223], v[196:199], v[64:67]
	v_mfma_f32_16x16x32_bf16 v[112:115], v[216:219], v[164:167], v[112:115]
	v_mfma_f32_16x16x32_bf16 v[104:107], v[224:227], v[164:167], v[104:107]
	v_mfma_f32_16x16x32_bf16 v[96:99], v[216:219], v[172:175], v[96:99]
	v_mfma_f32_16x16x32_bf16 v[88:91], v[224:227], v[172:175], v[88:91]
	v_mfma_f32_16x16x32_bf16 v[80:83], v[216:219], v[180:183], v[80:83]
	v_mfma_f32_16x16x32_bf16 v[72:75], v[224:227], v[180:183], v[72:75]
	v_mfma_f32_16x16x32_bf16 v[68:71], v[216:219], v[200:203], v[68:71]
	v_mfma_f32_16x16x32_bf16 v[64:67], v[224:227], v[200:203], v[64:67]
	s_setprio 0
	s_mov_b32 m0, s69
	v_lshl_add_u64 v[184:185], v[188:189], 0, s[88:89]
	s_barrier
	ds_read_b128 v[160:163], v147 offset:49152
	ds_read_b128 v[164:167], v147 offset:50176
	ds_read_b128 v[168:171], v147 offset:51200
	ds_read_b128 v[172:175], v147 offset:52224
	ds_read_b128 v[176:179], v147 offset:53248
	ds_read_b128 v[180:183], v147 offset:54272
	ds_read_b128 v[196:199], v147 offset:55296
	ds_read_b128 v[200:203], v147 offset:56320
	global_load_lds_dwordx4 v[184:185], off
	s_mov_b32 m0, s70
	v_lshl_add_u64 v[184:185], v[192:193], 0, s[88:89]
	global_load_lds_dwordx4 v[184:185], off
	s_barrier
; #define PG8_STAGE(bufoff, gbase, voff) do { _Pragma("unroll") for (int _i = 0; _i < 2; ++_i) \
;         __builtin_amdgcn_global_load_lds((const unsigned*)((const char*)(gbase) + (voff)[_i]), (LAS unsigned*)(lds + (bufoff) + ldsw + _i * 8192), 16, 0, 0); } while (0)
; #define PG8_MMA(ai, bj, At, Bt) do { __builtin_amdgcn_s_setprio(1); _Pragma("unroll") for (int m = 0; m < 4; ++m) _Pragma("unroll") for (int n = 0; n < 2; ++n) _Pragma("unroll") for (int k = 0; k < 2; ++k) \
;         acc[ai][bj][m][n] = __builtin_amdgcn_mfma_f32_16x16x32_bf16(Bt[n][k], At[m][k], acc[ai][bj][m][n], 0, 0, 0); __builtin_amdgcn_s_setprio(0); } while (0)
; #define PG8_WAIT_V(n) asm volatile("s_waitcnt vmcnt(" #n ")" ::: "memory")
; #define PG8_WAIT_L(n) asm volatile("s_waitcnt lgkmcnt(" #n ")" ::: "memory")
; #define PG8_BAR __builtin_amdgcn_s_barrier()
; #define PG8_SCHED __builtin_amdgcn_sched_barrier(0)
; template <class Epi>
; __device__ __forceinline__ void gemm_phase(LAS unsigned char* lds, const Gemm g, const StaticOrder& S, const Epi& E) {
;     ...
;             PG8_BAR; PG8_WAIT_L(0); PG8_MMA(1, 0, At, B0); PG8_BAR; PG8_SCHED;
;             PG8_STAGE(PG8_SB(1, 1), b3 + hB, voffB);
;             PG8_WAIT_V(6); PG8_BAR; PG8_MMA(1, 1, At, B1); PG8_BAR;
	s_waitcnt lgkmcnt(0)
	s_setprio 1
	v_mfma_f32_16x16x32_bf16 v[60:63], v[138:141], v[160:163], v[60:63]
	v_mfma_f32_16x16x32_bf16 v[56:59], v[152:155], v[160:163], v[56:59]
	v_mfma_f32_16x16x32_bf16 v[52:55], v[138:141], v[168:171], v[52:55]
	v_mfma_f32_16x16x32_bf16 v[44:47], v[152:155], v[168:171], v[44:47]
	v_mfma_f32_16x16x32_bf16 v[36:39], v[138:141], v[176:179], v[36:39]
	v_mfma_f32_16x16x32_bf16 v[28:31], v[152:155], v[176:179], v[28:31]
	v_mfma_f32_16x16x32_bf16 v[20:23], v[138:141], v[196:199], v[20:23]
	v_mfma_f32_16x16x32_bf16 v[12:15], v[152:155], v[196:199], v[12:15]
	v_mfma_f32_16x16x32_bf16 v[60:63], v[148:151], v[164:167], v[60:63]
	v_mfma_f32_16x16x32_bf16 v[56:59], v[156:159], v[164:167], v[56:59]
	v_mfma_f32_16x16x32_bf16 v[52:55], v[148:151], v[172:175], v[52:55]
	v_mfma_f32_16x16x32_bf16 v[44:47], v[156:159], v[172:175], v[44:47]
	v_mfma_f32_16x16x32_bf16 v[36:39], v[148:151], v[180:183], v[36:39]
	v_mfma_f32_16x16x32_bf16 v[28:31], v[156:159], v[180:183], v[28:31]
	v_mfma_f32_16x16x32_bf16 v[20:23], v[148:151], v[200:203], v[20:23]
	v_mfma_f32_16x16x32_bf16 v[12:15], v[156:159], v[200:203], v[12:15]
	s_setprio 0
	s_barrier
	s_add_u32 s10, s16, 0x18080
	s_addc_u32 s11, s17, 0
	s_add_i32 s16, s20, s63
	s_mov_b32 m0, s16
	v_lshl_add_u64 v[138:139], s[10:11], 0, v[144:145]
	global_load_lds_dwordx4 v[138:139], off
	s_add_i32 m0, s16, 0x2000
	v_lshl_add_u64 v[138:139], s[10:11], 0, v[132:133]
	global_load_lds_dwordx4 v[138:139], off
	s_waitcnt vmcnt(6)
	s_barrier
	s_setprio 1
	v_mfma_f32_16x16x32_bf16 v[48:51], v[204:207], v[160:163], v[48:51]
	v_mfma_f32_16x16x32_bf16 v[40:43], v[220:223], v[160:163], v[40:43]
	v_mfma_f32_16x16x32_bf16 v[32:35], v[204:207], v[168:171], v[32:35]
	v_mfma_f32_16x16x32_bf16 v[24:27], v[220:223], v[168:171], v[24:27]
	v_mfma_f32_16x16x32_bf16 v[16:19], v[204:207], v[176:179], v[16:19]
	v_mfma_f32_16x16x32_bf16 v[8:11], v[220:223], v[176:179], v[8:11]
	v_mfma_f32_16x16x32_bf16 v[4:7], v[204:207], v[196:199], v[4:7]
	v_mfma_f32_16x16x32_bf16 v[0:3], v[220:223], v[196:199], v[0:3]
	v_mfma_f32_16x16x32_bf16 v[48:51], v[216:219], v[164:167], v[48:51]
	v_mfma_f32_16x16x32_bf16 v[40:43], v[224:227], v[164:167], v[40:43]
	v_mfma_f32_16x16x32_bf16 v[32:35], v[216:219], v[172:175], v[32:35]
	v_mfma_f32_16x16x32_bf16 v[24:27], v[224:227], v[172:175], v[24:27]
	v_mfma_f32_16x16x32_bf16 v[16:19], v[216:219], v[180:183], v[16:19]
	v_mfma_f32_16x16x32_bf16 v[8:11], v[224:227], v[180:183], v[8:11]
	v_mfma_f32_16x16x32_bf16 v[4:7], v[216:219], v[200:203], v[4:7]
	v_mfma_f32_16x16x32_bf16 v[0:3], v[224:227], v[200:203], v[0:3]
	s_setprio 0
	s_add_i32 s78, s78, 2
	s_add_u32 s24, s24, 0x100
	s_addc_u32 s25, s25, 0
	s_cmp_gt_u32 s78, 3
	s_mov_b64 s[10:11], s[12:13]
	s_barrier
	s_cbranch_scc0 .LBB0_655
; __device__ __forceinline__ unsigned pk2(float lo, float hi) { unsigned r; asm("v_cvt_pk_bf16_f32 %0, %1, %2" : "=v"(r) : "v"(lo), "v"(hi)); return r; }
;     __device__ __forceinline__ void operator()(const f32x4 (&acc)[2][2][4][2], const Unit& u, int wr, int wc, int fr, int fq) const {
;     ...
;         const int row_t = rmap == 1 ? odd_phys_row0(u.pm, grp) : (rmap == 2 ? odd_phys_row0(u.pm % (BG * TPB), u.pm / (BG * TPB)) : u.pm * BM);
;         int c = col_t + 64 * wc + 16 * fq;
;         if (mode == 2) c = (c >> 6) * 96 + (c & 63);
; #pragma unroll
;         for (int ai = 0; ai < 2; ++ai)
; #pragma unroll
;             for (int m = 0; m < 4; ++m) {
;                 const int row = row_t + ai * HALF + wr * 64 + m * 16 + fr;
;                 bf16_t* rp = O + (size_t)row * ldc + c;
; #pragma unroll
;                 for (int bj = 0; bj < 2; ++bj) {
;                     const f32x4 v0 = acc[ai][bj][m][0], v1 = acc[ai][bj][m][1];
;                     u32x4 o; o.x = pk2(v0[0], v0[1]); o.y = pk2(v0[2], v0[3]); o.z = pk2(v1[0], v1[1]); o.w = pk2(v1[2], v1[3]);
;                     *(u32x4*)(rp + 8 * bj) = o;
;                 }
;             }
	v_lshl_or_b32 v140, s15, 8, v146
	v_lshl_add_u32 v150, s77, 8, v142
	v_ashrrev_i32_e32 v141, 31, v140
	v_mov_b64_e32 v[138:139], s[8:9]
	v_cvt_pk_bf16_f32 v68, v68, v69
	v_cvt_pk_bf16_f32 v69, v70, v71
	v_cvt_pk_bf16_f32 v70, v64, v65
	v_add_u32_e32 v64, 0x80, v150
	v_mad_i64_i32 v[148:149], s[10:11], v150, s90, v[138:139]
	v_lshlrev_b64 v[140:141], 1, v[140:141]
	v_cvt_pk_bf16_f32 v112, v112, v113
	v_cvt_pk_bf16_f32 v113, v114, v115
	v_cvt_pk_bf16_f32 v114, v104, v105
	v_or_b32_e32 v104, 16, v150
	v_mad_i64_i32 v[64:65], s[10:11], v64, s90, v[138:139]
	v_cvt_pk_bf16_f32 v48, v48, v49
	v_cvt_pk_bf16_f32 v49, v50, v51
	v_cvt_pk_bf16_f32 v50, v40, v41
	v_add_u32_e32 v40, 0x90, v150
	v_lshl_add_u64 v[148:149], v[148:149], 0, v[140:141]
	v_mad_i64_i32 v[104:105], s[10:11], v104, s90, v[138:139]
	v_cvt_pk_bf16_f32 v96, v96, v97
	v_cvt_pk_bf16_f32 v97, v98, v99
	v_cvt_pk_bf16_f32 v98, v88, v89
	v_or_b32_e32 v88, 32, v150
	v_lshl_add_u64 v[64:65], v[64:65], 0, v[140:141]
	v_mad_i64_i32 v[40:41], s[10:11], v40, s90, v[138:139]
	v_cvt_pk_bf16_f32 v32, v32, v33
	v_cvt_pk_bf16_f32 v33, v34, v35
	v_cvt_pk_bf16_f32 v34, v24, v25
	v_add_u32_e32 v24, 0xa0, v150
	v_cvt_pk_bf16_f32 v115, v106, v107
	global_store_dwordx4 v[148:149], v[112:115], off offset:16
	v_mad_i64_i32 v[88:89], s[10:11], v88, s90, v[138:139]
	s_nop 0
	v_lshl_add_u64 v[112:113], v[104:105], 0, v[140:141]
	v_cvt_pk_bf16_f32 v80, v80, v81
	v_cvt_pk_bf16_f32 v81, v82, v83
	v_cvt_pk_bf16_f32 v82, v72, v73
	v_or_b32_e32 v72, 48, v150
	v_cvt_pk_bf16_f32 v51, v42, v43
	global_store_dwordx4 v[64:65], v[48:51], off offset:16
	v_mad_i64_i32 v[24:25], s[10:11], v24, s90, v[138:139]
	s_nop 0
	v_lshl_add_u64 v[48:49], v[40:41], 0, v[140:141]
	v_cvt_pk_bf16_f32 v16, v16, v17
	v_cvt_pk_bf16_f32 v17, v18, v19
	v_cvt_pk_bf16_f32 v18, v8, v9
	v_add_u32_e32 v8, 0xb0, v150
	v_cvt_pk_bf16_f32 v99, v90, v91
	global_store_dwordx4 v[112:113], v[96:99], off offset:16
	v_mad_i64_i32 v[72:73], s[10:11], v72, s90, v[138:139]
	s_nop 0
	v_lshl_add_u64 v[96:97], v[88:89], 0, v[140:141]
	v_cvt_pk_bf16_f32 v35, v26, v27
	global_store_dwordx4 v[48:49], v[32:35], off offset:16
	v_mad_i64_i32 v[8:9], s[10:11], v8, s90, v[138:139]
	s_nop 0
	v_lshl_add_u64 v[32:33], v[24:25], 0, v[140:141]
	v_cvt_pk_bf16_f32 v83, v74, v75
	global_store_dwordx4 v[96:97], v[80:83], off offset:16
	v_cvt_pk_bf16_f32 v19, v10, v11
	global_store_dwordx4 v[32:33], v[16:19], off offset:16
	s_and_b64 vcc, exec, s[0:1]
	v_lshl_add_u64 v[80:81], v[72:73], 0, v[140:141]
	v_lshl_add_u64 v[16:17], v[8:9], 0, v[140:141]
	s_mov_b32 s15, s72
	s_mov_b32 s77, s76
	s_mov_b64 s[12:13], s[6:7]
	s_mov_b64 s[10:11], s[4:5]
	v_cvt_pk_bf16_f32 v124, v124, v125
	v_cvt_pk_bf16_f32 v125, v126, v127
	v_cvt_pk_bf16_f32 v126, v120, v121
	v_cvt_pk_bf16_f32 v127, v122, v123
	global_store_dwordx4 v[148:149], v[124:127], off
	v_cvt_pk_bf16_f32 v104, v116, v117
	v_cvt_pk_bf16_f32 v105, v118, v119
	v_cvt_pk_bf16_f32 v106, v108, v109
	v_cvt_pk_bf16_f32 v107, v110, v111
	global_store_dwordx4 v[112:113], v[104:107], off
	v_cvt_pk_bf16_f32 v88, v100, v101
	v_cvt_pk_bf16_f32 v89, v102, v103
	v_cvt_pk_bf16_f32 v90, v92, v93
	v_cvt_pk_bf16_f32 v91, v94, v95
	global_store_dwordx4 v[96:97], v[88:91], off
	v_cvt_pk_bf16_f32 v72, v84, v85
	v_cvt_pk_bf16_f32 v73, v86, v87
	v_cvt_pk_bf16_f32 v74, v76, v77
	v_cvt_pk_bf16_f32 v75, v78, v79
	global_store_dwordx4 v[80:81], v[72:75], off
	v_cvt_pk_bf16_f32 v71, v66, v67
	global_store_dwordx4 v[80:81], v[68:71], off offset:16
	v_cvt_pk_bf16_f32 v60, v60, v61
	v_cvt_pk_bf16_f32 v61, v62, v63
	v_cvt_pk_bf16_f32 v62, v56, v57
	v_cvt_pk_bf16_f32 v63, v58, v59
	global_store_dwordx4 v[64:65], v[60:63], off
	v_cvt_pk_bf16_f32 v40, v52, v53
	v_cvt_pk_bf16_f32 v41, v54, v55
	v_cvt_pk_bf16_f32 v42, v44, v45
	v_cvt_pk_bf16_f32 v43, v46, v47
	global_store_dwordx4 v[48:49], v[40:43], off
	v_cvt_pk_bf16_f32 v24, v36, v37
	v_cvt_pk_bf16_f32 v25, v38, v39
	v_cvt_pk_bf16_f32 v26, v28, v29
	v_cvt_pk_bf16_f32 v27, v30, v31
	global_store_dwordx4 v[32:33], v[24:27], off
	v_cvt_pk_bf16_f32 v8, v20, v21
	v_cvt_pk_bf16_f32 v9, v22, v23
	v_cvt_pk_bf16_f32 v10, v12, v13
	v_cvt_pk_bf16_f32 v11, v14, v15
	global_store_dwordx4 v[16:17], v[8:11], off
	v_cvt_pk_bf16_f32 v4, v4, v5
	v_cvt_pk_bf16_f32 v5, v6, v7
	v_cvt_pk_bf16_f32 v6, v0, v1
	v_cvt_pk_bf16_f32 v7, v2, v3
	global_store_dwordx4 v[16:17], v[4:7], off offset:16
	s_cbranch_vccz .LBB0_644
	s_waitcnt vmcnt(0)
	s_cmpk_gt_u32 s14, 0xff
	s_cbranch_scc1 .LBB0_659
	s_barrier

; #define PG8_STAGE(bufoff, gbase, voff) do { _Pragma("unroll") for (int _i = 0; _i < 2; ++_i) \
;         __builtin_amdgcn_global_load_lds((const unsigned*)((const char*)(gbase) + (voff)[_i]), (LAS unsigned*)(lds + (bufoff) + ldsw + _i * 8192), 16, 0, 0); } while (0)
; #define PG8_LDA(dst, b, h) do { _Pragma("unroll") for (int m = 0; m < 4; ++m) _Pragma("unroll") for (int k = 0; k < 2; ++k) dst[m][k] = *(const LAS bf16x8*)(lds + PG8_SA(b, h) + aoff + m * 2048 + k * 1024); } while (0)
; #define PG8_LDB(dst, b, h) do { _Pragma("unroll") for (int n = 0; n < 2; ++n) _Pragma("unroll") for (int k = 0; k < 2; ++k) dst[n][k] = *(const LAS bf16x8*)(lds + PG8_SB(b, h) + boff + n * 2048 + k * 1024); } while (0)
; #define PG8_MMA(ai, bj, At, Bt) do { __builtin_amdgcn_s_setprio(1); _Pragma("unroll") for (int m = 0; m < 4; ++m) _Pragma("unroll") for (int n = 0; n < 2; ++n) _Pragma("unroll") for (int k = 0; k < 2; ++k) \
;         acc[ai][bj][m][n] = __builtin_amdgcn_mfma_f32_16x16x32_bf16(Bt[n][k], At[m][k], acc[ai][bj][m][n], 0, 0, 0); __builtin_amdgcn_s_setprio(0); } while (0)
; template <class Epi>
; __device__ __forceinline__ void gemm_phase(LAS unsigned char* lds, const Gemm g, const StaticOrder& S, const Epi& E) {
;     ...
;         const bool has_next = S.next(ui + 1, nxt);
;         const char* nA = has_next ? g.arow(nxt.pm) : cA; const char* nB = has_next ? (const char*)g.Bt + (size_t)nxt.pn * tB : cB;
;         for (int t = 0; t < nt; t += 2) {
;             const bool last = (t == nt - 2);
;             const char* a1 = cA + (size_t)(t + 1) * kstep;
;             const char* a2 = last ? nA : cA + (size_t)(t + 2) * kstep; const char* b2 = last ? nB : cB + (size_t)(t + 2) * kstep;
;             const char* a3 = a2 + kstep; const char* b3 = b2 + kstep;
;             PG8_LDB(B0, 0, 0); PG8_SCHED; PG8_LDA(At, 0, 0); PG8_STAGE(PG8_SA(1, 1), a1 + hA, voffA);
;             PG8_WAIT_L(8); PG8_BAR; PG8_WAIT_L(0); PG8_MMA(0, 0, At, B0); PG8_BAR; PG8_SCHED;
;             PG8_LDB(B1, 0, 1); PG8_STAGE(PG8_SB(0, 0), b2, voffB);
;             PG8_BAR; PG8_WAIT_L(0); PG8_MMA(0, 1, At, B1); PG8_BAR;
;             PG8_LDA(At, 0, 1); PG8_STAGE(PG8_SA(0, 0), a2, voffA);
;             PG8_BAR; PG8_WAIT_L(0); PG8_MMA(1, 0, At, B0); PG8_BAR; PG8_SCHED;
;             PG8_STAGE(PG8_SB(0, 1), b2 + hB, voffB);
;             PG8_WAIT_V(6); PG8_BAR; PG8_MMA(1, 1, At, B1); PG8_BAR;
.LBB0_670:
	s_add_u32 s28, s82, s25
	s_addc_u32 s29, s83, 0
	s_add_u32 s30, s28, 0x100
	s_addc_u32 s31, s29, 0
	s_and_b64 s[26:27], s[34:35], exec
	s_cselect_b32 s93, s17, s31
	s_cselect_b32 s92, s16, s30
	s_add_u32 s25, s64, s25
	s_addc_u32 s26, s65, 0
	s_add_u32 s25, s25, 0x100
	s_addc_u32 s30, s26, 0
	s_add_i32 s31, 0, 0x10000
	s_and_b64 s[26:27], s[34:35], exec
	s_cselect_b32 vcc_hi, s13, s30
	s_cselect_b32 vcc_lo, s24, s25
	s_add_u32 s76, s28, 0xb0080
	s_addc_u32 s77, s29, 0
	s_add_i32 s39, s31, s63
	s_add_i32 m0, s40, 0xc000
	s_add_i32 s68, s40, 0xe000
	s_add_i32 s29, 0, 0x14000
	s_add_i32 s37, s39, 0x2000
	s_add_u32 s86, vcc_lo, 0x10000
	v_add_u32_e32 v146, s31, v150
	s_addc_u32 s87, vcc_hi, 0
	s_add_i32 s30, s29, s63
	ds_read_b128 v[136:139], v146
	ds_read_b128 v[140:143], v146 offset:1024
	ds_read_b128 v[158:161], v146 offset:2048
	ds_read_b128 v[162:165], v146 offset:3072
	s_add_i32 s38, s30, 0x2000
	s_add_i32 s27, 0, 0x18000
	s_add_u32 s84, s92, 0xb0000
	s_addc_u32 s85, s93, 0
	s_add_i32 s25, s27, s63
	s_add_i32 s26, 0, 0x1c000
	s_add_i32 s28, s25, 0x2000
	s_add_u32 s34, vcc_lo, 0x10080
	s_addc_u32 s35, vcc_hi, 0
	s_add_i32 s31, s26, s63
	s_add_i32 s36, s31, 0x2000
	v_lshl_add_u64 v[146:147], s[76:77], 0, v[134:135]
	ds_read_b128 v[166:169], v154
	ds_read_b128 v[170:173], v154 offset:1024
	ds_read_b128 v[174:177], v154 offset:2048
	ds_read_b128 v[178:181], v154 offset:3072
	ds_read_b128 v[182:185], v154 offset:4096
	ds_read_b128 v[196:199], v154 offset:5120
	ds_read_b128 v[200:203], v154 offset:6144
	ds_read_b128 v[204:207], v154 offset:7168
	global_load_lds_dwordx4 v[146:147], off
	s_mov_b32 m0, s68
	v_lshl_add_u64 v[146:147], s[76:77], 0, v[130:131]
	global_load_lds_dwordx4 v[146:147], off
	s_waitcnt lgkmcnt(8)
	s_barrier
	s_waitcnt lgkmcnt(0)
	s_setprio 1
	v_mfma_f32_16x16x32_bf16 v[124:127], v[136:139], v[166:169], v[124:127]
	v_mfma_f32_16x16x32_bf16 v[120:123], v[158:161], v[166:169], v[120:123]
	v_mfma_f32_16x16x32_bf16 v[116:119], v[136:139], v[174:177], v[116:119]
	v_mfma_f32_16x16x32_bf16 v[108:111], v[158:161], v[174:177], v[108:111]
	v_mfma_f32_16x16x32_bf16 v[100:103], v[136:139], v[182:185], v[100:103]
	v_mfma_f32_16x16x32_bf16 v[92:95], v[158:161], v[182:185], v[92:95]
	v_mfma_f32_16x16x32_bf16 v[84:87], v[136:139], v[200:203], v[84:87]
	v_mfma_f32_16x16x32_bf16 v[76:79], v[158:161], v[200:203], v[76:79]
	v_mfma_f32_16x16x32_bf16 v[124:127], v[140:143], v[170:173], v[124:127]
	v_mfma_f32_16x16x32_bf16 v[120:123], v[162:165], v[170:173], v[120:123]
	v_mfma_f32_16x16x32_bf16 v[116:119], v[140:143], v[178:181], v[116:119]
	v_mfma_f32_16x16x32_bf16 v[108:111], v[162:165], v[178:181], v[108:111]
	v_mfma_f32_16x16x32_bf16 v[100:103], v[140:143], v[196:199], v[100:103]
	v_mfma_f32_16x16x32_bf16 v[92:95], v[162:165], v[196:199], v[92:95]
	v_mfma_f32_16x16x32_bf16 v[84:87], v[140:143], v[204:207], v[84:87]
	v_mfma_f32_16x16x32_bf16 v[76:79], v[162:165], v[204:207], v[76:79]
	s_setprio 0
	s_barrier
	v_add_u32_e32 v146, s29, v150
	s_mov_b32 m0, s39
	ds_read_b128 v[216:219], v146
	ds_read_b128 v[220:223], v146 offset:1024
	ds_read_b128 v[224:227], v146 offset:2048
	ds_read_b128 v[228:231], v146 offset:3072
	v_lshl_add_u64 v[146:147], vcc, 0, v[132:133]
	global_load_lds_dwordx4 v[146:147], off
	s_mov_b32 m0, s37
	v_lshl_add_u64 v[186:187], vcc, 0, v[128:129]
	global_load_lds_dwordx4 v[186:187], off
	s_barrier
	s_waitcnt lgkmcnt(0)
	s_setprio 1
	v_mfma_f32_16x16x32_bf16 v[112:115], v[216:219], v[166:169], v[112:115]
	v_mfma_f32_16x16x32_bf16 v[104:107], v[224:227], v[166:169], v[104:107]
	v_mfma_f32_16x16x32_bf16 v[96:99], v[216:219], v[174:177], v[96:99]
	v_mfma_f32_16x16x32_bf16 v[88:91], v[224:227], v[174:177], v[88:91]
	v_mfma_f32_16x16x32_bf16 v[80:83], v[216:219], v[182:185], v[80:83]
	v_mfma_f32_16x16x32_bf16 v[72:75], v[224:227], v[182:185], v[72:75]
	v_mfma_f32_16x16x32_bf16 v[68:71], v[216:219], v[200:203], v[68:71]
	v_mfma_f32_16x16x32_bf16 v[64:67], v[224:227], v[200:203], v[64:67]
	v_mfma_f32_16x16x32_bf16 v[112:115], v[220:223], v[170:173], v[112:115]
	v_mfma_f32_16x16x32_bf16 v[104:107], v[228:231], v[170:173], v[104:107]
	v_mfma_f32_16x16x32_bf16 v[96:99], v[220:223], v[178:181], v[96:99]
	v_mfma_f32_16x16x32_bf16 v[88:91], v[228:231], v[178:181], v[88:91]
	v_mfma_f32_16x16x32_bf16 v[80:83], v[220:223], v[196:199], v[80:83]
	v_mfma_f32_16x16x32_bf16 v[72:75], v[228:231], v[196:199], v[72:75]
	v_mfma_f32_16x16x32_bf16 v[68:71], v[220:223], v[204:207], v[68:71]
	v_mfma_f32_16x16x32_bf16 v[64:67], v[228:231], v[204:207], v[64:67]
	s_setprio 0
	s_mov_b32 m0, s40
	v_lshl_add_u64 v[188:189], s[92:93], 0, v[134:135]
	s_barrier
	ds_read_b128 v[166:169], v154 offset:16384
	ds_read_b128 v[170:173], v154 offset:17408
	ds_read_b128 v[174:177], v154 offset:18432
	ds_read_b128 v[178:181], v154 offset:19456
	ds_read_b128 v[182:185], v154 offset:20480
	ds_read_b128 v[196:199], v154 offset:21504
	ds_read_b128 v[200:203], v154 offset:22528
	ds_read_b128 v[204:207], v154 offset:23552
	global_load_lds_dwordx4 v[188:189], off
	s_mov_b32 m0, s69
	v_lshl_add_u64 v[192:193], s[92:93], 0, v[130:131]
	global_load_lds_dwordx4 v[192:193], off
	s_barrier
; #define PG8_STAGE(bufoff, gbase, voff) do { _Pragma("unroll") for (int _i = 0; _i < 2; ++_i) \
;         __builtin_amdgcn_global_load_lds((const unsigned*)((const char*)(gbase) + (voff)[_i]), (LAS unsigned*)(lds + (bufoff) + ldsw + _i * 8192), 16, 0, 0); } while (0)
; #define PG8_LDA(dst, b, h) do { _Pragma("unroll") for (int m = 0; m < 4; ++m) _Pragma("unroll") for (int k = 0; k < 2; ++k) dst[m][k] = *(const LAS bf16x8*)(lds + PG8_SA(b, h) + aoff + m * 2048 + k * 1024); } while (0)
; #define PG8_LDB(dst, b, h) do { _Pragma("unroll") for (int n = 0; n < 2; ++n) _Pragma("unroll") for (int k = 0; k < 2; ++k) dst[n][k] = *(const LAS bf16x8*)(lds + PG8_SB(b, h) + boff + n * 2048 + k * 1024); } while (0)
; #define PG8_MMA(ai, bj, At, Bt) do { __builtin_amdgcn_s_setprio(1); _Pragma("unroll") for (int m = 0; m < 4; ++m) _Pragma("unroll") for (int n = 0; n < 2; ++n) _Pragma("unroll") for (int k = 0; k < 2; ++k) \
;         acc[ai][bj][m][n] = __builtin_amdgcn_mfma_f32_16x16x32_bf16(Bt[n][k], At[m][k], acc[ai][bj][m][n], 0, 0, 0); __builtin_amdgcn_s_setprio(0); } while (0)
; #define PG8_WAIT_V(n) asm volatile("s_waitcnt vmcnt(" #n ")" ::: "memory")
; #define PG8_WAIT_L(n) asm volatile("s_waitcnt lgkmcnt(" #n ")" ::: "memory")
; #define PG8_BAR __builtin_amdgcn_s_barrier()
; #define PG8_SCHED __builtin_amdgcn_sched_barrier(0)
; template <class Epi>
; __device__ __forceinline__ void gemm_phase(LAS unsigned char* lds, const Gemm g, const StaticOrder& S, const Epi& E) {
;     ...
;             PG8_WAIT_V(6); PG8_BAR; PG8_MMA(1, 1, At, B1); PG8_BAR;
;             PG8_LDB(B0, 1, 0); PG8_SCHED; PG8_LDA(At, 1, 0); PG8_STAGE(PG8_SA(0, 1), a2 + hA, voffA);
;             PG8_WAIT_L(8); PG8_BAR; PG8_WAIT_L(0); PG8_MMA(0, 0, At, B0); PG8_BAR; PG8_SCHED;
;             PG8_LDB(B1, 1, 1); PG8_STAGE(PG8_SB(1, 0), b3, voffB);
;             PG8_BAR; PG8_WAIT_L(0); PG8_MMA(0, 1, At, B1); PG8_BAR;
;             PG8_LDA(At, 1, 1); PG8_STAGE(PG8_SA(1, 0), a3, voffA);
;             PG8_BAR; PG8_WAIT_L(0); PG8_MMA(1, 0, At, B0); PG8_BAR; PG8_SCHED;
;             PG8_STAGE(PG8_SB(1, 1), b3 + hB, voffB);
;             PG8_WAIT_V(6); PG8_BAR; PG8_MMA(1, 1, At, B1); PG8_BAR;
	s_waitcnt lgkmcnt(0)
	s_setprio 1
	v_mfma_f32_16x16x32_bf16 v[60:63], v[136:139], v[166:169], v[60:63]
	v_mfma_f32_16x16x32_bf16 v[56:59], v[158:161], v[166:169], v[56:59]
	v_mfma_f32_16x16x32_bf16 v[52:55], v[136:139], v[174:177], v[52:55]
	v_mfma_f32_16x16x32_bf16 v[44:47], v[158:161], v[174:177], v[44:47]
	v_mfma_f32_16x16x32_bf16 v[36:39], v[136:139], v[182:185], v[36:39]
	v_mfma_f32_16x16x32_bf16 v[28:31], v[158:161], v[182:185], v[28:31]
	v_mfma_f32_16x16x32_bf16 v[20:23], v[136:139], v[200:203], v[20:23]
	v_mfma_f32_16x16x32_bf16 v[12:15], v[158:161], v[200:203], v[12:15]
	v_mfma_f32_16x16x32_bf16 v[60:63], v[140:143], v[170:173], v[60:63]
	v_mfma_f32_16x16x32_bf16 v[56:59], v[162:165], v[170:173], v[56:59]
	v_mfma_f32_16x16x32_bf16 v[52:55], v[140:143], v[178:181], v[52:55]
	v_mfma_f32_16x16x32_bf16 v[44:47], v[162:165], v[178:181], v[44:47]
	v_mfma_f32_16x16x32_bf16 v[36:39], v[140:143], v[196:199], v[36:39]
	v_mfma_f32_16x16x32_bf16 v[28:31], v[162:165], v[196:199], v[28:31]
	v_mfma_f32_16x16x32_bf16 v[20:23], v[140:143], v[204:207], v[20:23]
	v_mfma_f32_16x16x32_bf16 v[12:15], v[162:165], v[204:207], v[12:15]
	s_setprio 0
	s_barrier
	s_mov_b32 m0, s30
	v_lshl_add_u64 v[136:137], s[86:87], 0, v[132:133]
	global_load_lds_dwordx4 v[136:137], off
	s_mov_b32 m0, s38
	v_lshl_add_u64 v[136:137], s[86:87], 0, v[128:129]
	global_load_lds_dwordx4 v[136:137], off
	s_waitcnt vmcnt(6)
	s_barrier
	s_setprio 1
	v_mfma_f32_16x16x32_bf16 v[48:51], v[216:219], v[166:169], v[48:51]
	v_mfma_f32_16x16x32_bf16 v[40:43], v[224:227], v[166:169], v[40:43]
	v_mfma_f32_16x16x32_bf16 v[32:35], v[216:219], v[174:177], v[32:35]
	v_mfma_f32_16x16x32_bf16 v[24:27], v[224:227], v[174:177], v[24:27]
	v_mfma_f32_16x16x32_bf16 v[16:19], v[216:219], v[182:185], v[16:19]
	v_mfma_f32_16x16x32_bf16 v[8:11], v[224:227], v[182:185], v[8:11]
	v_mfma_f32_16x16x32_bf16 v[4:7], v[216:219], v[200:203], v[4:7]
	v_mfma_f32_16x16x32_bf16 v[0:3], v[224:227], v[200:203], v[0:3]
	v_mfma_f32_16x16x32_bf16 v[48:51], v[220:223], v[170:173], v[48:51]
	v_mfma_f32_16x16x32_bf16 v[40:43], v[228:231], v[170:173], v[40:43]
	v_mfma_f32_16x16x32_bf16 v[32:35], v[220:223], v[178:181], v[32:35]
	v_mfma_f32_16x16x32_bf16 v[24:27], v[228:231], v[178:181], v[24:27]
	v_mfma_f32_16x16x32_bf16 v[16:19], v[220:223], v[196:199], v[16:19]
	v_mfma_f32_16x16x32_bf16 v[8:11], v[228:231], v[196:199], v[8:11]
	v_mfma_f32_16x16x32_bf16 v[4:7], v[220:223], v[204:207], v[4:7]
	v_mfma_f32_16x16x32_bf16 v[0:3], v[228:231], v[204:207], v[0:3]
	s_setprio 0
	v_add_u32_e32 v157, s27, v150
	s_barrier
	ds_read_b128 v[136:139], v157
	ds_read_b128 v[140:143], v157 offset:1024
	ds_read_b128 v[158:161], v157 offset:2048
	ds_read_b128 v[162:165], v157 offset:3072
	s_mov_b32 m0, s70
	v_lshl_add_u64 v[216:217], s[84:85], 0, v[134:135]
	ds_read_b128 v[166:169], v154 offset:32768
	ds_read_b128 v[170:173], v154 offset:33792
	ds_read_b128 v[174:177], v154 offset:34816
	ds_read_b128 v[178:181], v154 offset:35840
	ds_read_b128 v[182:185], v154 offset:36864
	ds_read_b128 v[196:199], v154 offset:37888
	ds_read_b128 v[200:203], v154 offset:38912
	ds_read_b128 v[204:207], v154 offset:39936
	global_load_lds_dwordx4 v[216:217], off
	s_mov_b32 m0, s71
	v_lshl_add_u64 v[216:217], s[84:85], 0, v[130:131]
	global_load_lds_dwordx4 v[216:217], off
	s_waitcnt lgkmcnt(8)
	s_barrier
	s_waitcnt lgkmcnt(0)
	s_setprio 1
	v_mfma_f32_16x16x32_bf16 v[124:127], v[136:139], v[166:169], v[124:127]
	v_mfma_f32_16x16x32_bf16 v[120:123], v[158:161], v[166:169], v[120:123]
	v_mfma_f32_16x16x32_bf16 v[116:119], v[136:139], v[174:177], v[116:119]
	v_mfma_f32_16x16x32_bf16 v[108:111], v[158:161], v[174:177], v[108:111]
	v_mfma_f32_16x16x32_bf16 v[100:103], v[136:139], v[182:185], v[100:103]
	v_mfma_f32_16x16x32_bf16 v[92:95], v[158:161], v[182:185], v[92:95]
	v_mfma_f32_16x16x32_bf16 v[84:87], v[136:139], v[200:203], v[84:87]
	v_mfma_f32_16x16x32_bf16 v[76:79], v[158:161], v[200:203], v[76:79]
	v_mfma_f32_16x16x32_bf16 v[124:127], v[140:143], v[170:173], v[124:127]
	v_mfma_f32_16x16x32_bf16 v[120:123], v[162:165], v[170:173], v[120:123]
	v_mfma_f32_16x16x32_bf16 v[116:119], v[140:143], v[178:181], v[116:119]
	v_mfma_f32_16x16x32_bf16 v[108:111], v[162:165], v[178:181], v[108:111]
	v_mfma_f32_16x16x32_bf16 v[100:103], v[140:143], v[196:199], v[100:103]
	v_mfma_f32_16x16x32_bf16 v[92:95], v[162:165], v[196:199], v[92:95]
	v_mfma_f32_16x16x32_bf16 v[84:87], v[140:143], v[204:207], v[84:87]
	v_mfma_f32_16x16x32_bf16 v[76:79], v[162:165], v[204:207], v[76:79]
	s_setprio 0
	s_barrier
	s_mov_b32 m0, s25
	v_add_u32_e32 v157, s26, v150
	v_lshl_add_u64 v[146:147], v[146:147], 0, s[88:89]
	ds_read_b128 v[216:219], v157
	ds_read_b128 v[220:223], v157 offset:1024
	ds_read_b128 v[224:227], v157 offset:2048
	ds_read_b128 v[228:231], v157 offset:3072
	global_load_lds_dwordx4 v[146:147], off
	s_mov_b32 m0, s28
	v_lshl_add_u64 v[146:147], v[186:187], 0, s[88:89]
	global_load_lds_dwordx4 v[146:147], off
	s_barrier
	s_waitcnt lgkmcnt(0)
	s_setprio 1
	v_mfma_f32_16x16x32_bf16 v[112:115], v[216:219], v[166:169], v[112:115]
	v_mfma_f32_16x16x32_bf16 v[104:107], v[224:227], v[166:169], v[104:107]
	v_mfma_f32_16x16x32_bf16 v[96:99], v[216:219], v[174:177], v[96:99]
	v_mfma_f32_16x16x32_bf16 v[88:91], v[224:227], v[174:177], v[88:91]
	v_mfma_f32_16x16x32_bf16 v[80:83], v[216:219], v[182:185], v[80:83]
	v_mfma_f32_16x16x32_bf16 v[72:75], v[224:227], v[182:185], v[72:75]
	v_mfma_f32_16x16x32_bf16 v[68:71], v[216:219], v[200:203], v[68:71]
	v_mfma_f32_16x16x32_bf16 v[64:67], v[224:227], v[200:203], v[64:67]
	v_mfma_f32_16x16x32_bf16 v[112:115], v[220:223], v[170:173], v[112:115]
	v_mfma_f32_16x16x32_bf16 v[104:107], v[228:231], v[170:173], v[104:107]
	v_mfma_f32_16x16x32_bf16 v[96:99], v[220:223], v[178:181], v[96:99]
	v_mfma_f32_16x16x32_bf16 v[88:91], v[228:231], v[178:181], v[88:91]
	v_mfma_f32_16x16x32_bf16 v[80:83], v[220:223], v[196:199], v[80:83]
	v_mfma_f32_16x16x32_bf16 v[72:75], v[228:231], v[196:199], v[72:75]
	v_mfma_f32_16x16x32_bf16 v[68:71], v[220:223], v[204:207], v[68:71]
	v_mfma_f32_16x16x32_bf16 v[64:67], v[228:231], v[204:207], v[64:67]
	s_setprio 0
	s_mov_b32 m0, s72
	v_lshl_add_u64 v[146:147], v[188:189], 0, s[88:89]
	s_barrier
; #define LAS __attribute__((address_space(3)))
; __device__ __forceinline__ unsigned pk2(float lo, float hi) { unsigned r; asm("v_cvt_pk_bf16_f32 %0, %1, %2" : "=v"(r) : "v"(lo), "v"(hi)); return r; }
; #define PG8_WAIT_V(n) asm volatile("s_waitcnt vmcnt(" #n ")" ::: "memory")
; #define PG8_BAR __builtin_amdgcn_s_barrier()
; template <class Epi>
; __device__ __forceinline__ void gemm_phase(LAS unsigned char* lds, const Gemm g, const StaticOrder& S, const Epi& E) {
;     ...
;             PG8_BAR; PG8_WAIT_L(0); PG8_MMA(0, 1, At, B1); PG8_BAR;
;             PG8_LDA(At, 1, 1); PG8_STAGE(PG8_SA(1, 0), a3, voffA);
;             PG8_BAR; PG8_WAIT_L(0); PG8_MMA(1, 0, At, B0); PG8_BAR; PG8_SCHED;
;             PG8_STAGE(PG8_SB(1, 1), b3 + hB, voffB);
;             PG8_WAIT_V(6); PG8_BAR; PG8_MMA(1, 1, At, B1); PG8_BAR;
;     __device__ __forceinline__ void operator()(const f32x4 (&acc)[2][2][4][2], const Unit& u, int wr, int wc, int fr, int fq) const {
;         const int col_t = u.pn * BM;
;         if (mode != 0 && col_t >= vt0) {
;             const int bl = u.pm / TPB, key0 = (u.pm - bl * TPB) * 256;
;             LAS bf16_t* sc = (LAS bf16_t*)(trs + (wr * 4 + wc) * 2304);
;             const int lane = fq * 16 + fr;
; #pragma unroll
;             for (int ai = 0; ai < 2; ++ai)
; #pragma unroll
;                 for (int bj = 0; bj < 2; ++bj)
; #pragma unroll
;                     for (int n = 0; n < 2; ++n) {
; #pragma unroll
;                         for (int m = 0; m < 4; ++m) {
;                             const f32x4 v = acc[ai][bj][m][n];
;                             const unsigned p0 = pk2(v[0], v[1]), p1 = pk2(v[2], v[3]);
;                             LAS bf16_t* w = sc + (4 * fq) * 72 + 16 * m + fr;
;                             w[0] = (bf16_t)(p0 & 0xffffu); w[72] = (bf16_t)(p0 >> 16); w[144] = (bf16_t)(p1 & 0xffffu); w[216] = (bf16_t)(p1 >> 16);
;                         }
; #pragma unroll
;                         for (int j = 0; j < 2; ++j) {
;                             const int ch = lane + 64 * j, fi = ch >> 3, seg = ch & 7;
;                             const u32x4 o = *(const LAS u32x4*)(sc + fi * 72 + 8 * seg);
;                             const int f = col_t - vt0 + 64 * wc + 16 * (fi >> 2) + 8 * bj + 4 * n + (fi & 3);
;                             *(u32x4*)(Vt + ((size_t)bl * vtnf + f) * KEYS + key0 + ai * HALF + wr * 64 + 8 * seg) = o;
	ds_read_b128 v[166:169], v154 offset:49152
	ds_read_b128 v[170:173], v154 offset:50176
	ds_read_b128 v[174:177], v154 offset:51200
	ds_read_b128 v[178:181], v154 offset:52224
	ds_read_b128 v[182:185], v154 offset:53248
	ds_read_b128 v[196:199], v154 offset:54272
	ds_read_b128 v[200:203], v154 offset:55296
	ds_read_b128 v[204:207], v154 offset:56320
	global_load_lds_dwordx4 v[146:147], off
	s_mov_b32 m0, s78
	v_lshl_add_u64 v[146:147], v[192:193], 0, s[88:89]
	global_load_lds_dwordx4 v[146:147], off
	s_barrier
	s_waitcnt lgkmcnt(0)
	s_setprio 1
	v_mfma_f32_16x16x32_bf16 v[60:63], v[136:139], v[166:169], v[60:63]
	v_mfma_f32_16x16x32_bf16 v[56:59], v[158:161], v[166:169], v[56:59]
	v_mfma_f32_16x16x32_bf16 v[52:55], v[136:139], v[174:177], v[52:55]
	v_mfma_f32_16x16x32_bf16 v[44:47], v[158:161], v[174:177], v[44:47]
	v_mfma_f32_16x16x32_bf16 v[36:39], v[136:139], v[182:185], v[36:39]
	v_mfma_f32_16x16x32_bf16 v[28:31], v[158:161], v[182:185], v[28:31]
	v_mfma_f32_16x16x32_bf16 v[20:23], v[136:139], v[200:203], v[20:23]
	v_mfma_f32_16x16x32_bf16 v[12:15], v[158:161], v[200:203], v[12:15]
	v_mfma_f32_16x16x32_bf16 v[60:63], v[140:143], v[170:173], v[60:63]
	v_mfma_f32_16x16x32_bf16 v[56:59], v[162:165], v[170:173], v[56:59]
	v_mfma_f32_16x16x32_bf16 v[52:55], v[140:143], v[178:181], v[52:55]
	v_mfma_f32_16x16x32_bf16 v[44:47], v[162:165], v[178:181], v[44:47]
	v_mfma_f32_16x16x32_bf16 v[36:39], v[140:143], v[196:199], v[36:39]
	v_mfma_f32_16x16x32_bf16 v[28:31], v[162:165], v[196:199], v[28:31]
	v_mfma_f32_16x16x32_bf16 v[20:23], v[140:143], v[204:207], v[20:23]
	v_mfma_f32_16x16x32_bf16 v[12:15], v[162:165], v[204:207], v[12:15]
	s_setprio 0
	s_barrier
	s_mov_b32 m0, s31
	v_lshl_add_u64 v[136:137], s[34:35], 0, v[132:133]
	global_load_lds_dwordx4 v[136:137], off
	s_mov_b32 m0, s36
	v_lshl_add_u64 v[136:137], s[34:35], 0, v[128:129]
	global_load_lds_dwordx4 v[136:137], off
	s_waitcnt vmcnt(6)
	s_barrier
	s_setprio 1
	v_mfma_f32_16x16x32_bf16 v[48:51], v[216:219], v[166:169], v[48:51]
	v_mfma_f32_16x16x32_bf16 v[40:43], v[224:227], v[166:169], v[40:43]
	v_mfma_f32_16x16x32_bf16 v[32:35], v[216:219], v[174:177], v[32:35]
	v_mfma_f32_16x16x32_bf16 v[24:27], v[224:227], v[174:177], v[24:27]
	v_mfma_f32_16x16x32_bf16 v[16:19], v[216:219], v[182:185], v[16:19]
	v_mfma_f32_16x16x32_bf16 v[8:11], v[224:227], v[182:185], v[8:11]
	v_mfma_f32_16x16x32_bf16 v[4:7], v[216:219], v[200:203], v[4:7]
	v_mfma_f32_16x16x32_bf16 v[0:3], v[224:227], v[200:203], v[0:3]
	v_mfma_f32_16x16x32_bf16 v[48:51], v[220:223], v[170:173], v[48:51]
	v_mfma_f32_16x16x32_bf16 v[40:43], v[228:231], v[170:173], v[40:43]
	v_mfma_f32_16x16x32_bf16 v[32:35], v[220:223], v[178:181], v[32:35]
	v_mfma_f32_16x16x32_bf16 v[24:27], v[228:231], v[178:181], v[24:27]
	v_mfma_f32_16x16x32_bf16 v[16:19], v[220:223], v[196:199], v[16:19]
	v_mfma_f32_16x16x32_bf16 v[8:11], v[228:231], v[196:199], v[8:11]
	v_mfma_f32_16x16x32_bf16 v[4:7], v[220:223], v[204:207], v[4:7]
	v_mfma_f32_16x16x32_bf16 v[0:3], v[228:231], v[204:207], v[0:3]
	s_setprio 0
	s_movk_i32 s25, 0x100
	s_andn2_b64 vcc, exec, s[4:5]
	s_mov_b64 s[34:35], -1
	s_mov_b64 s[4:5], 0
	s_barrier
	s_cbranch_vccz .LBB0_670
	s_lshl_b32 s13, s15, 8
	s_cmp_lt_i32 s15, 2
	s_mov_b64 s[4:5], -1
	s_cbranch_scc1 .LBB0_673
	s_mul_hi_i32 s4, s81, 0x3e0f83e1
	s_lshr_b32 s5, s4, 31
	s_ashr_i32 s4, s4, 3
	v_cvt_pk_bf16_f32 v136, v124, v125
	s_add_i32 s4, s4, s5
	v_cvt_pk_bf16_f32 v137, v126, v127
	ds_write_b16 v151, v136
	ds_write_b16_d16_hi v151, v136 offset:144
	ds_write_b16 v151, v137 offset:288
	ds_write_b16_d16_hi v151, v137 offset:432
	v_cvt_pk_bf16_f32 v136, v116, v117
	s_mul_i32 s5, s4, 0xffffffdf
	v_cvt_pk_bf16_f32 v137, v118, v119
	ds_write_b16 v151, v136 offset:32
	ds_write_b16_d16_hi v151, v136 offset:176
	ds_write_b16 v151, v137 offset:320
	ds_write_b16_d16_hi v151, v137 offset:464
	v_cvt_pk_bf16_f32 v136, v100, v101
	s_add_i32 s5, s5, s81
	s_or_b32 s15, s13, s79
	v_cvt_pk_bf16_f32 v137, v102, v103
	ds_write_b16 v151, v136 offset:64
	ds_write_b16_d16_hi v151, v136 offset:208
	ds_write_b16 v151, v137 offset:352
	ds_write_b16_d16_hi v151, v137 offset:496
	v_cvt_pk_bf16_f32 v136, v84, v85
	s_lshl_b32 s24, s5, 8
	s_ashr_i32 s5, s4, 31
	v_cvt_pk_bf16_f32 v137, v86, v87
	ds_write_b16 v151, v136 offset:96
	ds_write_b16_d16_hi v151, v136 offset:240
	ds_write_b16 v151, v137 offset:384
	ds_write_b16_d16_hi v151, v137 offset:528
	v_add_u32_e32 v136, s15, v152
	s_lshl_b64 s[4:5], s[4:5], 9
	v_ashrrev_i32_e32 v137, 31, v136
	v_lshl_add_u64 v[136:137], s[4:5], 0, v[136:137]
	v_mov_b64_e32 v[162:163], s[8:9]
	s_ashr_i32 s25, s24, 31
	ds_read_b128 v[138:141], v155
	v_mad_u64_u32 v[142:143], s[26:27], v136, s91, v[162:163]
	v_mad_i32_i24 v143, v137, s91, v143
	s_lshl_b64 s[34:35], s[24:25], 1
	v_lshl_add_u64 v[136:137], v[142:143], 0, s[34:35]
	v_lshl_add_u64 v[136:137], v[136:137], 0, s[10:11]
	v_lshl_add_u64 v[136:137], v[136:137], 0, v[144:145]
	s_waitcnt lgkmcnt(0)
	global_store_dwordx4 v[136:137], v[138:141], off
	ds_read_b128 v[140:143], v156
	s_or_b32 s26, s15, 4
	v_add_u32_e32 v138, s15, v153
	v_ashrrev_i32_e32 v139, 31, v138
	v_lshl_add_u64 v[138:139], s[4:5], 0, v[138:139]
	v_mad_u64_u32 v[146:147], s[24:25], v138, s91, v[162:163]
	v_mad_i32_i24 v147, v139, s91, v147
	v_lshl_add_u64 v[138:139], v[146:147], 0, s[34:35]
	v_lshl_add_u64 v[138:139], v[138:139], 0, s[10:11]
	v_lshl_add_u64 v[138:139], v[138:139], 0, v[144:145]
	s_waitcnt lgkmcnt(0)
; #define LAS __attribute__((address_space(3)))
; __device__ __forceinline__ unsigned pk2(float lo, float hi) { unsigned r; asm("v_cvt_pk_bf16_f32 %0, %1, %2" : "=v"(r) : "v"(lo), "v"(hi)); return r; }
;     __device__ __forceinline__ void operator()(const f32x4 (&acc)[2][2][4][2], const Unit& u, int wr, int wc, int fr, int fq) const {
;     ...
; #pragma unroll
;             for (int ai = 0; ai < 2; ++ai)
; #pragma unroll
;                 for (int bj = 0; bj < 2; ++bj)
; #pragma unroll
;                     for (int n = 0; n < 2; ++n) {
; #pragma unroll
;                         for (int m = 0; m < 4; ++m) {
;                             const f32x4 v = acc[ai][bj][m][n];
;                             const unsigned p0 = pk2(v[0], v[1]), p1 = pk2(v[2], v[3]);
;                             LAS bf16_t* w = sc + (4 * fq) * 72 + 16 * m + fr;
;                             w[0] = (bf16_t)(p0 & 0xffffu); w[72] = (bf16_t)(p0 >> 16); w[144] = (bf16_t)(p1 & 0xffffu); w[216] = (bf16_t)(p1 >> 16);
;                         }
; #pragma unroll
;                         for (int j = 0; j < 2; ++j) {
;                             const int ch = lane + 64 * j, fi = ch >> 3, seg = ch & 7;
;                             const u32x4 o = *(const LAS u32x4*)(sc + fi * 72 + 8 * seg);
;                             const int f = col_t - vt0 + 64 * wc + 16 * (fi >> 2) + 8 * bj + 4 * n + (fi & 3);
;                             *(u32x4*)(Vt + ((size_t)bl * vtnf + f) * KEYS + key0 + ai * HALF + wr * 64 + 8 * seg) = o;
;                         }
;                     }
	global_store_dwordx4 v[138:139], v[140:143], off
	v_cvt_pk_bf16_f32 v157, v104, v105
	s_nop 1
	v_cvt_pk_bf16_f32 v140, v120, v121
	v_cvt_pk_bf16_f32 v141, v122, v123
	ds_write_b16 v151, v140
	ds_write_b16_d16_hi v151, v140 offset:144
	ds_write_b16 v151, v141 offset:288
	ds_write_b16_d16_hi v151, v141 offset:432
	v_cvt_pk_bf16_f32 v140, v108, v109
	v_cvt_pk_bf16_f32 v141, v110, v111
	ds_write_b16 v151, v140 offset:32
	ds_write_b16_d16_hi v151, v140 offset:176
	ds_write_b16 v151, v141 offset:320
	ds_write_b16_d16_hi v151, v141 offset:464
	v_cvt_pk_bf16_f32 v140, v92, v93
	v_cvt_pk_bf16_f32 v141, v94, v95
	ds_write_b16 v151, v140 offset:64
	ds_write_b16_d16_hi v151, v140 offset:208
	ds_write_b16 v151, v141 offset:352
	ds_write_b16_d16_hi v151, v141 offset:496
	v_cvt_pk_bf16_f32 v140, v76, v77
	v_cvt_pk_bf16_f32 v141, v78, v79
	ds_write_b16 v151, v140 offset:96
	ds_write_b16_d16_hi v151, v140 offset:240
	ds_write_b16 v151, v141 offset:384
	ds_write_b16_d16_hi v151, v141 offset:528
	v_add_u32_e32 v140, s26, v152
	v_ashrrev_i32_e32 v141, 31, v140
	v_lshl_add_u64 v[140:141], s[4:5], 0, v[140:141]
	ds_read_b128 v[158:161], v155
	v_mad_u64_u32 v[142:143], s[24:25], v140, s91, v[162:163]
	v_mad_i32_i24 v143, v141, s91, v143
	v_lshl_add_u64 v[140:141], v[142:143], 0, s[34:35]
	v_add_u32_e32 v142, s26, v153
	v_lshl_add_u64 v[140:141], v[140:141], 0, s[10:11]
	v_ashrrev_i32_e32 v143, 31, v142
	v_lshl_add_u64 v[140:141], v[140:141], 0, v[144:145]
	v_lshl_add_u64 v[142:143], s[4:5], 0, v[142:143]
	s_waitcnt lgkmcnt(0)
	global_store_dwordx4 v[140:141], v[158:161], off
	ds_read_b128 v[158:161], v156
	v_mad_u64_u32 v[146:147], s[24:25], v142, s91, v[162:163]
	v_mad_i32_i24 v147, v143, s91, v147
	v_lshl_add_u64 v[142:143], v[146:147], 0, s[34:35]
	v_lshl_add_u64 v[142:143], v[142:143], 0, s[10:11]
	v_lshl_add_u64 v[142:143], v[142:143], 0, v[144:145]
	v_cvt_pk_bf16_f32 v146, v112, v113
	s_waitcnt lgkmcnt(0)
	global_store_dwordx4 v[142:143], v[158:161], off
	v_cvt_pk_bf16_f32 v147, v114, v115
	ds_write_b16 v151, v146
	ds_write_b16_d16_hi v151, v146 offset:144
	ds_write_b16 v151, v147 offset:288
	ds_write_b16_d16_hi v151, v147 offset:432
	v_cvt_pk_bf16_f32 v146, v96, v97
	v_cvt_pk_bf16_f32 v147, v98, v99
	ds_write_b16 v151, v146 offset:32
	ds_write_b16_d16_hi v151, v146 offset:176
	ds_write_b16 v151, v147 offset:320
	ds_write_b16_d16_hi v151, v147 offset:464
	v_cvt_pk_bf16_f32 v146, v80, v81
	s_or_b32 s26, s15, 8
	v_cvt_pk_bf16_f32 v147, v82, v83
	ds_write_b16 v151, v146 offset:64
	ds_write_b16_d16_hi v151, v146 offset:208
	ds_write_b16 v151, v147 offset:352
	ds_write_b16_d16_hi v151, v147 offset:496
	v_cvt_pk_bf16_f32 v146, v68, v69
	v_cvt_pk_bf16_f32 v147, v70, v71
	ds_write_b16 v151, v146 offset:96
	ds_write_b16_d16_hi v151, v146 offset:240
	ds_write_b16 v151, v147 offset:384
	ds_write_b16_d16_hi v151, v147 offset:528
	v_add_u32_e32 v146, s26, v152
	v_ashrrev_i32_e32 v147, 31, v146
	v_lshl_add_u64 v[146:147], s[4:5], 0, v[146:147]
	ds_read_b128 v[158:161], v155
	v_mad_u64_u32 v[164:165], s[24:25], v146, s91, v[162:163]
	v_mad_i32_i24 v165, v147, s91, v165
	v_lshl_add_u64 v[146:147], v[164:165], 0, s[34:35]
	v_add_u32_e32 v164, s26, v153
	v_lshl_add_u64 v[146:147], v[146:147], 0, s[10:11]
	v_ashrrev_i32_e32 v165, 31, v164
	v_lshl_add_u64 v[146:147], v[146:147], 0, v[144:145]
	v_lshl_add_u64 v[164:165], s[4:5], 0, v[164:165]
	s_waitcnt lgkmcnt(0)
	global_store_dwordx4 v[146:147], v[158:161], off
	ds_read_b128 v[158:161], v156
	v_mad_u64_u32 v[166:167], s[24:25], v164, s91, v[162:163]
	v_mad_i32_i24 v167, v165, s91, v167
	v_lshl_add_u64 v[164:165], v[166:167], 0, s[34:35]
	v_lshl_add_u64 v[164:165], v[164:165], 0, s[10:11]
	v_lshl_add_u64 v[164:165], v[164:165], 0, v[144:145]
	s_waitcnt lgkmcnt(0)
	global_store_dwordx4 v[164:165], v[158:161], off
	s_or_b32 s15, s15, 12
	v_add_u32_e32 v166, s15, v152
	v_cvt_pk_bf16_f32 v158, v106, v107
	ds_write_b16 v151, v157
	ds_write_b16_d16_hi v151, v157 offset:144
	ds_write_b16 v151, v158 offset:288
	ds_write_b16_d16_hi v151, v158 offset:432
	v_cvt_pk_bf16_f32 v157, v88, v89
	v_cvt_pk_bf16_f32 v158, v90, v91
	ds_write_b16 v151, v157 offset:32
	ds_write_b16_d16_hi v151, v157 offset:176
	ds_write_b16 v151, v158 offset:320
	ds_write_b16_d16_hi v151, v158 offset:464
	v_cvt_pk_bf16_f32 v157, v72, v73
	v_cvt_pk_bf16_f32 v158, v74, v75
	ds_write_b16 v151, v157 offset:64
	ds_write_b16_d16_hi v151, v157 offset:208
	ds_write_b16 v151, v158 offset:352
	ds_write_b16_d16_hi v151, v158 offset:496
	v_cvt_pk_bf16_f32 v157, v64, v65
	v_ashrrev_i32_e32 v167, 31, v166
	v_cvt_pk_bf16_f32 v158, v66, v67
	ds_write_b16 v151, v157 offset:96
	ds_write_b16_d16_hi v151, v157 offset:240
	ds_write_b16 v151, v158 offset:384
	ds_write_b16_d16_hi v151, v158 offset:528
	v_lshl_add_u64 v[166:167], s[4:5], 0, v[166:167]
	ds_read_b128 v[158:161], v155
	v_mad_u64_u32 v[168:169], s[24:25], v166, s91, v[162:163]
	v_mad_i32_i24 v169, v167, s91, v169
	v_lshl_add_u64 v[166:167], v[168:169], 0, s[34:35]
	v_add_u32_e32 v168, s15, v153
	v_lshl_add_u64 v[166:167], v[166:167], 0, s[10:11]
	v_ashrrev_i32_e32 v169, 31, v168
	v_lshl_add_u64 v[166:167], v[166:167], 0, v[144:145]
	v_lshl_add_u64 v[168:169], s[4:5], 0, v[168:169]
	s_waitcnt lgkmcnt(0)
; #define LAS __attribute__((address_space(3)))
; __device__ __forceinline__ unsigned pk2(float lo, float hi) { unsigned r; asm("v_cvt_pk_bf16_f32 %0, %1, %2" : "=v"(r) : "v"(lo), "v"(hi)); return r; }
;     __device__ __forceinline__ void operator()(const f32x4 (&acc)[2][2][4][2], const Unit& u, int wr, int wc, int fr, int fq) const {
;     ...
; #pragma unroll
;             for (int ai = 0; ai < 2; ++ai)
; #pragma unroll
;                 for (int bj = 0; bj < 2; ++bj)
; #pragma unroll
;                     for (int n = 0; n < 2; ++n) {
; #pragma unroll
;                         for (int m = 0; m < 4; ++m) {
;                             const f32x4 v = acc[ai][bj][m][n];
;                             const unsigned p0 = pk2(v[0], v[1]), p1 = pk2(v[2], v[3]);
;                             LAS bf16_t* w = sc + (4 * fq) * 72 + 16 * m + fr;
;                             w[0] = (bf16_t)(p0 & 0xffffu); w[72] = (bf16_t)(p0 >> 16); w[144] = (bf16_t)(p1 & 0xffffu); w[216] = (bf16_t)(p1 >> 16);
;                         }
; #pragma unroll
;                         for (int j = 0; j < 2; ++j) {
;                             const int ch = lane + 64 * j, fi = ch >> 3, seg = ch & 7;
;                             const u32x4 o = *(const LAS u32x4*)(sc + fi * 72 + 8 * seg);
;                             const int f = col_t - vt0 + 64 * wc + 16 * (fi >> 2) + 8 * bj + 4 * n + (fi & 3);
;                             *(u32x4*)(Vt + ((size_t)bl * vtnf + f) * KEYS + key0 + ai * HALF + wr * 64 + 8 * seg) = o;
;                         }
;                     }
	global_store_dwordx4 v[166:167], v[158:161], off
	ds_read_b128 v[158:161], v156
	v_mad_u64_u32 v[162:163], s[4:5], v168, s91, v[162:163]
	v_mad_i32_i24 v163, v169, s91, v163
	v_lshl_add_u64 v[162:163], v[162:163], 0, s[34:35]
	v_lshl_add_u64 v[162:163], v[162:163], 0, s[10:11]
	v_lshl_add_u64 v[162:163], v[162:163], 0, v[144:145]
	v_cvt_pk_bf16_f32 v157, v60, v61
	s_waitcnt lgkmcnt(0)
	global_store_dwordx4 v[162:163], v[158:161], off
	s_mov_b64 s[4:5], 0
	s_nop 0
	v_cvt_pk_bf16_f32 v158, v62, v63
	ds_write_b16 v151, v157
	ds_write_b16_d16_hi v151, v157 offset:144
	ds_write_b16 v151, v158 offset:288
	ds_write_b16_d16_hi v151, v158 offset:432
	v_cvt_pk_bf16_f32 v157, v52, v53
	v_cvt_pk_bf16_f32 v158, v54, v55
	ds_write_b16 v151, v157 offset:32
	ds_write_b16_d16_hi v151, v157 offset:176
	ds_write_b16 v151, v158 offset:320
	ds_write_b16_d16_hi v151, v158 offset:464
	v_cvt_pk_bf16_f32 v157, v36, v37
	v_cvt_pk_bf16_f32 v158, v38, v39
	ds_write_b16 v151, v157 offset:64
	ds_write_b16_d16_hi v151, v157 offset:208
	ds_write_b16 v151, v158 offset:352
	ds_write_b16_d16_hi v151, v158 offset:496
	v_cvt_pk_bf16_f32 v157, v20, v21
	v_cvt_pk_bf16_f32 v158, v22, v23
	ds_write_b16 v151, v157 offset:96
	ds_write_b16_d16_hi v151, v157 offset:240
	ds_write_b16 v151, v158 offset:384
	ds_write_b16_d16_hi v151, v158 offset:528
	ds_read_b128 v[158:161], v155
	s_waitcnt lgkmcnt(0)
	global_store_dwordx4 v[136:137], v[158:161], off offset:256
	ds_read_b128 v[158:161], v156
	v_cvt_pk_bf16_f32 v136, v56, v57
	v_cvt_pk_bf16_f32 v137, v58, v59
	s_waitcnt lgkmcnt(0)
	global_store_dwordx4 v[138:139], v[158:161], off offset:256
	ds_write_b16 v151, v136
	ds_write_b16_d16_hi v151, v136 offset:144
	ds_write_b16 v151, v137 offset:288
	ds_write_b16_d16_hi v151, v137 offset:432
	v_cvt_pk_bf16_f32 v136, v44, v45
	v_cvt_pk_bf16_f32 v137, v46, v47
	ds_write_b16 v151, v136 offset:32
	ds_write_b16_d16_hi v151, v136 offset:176
	ds_write_b16 v151, v137 offset:320
	ds_write_b16_d16_hi v151, v137 offset:464
	v_cvt_pk_bf16_f32 v136, v28, v29
	v_cvt_pk_bf16_f32 v137, v30, v31
	ds_write_b16 v151, v136 offset:64
	ds_write_b16_d16_hi v151, v136 offset:208
	ds_write_b16 v151, v137 offset:352
	ds_write_b16_d16_hi v151, v137 offset:496
	v_cvt_pk_bf16_f32 v136, v12, v13
	v_cvt_pk_bf16_f32 v137, v14, v15
	ds_write_b16 v151, v136 offset:96
	ds_write_b16_d16_hi v151, v136 offset:240
	ds_write_b16 v151, v137 offset:384
	ds_write_b16_d16_hi v151, v137 offset:528
	ds_read_b128 v[136:139], v155
	s_waitcnt lgkmcnt(0)
	global_store_dwordx4 v[140:141], v[136:139], off offset:256
	ds_read_b128 v[136:139], v156
	s_waitcnt lgkmcnt(0)
	global_store_dwordx4 v[142:143], v[136:139], off offset:256
	s_nop 1
	v_cvt_pk_bf16_f32 v136, v48, v49
	v_cvt_pk_bf16_f32 v137, v50, v51
	ds_write_b16 v151, v136
	ds_write_b16_d16_hi v151, v136 offset:144
	ds_write_b16 v151, v137 offset:288
	ds_write_b16_d16_hi v151, v137 offset:432
	v_cvt_pk_bf16_f32 v136, v32, v33
	v_cvt_pk_bf16_f32 v137, v34, v35
	ds_write_b16 v151, v136 offset:32
	ds_write_b16_d16_hi v151, v136 offset:176
	ds_write_b16 v151, v137 offset:320
	ds_write_b16_d16_hi v151, v137 offset:464
	v_cvt_pk_bf16_f32 v136, v16, v17
	v_cvt_pk_bf16_f32 v137, v18, v19
	ds_write_b16 v151, v136 offset:64
	ds_write_b16_d16_hi v151, v136 offset:208
	ds_write_b16 v151, v137 offset:352
	ds_write_b16_d16_hi v151, v137 offset:496
	v_cvt_pk_bf16_f32 v136, v4, v5
	v_cvt_pk_bf16_f32 v137, v6, v7
	ds_write_b16 v151, v136 offset:96
	ds_write_b16_d16_hi v151, v136 offset:240
	ds_write_b16 v151, v137 offset:384
	ds_write_b16_d16_hi v151, v137 offset:528
	ds_read_b128 v[136:139], v155
	s_waitcnt lgkmcnt(0)
	global_store_dwordx4 v[146:147], v[136:139], off offset:256
	ds_read_b128 v[136:139], v156
	s_waitcnt lgkmcnt(0)
	global_store_dwordx4 v[164:165], v[136:139], off offset:256
	s_nop 1
	v_cvt_pk_bf16_f32 v136, v40, v41
	v_cvt_pk_bf16_f32 v137, v42, v43
	ds_write_b16 v151, v136
	ds_write_b16_d16_hi v151, v136 offset:144
	ds_write_b16 v151, v137 offset:288
	ds_write_b16_d16_hi v151, v137 offset:432
	v_cvt_pk_bf16_f32 v136, v24, v25
	v_cvt_pk_bf16_f32 v137, v26, v27
	ds_write_b16 v151, v136 offset:32
	ds_write_b16_d16_hi v151, v136 offset:176
	ds_write_b16 v151, v137 offset:320
	ds_write_b16_d16_hi v151, v137 offset:464
	v_cvt_pk_bf16_f32 v136, v8, v9
	v_cvt_pk_bf16_f32 v137, v10, v11
	ds_write_b16 v151, v136 offset:64
	ds_write_b16_d16_hi v151, v136 offset:208
	ds_write_b16 v151, v137 offset:352
	ds_write_b16_d16_hi v151, v137 offset:496
	v_cvt_pk_bf16_f32 v136, v0, v1
	v_cvt_pk_bf16_f32 v137, v2, v3
	ds_write_b16 v151, v136 offset:96
	ds_write_b16_d16_hi v151, v136 offset:240
	ds_write_b16 v151, v137 offset:384
	ds_write_b16_d16_hi v151, v137 offset:528
	ds_read_b128 v[136:139], v155
	s_waitcnt lgkmcnt(0)
	global_store_dwordx4 v[166:167], v[136:139], off offset:256
	ds_read_b128 v[136:139], v156
	s_waitcnt lgkmcnt(0)
	global_store_dwordx4 v[162:163], v[136:139], off offset:256

; #define PG8_STAGE(bufoff, gbase, voff) do { _Pragma("unroll") for (int _i = 0; _i < 2; ++_i) \
;         __builtin_amdgcn_global_load_lds((const unsigned*)((const char*)(gbase) + (voff)[_i]), (LAS unsigned*)(lds + (bufoff) + ldsw + _i * 8192), 16, 0, 0); } while (0)
; #define PG8_LDA(dst, b, h) do { _Pragma("unroll") for (int m = 0; m < 4; ++m) _Pragma("unroll") for (int k = 0; k < 2; ++k) dst[m][k] = *(const LAS bf16x8*)(lds + PG8_SA(b, h) + aoff + m * 2048 + k * 1024); } while (0)
; #define PG8_LDB(dst, b, h) do { _Pragma("unroll") for (int n = 0; n < 2; ++n) _Pragma("unroll") for (int k = 0; k < 2; ++k) dst[n][k] = *(const LAS bf16x8*)(lds + PG8_SB(b, h) + boff + n * 2048 + k * 1024); } while (0)
; #define PG8_MMA(ai, bj, At, Bt) do { __builtin_amdgcn_s_setprio(1); _Pragma("unroll") for (int m = 0; m < 4; ++m) _Pragma("unroll") for (int n = 0; n < 2; ++n) _Pragma("unroll") for (int k = 0; k < 2; ++k) \
;         acc[ai][bj][m][n] = __builtin_amdgcn_mfma_f32_16x16x32_bf16(Bt[n][k], At[m][k], acc[ai][bj][m][n], 0, 0, 0); __builtin_amdgcn_s_setprio(0); } while (0)
; #define PG8_WAIT_L(n) asm volatile("s_waitcnt lgkmcnt(" #n ")" ::: "memory")
; #define PG8_BAR __builtin_amdgcn_s_barrier()
; #define PG8_SCHED __builtin_amdgcn_sched_barrier(0)
; template <class Epi>
; __device__ __forceinline__ void gemm_phase(LAS unsigned char* lds, const Gemm g, const StaticOrder& S, const Epi& E) {
;     ...
;         const char* nA = has_next ? g.arow(nxt.pm) : cA; const char* nB = has_next ? (const char*)g.Bt + (size_t)nxt.pn * tB : cB;
;         for (int t = 0; t < nt; t += 2) {
;             const bool last = (t == nt - 2);
;             const char* a1 = cA + (size_t)(t + 1) * kstep;
;             const char* a2 = last ? nA : cA + (size_t)(t + 2) * kstep; const char* b2 = last ? nB : cB + (size_t)(t + 2) * kstep;
;             const char* a3 = a2 + kstep; const char* b3 = b2 + kstep;
;             PG8_LDB(B0, 0, 0); PG8_SCHED; PG8_LDA(At, 0, 0); PG8_STAGE(PG8_SA(1, 1), a1 + hA, voffA);
;             PG8_WAIT_L(8); PG8_BAR; PG8_WAIT_L(0); PG8_MMA(0, 0, At, B0); PG8_BAR; PG8_SCHED;
;             PG8_LDB(B1, 0, 1); PG8_STAGE(PG8_SB(0, 0), b2, voffB);
;             PG8_BAR; PG8_WAIT_L(0); PG8_MMA(0, 1, At, B1); PG8_BAR;
;             PG8_LDA(At, 0, 1); PG8_STAGE(PG8_SA(0, 0), a2, voffA);
;             PG8_BAR; PG8_WAIT_L(0); PG8_MMA(1, 0, At, B0); PG8_BAR; PG8_SCHED;
.LBB0_985:
	s_add_u32 s12, s10, 0x100
	s_addc_u32 s13, s11, 0
	s_add_i32 s26, 0, 0x10000
	v_add_u32_e32 v142, s26, v139
	ds_read_b128 v[134:137], v142
	ds_read_b128 v[146:149], v142 offset:1024
	ds_read_b128 v[150:153], v142 offset:2048
	ds_read_b128 v[154:157], v142 offset:3072
	s_cmp_eq_u32 s72, 20
	s_cselect_b32 s21, s5, s13
	s_cselect_b32 s20, s4, s12
	s_cselect_b32 s17, s7, s25
	s_cselect_b32 s16, s6, s24
	v_lshl_add_u64 v[142:143], s[10:11], 0, v[130:131]
	s_add_i32 m0, s61, 0xc000
	ds_read_b128 v[158:161], v141
	ds_read_b128 v[162:165], v141 offset:1024
	ds_read_b128 v[166:169], v141 offset:2048
	ds_read_b128 v[170:173], v141 offset:3072
	ds_read_b128 v[174:177], v141 offset:4096
	ds_read_b128 v[178:181], v141 offset:5120
	ds_read_b128 v[182:185], v141 offset:6144
	ds_read_b128 v[186:189], v141 offset:7168
	global_load_lds_dwordx4 v[142:143], off
	s_add_i32 m0, s61, 0xe000
	v_lshl_add_u64 v[142:143], s[10:11], 0, v[132:133]
	global_load_lds_dwordx4 v[142:143], off
	s_waitcnt lgkmcnt(8)
	s_barrier
	s_waitcnt lgkmcnt(0)
	s_setprio 1
	v_mfma_f32_16x16x32_bf16 v[124:127], v[134:137], v[158:161], v[124:127]
	v_mfma_f32_16x16x32_bf16 v[120:123], v[150:153], v[158:161], v[120:123]
	v_mfma_f32_16x16x32_bf16 v[116:119], v[134:137], v[166:169], v[116:119]
	v_mfma_f32_16x16x32_bf16 v[108:111], v[150:153], v[166:169], v[108:111]
	v_mfma_f32_16x16x32_bf16 v[100:103], v[134:137], v[174:177], v[100:103]
	v_mfma_f32_16x16x32_bf16 v[92:95], v[150:153], v[174:177], v[92:95]
	v_mfma_f32_16x16x32_bf16 v[84:87], v[134:137], v[182:185], v[84:87]
	v_mfma_f32_16x16x32_bf16 v[76:79], v[150:153], v[182:185], v[76:79]
	v_mfma_f32_16x16x32_bf16 v[124:127], v[146:149], v[162:165], v[124:127]
	v_mfma_f32_16x16x32_bf16 v[120:123], v[154:157], v[162:165], v[120:123]
	v_mfma_f32_16x16x32_bf16 v[116:119], v[146:149], v[170:173], v[116:119]
	v_mfma_f32_16x16x32_bf16 v[108:111], v[154:157], v[170:173], v[108:111]
	v_mfma_f32_16x16x32_bf16 v[100:103], v[146:149], v[178:181], v[100:103]
	v_mfma_f32_16x16x32_bf16 v[92:95], v[154:157], v[178:181], v[92:95]
	v_mfma_f32_16x16x32_bf16 v[84:87], v[146:149], v[186:189], v[84:87]
	v_mfma_f32_16x16x32_bf16 v[76:79], v[154:157], v[186:189], v[76:79]
	s_setprio 0
	s_barrier
	s_add_i32 s27, 0, 0x14000
	v_add_u32_e32 v142, s27, v139
	s_add_i32 s10, s26, s35
	ds_read_b128 v[196:199], v142
	ds_read_b128 v[200:203], v142 offset:1024
	ds_read_b128 v[204:207], v142 offset:2048
	ds_read_b128 v[214:217], v142 offset:3072
	v_lshl_add_u64 v[142:143], s[16:17], 0, v[144:145]
	s_mov_b32 m0, s10
	v_lshl_add_u64 v[192:193], s[16:17], 0, v[128:129]
	global_load_lds_dwordx4 v[142:143], off
	s_add_i32 m0, s10, 0x2000
	s_nop 0
	global_load_lds_dwordx4 v[192:193], off
	s_barrier
	s_waitcnt lgkmcnt(0)
	s_setprio 1
	v_mfma_f32_16x16x32_bf16 v[112:115], v[196:199], v[158:161], v[112:115]
	v_mfma_f32_16x16x32_bf16 v[104:107], v[204:207], v[158:161], v[104:107]
	v_mfma_f32_16x16x32_bf16 v[96:99], v[196:199], v[166:169], v[96:99]
	v_mfma_f32_16x16x32_bf16 v[88:91], v[204:207], v[166:169], v[88:91]
	v_mfma_f32_16x16x32_bf16 v[80:83], v[196:199], v[174:177], v[80:83]
	v_mfma_f32_16x16x32_bf16 v[72:75], v[204:207], v[174:177], v[72:75]
	v_mfma_f32_16x16x32_bf16 v[68:71], v[196:199], v[182:185], v[68:71]
	v_mfma_f32_16x16x32_bf16 v[64:67], v[204:207], v[182:185], v[64:67]
	v_mfma_f32_16x16x32_bf16 v[112:115], v[200:203], v[162:165], v[112:115]
	v_mfma_f32_16x16x32_bf16 v[104:107], v[214:217], v[162:165], v[104:107]
	v_mfma_f32_16x16x32_bf16 v[96:99], v[200:203], v[170:173], v[96:99]
	v_mfma_f32_16x16x32_bf16 v[88:91], v[214:217], v[170:173], v[88:91]
	v_mfma_f32_16x16x32_bf16 v[80:83], v[200:203], v[178:181], v[80:83]
	v_mfma_f32_16x16x32_bf16 v[72:75], v[214:217], v[178:181], v[72:75]
	v_mfma_f32_16x16x32_bf16 v[68:71], v[200:203], v[186:189], v[68:71]
	v_mfma_f32_16x16x32_bf16 v[64:67], v[214:217], v[186:189], v[64:67]
	s_setprio 0
	s_mov_b32 m0, s61
	v_lshl_add_u64 v[218:219], s[20:21], 0, v[144:145]
	s_barrier
	ds_read_b128 v[158:161], v141 offset:16384
	ds_read_b128 v[162:165], v141 offset:17408
	ds_read_b128 v[166:169], v141 offset:18432
	ds_read_b128 v[170:173], v141 offset:19456
	ds_read_b128 v[174:177], v141 offset:20480
	ds_read_b128 v[178:181], v141 offset:21504
	ds_read_b128 v[182:185], v141 offset:22528
	ds_read_b128 v[186:189], v141 offset:23552
	global_load_lds_dwordx4 v[218:219], off
	s_mov_b32 m0, s62
	v_lshl_add_u64 v[220:221], s[20:21], 0, v[128:129]
	global_load_lds_dwordx4 v[220:221], off
	s_barrier
	s_waitcnt lgkmcnt(0)
	s_setprio 1
	v_mfma_f32_16x16x32_bf16 v[60:63], v[134:137], v[158:161], v[60:63]
	v_mfma_f32_16x16x32_bf16 v[56:59], v[150:153], v[158:161], v[56:59]
	v_mfma_f32_16x16x32_bf16 v[52:55], v[134:137], v[166:169], v[52:55]
	v_mfma_f32_16x16x32_bf16 v[44:47], v[150:153], v[166:169], v[44:47]
	v_mfma_f32_16x16x32_bf16 v[36:39], v[134:137], v[174:177], v[36:39]
	v_mfma_f32_16x16x32_bf16 v[28:31], v[150:153], v[174:177], v[28:31]
	v_mfma_f32_16x16x32_bf16 v[20:23], v[134:137], v[182:185], v[20:23]
	v_mfma_f32_16x16x32_bf16 v[12:15], v[150:153], v[182:185], v[12:15]
	v_mfma_f32_16x16x32_bf16 v[60:63], v[146:149], v[162:165], v[60:63]
	v_mfma_f32_16x16x32_bf16 v[56:59], v[154:157], v[162:165], v[56:59]
	v_mfma_f32_16x16x32_bf16 v[52:55], v[146:149], v[170:173], v[52:55]
	v_mfma_f32_16x16x32_bf16 v[44:47], v[154:157], v[170:173], v[44:47]
	v_mfma_f32_16x16x32_bf16 v[36:39], v[146:149], v[178:181], v[36:39]
	v_mfma_f32_16x16x32_bf16 v[28:31], v[154:157], v[178:181], v[28:31]
	v_mfma_f32_16x16x32_bf16 v[20:23], v[146:149], v[186:189], v[20:23]
	v_mfma_f32_16x16x32_bf16 v[12:15], v[154:157], v[186:189], v[12:15]
	s_setprio 0
	s_barrier
; #define PG8_STAGE(bufoff, gbase, voff) do { _Pragma("unroll") for (int _i = 0; _i < 2; ++_i) \
;         __builtin_amdgcn_global_load_lds((const unsigned*)((const char*)(gbase) + (voff)[_i]), (LAS unsigned*)(lds + (bufoff) + ldsw + _i * 8192), 16, 0, 0); } while (0)
; #define PG8_LDA(dst, b, h) do { _Pragma("unroll") for (int m = 0; m < 4; ++m) _Pragma("unroll") for (int k = 0; k < 2; ++k) dst[m][k] = *(const LAS bf16x8*)(lds + PG8_SA(b, h) + aoff + m * 2048 + k * 1024); } while (0)
; #define PG8_LDB(dst, b, h) do { _Pragma("unroll") for (int n = 0; n < 2; ++n) _Pragma("unroll") for (int k = 0; k < 2; ++k) dst[n][k] = *(const LAS bf16x8*)(lds + PG8_SB(b, h) + boff + n * 2048 + k * 1024); } while (0)
; #define PG8_MMA(ai, bj, At, Bt) do { __builtin_amdgcn_s_setprio(1); _Pragma("unroll") for (int m = 0; m < 4; ++m) _Pragma("unroll") for (int n = 0; n < 2; ++n) _Pragma("unroll") for (int k = 0; k < 2; ++k) \
;         acc[ai][bj][m][n] = __builtin_amdgcn_mfma_f32_16x16x32_bf16(Bt[n][k], At[m][k], acc[ai][bj][m][n], 0, 0, 0); __builtin_amdgcn_s_setprio(0); } while (0)
; #define PG8_WAIT_V(n) asm volatile("s_waitcnt vmcnt(" #n ")" ::: "memory")
; #define PG8_WAIT_L(n) asm volatile("s_waitcnt lgkmcnt(" #n ")" ::: "memory")
; #define PG8_BAR __builtin_amdgcn_s_barrier()
; #define PG8_SCHED __builtin_amdgcn_sched_barrier(0)
; template <class Epi>
; __device__ __forceinline__ void gemm_phase(LAS unsigned char* lds, const Gemm g, const StaticOrder& S, const Epi& E) {
;     ...
;             PG8_STAGE(PG8_SB(0, 1), b2 + hB, voffB);
;             PG8_WAIT_V(6); PG8_BAR; PG8_MMA(1, 1, At, B1); PG8_BAR;
;             PG8_LDB(B0, 1, 0); PG8_SCHED; PG8_LDA(At, 1, 0); PG8_STAGE(PG8_SA(0, 1), a2 + hA, voffA);
;             PG8_WAIT_L(8); PG8_BAR; PG8_WAIT_L(0); PG8_MMA(0, 0, At, B0); PG8_BAR; PG8_SCHED;
;             PG8_LDB(B1, 1, 1); PG8_STAGE(PG8_SB(1, 0), b3, voffB);
;             PG8_BAR; PG8_WAIT_L(0); PG8_MMA(0, 1, At, B1); PG8_BAR;
	s_add_u32 s10, s16, 0x60000
	s_addc_u32 s11, s17, 0
	s_add_i32 s26, s27, s35
	s_mov_b32 m0, s26
	v_lshl_add_u64 v[134:135], s[10:11], 0, v[144:145]
	global_load_lds_dwordx4 v[134:135], off
	s_add_i32 m0, s26, 0x2000
	v_lshl_add_u64 v[134:135], s[10:11], 0, v[128:129]
	global_load_lds_dwordx4 v[134:135], off
	s_waitcnt vmcnt(6)
	s_barrier
	s_setprio 1
	v_mfma_f32_16x16x32_bf16 v[48:51], v[196:199], v[158:161], v[48:51]
	v_mfma_f32_16x16x32_bf16 v[40:43], v[204:207], v[158:161], v[40:43]
	v_mfma_f32_16x16x32_bf16 v[32:35], v[196:199], v[166:169], v[32:35]
	v_mfma_f32_16x16x32_bf16 v[24:27], v[204:207], v[166:169], v[24:27]
	v_mfma_f32_16x16x32_bf16 v[16:19], v[196:199], v[174:177], v[16:19]
	v_mfma_f32_16x16x32_bf16 v[8:11], v[204:207], v[174:177], v[8:11]
	v_mfma_f32_16x16x32_bf16 v[4:7], v[196:199], v[182:185], v[4:7]
	v_mfma_f32_16x16x32_bf16 v[0:3], v[204:207], v[182:185], v[0:3]
	v_mfma_f32_16x16x32_bf16 v[48:51], v[200:203], v[162:165], v[48:51]
	v_mfma_f32_16x16x32_bf16 v[40:43], v[214:217], v[162:165], v[40:43]
	v_mfma_f32_16x16x32_bf16 v[32:35], v[200:203], v[170:173], v[32:35]
	v_mfma_f32_16x16x32_bf16 v[24:27], v[214:217], v[170:173], v[24:27]
	v_mfma_f32_16x16x32_bf16 v[16:19], v[200:203], v[178:181], v[16:19]
	v_mfma_f32_16x16x32_bf16 v[8:11], v[214:217], v[178:181], v[8:11]
	v_mfma_f32_16x16x32_bf16 v[4:7], v[200:203], v[186:189], v[4:7]
	v_mfma_f32_16x16x32_bf16 v[0:3], v[214:217], v[186:189], v[0:3]
	s_setprio 0
	s_add_i32 s26, 0, 0x18000
	v_add_u32_e32 v154, s26, v139
	s_barrier
	ds_read_b128 v[134:137], v154
	ds_read_b128 v[146:149], v154 offset:1024
	ds_read_b128 v[150:153], v154 offset:2048
	ds_read_b128 v[154:157], v154 offset:3072
	s_add_u32 s10, s20, 0x60000
	s_addc_u32 s11, s21, 0
	s_mov_b32 m0, s63
	v_lshl_add_u64 v[196:197], s[10:11], 0, v[144:145]
	ds_read_b128 v[158:161], v141 offset:32768
	ds_read_b128 v[162:165], v141 offset:33792
	ds_read_b128 v[166:169], v141 offset:34816
	ds_read_b128 v[170:173], v141 offset:35840
	ds_read_b128 v[174:177], v141 offset:36864
	ds_read_b128 v[178:181], v141 offset:37888
	ds_read_b128 v[182:185], v141 offset:38912
	ds_read_b128 v[186:189], v141 offset:39936
	global_load_lds_dwordx4 v[196:197], off
	s_mov_b32 m0, s64
	v_lshl_add_u64 v[196:197], s[10:11], 0, v[128:129]
	global_load_lds_dwordx4 v[196:197], off
	s_waitcnt lgkmcnt(8)
	s_barrier
	s_waitcnt lgkmcnt(0)
	s_setprio 1
	v_mfma_f32_16x16x32_bf16 v[124:127], v[134:137], v[158:161], v[124:127]
	v_mfma_f32_16x16x32_bf16 v[120:123], v[150:153], v[158:161], v[120:123]
	v_mfma_f32_16x16x32_bf16 v[116:119], v[134:137], v[166:169], v[116:119]
	v_mfma_f32_16x16x32_bf16 v[108:111], v[150:153], v[166:169], v[108:111]
	v_mfma_f32_16x16x32_bf16 v[100:103], v[134:137], v[174:177], v[100:103]
	v_mfma_f32_16x16x32_bf16 v[92:95], v[150:153], v[174:177], v[92:95]
	v_mfma_f32_16x16x32_bf16 v[84:87], v[134:137], v[182:185], v[84:87]
	v_mfma_f32_16x16x32_bf16 v[76:79], v[150:153], v[182:185], v[76:79]
	v_mfma_f32_16x16x32_bf16 v[124:127], v[146:149], v[162:165], v[124:127]
	v_mfma_f32_16x16x32_bf16 v[120:123], v[154:157], v[162:165], v[120:123]
	v_mfma_f32_16x16x32_bf16 v[116:119], v[146:149], v[170:173], v[116:119]
	v_mfma_f32_16x16x32_bf16 v[108:111], v[154:157], v[170:173], v[108:111]
	v_mfma_f32_16x16x32_bf16 v[100:103], v[146:149], v[178:181], v[100:103]
	v_mfma_f32_16x16x32_bf16 v[92:95], v[154:157], v[178:181], v[92:95]
	v_mfma_f32_16x16x32_bf16 v[84:87], v[146:149], v[186:189], v[84:87]
	v_mfma_f32_16x16x32_bf16 v[76:79], v[154:157], v[186:189], v[76:79]
	s_setprio 0
	s_barrier
	s_add_i32 s20, 0, 0x1c000
	s_add_i32 s10, s26, s35
	v_add_u32_e32 v190, s20, v139
	v_lshl_add_u64 v[142:143], v[142:143], 0, s[88:89]
	s_mov_b32 m0, s10
	ds_read_b128 v[196:199], v190
	ds_read_b128 v[200:203], v190 offset:1024
	ds_read_b128 v[204:207], v190 offset:2048
	ds_read_b128 v[214:217], v190 offset:3072
	global_load_lds_dwordx4 v[142:143], off
	s_add_i32 m0, s10, 0x2000
	v_lshl_add_u64 v[142:143], v[192:193], 0, s[88:89]
	global_load_lds_dwordx4 v[142:143], off
	s_barrier
; #define PG8_STAGE(bufoff, gbase, voff) do { _Pragma("unroll") for (int _i = 0; _i < 2; ++_i) \
;         __builtin_amdgcn_global_load_lds((const unsigned*)((const char*)(gbase) + (voff)[_i]), (LAS unsigned*)(lds + (bufoff) + ldsw + _i * 8192), 16, 0, 0); } while (0)
; #define PG8_LDA(dst, b, h) do { _Pragma("unroll") for (int m = 0; m < 4; ++m) _Pragma("unroll") for (int k = 0; k < 2; ++k) dst[m][k] = *(const LAS bf16x8*)(lds + PG8_SA(b, h) + aoff + m * 2048 + k * 1024); } while (0)
; #define PG8_MMA(ai, bj, At, Bt) do { __builtin_amdgcn_s_setprio(1); _Pragma("unroll") for (int m = 0; m < 4; ++m) _Pragma("unroll") for (int n = 0; n < 2; ++n) _Pragma("unroll") for (int k = 0; k < 2; ++k) \
;         acc[ai][bj][m][n] = __builtin_amdgcn_mfma_f32_16x16x32_bf16(Bt[n][k], At[m][k], acc[ai][bj][m][n], 0, 0, 0); __builtin_amdgcn_s_setprio(0); } while (0)
; #define PG8_WAIT_V(n) asm volatile("s_waitcnt vmcnt(" #n ")" ::: "memory")
; #define PG8_WAIT_L(n) asm volatile("s_waitcnt lgkmcnt(" #n ")" ::: "memory")
; #define PG8_BAR __builtin_amdgcn_s_barrier()
; #define PG8_SCHED __builtin_amdgcn_sched_barrier(0)
; template <class Epi>
; __device__ __forceinline__ void gemm_phase(LAS unsigned char* lds, const Gemm g, const StaticOrder& S, const Epi& E) {
;     ...
;             PG8_BAR; PG8_WAIT_L(0); PG8_MMA(0, 1, At, B1); PG8_BAR;
;             PG8_LDA(At, 1, 1); PG8_STAGE(PG8_SA(1, 0), a3, voffA);
;             PG8_BAR; PG8_WAIT_L(0); PG8_MMA(1, 0, At, B0); PG8_BAR; PG8_SCHED;
;             PG8_STAGE(PG8_SB(1, 1), b3 + hB, voffB);
;             PG8_WAIT_V(6); PG8_BAR; PG8_MMA(1, 1, At, B1); PG8_BAR;
	s_waitcnt lgkmcnt(0)
	s_setprio 1
	v_mfma_f32_16x16x32_bf16 v[112:115], v[196:199], v[158:161], v[112:115]
	v_mfma_f32_16x16x32_bf16 v[104:107], v[204:207], v[158:161], v[104:107]
	v_mfma_f32_16x16x32_bf16 v[96:99], v[196:199], v[166:169], v[96:99]
	v_mfma_f32_16x16x32_bf16 v[88:91], v[204:207], v[166:169], v[88:91]
	v_mfma_f32_16x16x32_bf16 v[80:83], v[196:199], v[174:177], v[80:83]
	v_mfma_f32_16x16x32_bf16 v[72:75], v[204:207], v[174:177], v[72:75]
	v_mfma_f32_16x16x32_bf16 v[68:71], v[196:199], v[182:185], v[68:71]
	v_mfma_f32_16x16x32_bf16 v[64:67], v[204:207], v[182:185], v[64:67]
	v_mfma_f32_16x16x32_bf16 v[112:115], v[200:203], v[162:165], v[112:115]
	v_mfma_f32_16x16x32_bf16 v[104:107], v[214:217], v[162:165], v[104:107]
	v_mfma_f32_16x16x32_bf16 v[96:99], v[200:203], v[170:173], v[96:99]
	v_mfma_f32_16x16x32_bf16 v[88:91], v[214:217], v[170:173], v[88:91]
	v_mfma_f32_16x16x32_bf16 v[80:83], v[200:203], v[178:181], v[80:83]
	v_mfma_f32_16x16x32_bf16 v[72:75], v[214:217], v[178:181], v[72:75]
	v_mfma_f32_16x16x32_bf16 v[68:71], v[200:203], v[186:189], v[68:71]
	v_mfma_f32_16x16x32_bf16 v[64:67], v[214:217], v[186:189], v[64:67]
	s_setprio 0
	s_mov_b32 m0, s65
	v_lshl_add_u64 v[142:143], v[218:219], 0, s[88:89]
	s_barrier
	ds_read_b128 v[158:161], v141 offset:49152
	ds_read_b128 v[162:165], v141 offset:50176
	ds_read_b128 v[166:169], v141 offset:51200
	ds_read_b128 v[170:173], v141 offset:52224
	ds_read_b128 v[174:177], v141 offset:53248
	ds_read_b128 v[178:181], v141 offset:54272
	ds_read_b128 v[182:185], v141 offset:55296
	ds_read_b128 v[186:189], v141 offset:56320
	global_load_lds_dwordx4 v[142:143], off
	s_mov_b32 m0, s66
	v_lshl_add_u64 v[142:143], v[220:221], 0, s[88:89]
	global_load_lds_dwordx4 v[142:143], off
	s_barrier
	s_waitcnt lgkmcnt(0)
	s_setprio 1
	v_mfma_f32_16x16x32_bf16 v[60:63], v[134:137], v[158:161], v[60:63]
	v_mfma_f32_16x16x32_bf16 v[56:59], v[150:153], v[158:161], v[56:59]
	v_mfma_f32_16x16x32_bf16 v[52:55], v[134:137], v[166:169], v[52:55]
	v_mfma_f32_16x16x32_bf16 v[44:47], v[150:153], v[166:169], v[44:47]
	v_mfma_f32_16x16x32_bf16 v[36:39], v[134:137], v[174:177], v[36:39]
	v_mfma_f32_16x16x32_bf16 v[28:31], v[150:153], v[174:177], v[28:31]
	v_mfma_f32_16x16x32_bf16 v[20:23], v[134:137], v[182:185], v[20:23]
	v_mfma_f32_16x16x32_bf16 v[12:15], v[150:153], v[182:185], v[12:15]
	v_mfma_f32_16x16x32_bf16 v[60:63], v[146:149], v[162:165], v[60:63]
	v_mfma_f32_16x16x32_bf16 v[56:59], v[154:157], v[162:165], v[56:59]
	v_mfma_f32_16x16x32_bf16 v[52:55], v[146:149], v[170:173], v[52:55]
	v_mfma_f32_16x16x32_bf16 v[44:47], v[154:157], v[170:173], v[44:47]
	v_mfma_f32_16x16x32_bf16 v[36:39], v[146:149], v[178:181], v[36:39]
	v_mfma_f32_16x16x32_bf16 v[28:31], v[154:157], v[178:181], v[28:31]
	v_mfma_f32_16x16x32_bf16 v[20:23], v[146:149], v[186:189], v[20:23]
	v_mfma_f32_16x16x32_bf16 v[12:15], v[154:157], v[186:189], v[12:15]
	s_setprio 0
	s_barrier
	s_add_u32 s10, s16, 0x60080
	s_addc_u32 s11, s17, 0
	s_add_i32 s16, s20, s35
	s_mov_b32 m0, s16
	v_lshl_add_u64 v[134:135], s[10:11], 0, v[144:145]
	global_load_lds_dwordx4 v[134:135], off
	s_add_i32 m0, s16, 0x2000
	v_lshl_add_u64 v[134:135], s[10:11], 0, v[128:129]
	global_load_lds_dwordx4 v[134:135], off
	s_waitcnt vmcnt(6)
	s_barrier
	s_setprio 1
	v_mfma_f32_16x16x32_bf16 v[48:51], v[196:199], v[158:161], v[48:51]
	v_mfma_f32_16x16x32_bf16 v[40:43], v[204:207], v[158:161], v[40:43]
	v_mfma_f32_16x16x32_bf16 v[32:35], v[196:199], v[166:169], v[32:35]
	v_mfma_f32_16x16x32_bf16 v[24:27], v[204:207], v[166:169], v[24:27]
	v_mfma_f32_16x16x32_bf16 v[16:19], v[196:199], v[174:177], v[16:19]
	v_mfma_f32_16x16x32_bf16 v[8:11], v[204:207], v[174:177], v[8:11]
	v_mfma_f32_16x16x32_bf16 v[4:7], v[196:199], v[182:185], v[4:7]
	v_mfma_f32_16x16x32_bf16 v[0:3], v[204:207], v[182:185], v[0:3]
	v_mfma_f32_16x16x32_bf16 v[48:51], v[200:203], v[162:165], v[48:51]
	v_mfma_f32_16x16x32_bf16 v[40:43], v[214:217], v[162:165], v[40:43]
	v_mfma_f32_16x16x32_bf16 v[32:35], v[200:203], v[170:173], v[32:35]
	v_mfma_f32_16x16x32_bf16 v[24:27], v[214:217], v[170:173], v[24:27]
	v_mfma_f32_16x16x32_bf16 v[16:19], v[200:203], v[178:181], v[16:19]
	v_mfma_f32_16x16x32_bf16 v[8:11], v[214:217], v[178:181], v[8:11]
	v_mfma_f32_16x16x32_bf16 v[4:7], v[200:203], v[186:189], v[4:7]
	v_mfma_f32_16x16x32_bf16 v[0:3], v[214:217], v[186:189], v[0:3]
	s_setprio 0
	s_add_i32 s72, s72, 2
	s_add_u32 s24, s24, 0x100
	s_addc_u32 s25, s25, 0
	s_cmp_gt_u32 s72, 21
	s_mov_b64 s[10:11], s[12:13]
	s_barrier
	s_cbranch_scc0 .LBB0_985
	s_mul_hi_i32 s10, s71, 0x3e0f83e1
	s_lshr_b32 s11, s10, 31
	s_ashr_i32 s10, s10, 5
	s_add_i32 s11, s10, s11
	s_mul_i32 s10, s11, 0x84
	s_sub_i32 s10, s71, s10
	s_mul_i32 s12, s10, 0x7c2
	s_lshr_b32 s13, s12, 31
	s_lshr_b32 s12, s12, 16
	s_add_i32 s12, s12, s13
	s_sext_i32_i16 s12, s12
	s_mul_i32 s13, s12, 0xffffffdf
	s_lshl_b32 s11, s11, 2
	s_add_i32 s10, s13, s10
	s_add_i32 s12, s11, s12
	s_cmp_lg_u32 s10, 0
	s_cbranch_scc0 .LBB0_988
	s_lshl_b32 s11, s12, 13
	s_lshl_b32 s10, s10, 8
	s_add_i32 s10, s11, s10
	s_add_i32 s13, s10, 0xffffff00
	s_cbranch_execnz .LBB0_977
	s_branch .LBB0_976

; #define PG8_STAGE(bufoff, gbase, voff) do { _Pragma("unroll") for (int _i = 0; _i < 2; ++_i) \
;         __builtin_amdgcn_global_load_lds((const unsigned*)((const char*)(gbase) + (voff)[_i]), (LAS unsigned*)(lds + (bufoff) + ldsw + _i * 8192), 16, 0, 0); } while (0)
; #define PG8_LDA(dst, b, h) do { _Pragma("unroll") for (int m = 0; m < 4; ++m) _Pragma("unroll") for (int k = 0; k < 2; ++k) dst[m][k] = *(const LAS bf16x8*)(lds + PG8_SA(b, h) + aoff + m * 2048 + k * 1024); } while (0)
; #define PG8_LDB(dst, b, h) do { _Pragma("unroll") for (int n = 0; n < 2; ++n) _Pragma("unroll") for (int k = 0; k < 2; ++k) dst[n][k] = *(const LAS bf16x8*)(lds + PG8_SB(b, h) + boff + n * 2048 + k * 1024); } while (0)
; #define PG8_MMA(ai, bj, At, Bt) do { __builtin_amdgcn_s_setprio(1); _Pragma("unroll") for (int m = 0; m < 4; ++m) _Pragma("unroll") for (int n = 0; n < 2; ++n) _Pragma("unroll") for (int k = 0; k < 2; ++k) \
;         acc[ai][bj][m][n] = __builtin_amdgcn_mfma_f32_16x16x32_bf16(Bt[n][k], At[m][k], acc[ai][bj][m][n], 0, 0, 0); __builtin_amdgcn_s_setprio(0); } while (0)
; #define PG8_WAIT_L(n) asm volatile("s_waitcnt lgkmcnt(" #n ")" ::: "memory")
; #define PG8_BAR __builtin_amdgcn_s_barrier()
; #define PG8_SCHED __builtin_amdgcn_sched_barrier(0)
; template <class Epi>
; __device__ __forceinline__ void gemm_phase(LAS unsigned char* lds, const Gemm g, const StaticOrder& S, const Epi& E) {
;     ...
;         const char* nA = has_next ? g.arow(nxt.pm) : cA; const char* nB = has_next ? (const char*)g.Bt + (size_t)nxt.pn * tB : cB;
;         for (int t = 0; t < nt; t += 2) {
;             const bool last = (t == nt - 2);
;             const char* a1 = cA + (size_t)(t + 1) * kstep;
;             const char* a2 = last ? nA : cA + (size_t)(t + 2) * kstep; const char* b2 = last ? nB : cB + (size_t)(t + 2) * kstep;
;             const char* a3 = a2 + kstep; const char* b3 = b2 + kstep;
;             PG8_LDB(B0, 0, 0); PG8_SCHED; PG8_LDA(At, 0, 0); PG8_STAGE(PG8_SA(1, 1), a1 + hA, voffA);
;             PG8_WAIT_L(8); PG8_BAR; PG8_WAIT_L(0); PG8_MMA(0, 0, At, B0); PG8_BAR; PG8_SCHED;
;             PG8_LDB(B1, 0, 1); PG8_STAGE(PG8_SB(0, 0), b2, voffB);
;             PG8_BAR; PG8_WAIT_L(0); PG8_MMA(0, 1, At, B1); PG8_BAR;
;             PG8_LDA(At, 0, 1); PG8_STAGE(PG8_SA(0, 0), a2, voffA);
;             PG8_BAR; PG8_WAIT_L(0); PG8_MMA(1, 0, At, B0); PG8_BAR; PG8_SCHED;
.LBB0_1013:
	s_add_u32 s12, s10, 0x100
	s_addc_u32 s13, s11, 0
	s_add_i32 s26, 0, 0x10000
	v_add_u32_e32 v142, s26, v139
	ds_read_b128 v[134:137], v142
	ds_read_b128 v[146:149], v142 offset:1024
	ds_read_b128 v[150:153], v142 offset:2048
	ds_read_b128 v[154:157], v142 offset:3072
	s_cmp_eq_u32 s72, 20
	s_cselect_b32 s21, s5, s13
	s_cselect_b32 s20, s4, s12
	s_cselect_b32 s17, s7, s25
	s_cselect_b32 s16, s6, s24
	v_lshl_add_u64 v[142:143], s[10:11], 0, v[130:131]
	s_add_i32 m0, s61, 0xc000
	ds_read_b128 v[158:161], v141
	ds_read_b128 v[162:165], v141 offset:1024
	ds_read_b128 v[166:169], v141 offset:2048
	ds_read_b128 v[170:173], v141 offset:3072
	ds_read_b128 v[174:177], v141 offset:4096
	ds_read_b128 v[178:181], v141 offset:5120
	ds_read_b128 v[182:185], v141 offset:6144
	ds_read_b128 v[186:189], v141 offset:7168
	global_load_lds_dwordx4 v[142:143], off
	s_add_i32 m0, s61, 0xe000
	v_lshl_add_u64 v[142:143], s[10:11], 0, v[132:133]
	global_load_lds_dwordx4 v[142:143], off
	s_waitcnt lgkmcnt(8)
	s_barrier
	s_waitcnt lgkmcnt(0)
	s_setprio 1
	v_mfma_f32_16x16x32_bf16 v[124:127], v[134:137], v[158:161], v[124:127]
	v_mfma_f32_16x16x32_bf16 v[120:123], v[150:153], v[158:161], v[120:123]
	v_mfma_f32_16x16x32_bf16 v[116:119], v[134:137], v[166:169], v[116:119]
	v_mfma_f32_16x16x32_bf16 v[108:111], v[150:153], v[166:169], v[108:111]
	v_mfma_f32_16x16x32_bf16 v[100:103], v[134:137], v[174:177], v[100:103]
	v_mfma_f32_16x16x32_bf16 v[92:95], v[150:153], v[174:177], v[92:95]
	v_mfma_f32_16x16x32_bf16 v[84:87], v[134:137], v[182:185], v[84:87]
	v_mfma_f32_16x16x32_bf16 v[76:79], v[150:153], v[182:185], v[76:79]
	v_mfma_f32_16x16x32_bf16 v[124:127], v[146:149], v[162:165], v[124:127]
	v_mfma_f32_16x16x32_bf16 v[120:123], v[154:157], v[162:165], v[120:123]
	v_mfma_f32_16x16x32_bf16 v[116:119], v[146:149], v[170:173], v[116:119]
	v_mfma_f32_16x16x32_bf16 v[108:111], v[154:157], v[170:173], v[108:111]
	v_mfma_f32_16x16x32_bf16 v[100:103], v[146:149], v[178:181], v[100:103]
	v_mfma_f32_16x16x32_bf16 v[92:95], v[154:157], v[178:181], v[92:95]
	v_mfma_f32_16x16x32_bf16 v[84:87], v[146:149], v[186:189], v[84:87]
	v_mfma_f32_16x16x32_bf16 v[76:79], v[154:157], v[186:189], v[76:79]
	s_setprio 0
	s_barrier
	s_add_i32 s27, 0, 0x14000
	v_add_u32_e32 v142, s27, v139
	s_add_i32 s10, s26, s60
	ds_read_b128 v[196:199], v142
	ds_read_b128 v[200:203], v142 offset:1024
	ds_read_b128 v[204:207], v142 offset:2048
	ds_read_b128 v[214:217], v142 offset:3072
	v_lshl_add_u64 v[142:143], s[16:17], 0, v[144:145]
	s_mov_b32 m0, s10
	v_lshl_add_u64 v[192:193], s[16:17], 0, v[128:129]
	global_load_lds_dwordx4 v[142:143], off
	s_add_i32 m0, s10, 0x2000
	s_nop 0
	global_load_lds_dwordx4 v[192:193], off
	s_barrier
	s_waitcnt lgkmcnt(0)
	s_setprio 1
	v_mfma_f32_16x16x32_bf16 v[112:115], v[196:199], v[158:161], v[112:115]
	v_mfma_f32_16x16x32_bf16 v[104:107], v[204:207], v[158:161], v[104:107]
	v_mfma_f32_16x16x32_bf16 v[96:99], v[196:199], v[166:169], v[96:99]
	v_mfma_f32_16x16x32_bf16 v[88:91], v[204:207], v[166:169], v[88:91]
	v_mfma_f32_16x16x32_bf16 v[80:83], v[196:199], v[174:177], v[80:83]
	v_mfma_f32_16x16x32_bf16 v[72:75], v[204:207], v[174:177], v[72:75]
	v_mfma_f32_16x16x32_bf16 v[68:71], v[196:199], v[182:185], v[68:71]
	v_mfma_f32_16x16x32_bf16 v[64:67], v[204:207], v[182:185], v[64:67]
	v_mfma_f32_16x16x32_bf16 v[112:115], v[200:203], v[162:165], v[112:115]
	v_mfma_f32_16x16x32_bf16 v[104:107], v[214:217], v[162:165], v[104:107]
	v_mfma_f32_16x16x32_bf16 v[96:99], v[200:203], v[170:173], v[96:99]
	v_mfma_f32_16x16x32_bf16 v[88:91], v[214:217], v[170:173], v[88:91]
	v_mfma_f32_16x16x32_bf16 v[80:83], v[200:203], v[178:181], v[80:83]
	v_mfma_f32_16x16x32_bf16 v[72:75], v[214:217], v[178:181], v[72:75]
	v_mfma_f32_16x16x32_bf16 v[68:71], v[200:203], v[186:189], v[68:71]
	v_mfma_f32_16x16x32_bf16 v[64:67], v[214:217], v[186:189], v[64:67]
	s_setprio 0
	s_mov_b32 m0, s61
	v_lshl_add_u64 v[218:219], s[20:21], 0, v[144:145]
	s_barrier
	ds_read_b128 v[158:161], v141 offset:16384
	ds_read_b128 v[162:165], v141 offset:17408
	ds_read_b128 v[166:169], v141 offset:18432
	ds_read_b128 v[170:173], v141 offset:19456
	ds_read_b128 v[174:177], v141 offset:20480
	ds_read_b128 v[178:181], v141 offset:21504
	ds_read_b128 v[182:185], v141 offset:22528
	ds_read_b128 v[186:189], v141 offset:23552
	global_load_lds_dwordx4 v[218:219], off
	s_mov_b32 m0, s62
	v_lshl_add_u64 v[220:221], s[20:21], 0, v[128:129]
	global_load_lds_dwordx4 v[220:221], off
	s_barrier
	s_waitcnt lgkmcnt(0)
	s_setprio 1
	v_mfma_f32_16x16x32_bf16 v[60:63], v[134:137], v[158:161], v[60:63]
	v_mfma_f32_16x16x32_bf16 v[56:59], v[150:153], v[158:161], v[56:59]
	v_mfma_f32_16x16x32_bf16 v[52:55], v[134:137], v[166:169], v[52:55]
	v_mfma_f32_16x16x32_bf16 v[44:47], v[150:153], v[166:169], v[44:47]
	v_mfma_f32_16x16x32_bf16 v[36:39], v[134:137], v[174:177], v[36:39]
	v_mfma_f32_16x16x32_bf16 v[28:31], v[150:153], v[174:177], v[28:31]
	v_mfma_f32_16x16x32_bf16 v[20:23], v[134:137], v[182:185], v[20:23]
	v_mfma_f32_16x16x32_bf16 v[12:15], v[150:153], v[182:185], v[12:15]
	v_mfma_f32_16x16x32_bf16 v[60:63], v[146:149], v[162:165], v[60:63]
	v_mfma_f32_16x16x32_bf16 v[56:59], v[154:157], v[162:165], v[56:59]
	v_mfma_f32_16x16x32_bf16 v[52:55], v[146:149], v[170:173], v[52:55]
	v_mfma_f32_16x16x32_bf16 v[44:47], v[154:157], v[170:173], v[44:47]
	v_mfma_f32_16x16x32_bf16 v[36:39], v[146:149], v[178:181], v[36:39]
	v_mfma_f32_16x16x32_bf16 v[28:31], v[154:157], v[178:181], v[28:31]
	v_mfma_f32_16x16x32_bf16 v[20:23], v[146:149], v[186:189], v[20:23]
	v_mfma_f32_16x16x32_bf16 v[12:15], v[154:157], v[186:189], v[12:15]
	s_setprio 0
	s_barrier
; #define PG8_STAGE(bufoff, gbase, voff) do { _Pragma("unroll") for (int _i = 0; _i < 2; ++_i) \
;         __builtin_amdgcn_global_load_lds((const unsigned*)((const char*)(gbase) + (voff)[_i]), (LAS unsigned*)(lds + (bufoff) + ldsw + _i * 8192), 16, 0, 0); } while (0)
; #define PG8_LDA(dst, b, h) do { _Pragma("unroll") for (int m = 0; m < 4; ++m) _Pragma("unroll") for (int k = 0; k < 2; ++k) dst[m][k] = *(const LAS bf16x8*)(lds + PG8_SA(b, h) + aoff + m * 2048 + k * 1024); } while (0)
; #define PG8_LDB(dst, b, h) do { _Pragma("unroll") for (int n = 0; n < 2; ++n) _Pragma("unroll") for (int k = 0; k < 2; ++k) dst[n][k] = *(const LAS bf16x8*)(lds + PG8_SB(b, h) + boff + n * 2048 + k * 1024); } while (0)
; #define PG8_MMA(ai, bj, At, Bt) do { __builtin_amdgcn_s_setprio(1); _Pragma("unroll") for (int m = 0; m < 4; ++m) _Pragma("unroll") for (int n = 0; n < 2; ++n) _Pragma("unroll") for (int k = 0; k < 2; ++k) \
;         acc[ai][bj][m][n] = __builtin_amdgcn_mfma_f32_16x16x32_bf16(Bt[n][k], At[m][k], acc[ai][bj][m][n], 0, 0, 0); __builtin_amdgcn_s_setprio(0); } while (0)
; #define PG8_WAIT_V(n) asm volatile("s_waitcnt vmcnt(" #n ")" ::: "memory")
; #define PG8_WAIT_L(n) asm volatile("s_waitcnt lgkmcnt(" #n ")" ::: "memory")
; #define PG8_BAR __builtin_amdgcn_s_barrier()
; #define PG8_SCHED __builtin_amdgcn_sched_barrier(0)
; template <class Epi>
; __device__ __forceinline__ void gemm_phase(LAS unsigned char* lds, const Gemm g, const StaticOrder& S, const Epi& E) {
;     ...
;             PG8_STAGE(PG8_SB(0, 1), b2 + hB, voffB);
;             PG8_WAIT_V(6); PG8_BAR; PG8_MMA(1, 1, At, B1); PG8_BAR;
;             PG8_LDB(B0, 1, 0); PG8_SCHED; PG8_LDA(At, 1, 0); PG8_STAGE(PG8_SA(0, 1), a2 + hA, voffA);
;             PG8_WAIT_L(8); PG8_BAR; PG8_WAIT_L(0); PG8_MMA(0, 0, At, B0); PG8_BAR; PG8_SCHED;
;             PG8_LDB(B1, 1, 1); PG8_STAGE(PG8_SB(1, 0), b3, voffB);
;             PG8_BAR; PG8_WAIT_L(0); PG8_MMA(0, 1, At, B1); PG8_BAR;
;             PG8_LDA(At, 1, 1); PG8_STAGE(PG8_SA(1, 0), a3, voffA);
	s_add_u32 s10, s16, 0x60000
	s_addc_u32 s11, s17, 0
	s_add_i32 s26, s27, s60
	s_mov_b32 m0, s26
	v_lshl_add_u64 v[134:135], s[10:11], 0, v[144:145]
	global_load_lds_dwordx4 v[134:135], off
	s_add_i32 m0, s26, 0x2000
	v_lshl_add_u64 v[134:135], s[10:11], 0, v[128:129]
	global_load_lds_dwordx4 v[134:135], off
	s_waitcnt vmcnt(6)
	s_barrier
	s_setprio 1
	v_mfma_f32_16x16x32_bf16 v[48:51], v[196:199], v[158:161], v[48:51]
	v_mfma_f32_16x16x32_bf16 v[40:43], v[204:207], v[158:161], v[40:43]
	v_mfma_f32_16x16x32_bf16 v[32:35], v[196:199], v[166:169], v[32:35]
	v_mfma_f32_16x16x32_bf16 v[24:27], v[204:207], v[166:169], v[24:27]
	v_mfma_f32_16x16x32_bf16 v[16:19], v[196:199], v[174:177], v[16:19]
	v_mfma_f32_16x16x32_bf16 v[8:11], v[204:207], v[174:177], v[8:11]
	v_mfma_f32_16x16x32_bf16 v[4:7], v[196:199], v[182:185], v[4:7]
	v_mfma_f32_16x16x32_bf16 v[0:3], v[204:207], v[182:185], v[0:3]
	v_mfma_f32_16x16x32_bf16 v[48:51], v[200:203], v[162:165], v[48:51]
	v_mfma_f32_16x16x32_bf16 v[40:43], v[214:217], v[162:165], v[40:43]
	v_mfma_f32_16x16x32_bf16 v[32:35], v[200:203], v[170:173], v[32:35]
	v_mfma_f32_16x16x32_bf16 v[24:27], v[214:217], v[170:173], v[24:27]
	v_mfma_f32_16x16x32_bf16 v[16:19], v[200:203], v[178:181], v[16:19]
	v_mfma_f32_16x16x32_bf16 v[8:11], v[214:217], v[178:181], v[8:11]
	v_mfma_f32_16x16x32_bf16 v[4:7], v[200:203], v[186:189], v[4:7]
	v_mfma_f32_16x16x32_bf16 v[0:3], v[214:217], v[186:189], v[0:3]
	s_setprio 0
	s_add_i32 s26, 0, 0x18000
	v_add_u32_e32 v154, s26, v139
	s_barrier
	ds_read_b128 v[134:137], v154
	ds_read_b128 v[146:149], v154 offset:1024
	ds_read_b128 v[150:153], v154 offset:2048
	ds_read_b128 v[154:157], v154 offset:3072
	s_add_u32 s10, s20, 0x60000
	s_addc_u32 s11, s21, 0
	s_mov_b32 m0, s63
	v_lshl_add_u64 v[196:197], s[10:11], 0, v[144:145]
	ds_read_b128 v[158:161], v141 offset:32768
	ds_read_b128 v[162:165], v141 offset:33792
	ds_read_b128 v[166:169], v141 offset:34816
	ds_read_b128 v[170:173], v141 offset:35840
	ds_read_b128 v[174:177], v141 offset:36864
	ds_read_b128 v[178:181], v141 offset:37888
	ds_read_b128 v[182:185], v141 offset:38912
	ds_read_b128 v[186:189], v141 offset:39936
	global_load_lds_dwordx4 v[196:197], off
	s_mov_b32 m0, s64
	v_lshl_add_u64 v[196:197], s[10:11], 0, v[128:129]
	global_load_lds_dwordx4 v[196:197], off
	s_waitcnt lgkmcnt(8)
	s_barrier
	s_waitcnt lgkmcnt(0)
	s_setprio 1
	v_mfma_f32_16x16x32_bf16 v[124:127], v[134:137], v[158:161], v[124:127]
	v_mfma_f32_16x16x32_bf16 v[120:123], v[150:153], v[158:161], v[120:123]
	v_mfma_f32_16x16x32_bf16 v[116:119], v[134:137], v[166:169], v[116:119]
	v_mfma_f32_16x16x32_bf16 v[108:111], v[150:153], v[166:169], v[108:111]
	v_mfma_f32_16x16x32_bf16 v[100:103], v[134:137], v[174:177], v[100:103]
	v_mfma_f32_16x16x32_bf16 v[92:95], v[150:153], v[174:177], v[92:95]
	v_mfma_f32_16x16x32_bf16 v[84:87], v[134:137], v[182:185], v[84:87]
	v_mfma_f32_16x16x32_bf16 v[76:79], v[150:153], v[182:185], v[76:79]
	v_mfma_f32_16x16x32_bf16 v[124:127], v[146:149], v[162:165], v[124:127]
	v_mfma_f32_16x16x32_bf16 v[120:123], v[154:157], v[162:165], v[120:123]
	v_mfma_f32_16x16x32_bf16 v[116:119], v[146:149], v[170:173], v[116:119]
	v_mfma_f32_16x16x32_bf16 v[108:111], v[154:157], v[170:173], v[108:111]
	v_mfma_f32_16x16x32_bf16 v[100:103], v[146:149], v[178:181], v[100:103]
	v_mfma_f32_16x16x32_bf16 v[92:95], v[154:157], v[178:181], v[92:95]
	v_mfma_f32_16x16x32_bf16 v[84:87], v[146:149], v[186:189], v[84:87]
	v_mfma_f32_16x16x32_bf16 v[76:79], v[154:157], v[186:189], v[76:79]
	s_setprio 0
	s_barrier
	s_add_i32 s20, 0, 0x1c000
	s_add_i32 s10, s26, s60
	v_add_u32_e32 v190, s20, v139
	v_lshl_add_u64 v[142:143], v[142:143], 0, s[88:89]
	s_mov_b32 m0, s10
	ds_read_b128 v[196:199], v190
	ds_read_b128 v[200:203], v190 offset:1024
	ds_read_b128 v[204:207], v190 offset:2048
	ds_read_b128 v[214:217], v190 offset:3072
	global_load_lds_dwordx4 v[142:143], off
	s_add_i32 m0, s10, 0x2000
	v_lshl_add_u64 v[142:143], v[192:193], 0, s[88:89]
	global_load_lds_dwordx4 v[142:143], off
	s_barrier
	s_waitcnt lgkmcnt(0)
	s_setprio 1
	v_mfma_f32_16x16x32_bf16 v[112:115], v[196:199], v[158:161], v[112:115]
	v_mfma_f32_16x16x32_bf16 v[104:107], v[204:207], v[158:161], v[104:107]
	v_mfma_f32_16x16x32_bf16 v[96:99], v[196:199], v[166:169], v[96:99]
	v_mfma_f32_16x16x32_bf16 v[88:91], v[204:207], v[166:169], v[88:91]
	v_mfma_f32_16x16x32_bf16 v[80:83], v[196:199], v[174:177], v[80:83]
	v_mfma_f32_16x16x32_bf16 v[72:75], v[204:207], v[174:177], v[72:75]
	v_mfma_f32_16x16x32_bf16 v[68:71], v[196:199], v[182:185], v[68:71]
	v_mfma_f32_16x16x32_bf16 v[64:67], v[204:207], v[182:185], v[64:67]
	v_mfma_f32_16x16x32_bf16 v[112:115], v[200:203], v[162:165], v[112:115]
	v_mfma_f32_16x16x32_bf16 v[104:107], v[214:217], v[162:165], v[104:107]
	v_mfma_f32_16x16x32_bf16 v[96:99], v[200:203], v[170:173], v[96:99]
	v_mfma_f32_16x16x32_bf16 v[88:91], v[214:217], v[170:173], v[88:91]
	v_mfma_f32_16x16x32_bf16 v[80:83], v[200:203], v[178:181], v[80:83]
	v_mfma_f32_16x16x32_bf16 v[72:75], v[214:217], v[178:181], v[72:75]
	v_mfma_f32_16x16x32_bf16 v[68:71], v[200:203], v[186:189], v[68:71]
	v_mfma_f32_16x16x32_bf16 v[64:67], v[214:217], v[186:189], v[64:67]
	s_setprio 0
	s_mov_b32 m0, s65
	v_lshl_add_u64 v[142:143], v[218:219], 0, s[88:89]
	s_barrier
	ds_read_b128 v[158:161], v141 offset:49152
	ds_read_b128 v[162:165], v141 offset:50176
	ds_read_b128 v[166:169], v141 offset:51200
	ds_read_b128 v[170:173], v141 offset:52224
	ds_read_b128 v[174:177], v141 offset:53248
	ds_read_b128 v[178:181], v141 offset:54272
	ds_read_b128 v[182:185], v141 offset:55296
	ds_read_b128 v[186:189], v141 offset:56320
	global_load_lds_dwordx4 v[142:143], off
	s_mov_b32 m0, s66
	v_lshl_add_u64 v[142:143], v[220:221], 0, s[88:89]
	global_load_lds_dwordx4 v[142:143], off
	s_barrier
; #define PG8_STAGE(bufoff, gbase, voff) do { _Pragma("unroll") for (int _i = 0; _i < 2; ++_i) \
;         __builtin_amdgcn_global_load_lds((const unsigned*)((const char*)(gbase) + (voff)[_i]), (LAS unsigned*)(lds + (bufoff) + ldsw + _i * 8192), 16, 0, 0); } while (0)
; #define PG8_MMA(ai, bj, At, Bt) do { __builtin_amdgcn_s_setprio(1); _Pragma("unroll") for (int m = 0; m < 4; ++m) _Pragma("unroll") for (int n = 0; n < 2; ++n) _Pragma("unroll") for (int k = 0; k < 2; ++k) \
;         acc[ai][bj][m][n] = __builtin_amdgcn_mfma_f32_16x16x32_bf16(Bt[n][k], At[m][k], acc[ai][bj][m][n], 0, 0, 0); __builtin_amdgcn_s_setprio(0); } while (0)
; #define PG8_WAIT_V(n) asm volatile("s_waitcnt vmcnt(" #n ")" ::: "memory")
; #define PG8_WAIT_L(n) asm volatile("s_waitcnt lgkmcnt(" #n ")" ::: "memory")
; #define PG8_BAR __builtin_amdgcn_s_barrier()
; #define PG8_SCHED __builtin_amdgcn_sched_barrier(0)
; template <class Epi>
; __device__ __forceinline__ void gemm_phase(LAS unsigned char* lds, const Gemm g, const StaticOrder& S, const Epi& E) {
;     ...
;             PG8_BAR; PG8_WAIT_L(0); PG8_MMA(1, 0, At, B0); PG8_BAR; PG8_SCHED;
;             PG8_STAGE(PG8_SB(1, 1), b3 + hB, voffB);
;             PG8_WAIT_V(6); PG8_BAR; PG8_MMA(1, 1, At, B1); PG8_BAR;
	s_waitcnt lgkmcnt(0)
	s_setprio 1
	v_mfma_f32_16x16x32_bf16 v[60:63], v[134:137], v[158:161], v[60:63]
	v_mfma_f32_16x16x32_bf16 v[56:59], v[150:153], v[158:161], v[56:59]
	v_mfma_f32_16x16x32_bf16 v[52:55], v[134:137], v[166:169], v[52:55]
	v_mfma_f32_16x16x32_bf16 v[44:47], v[150:153], v[166:169], v[44:47]
	v_mfma_f32_16x16x32_bf16 v[36:39], v[134:137], v[174:177], v[36:39]
	v_mfma_f32_16x16x32_bf16 v[28:31], v[150:153], v[174:177], v[28:31]
	v_mfma_f32_16x16x32_bf16 v[20:23], v[134:137], v[182:185], v[20:23]
	v_mfma_f32_16x16x32_bf16 v[12:15], v[150:153], v[182:185], v[12:15]
	v_mfma_f32_16x16x32_bf16 v[60:63], v[146:149], v[162:165], v[60:63]
	v_mfma_f32_16x16x32_bf16 v[56:59], v[154:157], v[162:165], v[56:59]
	v_mfma_f32_16x16x32_bf16 v[52:55], v[146:149], v[170:173], v[52:55]
	v_mfma_f32_16x16x32_bf16 v[44:47], v[154:157], v[170:173], v[44:47]
	v_mfma_f32_16x16x32_bf16 v[36:39], v[146:149], v[178:181], v[36:39]
	v_mfma_f32_16x16x32_bf16 v[28:31], v[154:157], v[178:181], v[28:31]
	v_mfma_f32_16x16x32_bf16 v[20:23], v[146:149], v[186:189], v[20:23]
	v_mfma_f32_16x16x32_bf16 v[12:15], v[154:157], v[186:189], v[12:15]
	s_setprio 0
	s_barrier
	s_add_u32 s10, s16, 0x60080
	s_addc_u32 s11, s17, 0
	s_add_i32 s16, s20, s60
	s_mov_b32 m0, s16
	v_lshl_add_u64 v[134:135], s[10:11], 0, v[144:145]
	global_load_lds_dwordx4 v[134:135], off
	s_add_i32 m0, s16, 0x2000
	v_lshl_add_u64 v[134:135], s[10:11], 0, v[128:129]
	global_load_lds_dwordx4 v[134:135], off
	s_waitcnt vmcnt(6)
	s_barrier
	s_setprio 1
	v_mfma_f32_16x16x32_bf16 v[48:51], v[196:199], v[158:161], v[48:51]
	v_mfma_f32_16x16x32_bf16 v[40:43], v[204:207], v[158:161], v[40:43]
	v_mfma_f32_16x16x32_bf16 v[32:35], v[196:199], v[166:169], v[32:35]
	v_mfma_f32_16x16x32_bf16 v[24:27], v[204:207], v[166:169], v[24:27]
	v_mfma_f32_16x16x32_bf16 v[16:19], v[196:199], v[174:177], v[16:19]
	v_mfma_f32_16x16x32_bf16 v[8:11], v[204:207], v[174:177], v[8:11]
	v_mfma_f32_16x16x32_bf16 v[4:7], v[196:199], v[182:185], v[4:7]
	v_mfma_f32_16x16x32_bf16 v[0:3], v[204:207], v[182:185], v[0:3]
	v_mfma_f32_16x16x32_bf16 v[48:51], v[200:203], v[162:165], v[48:51]
	v_mfma_f32_16x16x32_bf16 v[40:43], v[214:217], v[162:165], v[40:43]
	v_mfma_f32_16x16x32_bf16 v[32:35], v[200:203], v[170:173], v[32:35]
	v_mfma_f32_16x16x32_bf16 v[24:27], v[214:217], v[170:173], v[24:27]
	v_mfma_f32_16x16x32_bf16 v[16:19], v[200:203], v[178:181], v[16:19]
	v_mfma_f32_16x16x32_bf16 v[8:11], v[214:217], v[178:181], v[8:11]
	v_mfma_f32_16x16x32_bf16 v[4:7], v[200:203], v[186:189], v[4:7]
	v_mfma_f32_16x16x32_bf16 v[0:3], v[214:217], v[186:189], v[0:3]
	s_setprio 0
	s_add_i32 s72, s72, 2
	s_add_u32 s24, s24, 0x100
	s_addc_u32 s25, s25, 0
	s_cmp_gt_u32 s72, 21
	s_mov_b64 s[10:11], s[12:13]
	s_barrier
	s_cbranch_scc0 .LBB0_1013
; __device__ __forceinline__ unsigned pk2(float lo, float hi) { unsigned r; asm("v_cvt_pk_bf16_f32 %0, %1, %2" : "=v"(r) : "v"(lo), "v"(hi)); return r; }
;     __device__ __forceinline__ void operator()(const f32x4 (&acc)[2][2][4][2], const Unit& u, int wr, int wc, int fr, int fq) const {
;     ...
;         int c = col_t + 64 * wc + 16 * fq;
;         if (mode == 2) c = (c >> 6) * 96 + (c & 63);
; #pragma unroll
;         for (int ai = 0; ai < 2; ++ai)
; #pragma unroll
;             for (int m = 0; m < 4; ++m) {
;                 const int row = row_t + ai * HALF + wr * 64 + m * 16 + fr;
;                 bf16_t* rp = O + (size_t)row * ldc + c;
; #pragma unroll
;                 for (int bj = 0; bj < 2; ++bj) {
;                     const f32x4 v0 = acc[ai][bj][m][0], v1 = acc[ai][bj][m][1];
;                     u32x4 o; o.x = pk2(v0[0], v0[1]); o.y = pk2(v0[2], v0[3]); o.z = pk2(v1[0], v1[1]); o.w = pk2(v1[2], v1[3]);
;                     *(u32x4*)(rp + 8 * bj) = o;
;                 }
;             }
	v_lshl_add_u32 v134, s71, 8, v138
	v_cvt_pk_bf16_f32 v68, v68, v69
	v_cvt_pk_bf16_f32 v69, v70, v71
	v_cvt_pk_bf16_f32 v70, v64, v65
	v_add_u32_e32 v64, 0x80, v134
	v_lshl_or_b32 v136, s15, 8, v140
	v_ashrrev_i32_e32 v135, 31, v134
	v_cvt_pk_bf16_f32 v112, v112, v113
	v_cvt_pk_bf16_f32 v113, v114, v115
	v_cvt_pk_bf16_f32 v114, v104, v105
	v_or_b32_e32 v104, 16, v134
	v_ashrrev_i32_e32 v65, 31, v64
	v_cvt_pk_bf16_f32 v48, v48, v49
	v_cvt_pk_bf16_f32 v49, v50, v51
	v_cvt_pk_bf16_f32 v50, v40, v41
	v_add_u32_e32 v40, 0x90, v134
	v_ashrrev_i32_e32 v137, 31, v136
	v_lshlrev_b64 v[142:143], 11, v[134:135]
	v_ashrrev_i32_e32 v105, 31, v104
	v_cvt_pk_bf16_f32 v96, v96, v97
	v_cvt_pk_bf16_f32 v97, v98, v99
	v_cvt_pk_bf16_f32 v98, v88, v89
	v_or_b32_e32 v88, 32, v134
	v_lshlrev_b64 v[64:65], 11, v[64:65]
	v_ashrrev_i32_e32 v41, 31, v40
	v_cvt_pk_bf16_f32 v32, v32, v33
	v_cvt_pk_bf16_f32 v33, v34, v35
	v_cvt_pk_bf16_f32 v34, v24, v25
	v_add_u32_e32 v24, 0xa0, v134
	v_lshl_add_u64 v[142:143], s[8:9], 0, v[142:143]
	v_lshlrev_b64 v[136:137], 1, v[136:137]
	v_lshlrev_b64 v[104:105], 11, v[104:105]
	v_ashrrev_i32_e32 v89, 31, v88
	v_cvt_pk_bf16_f32 v80, v80, v81
	v_cvt_pk_bf16_f32 v81, v82, v83
	v_cvt_pk_bf16_f32 v82, v72, v73
	v_or_b32_e32 v72, 48, v134
	v_lshl_add_u64 v[64:65], s[8:9], 0, v[64:65]
	v_lshlrev_b64 v[40:41], 11, v[40:41]
	v_ashrrev_i32_e32 v25, 31, v24
	v_cvt_pk_bf16_f32 v16, v16, v17
	v_cvt_pk_bf16_f32 v17, v18, v19
	v_cvt_pk_bf16_f32 v18, v8, v9
	v_add_u32_e32 v8, 0xb0, v134
	v_lshl_add_u64 v[142:143], v[142:143], 0, v[136:137]
	v_lshl_add_u64 v[104:105], s[8:9], 0, v[104:105]
	v_lshlrev_b64 v[88:89], 11, v[88:89]
	v_ashrrev_i32_e32 v73, 31, v72
	v_lshl_add_u64 v[64:65], v[64:65], 0, v[136:137]
	v_lshl_add_u64 v[40:41], s[8:9], 0, v[40:41]
	v_lshlrev_b64 v[24:25], 11, v[24:25]
	v_ashrrev_i32_e32 v9, 31, v8
	v_cvt_pk_bf16_f32 v115, v106, v107
	global_store_dwordx4 v[142:143], v[112:115], off offset:16
	v_lshl_add_u64 v[88:89], s[8:9], 0, v[88:89]
	v_lshlrev_b64 v[72:73], 11, v[72:73]
	v_lshl_add_u64 v[112:113], v[104:105], 0, v[136:137]
	v_cvt_pk_bf16_f32 v51, v42, v43
	global_store_dwordx4 v[64:65], v[48:51], off offset:16
	v_lshl_add_u64 v[24:25], s[8:9], 0, v[24:25]
	v_lshlrev_b64 v[8:9], 11, v[8:9]
	v_lshl_add_u64 v[48:49], v[40:41], 0, v[136:137]
	v_cvt_pk_bf16_f32 v99, v90, v91
	global_store_dwordx4 v[112:113], v[96:99], off offset:16
	v_lshl_add_u64 v[72:73], s[8:9], 0, v[72:73]
	v_cvt_pk_bf16_f32 v35, v26, v27
	global_store_dwordx4 v[48:49], v[32:35], off offset:16
	v_lshl_add_u64 v[96:97], v[88:89], 0, v[136:137]
	v_lshl_add_u64 v[8:9], s[8:9], 0, v[8:9]
	v_lshl_add_u64 v[32:33], v[24:25], 0, v[136:137]
	v_cvt_pk_bf16_f32 v83, v74, v75
	global_store_dwordx4 v[96:97], v[80:83], off offset:16
	v_cvt_pk_bf16_f32 v19, v10, v11
	global_store_dwordx4 v[32:33], v[16:19], off offset:16
	s_and_b64 vcc, exec, s[0:1]
	v_lshl_add_u64 v[80:81], v[72:73], 0, v[136:137]
	v_lshl_add_u64 v[16:17], v[8:9], 0, v[136:137]
	s_mov_b32 s15, s69
	s_mov_b32 s71, s70
	s_mov_b64 s[12:13], s[6:7]
	s_mov_b64 s[10:11], s[4:5]
	v_cvt_pk_bf16_f32 v124, v124, v125
	v_cvt_pk_bf16_f32 v125, v126, v127
	v_cvt_pk_bf16_f32 v126, v120, v121
	v_cvt_pk_bf16_f32 v127, v122, v123
	global_store_dwordx4 v[142:143], v[124:127], off
	v_cvt_pk_bf16_f32 v104, v116, v117
	v_cvt_pk_bf16_f32 v105, v118, v119
	v_cvt_pk_bf16_f32 v106, v108, v109
	v_cvt_pk_bf16_f32 v107, v110, v111
	global_store_dwordx4 v[112:113], v[104:107], off
	v_cvt_pk_bf16_f32 v88, v100, v101
	v_cvt_pk_bf16_f32 v89, v102, v103
	v_cvt_pk_bf16_f32 v90, v92, v93
	v_cvt_pk_bf16_f32 v91, v94, v95
	global_store_dwordx4 v[96:97], v[88:91], off
	v_cvt_pk_bf16_f32 v72, v84, v85
	v_cvt_pk_bf16_f32 v73, v86, v87
	v_cvt_pk_bf16_f32 v74, v76, v77
	v_cvt_pk_bf16_f32 v75, v78, v79
	global_store_dwordx4 v[80:81], v[72:75], off
	v_cvt_pk_bf16_f32 v71, v66, v67
	global_store_dwordx4 v[80:81], v[68:71], off offset:16
	v_cvt_pk_bf16_f32 v60, v60, v61
	v_cvt_pk_bf16_f32 v61, v62, v63
	v_cvt_pk_bf16_f32 v62, v56, v57
	v_cvt_pk_bf16_f32 v63, v58, v59
	global_store_dwordx4 v[64:65], v[60:63], off
	v_cvt_pk_bf16_f32 v40, v52, v53
	v_cvt_pk_bf16_f32 v41, v54, v55
	v_cvt_pk_bf16_f32 v42, v44, v45
	v_cvt_pk_bf16_f32 v43, v46, v47
	global_store_dwordx4 v[48:49], v[40:43], off
	v_cvt_pk_bf16_f32 v24, v36, v37
	v_cvt_pk_bf16_f32 v25, v38, v39
	v_cvt_pk_bf16_f32 v26, v28, v29
	v_cvt_pk_bf16_f32 v27, v30, v31
	global_store_dwordx4 v[32:33], v[24:27], off
	v_cvt_pk_bf16_f32 v8, v20, v21
	v_cvt_pk_bf16_f32 v9, v22, v23
	v_cvt_pk_bf16_f32 v10, v12, v13
	v_cvt_pk_bf16_f32 v11, v14, v15
	global_store_dwordx4 v[16:17], v[8:11], off
	v_cvt_pk_bf16_f32 v4, v4, v5
	v_cvt_pk_bf16_f32 v5, v6, v7
	v_cvt_pk_bf16_f32 v6, v0, v1
	v_cvt_pk_bf16_f32 v7, v2, v3
	global_store_dwordx4 v[16:17], v[4:7], off offset:16
	s_cbranch_vccz .LBB0_1002
	s_waitcnt vmcnt(0)
	s_cmpk_gt_u32 s34, 0xff
	s_cbranch_scc1 .LBB0_1017
	s_barrier

; #define PG8_STAGE(bufoff, gbase, voff) do { _Pragma("unroll") for (int _i = 0; _i < 2; ++_i) \
;         __builtin_amdgcn_global_load_lds((const unsigned*)((const char*)(gbase) + (voff)[_i]), (LAS unsigned*)(lds + (bufoff) + ldsw + _i * 8192), 16, 0, 0); } while (0)
; #define PG8_LDA(dst, b, h) do { _Pragma("unroll") for (int m = 0; m < 4; ++m) _Pragma("unroll") for (int k = 0; k < 2; ++k) dst[m][k] = *(const LAS bf16x8*)(lds + PG8_SA(b, h) + aoff + m * 2048 + k * 1024); } while (0)
; #define PG8_LDB(dst, b, h) do { _Pragma("unroll") for (int n = 0; n < 2; ++n) _Pragma("unroll") for (int k = 0; k < 2; ++k) dst[n][k] = *(const LAS bf16x8*)(lds + PG8_SB(b, h) + boff + n * 2048 + k * 1024); } while (0)
; #define PG8_MMA(ai, bj, At, Bt) do { __builtin_amdgcn_s_setprio(1); _Pragma("unroll") for (int m = 0; m < 4; ++m) _Pragma("unroll") for (int n = 0; n < 2; ++n) _Pragma("unroll") for (int k = 0; k < 2; ++k) \
;         acc[ai][bj][m][n] = __builtin_amdgcn_mfma_f32_16x16x32_bf16(Bt[n][k], At[m][k], acc[ai][bj][m][n], 0, 0, 0); __builtin_amdgcn_s_setprio(0); } while (0)
; #define PG8_WAIT_L(n) asm volatile("s_waitcnt lgkmcnt(" #n ")" ::: "memory")
; #define PG8_BAR __builtin_amdgcn_s_barrier()
; #define PG8_SCHED __builtin_amdgcn_sched_barrier(0)
; template <class Epi>
; __device__ __forceinline__ void gemm_phase(LAS unsigned char* lds, const Gemm g, const StaticOrder& S, const Epi& E) {
;     ...
;         const char* nA = has_next ? g.arow(nxt.pm) : cA; const char* nB = has_next ? (const char*)g.Bt + (size_t)nxt.pn * tB : cB;
;         for (int t = 0; t < nt; t += 2) {
;             const bool last = (t == nt - 2);
;             const char* a1 = cA + (size_t)(t + 1) * kstep;
;             const char* a2 = last ? nA : cA + (size_t)(t + 2) * kstep; const char* b2 = last ? nB : cB + (size_t)(t + 2) * kstep;
;             const char* a3 = a2 + kstep; const char* b3 = b2 + kstep;
;             PG8_LDB(B0, 0, 0); PG8_SCHED; PG8_LDA(At, 0, 0); PG8_STAGE(PG8_SA(1, 1), a1 + hA, voffA);
;             PG8_WAIT_L(8); PG8_BAR; PG8_WAIT_L(0); PG8_MMA(0, 0, At, B0); PG8_BAR; PG8_SCHED;
;             PG8_LDB(B1, 0, 1); PG8_STAGE(PG8_SB(0, 0), b2, voffB);
;             PG8_BAR; PG8_WAIT_L(0); PG8_MMA(0, 1, At, B1); PG8_BAR;
;             PG8_LDA(At, 0, 1); PG8_STAGE(PG8_SA(0, 0), a2, voffA);
;             PG8_BAR; PG8_WAIT_L(0); PG8_MMA(1, 0, At, B0); PG8_BAR; PG8_SCHED;
.LBB0_1079:
	s_add_u32 s16, s12, 0xfffc0080
	s_addc_u32 s17, s13, -1
	s_add_i32 s26, 0, 0x10000
	v_add_u32_e32 v142, s26, v139
	ds_read_b128 v[134:137], v142
	ds_read_b128 v[146:149], v142 offset:1024
	ds_read_b128 v[150:153], v142 offset:2048
	ds_read_b128 v[154:157], v142 offset:3072
	s_cmp_eq_u32 s77, 12
	s_cselect_b32 s21, s71, s17
	s_cselect_b32 s20, s72, s16
	s_cselect_b32 s17, s7, s76
	s_cselect_b32 s16, s24, s25
	v_lshl_add_u64 v[142:143], s[12:13], 0, v[130:131]
	s_add_i32 m0, s61, 0xc000
	ds_read_b128 v[158:161], v141
	ds_read_b128 v[162:165], v141 offset:1024
	ds_read_b128 v[166:169], v141 offset:2048
	ds_read_b128 v[170:173], v141 offset:3072
	ds_read_b128 v[174:177], v141 offset:4096
	ds_read_b128 v[178:181], v141 offset:5120
	ds_read_b128 v[182:185], v141 offset:6144
	ds_read_b128 v[196:199], v141 offset:7168
	global_load_lds_dwordx4 v[142:143], off
	s_add_i32 m0, s61, 0xe000
	v_lshl_add_u64 v[142:143], s[12:13], 0, v[132:133]
	global_load_lds_dwordx4 v[142:143], off
	s_waitcnt lgkmcnt(8)
	s_barrier
	s_waitcnt lgkmcnt(0)
	s_setprio 1
	v_mfma_f32_16x16x32_bf16 v[124:127], v[134:137], v[158:161], v[124:127]
	v_mfma_f32_16x16x32_bf16 v[120:123], v[150:153], v[158:161], v[120:123]
	v_mfma_f32_16x16x32_bf16 v[116:119], v[134:137], v[166:169], v[116:119]
	v_mfma_f32_16x16x32_bf16 v[108:111], v[150:153], v[166:169], v[108:111]
	v_mfma_f32_16x16x32_bf16 v[100:103], v[134:137], v[174:177], v[100:103]
	v_mfma_f32_16x16x32_bf16 v[92:95], v[150:153], v[174:177], v[92:95]
	v_mfma_f32_16x16x32_bf16 v[84:87], v[134:137], v[182:185], v[84:87]
	v_mfma_f32_16x16x32_bf16 v[76:79], v[150:153], v[182:185], v[76:79]
	v_mfma_f32_16x16x32_bf16 v[124:127], v[146:149], v[162:165], v[124:127]
	v_mfma_f32_16x16x32_bf16 v[120:123], v[154:157], v[162:165], v[120:123]
	v_mfma_f32_16x16x32_bf16 v[116:119], v[146:149], v[170:173], v[116:119]
	v_mfma_f32_16x16x32_bf16 v[108:111], v[154:157], v[170:173], v[108:111]
	v_mfma_f32_16x16x32_bf16 v[100:103], v[146:149], v[178:181], v[100:103]
	v_mfma_f32_16x16x32_bf16 v[92:95], v[154:157], v[178:181], v[92:95]
	v_mfma_f32_16x16x32_bf16 v[84:87], v[146:149], v[196:199], v[84:87]
	v_mfma_f32_16x16x32_bf16 v[76:79], v[154:157], v[196:199], v[76:79]
	s_setprio 0
	s_barrier
	s_add_i32 s28, 0, 0x14000
	v_add_u32_e32 v142, s28, v139
	s_add_i32 s26, s26, s35
	ds_read_b128 v[200:203], v142
	ds_read_b128 v[204:207], v142 offset:1024
	ds_read_b128 v[214:217], v142 offset:2048
	ds_read_b128 v[218:221], v142 offset:3072
	v_lshl_add_u64 v[142:143], s[16:17], 0, v[144:145]
	s_mov_b32 m0, s26
	v_lshl_add_u64 v[186:187], s[16:17], 0, v[128:129]
	global_load_lds_dwordx4 v[142:143], off
	s_add_i32 m0, s26, 0x2000
	s_nop 0
	global_load_lds_dwordx4 v[186:187], off
	s_barrier
	s_waitcnt lgkmcnt(0)
	s_setprio 1
	v_mfma_f32_16x16x32_bf16 v[112:115], v[200:203], v[158:161], v[112:115]
	v_mfma_f32_16x16x32_bf16 v[104:107], v[214:217], v[158:161], v[104:107]
	v_mfma_f32_16x16x32_bf16 v[96:99], v[200:203], v[166:169], v[96:99]
	v_mfma_f32_16x16x32_bf16 v[88:91], v[214:217], v[166:169], v[88:91]
	v_mfma_f32_16x16x32_bf16 v[80:83], v[200:203], v[174:177], v[80:83]
	v_mfma_f32_16x16x32_bf16 v[72:75], v[214:217], v[174:177], v[72:75]
	v_mfma_f32_16x16x32_bf16 v[68:71], v[200:203], v[182:185], v[68:71]
	v_mfma_f32_16x16x32_bf16 v[64:67], v[214:217], v[182:185], v[64:67]
	v_mfma_f32_16x16x32_bf16 v[112:115], v[204:207], v[162:165], v[112:115]
	v_mfma_f32_16x16x32_bf16 v[104:107], v[218:221], v[162:165], v[104:107]
	v_mfma_f32_16x16x32_bf16 v[96:99], v[204:207], v[170:173], v[96:99]
	v_mfma_f32_16x16x32_bf16 v[88:91], v[218:221], v[170:173], v[88:91]
	v_mfma_f32_16x16x32_bf16 v[80:83], v[204:207], v[178:181], v[80:83]
	v_mfma_f32_16x16x32_bf16 v[72:75], v[218:221], v[178:181], v[72:75]
	v_mfma_f32_16x16x32_bf16 v[68:71], v[204:207], v[196:199], v[68:71]
	v_mfma_f32_16x16x32_bf16 v[64:67], v[218:221], v[196:199], v[64:67]
	s_setprio 0
	s_mov_b32 m0, s61
	v_lshl_add_u64 v[188:189], s[20:21], 0, v[144:145]
	s_barrier
	ds_read_b128 v[158:161], v141 offset:16384
	ds_read_b128 v[162:165], v141 offset:17408
	ds_read_b128 v[166:169], v141 offset:18432
	ds_read_b128 v[170:173], v141 offset:19456
	ds_read_b128 v[174:177], v141 offset:20480
	ds_read_b128 v[178:181], v141 offset:21504
	ds_read_b128 v[182:185], v141 offset:22528
	ds_read_b128 v[196:199], v141 offset:23552
	global_load_lds_dwordx4 v[188:189], off
	s_mov_b32 m0, s62
	v_lshl_add_u64 v[192:193], s[20:21], 0, v[128:129]
	global_load_lds_dwordx4 v[192:193], off
	s_barrier
	s_waitcnt lgkmcnt(0)
	s_setprio 1
	v_mfma_f32_16x16x32_bf16 v[60:63], v[134:137], v[158:161], v[60:63]
	v_mfma_f32_16x16x32_bf16 v[56:59], v[150:153], v[158:161], v[56:59]
	v_mfma_f32_16x16x32_bf16 v[52:55], v[134:137], v[166:169], v[52:55]
	v_mfma_f32_16x16x32_bf16 v[44:47], v[150:153], v[166:169], v[44:47]
	v_mfma_f32_16x16x32_bf16 v[36:39], v[134:137], v[174:177], v[36:39]
	v_mfma_f32_16x16x32_bf16 v[28:31], v[150:153], v[174:177], v[28:31]
	v_mfma_f32_16x16x32_bf16 v[20:23], v[134:137], v[182:185], v[20:23]
	v_mfma_f32_16x16x32_bf16 v[12:15], v[150:153], v[182:185], v[12:15]
	v_mfma_f32_16x16x32_bf16 v[60:63], v[146:149], v[162:165], v[60:63]
	v_mfma_f32_16x16x32_bf16 v[56:59], v[154:157], v[162:165], v[56:59]
	v_mfma_f32_16x16x32_bf16 v[52:55], v[146:149], v[170:173], v[52:55]
	v_mfma_f32_16x16x32_bf16 v[44:47], v[154:157], v[170:173], v[44:47]
	v_mfma_f32_16x16x32_bf16 v[36:39], v[146:149], v[178:181], v[36:39]
	v_mfma_f32_16x16x32_bf16 v[28:31], v[154:157], v[178:181], v[28:31]
	v_mfma_f32_16x16x32_bf16 v[20:23], v[146:149], v[196:199], v[20:23]
	v_mfma_f32_16x16x32_bf16 v[12:15], v[154:157], v[196:199], v[12:15]
	s_setprio 0
	s_barrier
; #define PG8_STAGE(bufoff, gbase, voff) do { _Pragma("unroll") for (int _i = 0; _i < 2; ++_i) \
;         __builtin_amdgcn_global_load_lds((const unsigned*)((const char*)(gbase) + (voff)[_i]), (LAS unsigned*)(lds + (bufoff) + ldsw + _i * 8192), 16, 0, 0); } while (0)
; #define PG8_LDA(dst, b, h) do { _Pragma("unroll") for (int m = 0; m < 4; ++m) _Pragma("unroll") for (int k = 0; k < 2; ++k) dst[m][k] = *(const LAS bf16x8*)(lds + PG8_SA(b, h) + aoff + m * 2048 + k * 1024); } while (0)
; #define PG8_LDB(dst, b, h) do { _Pragma("unroll") for (int n = 0; n < 2; ++n) _Pragma("unroll") for (int k = 0; k < 2; ++k) dst[n][k] = *(const LAS bf16x8*)(lds + PG8_SB(b, h) + boff + n * 2048 + k * 1024); } while (0)
; #define PG8_MMA(ai, bj, At, Bt) do { __builtin_amdgcn_s_setprio(1); _Pragma("unroll") for (int m = 0; m < 4; ++m) _Pragma("unroll") for (int n = 0; n < 2; ++n) _Pragma("unroll") for (int k = 0; k < 2; ++k) \
;         acc[ai][bj][m][n] = __builtin_amdgcn_mfma_f32_16x16x32_bf16(Bt[n][k], At[m][k], acc[ai][bj][m][n], 0, 0, 0); __builtin_amdgcn_s_setprio(0); } while (0)
; #define PG8_WAIT_V(n) asm volatile("s_waitcnt vmcnt(" #n ")" ::: "memory")
; #define PG8_WAIT_L(n) asm volatile("s_waitcnt lgkmcnt(" #n ")" ::: "memory")
; #define PG8_BAR __builtin_amdgcn_s_barrier()
; #define PG8_SCHED __builtin_amdgcn_sched_barrier(0)
; template <class Epi>
; __device__ __forceinline__ void gemm_phase(LAS unsigned char* lds, const Gemm g, const StaticOrder& S, const Epi& E) {
;     ...
;             PG8_STAGE(PG8_SB(0, 1), b2 + hB, voffB);
;             PG8_WAIT_V(6); PG8_BAR; PG8_MMA(1, 1, At, B1); PG8_BAR;
;             PG8_LDB(B0, 1, 0); PG8_SCHED; PG8_LDA(At, 1, 0); PG8_STAGE(PG8_SA(0, 1), a2 + hA, voffA);
;             PG8_WAIT_L(8); PG8_BAR; PG8_WAIT_L(0); PG8_MMA(0, 0, At, B0); PG8_BAR; PG8_SCHED;
;             PG8_LDB(B1, 1, 1); PG8_STAGE(PG8_SB(1, 0), b3, voffB);
;             PG8_BAR; PG8_WAIT_L(0); PG8_MMA(0, 1, At, B1); PG8_BAR;
;             PG8_LDA(At, 1, 1); PG8_STAGE(PG8_SA(1, 0), a3, voffA);
	s_add_u32 s26, s16, 0x40000
	s_addc_u32 s27, s17, 0
	s_add_i32 s28, s28, s35
	s_mov_b32 m0, s28
	v_lshl_add_u64 v[134:135], s[26:27], 0, v[144:145]
	global_load_lds_dwordx4 v[134:135], off
	s_add_i32 m0, s28, 0x2000
	v_lshl_add_u64 v[134:135], s[26:27], 0, v[128:129]
	global_load_lds_dwordx4 v[134:135], off
	s_waitcnt vmcnt(6)
	s_barrier
	s_setprio 1
	v_mfma_f32_16x16x32_bf16 v[48:51], v[200:203], v[158:161], v[48:51]
	v_mfma_f32_16x16x32_bf16 v[40:43], v[214:217], v[158:161], v[40:43]
	v_mfma_f32_16x16x32_bf16 v[32:35], v[200:203], v[166:169], v[32:35]
	v_mfma_f32_16x16x32_bf16 v[24:27], v[214:217], v[166:169], v[24:27]
	v_mfma_f32_16x16x32_bf16 v[16:19], v[200:203], v[174:177], v[16:19]
	v_mfma_f32_16x16x32_bf16 v[8:11], v[214:217], v[174:177], v[8:11]
	v_mfma_f32_16x16x32_bf16 v[4:7], v[200:203], v[182:185], v[4:7]
	v_mfma_f32_16x16x32_bf16 v[0:3], v[214:217], v[182:185], v[0:3]
	v_mfma_f32_16x16x32_bf16 v[48:51], v[204:207], v[162:165], v[48:51]
	v_mfma_f32_16x16x32_bf16 v[40:43], v[218:221], v[162:165], v[40:43]
	v_mfma_f32_16x16x32_bf16 v[32:35], v[204:207], v[170:173], v[32:35]
	v_mfma_f32_16x16x32_bf16 v[24:27], v[218:221], v[170:173], v[24:27]
	v_mfma_f32_16x16x32_bf16 v[16:19], v[204:207], v[178:181], v[16:19]
	v_mfma_f32_16x16x32_bf16 v[8:11], v[218:221], v[178:181], v[8:11]
	v_mfma_f32_16x16x32_bf16 v[4:7], v[204:207], v[196:199], v[4:7]
	v_mfma_f32_16x16x32_bf16 v[0:3], v[218:221], v[196:199], v[0:3]
	s_setprio 0
	s_add_i32 s26, 0, 0x18000
	v_add_u32_e32 v154, s26, v139
	s_barrier
	ds_read_b128 v[134:137], v154
	ds_read_b128 v[146:149], v154 offset:1024
	ds_read_b128 v[150:153], v154 offset:2048
	ds_read_b128 v[154:157], v154 offset:3072
	s_add_u32 s20, s20, 0x40000
	s_addc_u32 s21, s21, 0
	s_mov_b32 m0, s63
	v_lshl_add_u64 v[200:201], s[20:21], 0, v[144:145]
	ds_read_b128 v[158:161], v141 offset:32768
	ds_read_b128 v[162:165], v141 offset:33792
	ds_read_b128 v[166:169], v141 offset:34816
	ds_read_b128 v[170:173], v141 offset:35840
	ds_read_b128 v[174:177], v141 offset:36864
	ds_read_b128 v[178:181], v141 offset:37888
	ds_read_b128 v[182:185], v141 offset:38912
	ds_read_b128 v[196:199], v141 offset:39936
	global_load_lds_dwordx4 v[200:201], off
	s_mov_b32 m0, s64
	v_lshl_add_u64 v[200:201], s[20:21], 0, v[128:129]
	global_load_lds_dwordx4 v[200:201], off
	s_waitcnt lgkmcnt(8)
	s_barrier
	s_waitcnt lgkmcnt(0)
	s_setprio 1
	v_mfma_f32_16x16x32_bf16 v[124:127], v[134:137], v[158:161], v[124:127]
	v_mfma_f32_16x16x32_bf16 v[120:123], v[150:153], v[158:161], v[120:123]
	v_mfma_f32_16x16x32_bf16 v[116:119], v[134:137], v[166:169], v[116:119]
	v_mfma_f32_16x16x32_bf16 v[108:111], v[150:153], v[166:169], v[108:111]
	v_mfma_f32_16x16x32_bf16 v[100:103], v[134:137], v[174:177], v[100:103]
	v_mfma_f32_16x16x32_bf16 v[92:95], v[150:153], v[174:177], v[92:95]
	v_mfma_f32_16x16x32_bf16 v[84:87], v[134:137], v[182:185], v[84:87]
	v_mfma_f32_16x16x32_bf16 v[76:79], v[150:153], v[182:185], v[76:79]
	v_mfma_f32_16x16x32_bf16 v[124:127], v[146:149], v[162:165], v[124:127]
	v_mfma_f32_16x16x32_bf16 v[120:123], v[154:157], v[162:165], v[120:123]
	v_mfma_f32_16x16x32_bf16 v[116:119], v[146:149], v[170:173], v[116:119]
	v_mfma_f32_16x16x32_bf16 v[108:111], v[154:157], v[170:173], v[108:111]
	v_mfma_f32_16x16x32_bf16 v[100:103], v[146:149], v[178:181], v[100:103]
	v_mfma_f32_16x16x32_bf16 v[92:95], v[154:157], v[178:181], v[92:95]
	v_mfma_f32_16x16x32_bf16 v[84:87], v[146:149], v[196:199], v[84:87]
	v_mfma_f32_16x16x32_bf16 v[76:79], v[154:157], v[196:199], v[76:79]
	s_setprio 0
	s_barrier
	s_add_i32 s20, 0, 0x1c000
	s_add_i32 s21, s26, s35
	v_add_u32_e32 v190, s20, v139
	v_lshl_add_u64 v[142:143], v[142:143], 0, s[88:89]
	s_mov_b32 m0, s21
	ds_read_b128 v[200:203], v190
	ds_read_b128 v[204:207], v190 offset:1024
	ds_read_b128 v[214:217], v190 offset:2048
	ds_read_b128 v[218:221], v190 offset:3072
	global_load_lds_dwordx4 v[142:143], off
	s_add_i32 m0, s21, 0x2000
	v_lshl_add_u64 v[142:143], v[186:187], 0, s[88:89]
	global_load_lds_dwordx4 v[142:143], off
	s_barrier
	s_waitcnt lgkmcnt(0)
	s_setprio 1
	v_mfma_f32_16x16x32_bf16 v[112:115], v[200:203], v[158:161], v[112:115]
	v_mfma_f32_16x16x32_bf16 v[104:107], v[214:217], v[158:161], v[104:107]
	v_mfma_f32_16x16x32_bf16 v[96:99], v[200:203], v[166:169], v[96:99]
	v_mfma_f32_16x16x32_bf16 v[88:91], v[214:217], v[166:169], v[88:91]
	v_mfma_f32_16x16x32_bf16 v[80:83], v[200:203], v[174:177], v[80:83]
	v_mfma_f32_16x16x32_bf16 v[72:75], v[214:217], v[174:177], v[72:75]
	v_mfma_f32_16x16x32_bf16 v[68:71], v[200:203], v[182:185], v[68:71]
	v_mfma_f32_16x16x32_bf16 v[64:67], v[214:217], v[182:185], v[64:67]
	v_mfma_f32_16x16x32_bf16 v[112:115], v[204:207], v[162:165], v[112:115]
	v_mfma_f32_16x16x32_bf16 v[104:107], v[218:221], v[162:165], v[104:107]
	v_mfma_f32_16x16x32_bf16 v[96:99], v[204:207], v[170:173], v[96:99]
	v_mfma_f32_16x16x32_bf16 v[88:91], v[218:221], v[170:173], v[88:91]
	v_mfma_f32_16x16x32_bf16 v[80:83], v[204:207], v[178:181], v[80:83]
	v_mfma_f32_16x16x32_bf16 v[72:75], v[218:221], v[178:181], v[72:75]
	v_mfma_f32_16x16x32_bf16 v[68:71], v[204:207], v[196:199], v[68:71]
	v_mfma_f32_16x16x32_bf16 v[64:67], v[218:221], v[196:199], v[64:67]
	s_setprio 0
	s_mov_b32 m0, s65
	v_lshl_add_u64 v[142:143], v[188:189], 0, s[88:89]
	s_barrier
	ds_read_b128 v[158:161], v141 offset:49152
	ds_read_b128 v[162:165], v141 offset:50176
	ds_read_b128 v[166:169], v141 offset:51200
	ds_read_b128 v[170:173], v141 offset:52224
	ds_read_b128 v[174:177], v141 offset:53248
	ds_read_b128 v[178:181], v141 offset:54272
	ds_read_b128 v[182:185], v141 offset:55296
	ds_read_b128 v[196:199], v141 offset:56320
	global_load_lds_dwordx4 v[142:143], off
	s_mov_b32 m0, s66
	v_lshl_add_u64 v[142:143], v[192:193], 0, s[88:89]
	global_load_lds_dwordx4 v[142:143], off
	s_barrier
; #define PG8_STAGE(bufoff, gbase, voff) do { _Pragma("unroll") for (int _i = 0; _i < 2; ++_i) \
;         __builtin_amdgcn_global_load_lds((const unsigned*)((const char*)(gbase) + (voff)[_i]), (LAS unsigned*)(lds + (bufoff) + ldsw + _i * 8192), 16, 0, 0); } while (0)
; #define PG8_MMA(ai, bj, At, Bt) do { __builtin_amdgcn_s_setprio(1); _Pragma("unroll") for (int m = 0; m < 4; ++m) _Pragma("unroll") for (int n = 0; n < 2; ++n) _Pragma("unroll") for (int k = 0; k < 2; ++k) \
;         acc[ai][bj][m][n] = __builtin_amdgcn_mfma_f32_16x16x32_bf16(Bt[n][k], At[m][k], acc[ai][bj][m][n], 0, 0, 0); __builtin_amdgcn_s_setprio(0); } while (0)
; #define PG8_WAIT_V(n) asm volatile("s_waitcnt vmcnt(" #n ")" ::: "memory")
; #define PG8_WAIT_L(n) asm volatile("s_waitcnt lgkmcnt(" #n ")" ::: "memory")
; #define PG8_BAR __builtin_amdgcn_s_barrier()
; #define PG8_SCHED __builtin_amdgcn_sched_barrier(0)
; template <class Epi>
; __device__ __forceinline__ void gemm_phase(LAS unsigned char* lds, const Gemm g, const StaticOrder& S, const Epi& E) {
;     ...
;             PG8_BAR; PG8_WAIT_L(0); PG8_MMA(1, 0, At, B0); PG8_BAR; PG8_SCHED;
;             PG8_STAGE(PG8_SB(1, 1), b3 + hB, voffB);
;             PG8_WAIT_V(6); PG8_BAR; PG8_MMA(1, 1, At, B1); PG8_BAR;
	s_waitcnt lgkmcnt(0)
	s_setprio 1
	v_mfma_f32_16x16x32_bf16 v[60:63], v[134:137], v[158:161], v[60:63]
	v_mfma_f32_16x16x32_bf16 v[56:59], v[150:153], v[158:161], v[56:59]
	v_mfma_f32_16x16x32_bf16 v[52:55], v[134:137], v[166:169], v[52:55]
	v_mfma_f32_16x16x32_bf16 v[44:47], v[150:153], v[166:169], v[44:47]
	v_mfma_f32_16x16x32_bf16 v[36:39], v[134:137], v[174:177], v[36:39]
	v_mfma_f32_16x16x32_bf16 v[28:31], v[150:153], v[174:177], v[28:31]
	v_mfma_f32_16x16x32_bf16 v[20:23], v[134:137], v[182:185], v[20:23]
	v_mfma_f32_16x16x32_bf16 v[12:15], v[150:153], v[182:185], v[12:15]
	v_mfma_f32_16x16x32_bf16 v[60:63], v[146:149], v[162:165], v[60:63]
	v_mfma_f32_16x16x32_bf16 v[56:59], v[154:157], v[162:165], v[56:59]
	v_mfma_f32_16x16x32_bf16 v[52:55], v[146:149], v[170:173], v[52:55]
	v_mfma_f32_16x16x32_bf16 v[44:47], v[154:157], v[170:173], v[44:47]
	v_mfma_f32_16x16x32_bf16 v[36:39], v[146:149], v[178:181], v[36:39]
	v_mfma_f32_16x16x32_bf16 v[28:31], v[154:157], v[178:181], v[28:31]
	v_mfma_f32_16x16x32_bf16 v[20:23], v[146:149], v[196:199], v[20:23]
	v_mfma_f32_16x16x32_bf16 v[12:15], v[154:157], v[196:199], v[12:15]
	s_setprio 0
	s_barrier
	s_add_u32 s16, s16, 0x40080
	s_addc_u32 s17, s17, 0
	s_add_i32 s20, s20, s35
	s_mov_b32 m0, s20
	v_lshl_add_u64 v[134:135], s[16:17], 0, v[144:145]
	global_load_lds_dwordx4 v[134:135], off
	s_add_i32 m0, s20, 0x2000
	v_lshl_add_u64 v[134:135], s[16:17], 0, v[128:129]
	global_load_lds_dwordx4 v[134:135], off
	s_waitcnt vmcnt(6)
	s_barrier
	s_setprio 1
	v_mfma_f32_16x16x32_bf16 v[48:51], v[200:203], v[158:161], v[48:51]
	v_mfma_f32_16x16x32_bf16 v[40:43], v[214:217], v[158:161], v[40:43]
	v_mfma_f32_16x16x32_bf16 v[32:35], v[200:203], v[166:169], v[32:35]
	v_mfma_f32_16x16x32_bf16 v[24:27], v[214:217], v[166:169], v[24:27]
	v_mfma_f32_16x16x32_bf16 v[16:19], v[200:203], v[174:177], v[16:19]
	v_mfma_f32_16x16x32_bf16 v[8:11], v[214:217], v[174:177], v[8:11]
	v_mfma_f32_16x16x32_bf16 v[4:7], v[200:203], v[182:185], v[4:7]
	v_mfma_f32_16x16x32_bf16 v[0:3], v[214:217], v[182:185], v[0:3]
	v_mfma_f32_16x16x32_bf16 v[48:51], v[204:207], v[162:165], v[48:51]
	v_mfma_f32_16x16x32_bf16 v[40:43], v[218:221], v[162:165], v[40:43]
	v_mfma_f32_16x16x32_bf16 v[32:35], v[204:207], v[170:173], v[32:35]
	v_mfma_f32_16x16x32_bf16 v[24:27], v[218:221], v[170:173], v[24:27]
	v_mfma_f32_16x16x32_bf16 v[16:19], v[204:207], v[178:181], v[16:19]
	v_mfma_f32_16x16x32_bf16 v[8:11], v[218:221], v[178:181], v[8:11]
	v_mfma_f32_16x16x32_bf16 v[4:7], v[204:207], v[196:199], v[4:7]
	v_mfma_f32_16x16x32_bf16 v[0:3], v[218:221], v[196:199], v[0:3]
	s_setprio 0
	s_add_i32 s77, s77, 2
	s_add_u32 s12, s12, 0x100
	s_addc_u32 s13, s13, 0
	s_add_u32 s25, s25, 0x100
	s_addc_u32 s76, s76, 0
	s_cmp_gt_u32 s77, 13
	s_barrier
	s_cbranch_scc0 .LBB0_1079
; __device__ __forceinline__ unsigned pk2(float lo, float hi) { unsigned r; asm("v_cvt_pk_bf16_f32 %0, %1, %2" : "=v"(r) : "v"(lo), "v"(hi)); return r; }
;     __device__ __forceinline__ void operator()(const f32x4 (&acc)[2][2][4][2], const Unit& u, int wr, int wc, int fr, int fq) const {
;     ...
;         int c = col_t + 64 * wc + 16 * fq;
;         if (mode == 2) c = (c >> 6) * 96 + (c & 63);
; #pragma unroll
;         for (int ai = 0; ai < 2; ++ai)
; #pragma unroll
;             for (int m = 0; m < 4; ++m) {
;                 const int row = row_t + ai * HALF + wr * 64 + m * 16 + fr;
;                 bf16_t* rp = O + (size_t)row * ldc + c;
; #pragma unroll
;                 for (int bj = 0; bj < 2; ++bj) {
;                     const f32x4 v0 = acc[ai][bj][m][0], v1 = acc[ai][bj][m][1];
;                     u32x4 o; o.x = pk2(v0[0], v0[1]); o.y = pk2(v0[2], v0[3]); o.z = pk2(v1[0], v1[1]); o.w = pk2(v1[2], v1[3]);
;                     *(u32x4*)(rp + 8 * bj) = o;
;                 }
;             }
	v_lshl_or_b32 v136, s15, 8, v140
	v_lshl_add_u32 v146, s70, 8, v138
	v_ashrrev_i32_e32 v137, 31, v136
	v_mov_b64_e32 v[134:135], s[4:5]
	s_movk_i32 s7, 0x1400
	v_cvt_pk_bf16_f32 v68, v68, v69
	v_cvt_pk_bf16_f32 v69, v70, v71
	v_cvt_pk_bf16_f32 v70, v64, v65
	v_add_u32_e32 v64, 0x80, v146
	v_mad_i64_i32 v[142:143], s[12:13], v146, s7, v[134:135]
	v_lshlrev_b64 v[136:137], 1, v[136:137]
	v_cvt_pk_bf16_f32 v112, v112, v113
	v_cvt_pk_bf16_f32 v113, v114, v115
	v_cvt_pk_bf16_f32 v114, v104, v105
	v_or_b32_e32 v104, 16, v146
	v_mad_i64_i32 v[64:65], s[12:13], v64, s7, v[134:135]
	v_cvt_pk_bf16_f32 v48, v48, v49
	v_cvt_pk_bf16_f32 v49, v50, v51
	v_cvt_pk_bf16_f32 v50, v40, v41
	v_add_u32_e32 v40, 0x90, v146
	v_lshl_add_u64 v[142:143], v[142:143], 0, v[136:137]
	v_mad_i64_i32 v[104:105], s[12:13], v104, s7, v[134:135]
	v_cvt_pk_bf16_f32 v96, v96, v97
	v_cvt_pk_bf16_f32 v97, v98, v99
	v_cvt_pk_bf16_f32 v98, v88, v89
	v_or_b32_e32 v88, 32, v146
	v_lshl_add_u64 v[64:65], v[64:65], 0, v[136:137]
	v_mad_i64_i32 v[40:41], s[12:13], v40, s7, v[134:135]
	v_cvt_pk_bf16_f32 v32, v32, v33
	v_cvt_pk_bf16_f32 v33, v34, v35
	v_cvt_pk_bf16_f32 v34, v24, v25
	v_add_u32_e32 v24, 0xa0, v146
	v_cvt_pk_bf16_f32 v115, v106, v107
	global_store_dwordx4 v[142:143], v[112:115], off offset:16
	v_mad_i64_i32 v[88:89], s[12:13], v88, s7, v[134:135]
	s_nop 0
	v_lshl_add_u64 v[112:113], v[104:105], 0, v[136:137]
	v_cvt_pk_bf16_f32 v80, v80, v81
	v_cvt_pk_bf16_f32 v81, v82, v83
	v_cvt_pk_bf16_f32 v82, v72, v73
	v_or_b32_e32 v72, 48, v146
	v_cvt_pk_bf16_f32 v51, v42, v43
	global_store_dwordx4 v[64:65], v[48:51], off offset:16
	v_mad_i64_i32 v[24:25], s[12:13], v24, s7, v[134:135]
	s_nop 0
	v_lshl_add_u64 v[48:49], v[40:41], 0, v[136:137]
	v_cvt_pk_bf16_f32 v16, v16, v17
	v_cvt_pk_bf16_f32 v17, v18, v19
	v_cvt_pk_bf16_f32 v18, v8, v9
	v_add_u32_e32 v8, 0xb0, v146
	v_cvt_pk_bf16_f32 v99, v90, v91
	global_store_dwordx4 v[112:113], v[96:99], off offset:16
	v_mad_i64_i32 v[72:73], s[12:13], v72, s7, v[134:135]
	s_nop 0
	v_lshl_add_u64 v[96:97], v[88:89], 0, v[136:137]
	v_cvt_pk_bf16_f32 v35, v26, v27
	global_store_dwordx4 v[48:49], v[32:35], off offset:16
	v_mad_i64_i32 v[8:9], s[12:13], v8, s7, v[134:135]
	s_nop 0
	v_lshl_add_u64 v[32:33], v[24:25], 0, v[136:137]
	v_cvt_pk_bf16_f32 v83, v74, v75
	global_store_dwordx4 v[96:97], v[80:83], off offset:16
	v_cvt_pk_bf16_f32 v19, v10, v11
	global_store_dwordx4 v[32:33], v[16:19], off offset:16
	s_and_b64 vcc, exec, s[0:1]
	v_lshl_add_u64 v[80:81], v[72:73], 0, v[136:137]
	v_lshl_add_u64 v[16:17], v[8:9], 0, v[136:137]
	s_mov_b32 s15, s6
	s_mov_b32 s70, s69
	s_mov_b64 s[16:17], s[10:11]
	s_mov_b64 s[12:13], s[8:9]
	v_cvt_pk_bf16_f32 v124, v124, v125
	v_cvt_pk_bf16_f32 v125, v126, v127
	v_cvt_pk_bf16_f32 v126, v120, v121
	v_cvt_pk_bf16_f32 v127, v122, v123
	global_store_dwordx4 v[142:143], v[124:127], off
	v_cvt_pk_bf16_f32 v104, v116, v117
	v_cvt_pk_bf16_f32 v105, v118, v119
	v_cvt_pk_bf16_f32 v106, v108, v109
	v_cvt_pk_bf16_f32 v107, v110, v111
	global_store_dwordx4 v[112:113], v[104:107], off
	v_cvt_pk_bf16_f32 v88, v100, v101
	v_cvt_pk_bf16_f32 v89, v102, v103
	v_cvt_pk_bf16_f32 v90, v92, v93
	v_cvt_pk_bf16_f32 v91, v94, v95
	global_store_dwordx4 v[96:97], v[88:91], off
	v_cvt_pk_bf16_f32 v72, v84, v85
	v_cvt_pk_bf16_f32 v73, v86, v87
	v_cvt_pk_bf16_f32 v74, v76, v77
	v_cvt_pk_bf16_f32 v75, v78, v79
	global_store_dwordx4 v[80:81], v[72:75], off
	v_cvt_pk_bf16_f32 v71, v66, v67
	global_store_dwordx4 v[80:81], v[68:71], off offset:16
	v_cvt_pk_bf16_f32 v60, v60, v61
	v_cvt_pk_bf16_f32 v61, v62, v63
	v_cvt_pk_bf16_f32 v62, v56, v57
	v_cvt_pk_bf16_f32 v63, v58, v59
	global_store_dwordx4 v[64:65], v[60:63], off
	v_cvt_pk_bf16_f32 v40, v52, v53
	v_cvt_pk_bf16_f32 v41, v54, v55
	v_cvt_pk_bf16_f32 v42, v44, v45
	v_cvt_pk_bf16_f32 v43, v46, v47
	global_store_dwordx4 v[48:49], v[40:43], off
	v_cvt_pk_bf16_f32 v24, v36, v37
	v_cvt_pk_bf16_f32 v25, v38, v39
	v_cvt_pk_bf16_f32 v26, v28, v29
	v_cvt_pk_bf16_f32 v27, v30, v31
	global_store_dwordx4 v[32:33], v[24:27], off
	v_cvt_pk_bf16_f32 v8, v20, v21
	v_cvt_pk_bf16_f32 v9, v22, v23
	v_cvt_pk_bf16_f32 v10, v12, v13
	v_cvt_pk_bf16_f32 v11, v14, v15
	global_store_dwordx4 v[16:17], v[8:11], off
	v_cvt_pk_bf16_f32 v4, v4, v5
	v_cvt_pk_bf16_f32 v5, v6, v7
	v_cvt_pk_bf16_f32 v6, v0, v1
	v_cvt_pk_bf16_f32 v7, v2, v3
	global_store_dwordx4 v[16:17], v[4:7], off offset:16
	s_cbranch_vccz .LBB0_1076
	s_waitcnt vmcnt(0)
	s_cmpk_gt_u32 s3, 0xff
	s_cbranch_scc1 .LBB0_1083
	s_barrier

; #define PG8_STAGE(bufoff, gbase, voff) do { _Pragma("unroll") for (int _i = 0; _i < 2; ++_i) \
;         __builtin_amdgcn_global_load_lds((const unsigned*)((const char*)(gbase) + (voff)[_i]), (LAS unsigned*)(lds + (bufoff) + ldsw + _i * 8192), 16, 0, 0); } while (0)
; #define PG8_LDA(dst, b, h) do { _Pragma("unroll") for (int m = 0; m < 4; ++m) _Pragma("unroll") for (int k = 0; k < 2; ++k) dst[m][k] = *(const LAS bf16x8*)(lds + PG8_SA(b, h) + aoff + m * 2048 + k * 1024); } while (0)
; #define PG8_LDB(dst, b, h) do { _Pragma("unroll") for (int n = 0; n < 2; ++n) _Pragma("unroll") for (int k = 0; k < 2; ++k) dst[n][k] = *(const LAS bf16x8*)(lds + PG8_SB(b, h) + boff + n * 2048 + k * 1024); } while (0)
; #define PG8_MMA(ai, bj, At, Bt) do { __builtin_amdgcn_s_setprio(1); _Pragma("unroll") for (int m = 0; m < 4; ++m) _Pragma("unroll") for (int n = 0; n < 2; ++n) _Pragma("unroll") for (int k = 0; k < 2; ++k) \
;         acc[ai][bj][m][n] = __builtin_amdgcn_mfma_f32_16x16x32_bf16(Bt[n][k], At[m][k], acc[ai][bj][m][n], 0, 0, 0); __builtin_amdgcn_s_setprio(0); } while (0)
; #define PG8_WAIT_L(n) asm volatile("s_waitcnt lgkmcnt(" #n ")" ::: "memory")
; #define PG8_BAR __builtin_amdgcn_s_barrier()
; #define PG8_SCHED __builtin_amdgcn_sched_barrier(0)
; template <class Epi>
; __device__ __forceinline__ void gemm_phase(LAS unsigned char* lds, const Gemm g, const StaticOrder& S, const Epi& E) {
;     ...
;         const char* nA = has_next ? g.arow(nxt.pm) : cA; const char* nB = has_next ? (const char*)g.Bt + (size_t)nxt.pn * tB : cB;
;         for (int t = 0; t < nt; t += 2) {
;             const bool last = (t == nt - 2);
;             const char* a1 = cA + (size_t)(t + 1) * kstep;
;             const char* a2 = last ? nA : cA + (size_t)(t + 2) * kstep; const char* b2 = last ? nB : cB + (size_t)(t + 2) * kstep;
;             const char* a3 = a2 + kstep; const char* b3 = b2 + kstep;
;             PG8_LDB(B0, 0, 0); PG8_SCHED; PG8_LDA(At, 0, 0); PG8_STAGE(PG8_SA(1, 1), a1 + hA, voffA);
;             PG8_WAIT_L(8); PG8_BAR; PG8_WAIT_L(0); PG8_MMA(0, 0, At, B0); PG8_BAR; PG8_SCHED;
;             PG8_LDB(B1, 0, 1); PG8_STAGE(PG8_SB(0, 0), b2, voffB);
;             PG8_BAR; PG8_WAIT_L(0); PG8_MMA(0, 1, At, B1); PG8_BAR;
;             PG8_LDA(At, 0, 1); PG8_STAGE(PG8_SA(0, 0), a2, voffA);
;             PG8_BAR; PG8_WAIT_L(0); PG8_MMA(1, 0, At, B0); PG8_BAR; PG8_SCHED;
.LBB0_1270:
	s_add_u32 s16, s12, 0xfffc0080
	s_addc_u32 s17, s13, -1
	s_add_i32 s26, 0, 0x10000
	v_add_u32_e32 v142, s26, v139
	ds_read_b128 v[134:137], v142
	ds_read_b128 v[146:149], v142 offset:1024
	ds_read_b128 v[150:153], v142 offset:2048
	ds_read_b128 v[154:157], v142 offset:3072
	s_cmp_eq_u32 s77, 12
	s_cselect_b32 s21, s71, s17
	s_cselect_b32 s20, s72, s16
	s_cselect_b32 s17, s7, s76
	s_cselect_b32 s16, s24, s25
	v_lshl_add_u64 v[142:143], s[12:13], 0, v[130:131]
	s_add_i32 m0, s61, 0xc000
	ds_read_b128 v[158:161], v141
	ds_read_b128 v[162:165], v141 offset:1024
	ds_read_b128 v[166:169], v141 offset:2048
	ds_read_b128 v[170:173], v141 offset:3072
	ds_read_b128 v[174:177], v141 offset:4096
	ds_read_b128 v[178:181], v141 offset:5120
	ds_read_b128 v[182:185], v141 offset:6144
	ds_read_b128 v[196:199], v141 offset:7168
	global_load_lds_dwordx4 v[142:143], off
	s_add_i32 m0, s61, 0xe000
	v_lshl_add_u64 v[142:143], s[12:13], 0, v[132:133]
	global_load_lds_dwordx4 v[142:143], off
	s_waitcnt lgkmcnt(8)
	s_barrier
	s_waitcnt lgkmcnt(0)
	s_setprio 1
	v_mfma_f32_16x16x32_bf16 v[124:127], v[134:137], v[158:161], v[124:127]
	v_mfma_f32_16x16x32_bf16 v[120:123], v[150:153], v[158:161], v[120:123]
	v_mfma_f32_16x16x32_bf16 v[116:119], v[134:137], v[166:169], v[116:119]
	v_mfma_f32_16x16x32_bf16 v[108:111], v[150:153], v[166:169], v[108:111]
	v_mfma_f32_16x16x32_bf16 v[100:103], v[134:137], v[174:177], v[100:103]
	v_mfma_f32_16x16x32_bf16 v[92:95], v[150:153], v[174:177], v[92:95]
	v_mfma_f32_16x16x32_bf16 v[84:87], v[134:137], v[182:185], v[84:87]
	v_mfma_f32_16x16x32_bf16 v[76:79], v[150:153], v[182:185], v[76:79]
	v_mfma_f32_16x16x32_bf16 v[124:127], v[146:149], v[162:165], v[124:127]
	v_mfma_f32_16x16x32_bf16 v[120:123], v[154:157], v[162:165], v[120:123]
	v_mfma_f32_16x16x32_bf16 v[116:119], v[146:149], v[170:173], v[116:119]
	v_mfma_f32_16x16x32_bf16 v[108:111], v[154:157], v[170:173], v[108:111]
	v_mfma_f32_16x16x32_bf16 v[100:103], v[146:149], v[178:181], v[100:103]
	v_mfma_f32_16x16x32_bf16 v[92:95], v[154:157], v[178:181], v[92:95]
	v_mfma_f32_16x16x32_bf16 v[84:87], v[146:149], v[196:199], v[84:87]
	v_mfma_f32_16x16x32_bf16 v[76:79], v[154:157], v[196:199], v[76:79]
	s_setprio 0
	s_barrier
	s_add_i32 s28, 0, 0x14000
	v_add_u32_e32 v142, s28, v139
	s_add_i32 s26, s26, s35
	ds_read_b128 v[200:203], v142
	ds_read_b128 v[204:207], v142 offset:1024
	ds_read_b128 v[214:217], v142 offset:2048
	ds_read_b128 v[218:221], v142 offset:3072
	v_lshl_add_u64 v[142:143], s[16:17], 0, v[144:145]
	s_mov_b32 m0, s26
	v_lshl_add_u64 v[186:187], s[16:17], 0, v[128:129]
	global_load_lds_dwordx4 v[142:143], off
	s_add_i32 m0, s26, 0x2000
	s_nop 0
	global_load_lds_dwordx4 v[186:187], off
	s_barrier
	s_waitcnt lgkmcnt(0)
	s_setprio 1
	v_mfma_f32_16x16x32_bf16 v[112:115], v[200:203], v[158:161], v[112:115]
	v_mfma_f32_16x16x32_bf16 v[104:107], v[214:217], v[158:161], v[104:107]
	v_mfma_f32_16x16x32_bf16 v[96:99], v[200:203], v[166:169], v[96:99]
	v_mfma_f32_16x16x32_bf16 v[88:91], v[214:217], v[166:169], v[88:91]
	v_mfma_f32_16x16x32_bf16 v[80:83], v[200:203], v[174:177], v[80:83]
	v_mfma_f32_16x16x32_bf16 v[72:75], v[214:217], v[174:177], v[72:75]
	v_mfma_f32_16x16x32_bf16 v[68:71], v[200:203], v[182:185], v[68:71]
	v_mfma_f32_16x16x32_bf16 v[64:67], v[214:217], v[182:185], v[64:67]
	v_mfma_f32_16x16x32_bf16 v[112:115], v[204:207], v[162:165], v[112:115]
	v_mfma_f32_16x16x32_bf16 v[104:107], v[218:221], v[162:165], v[104:107]
	v_mfma_f32_16x16x32_bf16 v[96:99], v[204:207], v[170:173], v[96:99]
	v_mfma_f32_16x16x32_bf16 v[88:91], v[218:221], v[170:173], v[88:91]
	v_mfma_f32_16x16x32_bf16 v[80:83], v[204:207], v[178:181], v[80:83]
	v_mfma_f32_16x16x32_bf16 v[72:75], v[218:221], v[178:181], v[72:75]
	v_mfma_f32_16x16x32_bf16 v[68:71], v[204:207], v[196:199], v[68:71]
	v_mfma_f32_16x16x32_bf16 v[64:67], v[218:221], v[196:199], v[64:67]
	s_setprio 0
	s_mov_b32 m0, s61
	v_lshl_add_u64 v[188:189], s[20:21], 0, v[144:145]
	s_barrier
	ds_read_b128 v[158:161], v141 offset:16384
	ds_read_b128 v[162:165], v141 offset:17408
	ds_read_b128 v[166:169], v141 offset:18432
	ds_read_b128 v[170:173], v141 offset:19456
	ds_read_b128 v[174:177], v141 offset:20480
	ds_read_b128 v[178:181], v141 offset:21504
	ds_read_b128 v[182:185], v141 offset:22528
	ds_read_b128 v[196:199], v141 offset:23552
	global_load_lds_dwordx4 v[188:189], off
	s_mov_b32 m0, s62
	v_lshl_add_u64 v[192:193], s[20:21], 0, v[128:129]
	global_load_lds_dwordx4 v[192:193], off
	s_barrier
	s_waitcnt lgkmcnt(0)
	s_setprio 1
	v_mfma_f32_16x16x32_bf16 v[60:63], v[134:137], v[158:161], v[60:63]
	v_mfma_f32_16x16x32_bf16 v[56:59], v[150:153], v[158:161], v[56:59]
	v_mfma_f32_16x16x32_bf16 v[52:55], v[134:137], v[166:169], v[52:55]
	v_mfma_f32_16x16x32_bf16 v[44:47], v[150:153], v[166:169], v[44:47]
	v_mfma_f32_16x16x32_bf16 v[36:39], v[134:137], v[174:177], v[36:39]
	v_mfma_f32_16x16x32_bf16 v[28:31], v[150:153], v[174:177], v[28:31]
	v_mfma_f32_16x16x32_bf16 v[20:23], v[134:137], v[182:185], v[20:23]
	v_mfma_f32_16x16x32_bf16 v[12:15], v[150:153], v[182:185], v[12:15]
	v_mfma_f32_16x16x32_bf16 v[60:63], v[146:149], v[162:165], v[60:63]
	v_mfma_f32_16x16x32_bf16 v[56:59], v[154:157], v[162:165], v[56:59]
	v_mfma_f32_16x16x32_bf16 v[52:55], v[146:149], v[170:173], v[52:55]
	v_mfma_f32_16x16x32_bf16 v[44:47], v[154:157], v[170:173], v[44:47]
	v_mfma_f32_16x16x32_bf16 v[36:39], v[146:149], v[178:181], v[36:39]
	v_mfma_f32_16x16x32_bf16 v[28:31], v[154:157], v[178:181], v[28:31]
	v_mfma_f32_16x16x32_bf16 v[20:23], v[146:149], v[196:199], v[20:23]
	v_mfma_f32_16x16x32_bf16 v[12:15], v[154:157], v[196:199], v[12:15]
	s_setprio 0
	s_barrier
; #define PG8_STAGE(bufoff, gbase, voff) do { _Pragma("unroll") for (int _i = 0; _i < 2; ++_i) \
;         __builtin_amdgcn_global_load_lds((const unsigned*)((const char*)(gbase) + (voff)[_i]), (LAS unsigned*)(lds + (bufoff) + ldsw + _i * 8192), 16, 0, 0); } while (0)
; #define PG8_LDA(dst, b, h) do { _Pragma("unroll") for (int m = 0; m < 4; ++m) _Pragma("unroll") for (int k = 0; k < 2; ++k) dst[m][k] = *(const LAS bf16x8*)(lds + PG8_SA(b, h) + aoff + m * 2048 + k * 1024); } while (0)
; #define PG8_LDB(dst, b, h) do { _Pragma("unroll") for (int n = 0; n < 2; ++n) _Pragma("unroll") for (int k = 0; k < 2; ++k) dst[n][k] = *(const LAS bf16x8*)(lds + PG8_SB(b, h) + boff + n * 2048 + k * 1024); } while (0)
; #define PG8_MMA(ai, bj, At, Bt) do { __builtin_amdgcn_s_setprio(1); _Pragma("unroll") for (int m = 0; m < 4; ++m) _Pragma("unroll") for (int n = 0; n < 2; ++n) _Pragma("unroll") for (int k = 0; k < 2; ++k) \
;         acc[ai][bj][m][n] = __builtin_amdgcn_mfma_f32_16x16x32_bf16(Bt[n][k], At[m][k], acc[ai][bj][m][n], 0, 0, 0); __builtin_amdgcn_s_setprio(0); } while (0)
; #define PG8_WAIT_V(n) asm volatile("s_waitcnt vmcnt(" #n ")" ::: "memory")
; #define PG8_WAIT_L(n) asm volatile("s_waitcnt lgkmcnt(" #n ")" ::: "memory")
; #define PG8_BAR __builtin_amdgcn_s_barrier()
; #define PG8_SCHED __builtin_amdgcn_sched_barrier(0)
; template <class Epi>
; __device__ __forceinline__ void gemm_phase(LAS unsigned char* lds, const Gemm g, const StaticOrder& S, const Epi& E) {
;     ...
;             PG8_STAGE(PG8_SB(0, 1), b2 + hB, voffB);
;             PG8_WAIT_V(6); PG8_BAR; PG8_MMA(1, 1, At, B1); PG8_BAR;
;             PG8_LDB(B0, 1, 0); PG8_SCHED; PG8_LDA(At, 1, 0); PG8_STAGE(PG8_SA(0, 1), a2 + hA, voffA);
;             PG8_WAIT_L(8); PG8_BAR; PG8_WAIT_L(0); PG8_MMA(0, 0, At, B0); PG8_BAR; PG8_SCHED;
;             PG8_LDB(B1, 1, 1); PG8_STAGE(PG8_SB(1, 0), b3, voffB);
;             PG8_BAR; PG8_WAIT_L(0); PG8_MMA(0, 1, At, B1); PG8_BAR;
;             PG8_LDA(At, 1, 1); PG8_STAGE(PG8_SA(1, 0), a3, voffA);
	s_add_u32 s26, s16, 0x40000
	s_addc_u32 s27, s17, 0
	s_add_i32 s28, s28, s35
	s_mov_b32 m0, s28
	v_lshl_add_u64 v[134:135], s[26:27], 0, v[144:145]
	global_load_lds_dwordx4 v[134:135], off
	s_add_i32 m0, s28, 0x2000
	v_lshl_add_u64 v[134:135], s[26:27], 0, v[128:129]
	global_load_lds_dwordx4 v[134:135], off
	s_waitcnt vmcnt(6)
	s_barrier
	s_setprio 1
	v_mfma_f32_16x16x32_bf16 v[48:51], v[200:203], v[158:161], v[48:51]
	v_mfma_f32_16x16x32_bf16 v[40:43], v[214:217], v[158:161], v[40:43]
	v_mfma_f32_16x16x32_bf16 v[32:35], v[200:203], v[166:169], v[32:35]
	v_mfma_f32_16x16x32_bf16 v[24:27], v[214:217], v[166:169], v[24:27]
	v_mfma_f32_16x16x32_bf16 v[16:19], v[200:203], v[174:177], v[16:19]
	v_mfma_f32_16x16x32_bf16 v[8:11], v[214:217], v[174:177], v[8:11]
	v_mfma_f32_16x16x32_bf16 v[4:7], v[200:203], v[182:185], v[4:7]
	v_mfma_f32_16x16x32_bf16 v[0:3], v[214:217], v[182:185], v[0:3]
	v_mfma_f32_16x16x32_bf16 v[48:51], v[204:207], v[162:165], v[48:51]
	v_mfma_f32_16x16x32_bf16 v[40:43], v[218:221], v[162:165], v[40:43]
	v_mfma_f32_16x16x32_bf16 v[32:35], v[204:207], v[170:173], v[32:35]
	v_mfma_f32_16x16x32_bf16 v[24:27], v[218:221], v[170:173], v[24:27]
	v_mfma_f32_16x16x32_bf16 v[16:19], v[204:207], v[178:181], v[16:19]
	v_mfma_f32_16x16x32_bf16 v[8:11], v[218:221], v[178:181], v[8:11]
	v_mfma_f32_16x16x32_bf16 v[4:7], v[204:207], v[196:199], v[4:7]
	v_mfma_f32_16x16x32_bf16 v[0:3], v[218:221], v[196:199], v[0:3]
	s_setprio 0
	s_add_i32 s26, 0, 0x18000
	v_add_u32_e32 v154, s26, v139
	s_barrier
	ds_read_b128 v[134:137], v154
	ds_read_b128 v[146:149], v154 offset:1024
	ds_read_b128 v[150:153], v154 offset:2048
	ds_read_b128 v[154:157], v154 offset:3072
	s_add_u32 s20, s20, 0x40000
	s_addc_u32 s21, s21, 0
	s_mov_b32 m0, s63
	v_lshl_add_u64 v[200:201], s[20:21], 0, v[144:145]
	ds_read_b128 v[158:161], v141 offset:32768
	ds_read_b128 v[162:165], v141 offset:33792
	ds_read_b128 v[166:169], v141 offset:34816
	ds_read_b128 v[170:173], v141 offset:35840
	ds_read_b128 v[174:177], v141 offset:36864
	ds_read_b128 v[178:181], v141 offset:37888
	ds_read_b128 v[182:185], v141 offset:38912
	ds_read_b128 v[196:199], v141 offset:39936
	global_load_lds_dwordx4 v[200:201], off
	s_mov_b32 m0, s64
	v_lshl_add_u64 v[200:201], s[20:21], 0, v[128:129]
	global_load_lds_dwordx4 v[200:201], off
	s_waitcnt lgkmcnt(8)
	s_barrier
	s_waitcnt lgkmcnt(0)
	s_setprio 1
	v_mfma_f32_16x16x32_bf16 v[124:127], v[134:137], v[158:161], v[124:127]
	v_mfma_f32_16x16x32_bf16 v[120:123], v[150:153], v[158:161], v[120:123]
	v_mfma_f32_16x16x32_bf16 v[116:119], v[134:137], v[166:169], v[116:119]
	v_mfma_f32_16x16x32_bf16 v[108:111], v[150:153], v[166:169], v[108:111]
	v_mfma_f32_16x16x32_bf16 v[100:103], v[134:137], v[174:177], v[100:103]
	v_mfma_f32_16x16x32_bf16 v[92:95], v[150:153], v[174:177], v[92:95]
	v_mfma_f32_16x16x32_bf16 v[84:87], v[134:137], v[182:185], v[84:87]
	v_mfma_f32_16x16x32_bf16 v[76:79], v[150:153], v[182:185], v[76:79]
	v_mfma_f32_16x16x32_bf16 v[124:127], v[146:149], v[162:165], v[124:127]
	v_mfma_f32_16x16x32_bf16 v[120:123], v[154:157], v[162:165], v[120:123]
	v_mfma_f32_16x16x32_bf16 v[116:119], v[146:149], v[170:173], v[116:119]
	v_mfma_f32_16x16x32_bf16 v[108:111], v[154:157], v[170:173], v[108:111]
	v_mfma_f32_16x16x32_bf16 v[100:103], v[146:149], v[178:181], v[100:103]
	v_mfma_f32_16x16x32_bf16 v[92:95], v[154:157], v[178:181], v[92:95]
	v_mfma_f32_16x16x32_bf16 v[84:87], v[146:149], v[196:199], v[84:87]
	v_mfma_f32_16x16x32_bf16 v[76:79], v[154:157], v[196:199], v[76:79]
	s_setprio 0
	s_barrier
	s_add_i32 s20, 0, 0x1c000
	s_add_i32 s21, s26, s35
	v_add_u32_e32 v190, s20, v139
	v_lshl_add_u64 v[142:143], v[142:143], 0, s[88:89]
	s_mov_b32 m0, s21
	ds_read_b128 v[200:203], v190
	ds_read_b128 v[204:207], v190 offset:1024
	ds_read_b128 v[214:217], v190 offset:2048
	ds_read_b128 v[218:221], v190 offset:3072
	global_load_lds_dwordx4 v[142:143], off
	s_add_i32 m0, s21, 0x2000
	v_lshl_add_u64 v[142:143], v[186:187], 0, s[88:89]
	global_load_lds_dwordx4 v[142:143], off
	s_barrier
	s_waitcnt lgkmcnt(0)
	s_setprio 1
	v_mfma_f32_16x16x32_bf16 v[112:115], v[200:203], v[158:161], v[112:115]
	v_mfma_f32_16x16x32_bf16 v[104:107], v[214:217], v[158:161], v[104:107]
	v_mfma_f32_16x16x32_bf16 v[96:99], v[200:203], v[166:169], v[96:99]
	v_mfma_f32_16x16x32_bf16 v[88:91], v[214:217], v[166:169], v[88:91]
	v_mfma_f32_16x16x32_bf16 v[80:83], v[200:203], v[174:177], v[80:83]
	v_mfma_f32_16x16x32_bf16 v[72:75], v[214:217], v[174:177], v[72:75]
	v_mfma_f32_16x16x32_bf16 v[68:71], v[200:203], v[182:185], v[68:71]
	v_mfma_f32_16x16x32_bf16 v[64:67], v[214:217], v[182:185], v[64:67]
	v_mfma_f32_16x16x32_bf16 v[112:115], v[204:207], v[162:165], v[112:115]
	v_mfma_f32_16x16x32_bf16 v[104:107], v[218:221], v[162:165], v[104:107]
	v_mfma_f32_16x16x32_bf16 v[96:99], v[204:207], v[170:173], v[96:99]
	v_mfma_f32_16x16x32_bf16 v[88:91], v[218:221], v[170:173], v[88:91]
	v_mfma_f32_16x16x32_bf16 v[80:83], v[204:207], v[178:181], v[80:83]
	v_mfma_f32_16x16x32_bf16 v[72:75], v[218:221], v[178:181], v[72:75]
	v_mfma_f32_16x16x32_bf16 v[68:71], v[204:207], v[196:199], v[68:71]
	v_mfma_f32_16x16x32_bf16 v[64:67], v[218:221], v[196:199], v[64:67]
	s_setprio 0
	s_mov_b32 m0, s65
	v_lshl_add_u64 v[142:143], v[188:189], 0, s[88:89]
	s_barrier
	ds_read_b128 v[158:161], v141 offset:49152
	ds_read_b128 v[162:165], v141 offset:50176
	ds_read_b128 v[166:169], v141 offset:51200
	ds_read_b128 v[170:173], v141 offset:52224
	ds_read_b128 v[174:177], v141 offset:53248
	ds_read_b128 v[178:181], v141 offset:54272
	ds_read_b128 v[182:185], v141 offset:55296
	ds_read_b128 v[196:199], v141 offset:56320
	global_load_lds_dwordx4 v[142:143], off
	s_mov_b32 m0, s66
	v_lshl_add_u64 v[142:143], v[192:193], 0, s[88:89]
	global_load_lds_dwordx4 v[142:143], off
	s_barrier
; #define PG8_STAGE(bufoff, gbase, voff) do { _Pragma("unroll") for (int _i = 0; _i < 2; ++_i) \
;         __builtin_amdgcn_global_load_lds((const unsigned*)((const char*)(gbase) + (voff)[_i]), (LAS unsigned*)(lds + (bufoff) + ldsw + _i * 8192), 16, 0, 0); } while (0)
; #define PG8_MMA(ai, bj, At, Bt) do { __builtin_amdgcn_s_setprio(1); _Pragma("unroll") for (int m = 0; m < 4; ++m) _Pragma("unroll") for (int n = 0; n < 2; ++n) _Pragma("unroll") for (int k = 0; k < 2; ++k) \
;         acc[ai][bj][m][n] = __builtin_amdgcn_mfma_f32_16x16x32_bf16(Bt[n][k], At[m][k], acc[ai][bj][m][n], 0, 0, 0); __builtin_amdgcn_s_setprio(0); } while (0)
; #define PG8_WAIT_V(n) asm volatile("s_waitcnt vmcnt(" #n ")" ::: "memory")
; #define PG8_WAIT_L(n) asm volatile("s_waitcnt lgkmcnt(" #n ")" ::: "memory")
; #define PG8_BAR __builtin_amdgcn_s_barrier()
; #define PG8_SCHED __builtin_amdgcn_sched_barrier(0)
; template <class Epi>
; __device__ __forceinline__ void gemm_phase(LAS unsigned char* lds, const Gemm g, const StaticOrder& S, const Epi& E) {
;     ...
;             PG8_BAR; PG8_WAIT_L(0); PG8_MMA(1, 0, At, B0); PG8_BAR; PG8_SCHED;
;             PG8_STAGE(PG8_SB(1, 1), b3 + hB, voffB);
;             PG8_WAIT_V(6); PG8_BAR; PG8_MMA(1, 1, At, B1); PG8_BAR;
	s_waitcnt lgkmcnt(0)
	s_setprio 1
	v_mfma_f32_16x16x32_bf16 v[60:63], v[134:137], v[158:161], v[60:63]
	v_mfma_f32_16x16x32_bf16 v[56:59], v[150:153], v[158:161], v[56:59]
	v_mfma_f32_16x16x32_bf16 v[52:55], v[134:137], v[166:169], v[52:55]
	v_mfma_f32_16x16x32_bf16 v[44:47], v[150:153], v[166:169], v[44:47]
	v_mfma_f32_16x16x32_bf16 v[36:39], v[134:137], v[174:177], v[36:39]
	v_mfma_f32_16x16x32_bf16 v[28:31], v[150:153], v[174:177], v[28:31]
	v_mfma_f32_16x16x32_bf16 v[20:23], v[134:137], v[182:185], v[20:23]
	v_mfma_f32_16x16x32_bf16 v[12:15], v[150:153], v[182:185], v[12:15]
	v_mfma_f32_16x16x32_bf16 v[60:63], v[146:149], v[162:165], v[60:63]
	v_mfma_f32_16x16x32_bf16 v[56:59], v[154:157], v[162:165], v[56:59]
	v_mfma_f32_16x16x32_bf16 v[52:55], v[146:149], v[170:173], v[52:55]
	v_mfma_f32_16x16x32_bf16 v[44:47], v[154:157], v[170:173], v[44:47]
	v_mfma_f32_16x16x32_bf16 v[36:39], v[146:149], v[178:181], v[36:39]
	v_mfma_f32_16x16x32_bf16 v[28:31], v[154:157], v[178:181], v[28:31]
	v_mfma_f32_16x16x32_bf16 v[20:23], v[146:149], v[196:199], v[20:23]
	v_mfma_f32_16x16x32_bf16 v[12:15], v[154:157], v[196:199], v[12:15]
	s_setprio 0
	s_barrier
	s_add_u32 s16, s16, 0x40080
	s_addc_u32 s17, s17, 0
	s_add_i32 s20, s20, s35
	s_mov_b32 m0, s20
	v_lshl_add_u64 v[134:135], s[16:17], 0, v[144:145]
	global_load_lds_dwordx4 v[134:135], off
	s_add_i32 m0, s20, 0x2000
	v_lshl_add_u64 v[134:135], s[16:17], 0, v[128:129]
	global_load_lds_dwordx4 v[134:135], off
	s_waitcnt vmcnt(6)
	s_barrier
	s_setprio 1
	v_mfma_f32_16x16x32_bf16 v[48:51], v[200:203], v[158:161], v[48:51]
	v_mfma_f32_16x16x32_bf16 v[40:43], v[214:217], v[158:161], v[40:43]
	v_mfma_f32_16x16x32_bf16 v[32:35], v[200:203], v[166:169], v[32:35]
	v_mfma_f32_16x16x32_bf16 v[24:27], v[214:217], v[166:169], v[24:27]
	v_mfma_f32_16x16x32_bf16 v[16:19], v[200:203], v[174:177], v[16:19]
	v_mfma_f32_16x16x32_bf16 v[8:11], v[214:217], v[174:177], v[8:11]
	v_mfma_f32_16x16x32_bf16 v[4:7], v[200:203], v[182:185], v[4:7]
	v_mfma_f32_16x16x32_bf16 v[0:3], v[214:217], v[182:185], v[0:3]
	v_mfma_f32_16x16x32_bf16 v[48:51], v[204:207], v[162:165], v[48:51]
	v_mfma_f32_16x16x32_bf16 v[40:43], v[218:221], v[162:165], v[40:43]
	v_mfma_f32_16x16x32_bf16 v[32:35], v[204:207], v[170:173], v[32:35]
	v_mfma_f32_16x16x32_bf16 v[24:27], v[218:221], v[170:173], v[24:27]
	v_mfma_f32_16x16x32_bf16 v[16:19], v[204:207], v[178:181], v[16:19]
	v_mfma_f32_16x16x32_bf16 v[8:11], v[218:221], v[178:181], v[8:11]
	v_mfma_f32_16x16x32_bf16 v[4:7], v[204:207], v[196:199], v[4:7]
	v_mfma_f32_16x16x32_bf16 v[0:3], v[218:221], v[196:199], v[0:3]
	s_setprio 0
	s_add_i32 s77, s77, 2
	s_add_u32 s12, s12, 0x100
	s_addc_u32 s13, s13, 0
	s_add_u32 s25, s25, 0x100
	s_addc_u32 s76, s76, 0
	s_cmp_gt_u32 s77, 13
	s_barrier
	s_cbranch_scc0 .LBB0_1270
; __device__ __forceinline__ unsigned pk2(float lo, float hi) { unsigned r; asm("v_cvt_pk_bf16_f32 %0, %1, %2" : "=v"(r) : "v"(lo), "v"(hi)); return r; }
;     __device__ __forceinline__ void operator()(const f32x4 (&acc)[2][2][4][2], const Unit& u, int wr, int wc, int fr, int fq) const {
;     ...
;         int c = col_t + 64 * wc + 16 * fq;
;         if (mode == 2) c = (c >> 6) * 96 + (c & 63);
; #pragma unroll
;         for (int ai = 0; ai < 2; ++ai)
; #pragma unroll
;             for (int m = 0; m < 4; ++m) {
;                 const int row = row_t + ai * HALF + wr * 64 + m * 16 + fr;
;                 bf16_t* rp = O + (size_t)row * ldc + c;
; #pragma unroll
;                 for (int bj = 0; bj < 2; ++bj) {
;                     const f32x4 v0 = acc[ai][bj][m][0], v1 = acc[ai][bj][m][1];
;                     u32x4 o; o.x = pk2(v0[0], v0[1]); o.y = pk2(v0[2], v0[3]); o.z = pk2(v1[0], v1[1]); o.w = pk2(v1[2], v1[3]);
;                     *(u32x4*)(rp + 8 * bj) = o;
;                 }
;             }
	v_lshl_add_u32 v134, s70, 8, v138
	v_cvt_pk_bf16_f32 v68, v68, v69
	v_cvt_pk_bf16_f32 v69, v70, v71
	v_cvt_pk_bf16_f32 v70, v64, v65
	v_add_u32_e32 v64, 0x80, v134
	v_lshl_or_b32 v136, s15, 8, v140
	v_ashrrev_i32_e32 v135, 31, v134
	v_cvt_pk_bf16_f32 v112, v112, v113
	v_cvt_pk_bf16_f32 v113, v114, v115
	v_cvt_pk_bf16_f32 v114, v104, v105
	v_or_b32_e32 v104, 16, v134
	v_ashrrev_i32_e32 v65, 31, v64
	v_cvt_pk_bf16_f32 v48, v48, v49
	v_cvt_pk_bf16_f32 v49, v50, v51
	v_cvt_pk_bf16_f32 v50, v40, v41
	v_add_u32_e32 v40, 0x90, v134
	v_ashrrev_i32_e32 v137, 31, v136
	v_lshlrev_b64 v[142:143], 11, v[134:135]
	v_ashrrev_i32_e32 v105, 31, v104
	v_cvt_pk_bf16_f32 v96, v96, v97
	v_cvt_pk_bf16_f32 v97, v98, v99
	v_cvt_pk_bf16_f32 v98, v88, v89
	v_or_b32_e32 v88, 32, v134
	v_lshlrev_b64 v[64:65], 11, v[64:65]
	v_ashrrev_i32_e32 v41, 31, v40
	v_cvt_pk_bf16_f32 v32, v32, v33
	v_cvt_pk_bf16_f32 v33, v34, v35
	v_cvt_pk_bf16_f32 v34, v24, v25
	v_add_u32_e32 v24, 0xa0, v134
	v_lshl_add_u64 v[142:143], s[4:5], 0, v[142:143]
	v_lshlrev_b64 v[136:137], 1, v[136:137]
	v_lshlrev_b64 v[104:105], 11, v[104:105]
	v_ashrrev_i32_e32 v89, 31, v88
	v_cvt_pk_bf16_f32 v80, v80, v81
	v_cvt_pk_bf16_f32 v81, v82, v83
	v_cvt_pk_bf16_f32 v82, v72, v73
	v_or_b32_e32 v72, 48, v134
	v_lshl_add_u64 v[64:65], s[4:5], 0, v[64:65]
	v_lshlrev_b64 v[40:41], 11, v[40:41]
	v_ashrrev_i32_e32 v25, 31, v24
	v_cvt_pk_bf16_f32 v16, v16, v17
	v_cvt_pk_bf16_f32 v17, v18, v19
	v_cvt_pk_bf16_f32 v18, v8, v9
	v_add_u32_e32 v8, 0xb0, v134
	v_lshl_add_u64 v[142:143], v[142:143], 0, v[136:137]
	v_lshl_add_u64 v[104:105], s[4:5], 0, v[104:105]
	v_lshlrev_b64 v[88:89], 11, v[88:89]
	v_ashrrev_i32_e32 v73, 31, v72
	v_lshl_add_u64 v[64:65], v[64:65], 0, v[136:137]
	v_lshl_add_u64 v[40:41], s[4:5], 0, v[40:41]
	v_lshlrev_b64 v[24:25], 11, v[24:25]
	v_ashrrev_i32_e32 v9, 31, v8
	v_cvt_pk_bf16_f32 v115, v106, v107
	global_store_dwordx4 v[142:143], v[112:115], off offset:16
	v_lshl_add_u64 v[88:89], s[4:5], 0, v[88:89]
	v_lshlrev_b64 v[72:73], 11, v[72:73]
	v_lshl_add_u64 v[112:113], v[104:105], 0, v[136:137]
	v_cvt_pk_bf16_f32 v51, v42, v43
	global_store_dwordx4 v[64:65], v[48:51], off offset:16
	v_lshl_add_u64 v[24:25], s[4:5], 0, v[24:25]
	v_lshlrev_b64 v[8:9], 11, v[8:9]
	v_lshl_add_u64 v[48:49], v[40:41], 0, v[136:137]
	v_cvt_pk_bf16_f32 v99, v90, v91
	global_store_dwordx4 v[112:113], v[96:99], off offset:16
	v_lshl_add_u64 v[72:73], s[4:5], 0, v[72:73]
	v_cvt_pk_bf16_f32 v35, v26, v27
	global_store_dwordx4 v[48:49], v[32:35], off offset:16
	v_lshl_add_u64 v[96:97], v[88:89], 0, v[136:137]
	v_lshl_add_u64 v[8:9], s[4:5], 0, v[8:9]
	v_lshl_add_u64 v[32:33], v[24:25], 0, v[136:137]
	v_cvt_pk_bf16_f32 v83, v74, v75
	global_store_dwordx4 v[96:97], v[80:83], off offset:16
	v_cvt_pk_bf16_f32 v19, v10, v11
	global_store_dwordx4 v[32:33], v[16:19], off offset:16
	s_and_b64 vcc, exec, s[0:1]
	v_lshl_add_u64 v[80:81], v[72:73], 0, v[136:137]
	v_lshl_add_u64 v[16:17], v[8:9], 0, v[136:137]
	s_mov_b32 s15, s6
	s_mov_b32 s70, s69
	s_mov_b64 s[16:17], s[10:11]
	s_mov_b64 s[12:13], s[8:9]
	v_cvt_pk_bf16_f32 v124, v124, v125
	v_cvt_pk_bf16_f32 v125, v126, v127
	v_cvt_pk_bf16_f32 v126, v120, v121
	v_cvt_pk_bf16_f32 v127, v122, v123
	global_store_dwordx4 v[142:143], v[124:127], off
	v_cvt_pk_bf16_f32 v104, v116, v117
	v_cvt_pk_bf16_f32 v105, v118, v119
	v_cvt_pk_bf16_f32 v106, v108, v109
	v_cvt_pk_bf16_f32 v107, v110, v111
	global_store_dwordx4 v[112:113], v[104:107], off
	v_cvt_pk_bf16_f32 v88, v100, v101
	v_cvt_pk_bf16_f32 v89, v102, v103
	v_cvt_pk_bf16_f32 v90, v92, v93
	v_cvt_pk_bf16_f32 v91, v94, v95
	global_store_dwordx4 v[96:97], v[88:91], off
	v_cvt_pk_bf16_f32 v72, v84, v85
	v_cvt_pk_bf16_f32 v73, v86, v87
	v_cvt_pk_bf16_f32 v74, v76, v77
	v_cvt_pk_bf16_f32 v75, v78, v79
	global_store_dwordx4 v[80:81], v[72:75], off
	v_cvt_pk_bf16_f32 v71, v66, v67
	global_store_dwordx4 v[80:81], v[68:71], off offset:16
	v_cvt_pk_bf16_f32 v60, v60, v61
	v_cvt_pk_bf16_f32 v61, v62, v63
	v_cvt_pk_bf16_f32 v62, v56, v57
	v_cvt_pk_bf16_f32 v63, v58, v59
	global_store_dwordx4 v[64:65], v[60:63], off
	v_cvt_pk_bf16_f32 v40, v52, v53
	v_cvt_pk_bf16_f32 v41, v54, v55
	v_cvt_pk_bf16_f32 v42, v44, v45
	v_cvt_pk_bf16_f32 v43, v46, v47
	global_store_dwordx4 v[48:49], v[40:43], off
	v_cvt_pk_bf16_f32 v24, v36, v37
	v_cvt_pk_bf16_f32 v25, v38, v39
	v_cvt_pk_bf16_f32 v26, v28, v29
	v_cvt_pk_bf16_f32 v27, v30, v31
	global_store_dwordx4 v[32:33], v[24:27], off
	v_cvt_pk_bf16_f32 v8, v20, v21
	v_cvt_pk_bf16_f32 v9, v22, v23
	v_cvt_pk_bf16_f32 v10, v12, v13
	v_cvt_pk_bf16_f32 v11, v14, v15
	global_store_dwordx4 v[16:17], v[8:11], off
	v_cvt_pk_bf16_f32 v4, v4, v5
	v_cvt_pk_bf16_f32 v5, v6, v7
	v_cvt_pk_bf16_f32 v6, v0, v1
	v_cvt_pk_bf16_f32 v7, v2, v3
	global_store_dwordx4 v[16:17], v[4:7], off offset:16
	s_cbranch_vccz .LBB0_1267
	s_waitcnt vmcnt(0)
	s_cmpk_gt_u32 s3, 0xff
	s_cbranch_scc1 .LBB0_1274
	s_barrier

; #define PG8_STAGE(bufoff, gbase, voff) do { _Pragma("unroll") for (int _i = 0; _i < 2; ++_i) \
;         __builtin_amdgcn_global_load_lds((const unsigned*)((const char*)(gbase) + (voff)[_i]), (LAS unsigned*)(lds + (bufoff) + ldsw + _i * 8192), 16, 0, 0); } while (0)
; #define PG8_LDA(dst, b, h) do { _Pragma("unroll") for (int m = 0; m < 4; ++m) _Pragma("unroll") for (int k = 0; k < 2; ++k) dst[m][k] = *(const LAS bf16x8*)(lds + PG8_SA(b, h) + aoff + m * 2048 + k * 1024); } while (0)
; #define PG8_LDB(dst, b, h) do { _Pragma("unroll") for (int n = 0; n < 2; ++n) _Pragma("unroll") for (int k = 0; k < 2; ++k) dst[n][k] = *(const LAS bf16x8*)(lds + PG8_SB(b, h) + boff + n * 2048 + k * 1024); } while (0)
; #define PG8_MMA(ai, bj, At, Bt) do { __builtin_amdgcn_s_setprio(1); _Pragma("unroll") for (int m = 0; m < 4; ++m) _Pragma("unroll") for (int n = 0; n < 2; ++n) _Pragma("unroll") for (int k = 0; k < 2; ++k) \
;         acc[ai][bj][m][n] = __builtin_amdgcn_mfma_f32_16x16x32_bf16(Bt[n][k], At[m][k], acc[ai][bj][m][n], 0, 0, 0); __builtin_amdgcn_s_setprio(0); } while (0)
; #define PG8_WAIT_L(n) asm volatile("s_waitcnt lgkmcnt(" #n ")" ::: "memory")
; #define PG8_BAR __builtin_amdgcn_s_barrier()
; #define PG8_SCHED __builtin_amdgcn_sched_barrier(0)
; template <class Epi>
; __device__ __forceinline__ void gemm_phase(LAS unsigned char* lds, const Gemm g, const StaticOrder& S, const Epi& E) {
;     ...
;         const char* nA = has_next ? g.arow(nxt.pm) : cA; const char* nB = has_next ? (const char*)g.Bt + (size_t)nxt.pn * tB : cB;
;         for (int t = 0; t < nt; t += 2) {
;             const bool last = (t == nt - 2);
;             const char* a1 = cA + (size_t)(t + 1) * kstep;
;             const char* a2 = last ? nA : cA + (size_t)(t + 2) * kstep; const char* b2 = last ? nB : cB + (size_t)(t + 2) * kstep;
;             const char* a3 = a2 + kstep; const char* b3 = b2 + kstep;
;             PG8_LDB(B0, 0, 0); PG8_SCHED; PG8_LDA(At, 0, 0); PG8_STAGE(PG8_SA(1, 1), a1 + hA, voffA);
;             PG8_WAIT_L(8); PG8_BAR; PG8_WAIT_L(0); PG8_MMA(0, 0, At, B0); PG8_BAR; PG8_SCHED;
;             PG8_LDB(B1, 0, 1); PG8_STAGE(PG8_SB(0, 0), b2, voffB);
;             PG8_BAR; PG8_WAIT_L(0); PG8_MMA(0, 1, At, B1); PG8_BAR;
;             PG8_LDA(At, 0, 1); PG8_STAGE(PG8_SA(0, 0), a2, voffA);
;             PG8_BAR; PG8_WAIT_L(0); PG8_MMA(1, 0, At, B0); PG8_BAR; PG8_SCHED;
.LBB0_1394:
	s_add_u32 s20, s16, 0xfffc0080
	s_addc_u32 s21, s17, -1
	s_add_i32 s26, 0, 0x10000
	v_add_u32_e32 v139, s26, v137
	ds_read_b128 v[140:143], v139
	ds_read_b128 v[146:149], v139 offset:1024
	ds_read_b128 v[150:153], v139 offset:2048
	ds_read_b128 v[154:157], v139 offset:3072
	s_cmp_eq_u32 s85, 12
	s_cselect_b32 s35, s82, s21
	s_cselect_b32 s34, s83, s20
	s_cselect_b32 s21, s9, s84
	s_cselect_b32 s20, s24, s25
	v_lshl_add_u64 v[192:193], s[16:17], 0, v[132:133]
	s_add_i32 m0, s70, 0xc000
	ds_read_b128 v[158:161], v138
	ds_read_b128 v[162:165], v138 offset:1024
	ds_read_b128 v[166:169], v138 offset:2048
	ds_read_b128 v[170:173], v138 offset:3072
	ds_read_b128 v[174:177], v138 offset:4096
	ds_read_b128 v[178:181], v138 offset:5120
	ds_read_b128 v[182:185], v138 offset:6144
	ds_read_b128 v[186:189], v138 offset:7168
	global_load_lds_dwordx4 v[192:193], off
	s_add_i32 m0, s70, 0xe000
	v_lshl_add_u64 v[192:193], s[16:17], 0, v[134:135]
	global_load_lds_dwordx4 v[192:193], off
	s_waitcnt lgkmcnt(8)
	s_barrier
	s_waitcnt lgkmcnt(0)
	s_setprio 1
	v_mfma_f32_16x16x32_bf16 v[120:123], v[140:143], v[158:161], v[120:123]
	v_mfma_f32_16x16x32_bf16 v[124:127], v[150:153], v[158:161], v[124:127]
	v_mfma_f32_16x16x32_bf16 v[104:107], v[140:143], v[166:169], v[104:107]
	v_mfma_f32_16x16x32_bf16 v[108:111], v[150:153], v[166:169], v[108:111]
	v_mfma_f32_16x16x32_bf16 v[88:91], v[140:143], v[174:177], v[88:91]
	v_mfma_f32_16x16x32_bf16 v[92:95], v[150:153], v[174:177], v[92:95]
	v_mfma_f32_16x16x32_bf16 v[72:75], v[140:143], v[182:185], v[72:75]
	v_mfma_f32_16x16x32_bf16 v[76:79], v[150:153], v[182:185], v[76:79]
	v_mfma_f32_16x16x32_bf16 v[120:123], v[146:149], v[162:165], v[120:123]
	v_mfma_f32_16x16x32_bf16 v[124:127], v[154:157], v[162:165], v[124:127]
	v_mfma_f32_16x16x32_bf16 v[104:107], v[146:149], v[170:173], v[104:107]
	v_mfma_f32_16x16x32_bf16 v[108:111], v[154:157], v[170:173], v[108:111]
	v_mfma_f32_16x16x32_bf16 v[88:91], v[146:149], v[178:181], v[88:91]
	v_mfma_f32_16x16x32_bf16 v[92:95], v[154:157], v[178:181], v[92:95]
	v_mfma_f32_16x16x32_bf16 v[72:75], v[146:149], v[186:189], v[72:75]
	v_mfma_f32_16x16x32_bf16 v[76:79], v[154:157], v[186:189], v[76:79]
	s_setprio 0
	s_barrier
	s_add_i32 s28, 0, 0x14000
	s_add_i32 s26, s26, s64
	v_add_u32_e32 v139, s28, v137
	v_lshl_add_u64 v[192:193], s[20:21], 0, v[130:131]
	s_mov_b32 m0, s26
	ds_read_b128 v[196:199], v139
	ds_read_b128 v[200:203], v139 offset:1024
	ds_read_b128 v[204:207], v139 offset:2048
	ds_read_b128 v[214:217], v139 offset:3072
	global_load_lds_dwordx4 v[192:193], off
	s_add_i32 m0, s26, 0x2000
	v_lshl_add_u64 v[218:219], s[20:21], 0, v[128:129]
	global_load_lds_dwordx4 v[218:219], off
	s_barrier
	s_waitcnt lgkmcnt(0)
	s_setprio 1
	v_mfma_f32_16x16x32_bf16 v[112:115], v[196:199], v[158:161], v[112:115]
	v_mfma_f32_16x16x32_bf16 v[116:119], v[204:207], v[158:161], v[116:119]
	v_mfma_f32_16x16x32_bf16 v[96:99], v[196:199], v[166:169], v[96:99]
	v_mfma_f32_16x16x32_bf16 v[100:103], v[204:207], v[166:169], v[100:103]
	v_mfma_f32_16x16x32_bf16 v[80:83], v[196:199], v[174:177], v[80:83]
	v_mfma_f32_16x16x32_bf16 v[84:87], v[204:207], v[174:177], v[84:87]
	v_mfma_f32_16x16x32_bf16 v[64:67], v[196:199], v[182:185], v[64:67]
	v_mfma_f32_16x16x32_bf16 v[68:71], v[204:207], v[182:185], v[68:71]
	v_mfma_f32_16x16x32_bf16 v[112:115], v[200:203], v[162:165], v[112:115]
	v_mfma_f32_16x16x32_bf16 v[116:119], v[214:217], v[162:165], v[116:119]
	v_mfma_f32_16x16x32_bf16 v[96:99], v[200:203], v[170:173], v[96:99]
	v_mfma_f32_16x16x32_bf16 v[100:103], v[214:217], v[170:173], v[100:103]
	v_mfma_f32_16x16x32_bf16 v[80:83], v[200:203], v[178:181], v[80:83]
	v_mfma_f32_16x16x32_bf16 v[84:87], v[214:217], v[178:181], v[84:87]
	v_mfma_f32_16x16x32_bf16 v[64:67], v[200:203], v[186:189], v[64:67]
	v_mfma_f32_16x16x32_bf16 v[68:71], v[214:217], v[186:189], v[68:71]
	s_setprio 0
	s_mov_b32 m0, s70
	v_lshl_add_u64 v[220:221], s[34:35], 0, v[130:131]
	s_barrier
	ds_read_b128 v[158:161], v138 offset:16384
	ds_read_b128 v[162:165], v138 offset:17408
	ds_read_b128 v[166:169], v138 offset:18432
	ds_read_b128 v[170:173], v138 offset:19456
	ds_read_b128 v[174:177], v138 offset:20480
	ds_read_b128 v[178:181], v138 offset:21504
	ds_read_b128 v[182:185], v138 offset:22528
	ds_read_b128 v[186:189], v138 offset:23552
	global_load_lds_dwordx4 v[220:221], off
	s_mov_b32 m0, s71
	v_lshl_add_u64 v[222:223], s[34:35], 0, v[128:129]
	global_load_lds_dwordx4 v[222:223], off
	s_barrier
	s_waitcnt lgkmcnt(0)
	s_setprio 1
	v_mfma_f32_16x16x32_bf16 v[56:59], v[140:143], v[158:161], v[56:59]
	v_mfma_f32_16x16x32_bf16 v[60:63], v[150:153], v[158:161], v[60:63]
	v_mfma_f32_16x16x32_bf16 v[40:43], v[140:143], v[166:169], v[40:43]
	v_mfma_f32_16x16x32_bf16 v[44:47], v[150:153], v[166:169], v[44:47]
	v_mfma_f32_16x16x32_bf16 v[24:27], v[140:143], v[174:177], v[24:27]
	v_mfma_f32_16x16x32_bf16 v[28:31], v[150:153], v[174:177], v[28:31]
	v_mfma_f32_16x16x32_bf16 v[8:11], v[140:143], v[182:185], v[8:11]
	v_mfma_f32_16x16x32_bf16 v[12:15], v[150:153], v[182:185], v[12:15]
	v_mfma_f32_16x16x32_bf16 v[56:59], v[146:149], v[162:165], v[56:59]
	v_mfma_f32_16x16x32_bf16 v[60:63], v[154:157], v[162:165], v[60:63]
	v_mfma_f32_16x16x32_bf16 v[40:43], v[146:149], v[170:173], v[40:43]
	v_mfma_f32_16x16x32_bf16 v[44:47], v[154:157], v[170:173], v[44:47]
	v_mfma_f32_16x16x32_bf16 v[24:27], v[146:149], v[178:181], v[24:27]
	v_mfma_f32_16x16x32_bf16 v[28:31], v[154:157], v[178:181], v[28:31]
	v_mfma_f32_16x16x32_bf16 v[8:11], v[146:149], v[186:189], v[8:11]
	v_mfma_f32_16x16x32_bf16 v[12:15], v[154:157], v[186:189], v[12:15]
	s_setprio 0
	s_barrier
; #define PG8_STAGE(bufoff, gbase, voff) do { _Pragma("unroll") for (int _i = 0; _i < 2; ++_i) \
;         __builtin_amdgcn_global_load_lds((const unsigned*)((const char*)(gbase) + (voff)[_i]), (LAS unsigned*)(lds + (bufoff) + ldsw + _i * 8192), 16, 0, 0); } while (0)
; #define PG8_LDA(dst, b, h) do { _Pragma("unroll") for (int m = 0; m < 4; ++m) _Pragma("unroll") for (int k = 0; k < 2; ++k) dst[m][k] = *(const LAS bf16x8*)(lds + PG8_SA(b, h) + aoff + m * 2048 + k * 1024); } while (0)
; #define PG8_LDB(dst, b, h) do { _Pragma("unroll") for (int n = 0; n < 2; ++n) _Pragma("unroll") for (int k = 0; k < 2; ++k) dst[n][k] = *(const LAS bf16x8*)(lds + PG8_SB(b, h) + boff + n * 2048 + k * 1024); } while (0)
; #define PG8_MMA(ai, bj, At, Bt) do { __builtin_amdgcn_s_setprio(1); _Pragma("unroll") for (int m = 0; m < 4; ++m) _Pragma("unroll") for (int n = 0; n < 2; ++n) _Pragma("unroll") for (int k = 0; k < 2; ++k) \
;         acc[ai][bj][m][n] = __builtin_amdgcn_mfma_f32_16x16x32_bf16(Bt[n][k], At[m][k], acc[ai][bj][m][n], 0, 0, 0); __builtin_amdgcn_s_setprio(0); } while (0)
; #define PG8_WAIT_V(n) asm volatile("s_waitcnt vmcnt(" #n ")" ::: "memory")
; #define PG8_WAIT_L(n) asm volatile("s_waitcnt lgkmcnt(" #n ")" ::: "memory")
; #define PG8_BAR __builtin_amdgcn_s_barrier()
; #define PG8_SCHED __builtin_amdgcn_sched_barrier(0)
; template <class Epi>
; __device__ __forceinline__ void gemm_phase(LAS unsigned char* lds, const Gemm g, const StaticOrder& S, const Epi& E) {
;     ...
;             PG8_STAGE(PG8_SB(0, 1), b2 + hB, voffB);
;             PG8_WAIT_V(6); PG8_BAR; PG8_MMA(1, 1, At, B1); PG8_BAR;
;             PG8_LDB(B0, 1, 0); PG8_SCHED; PG8_LDA(At, 1, 0); PG8_STAGE(PG8_SA(0, 1), a2 + hA, voffA);
;             PG8_WAIT_L(8); PG8_BAR; PG8_WAIT_L(0); PG8_MMA(0, 0, At, B0); PG8_BAR; PG8_SCHED;
;             PG8_LDB(B1, 1, 1); PG8_STAGE(PG8_SB(1, 0), b3, voffB);
;             PG8_BAR; PG8_WAIT_L(0); PG8_MMA(0, 1, At, B1); PG8_BAR;
;             PG8_LDA(At, 1, 1); PG8_STAGE(PG8_SA(1, 0), a3, voffA);
	s_add_u32 s26, s20, 0x40000
	s_addc_u32 s27, s21, 0
	s_add_i32 s28, s28, s64
	s_mov_b32 m0, s28
	v_lshl_add_u64 v[140:141], s[26:27], 0, v[130:131]
	global_load_lds_dwordx4 v[140:141], off
	s_add_i32 m0, s28, 0x2000
	v_lshl_add_u64 v[140:141], s[26:27], 0, v[128:129]
	global_load_lds_dwordx4 v[140:141], off
	s_waitcnt vmcnt(6)
	s_barrier
	s_setprio 1
	v_mfma_f32_16x16x32_bf16 v[48:51], v[196:199], v[158:161], v[48:51]
	v_mfma_f32_16x16x32_bf16 v[52:55], v[204:207], v[158:161], v[52:55]
	v_mfma_f32_16x16x32_bf16 v[32:35], v[196:199], v[166:169], v[32:35]
	v_mfma_f32_16x16x32_bf16 v[36:39], v[204:207], v[166:169], v[36:39]
	v_mfma_f32_16x16x32_bf16 v[16:19], v[196:199], v[174:177], v[16:19]
	v_mfma_f32_16x16x32_bf16 v[20:23], v[204:207], v[174:177], v[20:23]
	v_mfma_f32_16x16x32_bf16 v[0:3], v[196:199], v[182:185], v[0:3]
	v_mfma_f32_16x16x32_bf16 v[4:7], v[204:207], v[182:185], v[4:7]
	v_mfma_f32_16x16x32_bf16 v[48:51], v[200:203], v[162:165], v[48:51]
	v_mfma_f32_16x16x32_bf16 v[52:55], v[214:217], v[162:165], v[52:55]
	v_mfma_f32_16x16x32_bf16 v[32:35], v[200:203], v[170:173], v[32:35]
	v_mfma_f32_16x16x32_bf16 v[36:39], v[214:217], v[170:173], v[36:39]
	v_mfma_f32_16x16x32_bf16 v[16:19], v[200:203], v[178:181], v[16:19]
	v_mfma_f32_16x16x32_bf16 v[20:23], v[214:217], v[178:181], v[20:23]
	v_mfma_f32_16x16x32_bf16 v[0:3], v[200:203], v[186:189], v[0:3]
	v_mfma_f32_16x16x32_bf16 v[4:7], v[214:217], v[186:189], v[4:7]
	s_setprio 0
	s_add_i32 s28, 0, 0x18000
	v_add_u32_e32 v139, s28, v137
	s_barrier
	ds_read_b128 v[140:143], v139
	ds_read_b128 v[146:149], v139 offset:1024
	ds_read_b128 v[150:153], v139 offset:2048
	ds_read_b128 v[154:157], v139 offset:3072
	s_add_u32 s26, s34, 0x40000
	s_addc_u32 s27, s35, 0
	s_mov_b32 m0, s72
	v_lshl_add_u64 v[196:197], s[26:27], 0, v[130:131]
	ds_read_b128 v[158:161], v138 offset:32768
	ds_read_b128 v[162:165], v138 offset:33792
	ds_read_b128 v[166:169], v138 offset:34816
	ds_read_b128 v[170:173], v138 offset:35840
	ds_read_b128 v[174:177], v138 offset:36864
	ds_read_b128 v[178:181], v138 offset:37888
	ds_read_b128 v[182:185], v138 offset:38912
	ds_read_b128 v[186:189], v138 offset:39936
	global_load_lds_dwordx4 v[196:197], off
	s_mov_b32 m0, s76
	v_lshl_add_u64 v[196:197], s[26:27], 0, v[128:129]
	global_load_lds_dwordx4 v[196:197], off
	s_waitcnt lgkmcnt(8)
	s_barrier
	s_waitcnt lgkmcnt(0)
	s_setprio 1
	v_mfma_f32_16x16x32_bf16 v[120:123], v[140:143], v[158:161], v[120:123]
	v_mfma_f32_16x16x32_bf16 v[124:127], v[150:153], v[158:161], v[124:127]
	v_mfma_f32_16x16x32_bf16 v[104:107], v[140:143], v[166:169], v[104:107]
	v_mfma_f32_16x16x32_bf16 v[108:111], v[150:153], v[166:169], v[108:111]
	v_mfma_f32_16x16x32_bf16 v[88:91], v[140:143], v[174:177], v[88:91]
	v_mfma_f32_16x16x32_bf16 v[92:95], v[150:153], v[174:177], v[92:95]
	v_mfma_f32_16x16x32_bf16 v[72:75], v[140:143], v[182:185], v[72:75]
	v_mfma_f32_16x16x32_bf16 v[76:79], v[150:153], v[182:185], v[76:79]
	v_mfma_f32_16x16x32_bf16 v[120:123], v[146:149], v[162:165], v[120:123]
	v_mfma_f32_16x16x32_bf16 v[124:127], v[154:157], v[162:165], v[124:127]
	v_mfma_f32_16x16x32_bf16 v[104:107], v[146:149], v[170:173], v[104:107]
	v_mfma_f32_16x16x32_bf16 v[108:111], v[154:157], v[170:173], v[108:111]
	v_mfma_f32_16x16x32_bf16 v[88:91], v[146:149], v[178:181], v[88:91]
	v_mfma_f32_16x16x32_bf16 v[92:95], v[154:157], v[178:181], v[92:95]
	v_mfma_f32_16x16x32_bf16 v[72:75], v[146:149], v[186:189], v[72:75]
	v_mfma_f32_16x16x32_bf16 v[76:79], v[154:157], v[186:189], v[76:79]
	s_setprio 0
	s_barrier
	s_add_i32 s26, 0, 0x1c000
	s_add_i32 s27, s28, s64
	v_add_u32_e32 v139, s26, v137
	v_lshl_add_u64 v[192:193], v[192:193], 0, s[88:89]
	s_mov_b32 m0, s27
	ds_read_b128 v[196:199], v139
	ds_read_b128 v[200:203], v139 offset:1024
	ds_read_b128 v[204:207], v139 offset:2048
	ds_read_b128 v[214:217], v139 offset:3072
	global_load_lds_dwordx4 v[192:193], off
	s_add_i32 m0, s27, 0x2000
	v_lshl_add_u64 v[192:193], v[218:219], 0, s[88:89]
	global_load_lds_dwordx4 v[192:193], off
	s_barrier
	s_waitcnt lgkmcnt(0)
	s_setprio 1
	v_mfma_f32_16x16x32_bf16 v[112:115], v[196:199], v[158:161], v[112:115]
	v_mfma_f32_16x16x32_bf16 v[116:119], v[204:207], v[158:161], v[116:119]
	v_mfma_f32_16x16x32_bf16 v[96:99], v[196:199], v[166:169], v[96:99]
	v_mfma_f32_16x16x32_bf16 v[100:103], v[204:207], v[166:169], v[100:103]
	v_mfma_f32_16x16x32_bf16 v[80:83], v[196:199], v[174:177], v[80:83]
	v_mfma_f32_16x16x32_bf16 v[84:87], v[204:207], v[174:177], v[84:87]
	v_mfma_f32_16x16x32_bf16 v[64:67], v[196:199], v[182:185], v[64:67]
	v_mfma_f32_16x16x32_bf16 v[68:71], v[204:207], v[182:185], v[68:71]
	v_mfma_f32_16x16x32_bf16 v[112:115], v[200:203], v[162:165], v[112:115]
	v_mfma_f32_16x16x32_bf16 v[116:119], v[214:217], v[162:165], v[116:119]
	v_mfma_f32_16x16x32_bf16 v[96:99], v[200:203], v[170:173], v[96:99]
	v_mfma_f32_16x16x32_bf16 v[100:103], v[214:217], v[170:173], v[100:103]
	v_mfma_f32_16x16x32_bf16 v[80:83], v[200:203], v[178:181], v[80:83]
	v_mfma_f32_16x16x32_bf16 v[84:87], v[214:217], v[178:181], v[84:87]
	v_mfma_f32_16x16x32_bf16 v[64:67], v[200:203], v[186:189], v[64:67]
	v_mfma_f32_16x16x32_bf16 v[68:71], v[214:217], v[186:189], v[68:71]
	s_setprio 0
	s_mov_b32 m0, s77
	v_lshl_add_u64 v[192:193], v[220:221], 0, s[88:89]
	s_barrier
	ds_read_b128 v[158:161], v138 offset:49152
	ds_read_b128 v[162:165], v138 offset:50176
	ds_read_b128 v[166:169], v138 offset:51200
	ds_read_b128 v[170:173], v138 offset:52224
	ds_read_b128 v[174:177], v138 offset:53248
	ds_read_b128 v[178:181], v138 offset:54272
	ds_read_b128 v[182:185], v138 offset:55296
	ds_read_b128 v[186:189], v138 offset:56320
	global_load_lds_dwordx4 v[192:193], off
	s_mov_b32 m0, s78
	v_lshl_add_u64 v[192:193], v[222:223], 0, s[88:89]
	global_load_lds_dwordx4 v[192:193], off
	s_barrier
; __device__ __forceinline__ unsigned pk2(float lo, float hi) { unsigned r; asm("v_cvt_pk_bf16_f32 %0, %1, %2" : "=v"(r) : "v"(lo), "v"(hi)); return r; }
; #define PG8_STAGE(bufoff, gbase, voff) do { _Pragma("unroll") for (int _i = 0; _i < 2; ++_i) \
;         __builtin_amdgcn_global_load_lds((const unsigned*)((const char*)(gbase) + (voff)[_i]), (LAS unsigned*)(lds + (bufoff) + ldsw + _i * 8192), 16, 0, 0); } while (0)
; #define PG8_MMA(ai, bj, At, Bt) do { __builtin_amdgcn_s_setprio(1); _Pragma("unroll") for (int m = 0; m < 4; ++m) _Pragma("unroll") for (int n = 0; n < 2; ++n) _Pragma("unroll") for (int k = 0; k < 2; ++k) \
;         acc[ai][bj][m][n] = __builtin_amdgcn_mfma_f32_16x16x32_bf16(Bt[n][k], At[m][k], acc[ai][bj][m][n], 0, 0, 0); __builtin_amdgcn_s_setprio(0); } while (0)
; #define PG8_WAIT_V(n) asm volatile("s_waitcnt vmcnt(" #n ")" ::: "memory")
; #define PG8_WAIT_L(n) asm volatile("s_waitcnt lgkmcnt(" #n ")" ::: "memory")
; #define PG8_BAR __builtin_amdgcn_s_barrier()
; #define PG8_SCHED __builtin_amdgcn_sched_barrier(0)
; template <class Epi>
; __device__ __forceinline__ void gemm_phase(LAS unsigned char* lds, const Gemm g, const StaticOrder& S, const Epi& E) {
;     ...
;             PG8_BAR; PG8_WAIT_L(0); PG8_MMA(1, 0, At, B0); PG8_BAR; PG8_SCHED;
;             PG8_STAGE(PG8_SB(1, 1), b3 + hB, voffB);
;             PG8_WAIT_V(6); PG8_BAR; PG8_MMA(1, 1, At, B1); PG8_BAR;
;     static __device__ __forceinline__ float sg(float g, float u) { return (g * u) * __builtin_amdgcn_rcpf(1.f + __builtin_amdgcn_exp2f(-g)); }
;     __device__ __forceinline__ void operator()(const f32x4 (&acc)[2][2][4][2], const Unit& u, int wr, int wc, int fr, int fq) const {
; #pragma unroll
;         for (int ai = 0; ai < 2; ++ai)
; #pragma unroll
;             for (int m = 0; m < 4; ++m) {
;                 const int row = u.pm * BM + ai * HALF + wr * 64 + m * 16 + fr;
;                 const f32x4 g0 = acc[ai][0][m][0], u0 = acc[ai][0][m][1], g1 = acc[ai][1][m][0], u1 = acc[ai][1][m][1];
;                 u32x4 o; o.x = pk2(sg(g0[0], u0[0]), sg(g0[1], u0[1])); o.y = pk2(sg(g0[2], u0[2]), sg(g0[3], u0[3]));
;                 o.z = pk2(sg(g1[0], u1[0]), sg(g1[1], u1[1])); o.w = pk2(sg(g1[2], u1[2]), sg(g1[3], u1[3]));
;                 *(u32x4*)(O + (size_t)row * DFF + u.pn * 128 + wc * 32 + fq * 8) = o;
	s_waitcnt lgkmcnt(0)
	s_setprio 1
	v_mfma_f32_16x16x32_bf16 v[56:59], v[140:143], v[158:161], v[56:59]
	v_mfma_f32_16x16x32_bf16 v[60:63], v[150:153], v[158:161], v[60:63]
	v_mfma_f32_16x16x32_bf16 v[40:43], v[140:143], v[166:169], v[40:43]
	v_mfma_f32_16x16x32_bf16 v[44:47], v[150:153], v[166:169], v[44:47]
	v_mfma_f32_16x16x32_bf16 v[24:27], v[140:143], v[174:177], v[24:27]
	v_mfma_f32_16x16x32_bf16 v[28:31], v[150:153], v[174:177], v[28:31]
	v_mfma_f32_16x16x32_bf16 v[8:11], v[140:143], v[182:185], v[8:11]
	v_mfma_f32_16x16x32_bf16 v[12:15], v[150:153], v[182:185], v[12:15]
	v_mfma_f32_16x16x32_bf16 v[56:59], v[146:149], v[162:165], v[56:59]
	v_mfma_f32_16x16x32_bf16 v[60:63], v[154:157], v[162:165], v[60:63]
	v_mfma_f32_16x16x32_bf16 v[40:43], v[146:149], v[170:173], v[40:43]
	v_mfma_f32_16x16x32_bf16 v[44:47], v[154:157], v[170:173], v[44:47]
	v_mfma_f32_16x16x32_bf16 v[24:27], v[146:149], v[178:181], v[24:27]
	v_mfma_f32_16x16x32_bf16 v[28:31], v[154:157], v[178:181], v[28:31]
	v_mfma_f32_16x16x32_bf16 v[8:11], v[146:149], v[186:189], v[8:11]
	v_mfma_f32_16x16x32_bf16 v[12:15], v[154:157], v[186:189], v[12:15]
	s_setprio 0
	s_barrier
	s_add_u32 s20, s20, 0x40080
	s_addc_u32 s21, s21, 0
	s_add_i32 s26, s26, s64
	s_mov_b32 m0, s26
	v_lshl_add_u64 v[140:141], s[20:21], 0, v[130:131]
	global_load_lds_dwordx4 v[140:141], off
	s_add_i32 m0, s26, 0x2000
	v_lshl_add_u64 v[140:141], s[20:21], 0, v[128:129]
	global_load_lds_dwordx4 v[140:141], off
	s_waitcnt vmcnt(6)
	s_barrier
	s_setprio 1
	v_mfma_f32_16x16x32_bf16 v[48:51], v[196:199], v[158:161], v[48:51]
	v_mfma_f32_16x16x32_bf16 v[52:55], v[204:207], v[158:161], v[52:55]
	v_mfma_f32_16x16x32_bf16 v[32:35], v[196:199], v[166:169], v[32:35]
	v_mfma_f32_16x16x32_bf16 v[36:39], v[204:207], v[166:169], v[36:39]
	v_mfma_f32_16x16x32_bf16 v[16:19], v[196:199], v[174:177], v[16:19]
	v_mfma_f32_16x16x32_bf16 v[20:23], v[204:207], v[174:177], v[20:23]
	v_mfma_f32_16x16x32_bf16 v[0:3], v[196:199], v[182:185], v[0:3]
	v_mfma_f32_16x16x32_bf16 v[4:7], v[204:207], v[182:185], v[4:7]
	v_mfma_f32_16x16x32_bf16 v[48:51], v[200:203], v[162:165], v[48:51]
	v_mfma_f32_16x16x32_bf16 v[52:55], v[214:217], v[162:165], v[52:55]
	v_mfma_f32_16x16x32_bf16 v[32:35], v[200:203], v[170:173], v[32:35]
	v_mfma_f32_16x16x32_bf16 v[36:39], v[214:217], v[170:173], v[36:39]
	v_mfma_f32_16x16x32_bf16 v[16:19], v[200:203], v[178:181], v[16:19]
	v_mfma_f32_16x16x32_bf16 v[20:23], v[214:217], v[178:181], v[20:23]
	v_mfma_f32_16x16x32_bf16 v[0:3], v[200:203], v[186:189], v[0:3]
	v_mfma_f32_16x16x32_bf16 v[4:7], v[214:217], v[186:189], v[4:7]
	s_setprio 0
	s_add_i32 s85, s85, 2
	s_add_u32 s16, s16, 0x100
	s_addc_u32 s17, s17, 0
	s_add_u32 s25, s25, 0x100
	s_addc_u32 s84, s84, 0
	s_cmp_gt_u32 s85, 13
	s_barrier
	s_cbranch_scc0 .LBB0_1394
	v_mul_f32_e32 v124, v120, v124
	v_exp_f32_e64 v120, -v120
	v_mul_f32_e32 v108, v104, v108
	v_exp_f32_e64 v104, -v104
	v_mul_f32_e32 v92, v88, v92
	v_add_f32_e32 v120, 1.0, v120
	v_rcp_f32_e32 v120, v120
	v_add_f32_e32 v104, 1.0, v104
	v_rcp_f32_e32 v104, v104
	v_exp_f32_e64 v88, -v88
	v_mul_f32_e32 v120, v124, v120
	v_mul_f32_e32 v124, v121, v125
	v_exp_f32_e64 v121, -v121
	v_mul_f32_e32 v104, v108, v104
	v_mul_f32_e32 v108, v105, v109
	v_exp_f32_e64 v105, -v105
	v_add_f32_e32 v121, 1.0, v121
	v_rcp_f32_e32 v121, v121
	v_add_f32_e32 v88, 1.0, v88
	v_rcp_f32_e32 v88, v88
	v_mul_f32_e32 v76, v72, v76
	v_exp_f32_e64 v72, -v72
	v_mul_f32_e32 v121, v124, v121
	v_cvt_pk_bf16_f32 v120, v120, v121
	v_mul_f32_e32 v121, v122, v126
	v_exp_f32_e64 v122, -v122
	v_mul_f32_e32 v116, v112, v116
	v_exp_f32_e64 v112, -v112
	v_add_f32_e32 v105, 1.0, v105
	v_rcp_f32_e32 v105, v105
	v_mul_f32_e32 v88, v92, v88
	v_mul_f32_e32 v92, v89, v93
	v_exp_f32_e64 v89, -v89
	v_add_f32_e32 v72, 1.0, v72
	v_rcp_f32_e32 v72, v72
	v_mul_f32_e32 v60, v56, v60
	v_exp_f32_e64 v56, -v56
	v_add_f32_e32 v122, 1.0, v122
	v_add_f32_e32 v112, 1.0, v112
	v_rcp_f32_e32 v122, v122
	v_rcp_f32_e32 v112, v112
	v_mul_f32_e32 v105, v108, v105
	v_add_f32_e32 v89, 1.0, v89
	v_cvt_pk_bf16_f32 v104, v104, v105
	v_mul_f32_e32 v105, v106, v110
	v_exp_f32_e64 v106, -v106
	v_mul_f32_e32 v100, v96, v100
	v_exp_f32_e64 v96, -v96
	v_rcp_f32_e32 v89, v89
	v_mul_f32_e32 v72, v76, v72
	v_mul_f32_e32 v76, v73, v77
	v_exp_f32_e64 v73, -v73
	v_add_f32_e32 v56, 1.0, v56
	v_rcp_f32_e32 v56, v56
	v_mul_f32_e32 v44, v40, v44
	v_exp_f32_e64 v40, -v40
	v_mul_f32_e32 v121, v121, v122
	v_mul_f32_e32 v122, v123, v127
	v_exp_f32_e64 v123, -v123
	v_mul_f32_e32 v112, v116, v112
	v_mul_f32_e32 v116, v113, v117
	v_exp_f32_e64 v113, -v113
	v_add_f32_e32 v106, 1.0, v106
	v_add_f32_e32 v96, 1.0, v96
	v_mul_f32_e32 v89, v92, v89
	v_add_f32_e32 v73, 1.0, v73
	v_rcp_f32_e32 v106, v106
	v_rcp_f32_e32 v96, v96
	v_cvt_pk_bf16_f32 v88, v88, v89
	v_mul_f32_e32 v89, v90, v94
	v_exp_f32_e64 v90, -v90
	v_mul_f32_e32 v84, v80, v84
	v_exp_f32_e64 v80, -v80
	v_rcp_f32_e32 v73, v73
	v_mul_f32_e32 v56, v60, v56
	v_mul_f32_e32 v60, v57, v61
	v_exp_f32_e64 v57, -v57
	v_add_f32_e32 v40, 1.0, v40
	v_rcp_f32_e32 v40, v40
	v_mul_f32_e32 v28, v24, v28
	v_exp_f32_e64 v24, -v24
	v_add_f32_e32 v123, 1.0, v123
	v_add_f32_e32 v113, 1.0, v113
	v_rcp_f32_e32 v123, v123
	v_rcp_f32_e32 v113, v113
	v_mul_f32_e32 v105, v105, v106
	v_mul_f32_e32 v106, v107, v111
	v_exp_f32_e64 v107, -v107
	v_mul_f32_e32 v96, v100, v96
	v_mul_f32_e32 v100, v97, v101
	v_exp_f32_e64 v97, -v97
	v_add_f32_e32 v90, 1.0, v90
	v_add_f32_e32 v80, 1.0, v80
	v_mul_f32_e32 v73, v76, v73
	v_add_f32_e32 v57, 1.0, v57
	v_rcp_f32_e32 v90, v90
	v_rcp_f32_e32 v80, v80
	v_cvt_pk_bf16_f32 v72, v72, v73
	v_mul_f32_e32 v73, v74, v78
	v_exp_f32_e64 v74, -v74
; __device__ __forceinline__ unsigned pk2(float lo, float hi) { unsigned r; asm("v_cvt_pk_bf16_f32 %0, %1, %2" : "=v"(r) : "v"(lo), "v"(hi)); return r; }
;     static __device__ __forceinline__ float sg(float g, float u) { return (g * u) * __builtin_amdgcn_rcpf(1.f + __builtin_amdgcn_exp2f(-g)); }
;     __device__ __forceinline__ void operator()(const f32x4 (&acc)[2][2][4][2], const Unit& u, int wr, int wc, int fr, int fq) const {
; #pragma unroll
;         for (int ai = 0; ai < 2; ++ai)
; #pragma unroll
;             for (int m = 0; m < 4; ++m) {
;                 const int row = u.pm * BM + ai * HALF + wr * 64 + m * 16 + fr;
;                 const f32x4 g0 = acc[ai][0][m][0], u0 = acc[ai][0][m][1], g1 = acc[ai][1][m][0], u1 = acc[ai][1][m][1];
;                 u32x4 o; o.x = pk2(sg(g0[0], u0[0]), sg(g0[1], u0[1])); o.y = pk2(sg(g0[2], u0[2]), sg(g0[3], u0[3]));
;                 o.z = pk2(sg(g1[0], u1[0]), sg(g1[1], u1[1])); o.w = pk2(sg(g1[2], u1[2]), sg(g1[3], u1[3]));
;                 *(u32x4*)(O + (size_t)row * DFF + u.pn * 128 + wc * 32 + fq * 8) = o;
	v_mul_f32_e32 v68, v64, v68
	v_exp_f32_e64 v64, -v64
	v_rcp_f32_e32 v57, v57
	v_mul_f32_e32 v40, v44, v40
	v_mul_f32_e32 v44, v41, v45
	v_exp_f32_e64 v41, -v41
	v_add_f32_e32 v24, 1.0, v24
	v_rcp_f32_e32 v24, v24
	v_mul_f32_e32 v12, v8, v12
	v_exp_f32_e64 v8, -v8
	v_mul_f32_e32 v122, v122, v123
	v_mul_f32_e32 v113, v116, v113
	v_cvt_pk_bf16_f32 v121, v121, v122
	v_cvt_pk_bf16_f32 v122, v112, v113
	v_exp_f32_e64 v113, -v114
	v_add_f32_e32 v107, 1.0, v107
	v_add_f32_e32 v97, 1.0, v97
	v_mul_f32_e32 v112, v114, v118
	v_exp_f32_e64 v114, -v115
	v_rcp_f32_e32 v107, v107
	v_rcp_f32_e32 v97, v97
	v_mul_f32_e32 v89, v89, v90
	v_mul_f32_e32 v90, v91, v95
	v_exp_f32_e64 v91, -v91
	v_mul_f32_e32 v80, v84, v80
	v_mul_f32_e32 v84, v81, v85
	v_exp_f32_e64 v81, -v81
	v_add_f32_e32 v74, 1.0, v74
	v_add_f32_e32 v64, 1.0, v64
	v_mul_f32_e32 v57, v60, v57
	v_add_f32_e32 v41, 1.0, v41
	v_rcp_f32_e32 v74, v74
	v_rcp_f32_e32 v64, v64
	v_cvt_pk_bf16_f32 v56, v56, v57
	v_mul_f32_e32 v57, v58, v62
	v_exp_f32_e64 v58, -v58
	v_mul_f32_e32 v52, v48, v52
	v_exp_f32_e64 v48, -v48
	v_rcp_f32_e32 v41, v41
	v_mul_f32_e32 v24, v28, v24
	v_mul_f32_e32 v28, v25, v29
	v_exp_f32_e64 v25, -v25
	v_add_f32_e32 v8, 1.0, v8
	v_rcp_f32_e32 v8, v8
	v_add_f32_e32 v113, 1.0, v113
	v_rcp_f32_e32 v113, v113
	v_add_f32_e32 v114, 1.0, v114
	v_mul_f32_e32 v106, v106, v107
	v_mul_f32_e32 v97, v100, v97
	v_add_f32_e32 v91, 1.0, v91
	v_add_f32_e32 v81, 1.0, v81
	v_rcp_f32_e32 v114, v114
	v_cvt_pk_bf16_f32 v105, v105, v106
	v_cvt_pk_bf16_f32 v106, v96, v97
	v_exp_f32_e64 v97, -v98
	v_rcp_f32_e32 v91, v91
	v_rcp_f32_e32 v81, v81
	v_mul_f32_e32 v73, v73, v74
	v_mul_f32_e32 v74, v75, v79
	v_exp_f32_e64 v75, -v75
	v_mul_f32_e32 v64, v68, v64
	v_mul_f32_e32 v68, v65, v69
	v_exp_f32_e64 v65, -v65
	v_add_f32_e32 v58, 1.0, v58
	v_add_f32_e32 v48, 1.0, v48
	v_mul_f32_e32 v41, v44, v41
	v_add_f32_e32 v25, 1.0, v25
	v_mul_f32_e32 v96, v98, v102
	v_exp_f32_e64 v98, -v99
	v_rcp_f32_e32 v58, v58
	v_rcp_f32_e32 v48, v48
	v_cvt_pk_bf16_f32 v40, v40, v41
	v_mul_f32_e32 v41, v42, v46
	v_exp_f32_e64 v42, -v42
	v_mul_f32_e32 v36, v32, v36
	v_exp_f32_e64 v32, -v32
	v_rcp_f32_e32 v25, v25
	v_mul_f32_e32 v8, v12, v8
	v_mul_f32_e32 v12, v9, v13
	v_exp_f32_e64 v9, -v9
	v_mul_f32_e32 v112, v112, v113
	v_mul_f32_e32 v113, v115, v119
	s_lshl_b32 s16, s15, 7
	v_mul_f32_e32 v113, v113, v114
	v_add_f32_e32 v97, 1.0, v97
	v_mul_f32_e32 v90, v90, v91
	v_mul_f32_e32 v81, v84, v81
	v_add_f32_e32 v75, 1.0, v75
	v_add_f32_e32 v65, 1.0, v65
	v_lshl_add_u32 v139, s81, 8, v136
	s_ashr_i32 s17, s16, 31
	v_cvt_pk_bf16_f32 v123, v112, v113
	v_mov_b64_e32 v[112:113], s[6:7]
	v_rcp_f32_e32 v97, v97
	v_add_f32_e32 v98, 1.0, v98
	v_cvt_pk_bf16_f32 v89, v89, v90
	v_cvt_pk_bf16_f32 v90, v80, v81
	v_exp_f32_e64 v81, -v82
	v_rcp_f32_e32 v75, v75
	v_rcp_f32_e32 v65, v65
	v_mul_f32_e32 v57, v57, v58
	v_mul_f32_e32 v58, v59, v63
	v_exp_f32_e64 v59, -v59
	v_mul_f32_e32 v48, v52, v48
	v_mul_f32_e32 v52, v49, v53
	v_exp_f32_e64 v49, -v49
	v_add_f32_e32 v42, 1.0, v42
	v_add_f32_e32 v32, 1.0, v32
	v_mul_f32_e32 v25, v28, v25
	v_add_f32_e32 v9, 1.0, v9
	v_mad_i64_i32 v[114:115], s[20:21], v139, s33, v[112:113]
	s_lshl_b64 s[16:17], s[16:17], 1
	v_rcp_f32_e32 v98, v98
	v_mul_f32_e32 v80, v82, v86
	v_exp_f32_e64 v82, -v83
	v_rcp_f32_e32 v42, v42
	v_rcp_f32_e32 v32, v32
	v_cvt_pk_bf16_f32 v24, v24, v25
	v_mul_f32_e32 v25, v26, v30
	v_exp_f32_e64 v26, -v26
	v_mul_f32_e32 v20, v16, v20
	v_exp_f32_e64 v16, -v16
	v_rcp_f32_e32 v9, v9
	v_lshl_add_u64 v[114:115], v[114:115], 0, s[16:17]
	v_lshl_add_u64 v[114:115], v[114:115], 0, s[66:67]
	v_lshl_add_u64 v[114:115], v[114:115], 0, v[144:145]
	v_mul_f32_e32 v96, v96, v97
	v_mul_f32_e32 v97, v99, v103
	v_add_f32_e32 v81, 1.0, v81
	v_mul_f32_e32 v74, v74, v75
	v_mul_f32_e32 v65, v68, v65
	v_add_f32_e32 v59, 1.0, v59
	v_add_f32_e32 v49, 1.0, v49
	global_store_dwordx4 v[114:115], v[120:123], off
	v_or_b32_e32 v114, 16, v139
	v_mul_f32_e32 v97, v97, v98
	v_rcp_f32_e32 v81, v81
	v_add_f32_e32 v82, 1.0, v82
	v_cvt_pk_bf16_f32 v73, v73, v74
	v_cvt_pk_bf16_f32 v74, v64, v65
	v_exp_f32_e64 v65, -v66
	v_rcp_f32_e32 v59, v59
	v_rcp_f32_e32 v49, v49
	v_mul_f32_e32 v41, v41, v42
	v_mul_f32_e32 v42, v43, v47
	v_exp_f32_e64 v43, -v43
	v_mul_f32_e32 v32, v36, v32
	v_mul_f32_e32 v36, v33, v37
	v_exp_f32_e64 v33, -v33
	v_add_f32_e32 v26, 1.0, v26
	v_add_f32_e32 v16, 1.0, v16
	v_mul_f32_e32 v9, v12, v9
	v_cvt_pk_bf16_f32 v107, v96, v97
	v_mad_i64_i32 v[96:97], s[20:21], v114, s33, v[112:113]
	v_rcp_f32_e32 v82, v82
	v_mul_f32_e32 v64, v66, v70
	v_exp_f32_e64 v66, -v67
	v_rcp_f32_e32 v26, v26
	v_rcp_f32_e32 v16, v16
	v_cvt_pk_bf16_f32 v8, v8, v9
	v_mul_f32_e32 v9, v10, v14
	v_exp_f32_e64 v10, -v10
	v_mul_f32_e32 v4, v0, v4
	v_exp_f32_e64 v0, -v0
	v_lshl_add_u64 v[96:97], v[96:97], 0, s[16:17]
; __device__ __forceinline__ unsigned pk2(float lo, float hi) { unsigned r; asm("v_cvt_pk_bf16_f32 %0, %1, %2" : "=v"(r) : "v"(lo), "v"(hi)); return r; }
;     static __device__ __forceinline__ float sg(float g, float u) { return (g * u) * __builtin_amdgcn_rcpf(1.f + __builtin_amdgcn_exp2f(-g)); }
;     __device__ __forceinline__ void operator()(const f32x4 (&acc)[2][2][4][2], const Unit& u, int wr, int wc, int fr, int fq) const {
; #pragma unroll
;         for (int ai = 0; ai < 2; ++ai)
; #pragma unroll
;             for (int m = 0; m < 4; ++m) {
;                 const int row = u.pm * BM + ai * HALF + wr * 64 + m * 16 + fr;
;                 const f32x4 g0 = acc[ai][0][m][0], u0 = acc[ai][0][m][1], g1 = acc[ai][1][m][0], u1 = acc[ai][1][m][1];
;                 u32x4 o; o.x = pk2(sg(g0[0], u0[0]), sg(g0[1], u0[1])); o.y = pk2(sg(g0[2], u0[2]), sg(g0[3], u0[3]));
;                 o.z = pk2(sg(g1[0], u1[0]), sg(g1[1], u1[1])); o.w = pk2(sg(g1[2], u1[2]), sg(g1[3], u1[3]));
;                 *(u32x4*)(O + (size_t)row * DFF + u.pn * 128 + wc * 32 + fq * 8) = o;
	v_lshl_add_u64 v[96:97], v[96:97], 0, s[66:67]
	v_lshl_add_u64 v[96:97], v[96:97], 0, v[144:145]
	v_mul_f32_e32 v80, v80, v81
	v_mul_f32_e32 v81, v83, v87
	v_add_f32_e32 v65, 1.0, v65
	v_mul_f32_e32 v58, v58, v59
	v_mul_f32_e32 v49, v52, v49
	v_add_f32_e32 v43, 1.0, v43
	v_add_f32_e32 v33, 1.0, v33
	global_store_dwordx4 v[96:97], v[104:107], off
	v_or_b32_e32 v96, 32, v139
	v_mul_f32_e32 v81, v81, v82
	v_rcp_f32_e32 v65, v65
	v_add_f32_e32 v66, 1.0, v66
	v_cvt_pk_bf16_f32 v57, v57, v58
	v_cvt_pk_bf16_f32 v58, v48, v49
	v_exp_f32_e64 v49, -v50
	v_rcp_f32_e32 v43, v43
	v_rcp_f32_e32 v33, v33
	v_mul_f32_e32 v25, v25, v26
	v_mul_f32_e32 v26, v27, v31
	v_exp_f32_e64 v27, -v27
	v_mul_f32_e32 v16, v20, v16
	v_mul_f32_e32 v20, v17, v21
	v_exp_f32_e64 v17, -v17
	v_add_f32_e32 v10, 1.0, v10
	v_add_f32_e32 v0, 1.0, v0
	v_cvt_pk_bf16_f32 v91, v80, v81
	v_mad_i64_i32 v[80:81], s[20:21], v96, s33, v[112:113]
	v_rcp_f32_e32 v66, v66
	v_mul_f32_e32 v48, v50, v54
	v_exp_f32_e64 v50, -v51
	v_rcp_f32_e32 v10, v10
	v_rcp_f32_e32 v0, v0
	v_lshl_add_u64 v[80:81], v[80:81], 0, s[16:17]
	v_lshl_add_u64 v[80:81], v[80:81], 0, s[66:67]
	v_lshl_add_u64 v[80:81], v[80:81], 0, v[144:145]
	v_mul_f32_e32 v64, v64, v65
	v_mul_f32_e32 v65, v67, v71
	v_add_f32_e32 v49, 1.0, v49
	v_mul_f32_e32 v42, v42, v43
	v_mul_f32_e32 v33, v36, v33
	v_add_f32_e32 v27, 1.0, v27
	v_add_f32_e32 v17, 1.0, v17
	global_store_dwordx4 v[80:81], v[88:91], off
	v_or_b32_e32 v80, 48, v139
	v_mul_f32_e32 v65, v65, v66
	v_rcp_f32_e32 v49, v49
	v_add_f32_e32 v50, 1.0, v50
	v_cvt_pk_bf16_f32 v41, v41, v42
	v_cvt_pk_bf16_f32 v42, v32, v33
	v_exp_f32_e64 v33, -v34
	v_rcp_f32_e32 v27, v27
	v_rcp_f32_e32 v17, v17
	v_mul_f32_e32 v9, v9, v10
	v_mul_f32_e32 v10, v11, v15
	v_exp_f32_e64 v11, -v11
	v_mul_f32_e32 v0, v4, v0
	v_mul_f32_e32 v4, v1, v5
	v_exp_f32_e64 v1, -v1
	v_cvt_pk_bf16_f32 v75, v64, v65
	v_mad_i64_i32 v[64:65], s[20:21], v80, s33, v[112:113]
	v_rcp_f32_e32 v50, v50
	v_mul_f32_e32 v32, v34, v38
	v_exp_f32_e64 v34, -v35
	v_lshl_add_u64 v[64:65], v[64:65], 0, s[16:17]
	v_lshl_add_u64 v[64:65], v[64:65], 0, s[66:67]
	v_lshl_add_u64 v[64:65], v[64:65], 0, v[144:145]
	v_mul_f32_e32 v48, v48, v49
	v_mul_f32_e32 v49, v51, v55
	v_add_f32_e32 v33, 1.0, v33
	v_mul_f32_e32 v26, v26, v27
	v_mul_f32_e32 v17, v20, v17
	v_add_f32_e32 v11, 1.0, v11
	v_add_f32_e32 v1, 1.0, v1
	global_store_dwordx4 v[64:65], v[72:75], off
	v_add_u32_e32 v64, 0x80, v139
	v_mul_f32_e32 v49, v49, v50
	v_rcp_f32_e32 v33, v33
	v_add_f32_e32 v34, 1.0, v34
	v_cvt_pk_bf16_f32 v25, v25, v26
	v_cvt_pk_bf16_f32 v26, v16, v17
	v_exp_f32_e64 v17, -v18
	v_rcp_f32_e32 v11, v11
	v_rcp_f32_e32 v1, v1
	v_cvt_pk_bf16_f32 v59, v48, v49
	v_mad_i64_i32 v[48:49], s[20:21], v64, s33, v[112:113]
	v_rcp_f32_e32 v34, v34
	v_mul_f32_e32 v16, v18, v22
	v_exp_f32_e64 v18, -v19
	v_lshl_add_u64 v[48:49], v[48:49], 0, s[16:17]
	v_lshl_add_u64 v[48:49], v[48:49], 0, s[66:67]
	v_lshl_add_u64 v[48:49], v[48:49], 0, v[144:145]
	v_mul_f32_e32 v32, v32, v33
	v_mul_f32_e32 v33, v35, v39
	v_add_f32_e32 v17, 1.0, v17
	v_mul_f32_e32 v10, v10, v11
	v_mul_f32_e32 v1, v4, v1
	global_store_dwordx4 v[48:49], v[56:59], off
	v_add_u32_e32 v48, 0x90, v139
	v_mul_f32_e32 v33, v33, v34
	v_rcp_f32_e32 v17, v17
	v_add_f32_e32 v18, 1.0, v18
	v_cvt_pk_bf16_f32 v9, v9, v10
	v_cvt_pk_bf16_f32 v10, v0, v1
	v_exp_f32_e64 v1, -v2
	v_cvt_pk_bf16_f32 v43, v32, v33
	v_mad_i64_i32 v[32:33], s[20:21], v48, s33, v[112:113]
	v_rcp_f32_e32 v18, v18
	v_mul_f32_e32 v0, v2, v6
	v_exp_f32_e64 v2, -v3
	v_lshl_add_u64 v[32:33], v[32:33], 0, s[16:17]
	v_lshl_add_u64 v[32:33], v[32:33], 0, s[66:67]
	v_lshl_add_u64 v[32:33], v[32:33], 0, v[144:145]
	v_mul_f32_e32 v16, v16, v17
	v_mul_f32_e32 v17, v19, v23
	v_add_f32_e32 v1, 1.0, v1
	global_store_dwordx4 v[32:33], v[40:43], off
	v_add_u32_e32 v32, 0xa0, v139
	v_mul_f32_e32 v17, v17, v18
	v_rcp_f32_e32 v1, v1
	v_add_f32_e32 v2, 1.0, v2
	v_cvt_pk_bf16_f32 v27, v16, v17
	v_mad_i64_i32 v[16:17], s[20:21], v32, s33, v[112:113]
	v_rcp_f32_e32 v2, v2
	v_lshl_add_u64 v[16:17], v[16:17], 0, s[16:17]
	v_lshl_add_u64 v[16:17], v[16:17], 0, s[66:67]
	v_lshl_add_u64 v[16:17], v[16:17], 0, v[144:145]
	v_mul_f32_e32 v0, v0, v1
	v_mul_f32_e32 v1, v3, v7
	global_store_dwordx4 v[16:17], v[24:27], off
	v_add_u32_e32 v16, 0xb0, v139
	v_mul_f32_e32 v1, v1, v2
	v_cvt_pk_bf16_f32 v11, v0, v1
	v_mad_i64_i32 v[0:1], s[20:21], v16, s33, v[112:113]
	v_lshl_add_u64 v[0:1], v[0:1], 0, s[16:17]
	v_lshl_add_u64 v[0:1], v[0:1], 0, s[66:67]
	v_lshl_add_u64 v[0:1], v[0:1], 0, v[144:145]
	s_and_b64 vcc, exec, s[0:1]
	s_mov_b32 s15, s8
	s_mov_b32 s81, s80
	s_mov_b64 s[20:21], s[12:13]
	s_mov_b64 s[16:17], s[10:11]
	global_store_dwordx4 v[0:1], v[8:11], off
	s_cbranch_vccz .LBB0_1391
	s_waitcnt vmcnt(0)
	s_cmpk_gt_u32 s23, 0xff
	s_cbranch_scc1 .LBB0_1398
	s_barrier

; #define PG8_STAGE(bufoff, gbase, voff) do { _Pragma("unroll") for (int _i = 0; _i < 2; ++_i) \
;         __builtin_amdgcn_global_load_lds((const unsigned*)((const char*)(gbase) + (voff)[_i]), (LAS unsigned*)(lds + (bufoff) + ldsw + _i * 8192), 16, 0, 0); } while (0)
; #define PG8_LDA(dst, b, h) do { _Pragma("unroll") for (int m = 0; m < 4; ++m) _Pragma("unroll") for (int k = 0; k < 2; ++k) dst[m][k] = *(const LAS bf16x8*)(lds + PG8_SA(b, h) + aoff + m * 2048 + k * 1024); } while (0)
; #define PG8_LDB(dst, b, h) do { _Pragma("unroll") for (int n = 0; n < 2; ++n) _Pragma("unroll") for (int k = 0; k < 2; ++k) dst[n][k] = *(const LAS bf16x8*)(lds + PG8_SB(b, h) + boff + n * 2048 + k * 1024); } while (0)
; #define PG8_MMA(ai, bj, At, Bt) do { __builtin_amdgcn_s_setprio(1); _Pragma("unroll") for (int m = 0; m < 4; ++m) _Pragma("unroll") for (int n = 0; n < 2; ++n) _Pragma("unroll") for (int k = 0; k < 2; ++k) \
;         acc[ai][bj][m][n] = __builtin_amdgcn_mfma_f32_16x16x32_bf16(Bt[n][k], At[m][k], acc[ai][bj][m][n], 0, 0, 0); __builtin_amdgcn_s_setprio(0); } while (0)
; #define PG8_WAIT_L(n) asm volatile("s_waitcnt lgkmcnt(" #n ")" ::: "memory")
; #define PG8_BAR __builtin_amdgcn_s_barrier()
; #define PG8_SCHED __builtin_amdgcn_sched_barrier(0)
; template <class Epi>
; __device__ __forceinline__ void gemm_phase(LAS unsigned char* lds, const Gemm g, const StaticOrder& S, const Epi& E) {
;     ...
;         const char* nA = has_next ? g.arow(nxt.pm) : cA; const char* nB = has_next ? (const char*)g.Bt + (size_t)nxt.pn * tB : cB;
;         for (int t = 0; t < nt; t += 2) {
;             const bool last = (t == nt - 2);
;             const char* a1 = cA + (size_t)(t + 1) * kstep;
;             const char* a2 = last ? nA : cA + (size_t)(t + 2) * kstep; const char* b2 = last ? nB : cB + (size_t)(t + 2) * kstep;
;             const char* a3 = a2 + kstep; const char* b3 = b2 + kstep;
;             PG8_LDB(B0, 0, 0); PG8_SCHED; PG8_LDA(At, 0, 0); PG8_STAGE(PG8_SA(1, 1), a1 + hA, voffA);
;             PG8_WAIT_L(8); PG8_BAR; PG8_WAIT_L(0); PG8_MMA(0, 0, At, B0); PG8_BAR; PG8_SCHED;
;             PG8_LDB(B1, 0, 1); PG8_STAGE(PG8_SB(0, 0), b2, voffB);
;             PG8_BAR; PG8_WAIT_L(0); PG8_MMA(0, 1, At, B1); PG8_BAR;
;             PG8_LDA(At, 0, 1); PG8_STAGE(PG8_SA(0, 0), a2, voffA);
;             PG8_BAR; PG8_WAIT_L(0); PG8_MMA(1, 0, At, B0); PG8_BAR; PG8_SCHED;
.LBB0_1462:
	s_add_u32 s12, s10, 0x100
	s_addc_u32 s13, s11, 0
	s_add_i32 s26, 0, 0x10000
	v_add_u32_e32 v142, s26, v139
	ds_read_b128 v[134:137], v142
	ds_read_b128 v[146:149], v142 offset:1024
	ds_read_b128 v[150:153], v142 offset:2048
	ds_read_b128 v[154:157], v142 offset:3072
	s_cmp_eq_u32 s78, 40
	s_cselect_b32 s21, s5, s13
	s_cselect_b32 s20, s4, s12
	s_cselect_b32 s17, s7, s25
	s_cselect_b32 s16, s6, s24
	v_lshl_add_u64 v[142:143], s[10:11], 0, v[130:131]
	s_add_i32 m0, s63, 0xc000
	ds_read_b128 v[158:161], v141
	ds_read_b128 v[162:165], v141 offset:1024
	ds_read_b128 v[166:169], v141 offset:2048
	ds_read_b128 v[170:173], v141 offset:3072
	ds_read_b128 v[174:177], v141 offset:4096
	ds_read_b128 v[178:181], v141 offset:5120
	ds_read_b128 v[182:185], v141 offset:6144
	ds_read_b128 v[186:189], v141 offset:7168
	global_load_lds_dwordx4 v[142:143], off
	s_add_i32 m0, s63, 0xe000
	v_lshl_add_u64 v[142:143], s[10:11], 0, v[132:133]
	global_load_lds_dwordx4 v[142:143], off
	s_waitcnt lgkmcnt(8)
	s_barrier
	s_waitcnt lgkmcnt(0)
	s_setprio 1
	v_mfma_f32_16x16x32_bf16 v[124:127], v[134:137], v[158:161], v[124:127]
	v_mfma_f32_16x16x32_bf16 v[120:123], v[150:153], v[158:161], v[120:123]
	v_mfma_f32_16x16x32_bf16 v[116:119], v[134:137], v[166:169], v[116:119]
	v_mfma_f32_16x16x32_bf16 v[108:111], v[150:153], v[166:169], v[108:111]
	v_mfma_f32_16x16x32_bf16 v[100:103], v[134:137], v[174:177], v[100:103]
	v_mfma_f32_16x16x32_bf16 v[92:95], v[150:153], v[174:177], v[92:95]
	v_mfma_f32_16x16x32_bf16 v[84:87], v[134:137], v[182:185], v[84:87]
	v_mfma_f32_16x16x32_bf16 v[76:79], v[150:153], v[182:185], v[76:79]
	v_mfma_f32_16x16x32_bf16 v[124:127], v[146:149], v[162:165], v[124:127]
	v_mfma_f32_16x16x32_bf16 v[120:123], v[154:157], v[162:165], v[120:123]
	v_mfma_f32_16x16x32_bf16 v[116:119], v[146:149], v[170:173], v[116:119]
	v_mfma_f32_16x16x32_bf16 v[108:111], v[154:157], v[170:173], v[108:111]
	v_mfma_f32_16x16x32_bf16 v[100:103], v[146:149], v[178:181], v[100:103]
	v_mfma_f32_16x16x32_bf16 v[92:95], v[154:157], v[178:181], v[92:95]
	v_mfma_f32_16x16x32_bf16 v[84:87], v[146:149], v[186:189], v[84:87]
	v_mfma_f32_16x16x32_bf16 v[76:79], v[154:157], v[186:189], v[76:79]
	s_setprio 0
	s_barrier
	s_add_i32 s27, 0, 0x14000
	v_add_u32_e32 v142, s27, v139
	s_add_i32 s10, s26, s61
	ds_read_b128 v[196:199], v142
	ds_read_b128 v[200:203], v142 offset:1024
	ds_read_b128 v[204:207], v142 offset:2048
	ds_read_b128 v[214:217], v142 offset:3072
	v_lshl_add_u64 v[142:143], s[16:17], 0, v[144:145]
	s_mov_b32 m0, s10
	v_lshl_add_u64 v[192:193], s[16:17], 0, v[128:129]
	global_load_lds_dwordx4 v[142:143], off
	s_add_i32 m0, s10, 0x2000
	s_nop 0
	global_load_lds_dwordx4 v[192:193], off
	s_barrier
	s_waitcnt lgkmcnt(0)
	s_setprio 1
	v_mfma_f32_16x16x32_bf16 v[112:115], v[196:199], v[158:161], v[112:115]
	v_mfma_f32_16x16x32_bf16 v[104:107], v[204:207], v[158:161], v[104:107]
	v_mfma_f32_16x16x32_bf16 v[96:99], v[196:199], v[166:169], v[96:99]
	v_mfma_f32_16x16x32_bf16 v[88:91], v[204:207], v[166:169], v[88:91]
	v_mfma_f32_16x16x32_bf16 v[80:83], v[196:199], v[174:177], v[80:83]
	v_mfma_f32_16x16x32_bf16 v[72:75], v[204:207], v[174:177], v[72:75]
	v_mfma_f32_16x16x32_bf16 v[68:71], v[196:199], v[182:185], v[68:71]
	v_mfma_f32_16x16x32_bf16 v[64:67], v[204:207], v[182:185], v[64:67]
	v_mfma_f32_16x16x32_bf16 v[112:115], v[200:203], v[162:165], v[112:115]
	v_mfma_f32_16x16x32_bf16 v[104:107], v[214:217], v[162:165], v[104:107]
	v_mfma_f32_16x16x32_bf16 v[96:99], v[200:203], v[170:173], v[96:99]
	v_mfma_f32_16x16x32_bf16 v[88:91], v[214:217], v[170:173], v[88:91]
	v_mfma_f32_16x16x32_bf16 v[80:83], v[200:203], v[178:181], v[80:83]
	v_mfma_f32_16x16x32_bf16 v[72:75], v[214:217], v[178:181], v[72:75]
	v_mfma_f32_16x16x32_bf16 v[68:71], v[200:203], v[186:189], v[68:71]
	v_mfma_f32_16x16x32_bf16 v[64:67], v[214:217], v[186:189], v[64:67]
	s_setprio 0
	s_mov_b32 m0, s63
	v_lshl_add_u64 v[218:219], s[20:21], 0, v[144:145]
	s_barrier
	ds_read_b128 v[158:161], v141 offset:16384
	ds_read_b128 v[162:165], v141 offset:17408
	ds_read_b128 v[166:169], v141 offset:18432
	ds_read_b128 v[170:173], v141 offset:19456
	ds_read_b128 v[174:177], v141 offset:20480
	ds_read_b128 v[178:181], v141 offset:21504
	ds_read_b128 v[182:185], v141 offset:22528
	ds_read_b128 v[186:189], v141 offset:23552
	global_load_lds_dwordx4 v[218:219], off
	s_mov_b32 m0, s64
	v_lshl_add_u64 v[220:221], s[20:21], 0, v[128:129]
	global_load_lds_dwordx4 v[220:221], off
	s_barrier
	s_waitcnt lgkmcnt(0)
	s_setprio 1
	v_mfma_f32_16x16x32_bf16 v[60:63], v[134:137], v[158:161], v[60:63]
	v_mfma_f32_16x16x32_bf16 v[56:59], v[150:153], v[158:161], v[56:59]
	v_mfma_f32_16x16x32_bf16 v[52:55], v[134:137], v[166:169], v[52:55]
	v_mfma_f32_16x16x32_bf16 v[44:47], v[150:153], v[166:169], v[44:47]
	v_mfma_f32_16x16x32_bf16 v[36:39], v[134:137], v[174:177], v[36:39]
	v_mfma_f32_16x16x32_bf16 v[28:31], v[150:153], v[174:177], v[28:31]
	v_mfma_f32_16x16x32_bf16 v[20:23], v[134:137], v[182:185], v[20:23]
	v_mfma_f32_16x16x32_bf16 v[12:15], v[150:153], v[182:185], v[12:15]
	v_mfma_f32_16x16x32_bf16 v[60:63], v[146:149], v[162:165], v[60:63]
	v_mfma_f32_16x16x32_bf16 v[56:59], v[154:157], v[162:165], v[56:59]
	v_mfma_f32_16x16x32_bf16 v[52:55], v[146:149], v[170:173], v[52:55]
	v_mfma_f32_16x16x32_bf16 v[44:47], v[154:157], v[170:173], v[44:47]
	v_mfma_f32_16x16x32_bf16 v[36:39], v[146:149], v[178:181], v[36:39]
	v_mfma_f32_16x16x32_bf16 v[28:31], v[154:157], v[178:181], v[28:31]
	v_mfma_f32_16x16x32_bf16 v[20:23], v[146:149], v[186:189], v[20:23]
	v_mfma_f32_16x16x32_bf16 v[12:15], v[154:157], v[186:189], v[12:15]
	s_setprio 0
	s_barrier
; #define PG8_STAGE(bufoff, gbase, voff) do { _Pragma("unroll") for (int _i = 0; _i < 2; ++_i) \
;         __builtin_amdgcn_global_load_lds((const unsigned*)((const char*)(gbase) + (voff)[_i]), (LAS unsigned*)(lds + (bufoff) + ldsw + _i * 8192), 16, 0, 0); } while (0)
; #define PG8_LDA(dst, b, h) do { _Pragma("unroll") for (int m = 0; m < 4; ++m) _Pragma("unroll") for (int k = 0; k < 2; ++k) dst[m][k] = *(const LAS bf16x8*)(lds + PG8_SA(b, h) + aoff + m * 2048 + k * 1024); } while (0)
; #define PG8_LDB(dst, b, h) do { _Pragma("unroll") for (int n = 0; n < 2; ++n) _Pragma("unroll") for (int k = 0; k < 2; ++k) dst[n][k] = *(const LAS bf16x8*)(lds + PG8_SB(b, h) + boff + n * 2048 + k * 1024); } while (0)
; #define PG8_MMA(ai, bj, At, Bt) do { __builtin_amdgcn_s_setprio(1); _Pragma("unroll") for (int m = 0; m < 4; ++m) _Pragma("unroll") for (int n = 0; n < 2; ++n) _Pragma("unroll") for (int k = 0; k < 2; ++k) \
;         acc[ai][bj][m][n] = __builtin_amdgcn_mfma_f32_16x16x32_bf16(Bt[n][k], At[m][k], acc[ai][bj][m][n], 0, 0, 0); __builtin_amdgcn_s_setprio(0); } while (0)
; #define PG8_WAIT_V(n) asm volatile("s_waitcnt vmcnt(" #n ")" ::: "memory")
; #define PG8_WAIT_L(n) asm volatile("s_waitcnt lgkmcnt(" #n ")" ::: "memory")
; #define PG8_BAR __builtin_amdgcn_s_barrier()
; #define PG8_SCHED __builtin_amdgcn_sched_barrier(0)
; template <class Epi>
; __device__ __forceinline__ void gemm_phase(LAS unsigned char* lds, const Gemm g, const StaticOrder& S, const Epi& E) {
;     ...
;             PG8_STAGE(PG8_SB(0, 1), b2 + hB, voffB);
;             PG8_WAIT_V(6); PG8_BAR; PG8_MMA(1, 1, At, B1); PG8_BAR;
;             PG8_LDB(B0, 1, 0); PG8_SCHED; PG8_LDA(At, 1, 0); PG8_STAGE(PG8_SA(0, 1), a2 + hA, voffA);
;             PG8_WAIT_L(8); PG8_BAR; PG8_WAIT_L(0); PG8_MMA(0, 0, At, B0); PG8_BAR; PG8_SCHED;
;             PG8_LDB(B1, 1, 1); PG8_STAGE(PG8_SB(1, 0), b3, voffB);
;             PG8_BAR; PG8_WAIT_L(0); PG8_MMA(0, 1, At, B1); PG8_BAR;
;             PG8_LDA(At, 1, 1); PG8_STAGE(PG8_SA(1, 0), a3, voffA);
	s_add_u32 s10, s16, 0xb0000
	s_addc_u32 s11, s17, 0
	s_add_i32 s26, s27, s61
	s_mov_b32 m0, s26
	v_lshl_add_u64 v[134:135], s[10:11], 0, v[144:145]
	global_load_lds_dwordx4 v[134:135], off
	s_add_i32 m0, s26, 0x2000
	v_lshl_add_u64 v[134:135], s[10:11], 0, v[128:129]
	global_load_lds_dwordx4 v[134:135], off
	s_waitcnt vmcnt(6)
	s_barrier
	s_setprio 1
	v_mfma_f32_16x16x32_bf16 v[48:51], v[196:199], v[158:161], v[48:51]
	v_mfma_f32_16x16x32_bf16 v[40:43], v[204:207], v[158:161], v[40:43]
	v_mfma_f32_16x16x32_bf16 v[32:35], v[196:199], v[166:169], v[32:35]
	v_mfma_f32_16x16x32_bf16 v[24:27], v[204:207], v[166:169], v[24:27]
	v_mfma_f32_16x16x32_bf16 v[16:19], v[196:199], v[174:177], v[16:19]
	v_mfma_f32_16x16x32_bf16 v[8:11], v[204:207], v[174:177], v[8:11]
	v_mfma_f32_16x16x32_bf16 v[4:7], v[196:199], v[182:185], v[4:7]
	v_mfma_f32_16x16x32_bf16 v[0:3], v[204:207], v[182:185], v[0:3]
	v_mfma_f32_16x16x32_bf16 v[48:51], v[200:203], v[162:165], v[48:51]
	v_mfma_f32_16x16x32_bf16 v[40:43], v[214:217], v[162:165], v[40:43]
	v_mfma_f32_16x16x32_bf16 v[32:35], v[200:203], v[170:173], v[32:35]
	v_mfma_f32_16x16x32_bf16 v[24:27], v[214:217], v[170:173], v[24:27]
	v_mfma_f32_16x16x32_bf16 v[16:19], v[200:203], v[178:181], v[16:19]
	v_mfma_f32_16x16x32_bf16 v[8:11], v[214:217], v[178:181], v[8:11]
	v_mfma_f32_16x16x32_bf16 v[4:7], v[200:203], v[186:189], v[4:7]
	v_mfma_f32_16x16x32_bf16 v[0:3], v[214:217], v[186:189], v[0:3]
	s_setprio 0
	s_add_i32 s26, 0, 0x18000
	v_add_u32_e32 v154, s26, v139
	s_barrier
	ds_read_b128 v[134:137], v154
	ds_read_b128 v[146:149], v154 offset:1024
	ds_read_b128 v[150:153], v154 offset:2048
	ds_read_b128 v[154:157], v154 offset:3072
	s_add_u32 s10, s20, 0xb0000
	s_addc_u32 s11, s21, 0
	s_mov_b32 m0, s65
	v_lshl_add_u64 v[196:197], s[10:11], 0, v[144:145]
	ds_read_b128 v[158:161], v141 offset:32768
	ds_read_b128 v[162:165], v141 offset:33792
	ds_read_b128 v[166:169], v141 offset:34816
	ds_read_b128 v[170:173], v141 offset:35840
	ds_read_b128 v[174:177], v141 offset:36864
	ds_read_b128 v[178:181], v141 offset:37888
	ds_read_b128 v[182:185], v141 offset:38912
	ds_read_b128 v[186:189], v141 offset:39936
	global_load_lds_dwordx4 v[196:197], off
	s_mov_b32 m0, s68
	v_lshl_add_u64 v[196:197], s[10:11], 0, v[128:129]
	global_load_lds_dwordx4 v[196:197], off
	s_waitcnt lgkmcnt(8)
	s_barrier
	s_waitcnt lgkmcnt(0)
	s_setprio 1
	v_mfma_f32_16x16x32_bf16 v[124:127], v[134:137], v[158:161], v[124:127]
	v_mfma_f32_16x16x32_bf16 v[120:123], v[150:153], v[158:161], v[120:123]
	v_mfma_f32_16x16x32_bf16 v[116:119], v[134:137], v[166:169], v[116:119]
	v_mfma_f32_16x16x32_bf16 v[108:111], v[150:153], v[166:169], v[108:111]
	v_mfma_f32_16x16x32_bf16 v[100:103], v[134:137], v[174:177], v[100:103]
	v_mfma_f32_16x16x32_bf16 v[92:95], v[150:153], v[174:177], v[92:95]
	v_mfma_f32_16x16x32_bf16 v[84:87], v[134:137], v[182:185], v[84:87]
	v_mfma_f32_16x16x32_bf16 v[76:79], v[150:153], v[182:185], v[76:79]
	v_mfma_f32_16x16x32_bf16 v[124:127], v[146:149], v[162:165], v[124:127]
	v_mfma_f32_16x16x32_bf16 v[120:123], v[154:157], v[162:165], v[120:123]
	v_mfma_f32_16x16x32_bf16 v[116:119], v[146:149], v[170:173], v[116:119]
	v_mfma_f32_16x16x32_bf16 v[108:111], v[154:157], v[170:173], v[108:111]
	v_mfma_f32_16x16x32_bf16 v[100:103], v[146:149], v[178:181], v[100:103]
	v_mfma_f32_16x16x32_bf16 v[92:95], v[154:157], v[178:181], v[92:95]
	v_mfma_f32_16x16x32_bf16 v[84:87], v[146:149], v[186:189], v[84:87]
	v_mfma_f32_16x16x32_bf16 v[76:79], v[154:157], v[186:189], v[76:79]
	s_setprio 0
	s_barrier
	s_add_i32 s20, 0, 0x1c000
	s_add_i32 s10, s26, s61
	v_add_u32_e32 v190, s20, v139
	v_lshl_add_u64 v[142:143], v[142:143], 0, s[88:89]
	s_mov_b32 m0, s10
	ds_read_b128 v[196:199], v190
	ds_read_b128 v[200:203], v190 offset:1024
	ds_read_b128 v[204:207], v190 offset:2048
	ds_read_b128 v[214:217], v190 offset:3072
	global_load_lds_dwordx4 v[142:143], off
	s_add_i32 m0, s10, 0x2000
	v_lshl_add_u64 v[142:143], v[192:193], 0, s[88:89]
	global_load_lds_dwordx4 v[142:143], off
	s_barrier
	s_waitcnt lgkmcnt(0)
	s_setprio 1
	v_mfma_f32_16x16x32_bf16 v[112:115], v[196:199], v[158:161], v[112:115]
	v_mfma_f32_16x16x32_bf16 v[104:107], v[204:207], v[158:161], v[104:107]
	v_mfma_f32_16x16x32_bf16 v[96:99], v[196:199], v[166:169], v[96:99]
	v_mfma_f32_16x16x32_bf16 v[88:91], v[204:207], v[166:169], v[88:91]
	v_mfma_f32_16x16x32_bf16 v[80:83], v[196:199], v[174:177], v[80:83]
	v_mfma_f32_16x16x32_bf16 v[72:75], v[204:207], v[174:177], v[72:75]
	v_mfma_f32_16x16x32_bf16 v[68:71], v[196:199], v[182:185], v[68:71]
	v_mfma_f32_16x16x32_bf16 v[64:67], v[204:207], v[182:185], v[64:67]
	v_mfma_f32_16x16x32_bf16 v[112:115], v[200:203], v[162:165], v[112:115]
	v_mfma_f32_16x16x32_bf16 v[104:107], v[214:217], v[162:165], v[104:107]
	v_mfma_f32_16x16x32_bf16 v[96:99], v[200:203], v[170:173], v[96:99]
	v_mfma_f32_16x16x32_bf16 v[88:91], v[214:217], v[170:173], v[88:91]
	v_mfma_f32_16x16x32_bf16 v[80:83], v[200:203], v[178:181], v[80:83]
	v_mfma_f32_16x16x32_bf16 v[72:75], v[214:217], v[178:181], v[72:75]
	v_mfma_f32_16x16x32_bf16 v[68:71], v[200:203], v[186:189], v[68:71]
	v_mfma_f32_16x16x32_bf16 v[64:67], v[214:217], v[186:189], v[64:67]
	s_setprio 0
	s_mov_b32 m0, s69
	v_lshl_add_u64 v[142:143], v[218:219], 0, s[88:89]
	s_barrier
	ds_read_b128 v[158:161], v141 offset:49152
	ds_read_b128 v[162:165], v141 offset:50176
	ds_read_b128 v[166:169], v141 offset:51200
	ds_read_b128 v[170:173], v141 offset:52224
	ds_read_b128 v[174:177], v141 offset:53248
	ds_read_b128 v[178:181], v141 offset:54272
	ds_read_b128 v[182:185], v141 offset:55296
	ds_read_b128 v[186:189], v141 offset:56320
	global_load_lds_dwordx4 v[142:143], off
	s_mov_b32 m0, s70
	v_lshl_add_u64 v[142:143], v[220:221], 0, s[88:89]
	global_load_lds_dwordx4 v[142:143], off
	s_barrier
; #define PG8_STAGE(bufoff, gbase, voff) do { _Pragma("unroll") for (int _i = 0; _i < 2; ++_i) \
;         __builtin_amdgcn_global_load_lds((const unsigned*)((const char*)(gbase) + (voff)[_i]), (LAS unsigned*)(lds + (bufoff) + ldsw + _i * 8192), 16, 0, 0); } while (0)
; #define PG8_MMA(ai, bj, At, Bt) do { __builtin_amdgcn_s_setprio(1); _Pragma("unroll") for (int m = 0; m < 4; ++m) _Pragma("unroll") for (int n = 0; n < 2; ++n) _Pragma("unroll") for (int k = 0; k < 2; ++k) \
;         acc[ai][bj][m][n] = __builtin_amdgcn_mfma_f32_16x16x32_bf16(Bt[n][k], At[m][k], acc[ai][bj][m][n], 0, 0, 0); __builtin_amdgcn_s_setprio(0); } while (0)
; #define PG8_WAIT_V(n) asm volatile("s_waitcnt vmcnt(" #n ")" ::: "memory")
; #define PG8_WAIT_L(n) asm volatile("s_waitcnt lgkmcnt(" #n ")" ::: "memory")
; #define PG8_BAR __builtin_amdgcn_s_barrier()
; #define PG8_SCHED __builtin_amdgcn_sched_barrier(0)
; template <class Epi>
; __device__ __forceinline__ void gemm_phase(LAS unsigned char* lds, const Gemm g, const StaticOrder& S, const Epi& E) {
;     ...
;             PG8_BAR; PG8_WAIT_L(0); PG8_MMA(1, 0, At, B0); PG8_BAR; PG8_SCHED;
;             PG8_STAGE(PG8_SB(1, 1), b3 + hB, voffB);
;             PG8_WAIT_V(6); PG8_BAR; PG8_MMA(1, 1, At, B1); PG8_BAR;
	s_waitcnt lgkmcnt(0)
	s_setprio 1
	v_mfma_f32_16x16x32_bf16 v[60:63], v[134:137], v[158:161], v[60:63]
	v_mfma_f32_16x16x32_bf16 v[56:59], v[150:153], v[158:161], v[56:59]
	v_mfma_f32_16x16x32_bf16 v[52:55], v[134:137], v[166:169], v[52:55]
	v_mfma_f32_16x16x32_bf16 v[44:47], v[150:153], v[166:169], v[44:47]
	v_mfma_f32_16x16x32_bf16 v[36:39], v[134:137], v[174:177], v[36:39]
	v_mfma_f32_16x16x32_bf16 v[28:31], v[150:153], v[174:177], v[28:31]
	v_mfma_f32_16x16x32_bf16 v[20:23], v[134:137], v[182:185], v[20:23]
	v_mfma_f32_16x16x32_bf16 v[12:15], v[150:153], v[182:185], v[12:15]
	v_mfma_f32_16x16x32_bf16 v[60:63], v[146:149], v[162:165], v[60:63]
	v_mfma_f32_16x16x32_bf16 v[56:59], v[154:157], v[162:165], v[56:59]
	v_mfma_f32_16x16x32_bf16 v[52:55], v[146:149], v[170:173], v[52:55]
	v_mfma_f32_16x16x32_bf16 v[44:47], v[154:157], v[170:173], v[44:47]
	v_mfma_f32_16x16x32_bf16 v[36:39], v[146:149], v[178:181], v[36:39]
	v_mfma_f32_16x16x32_bf16 v[28:31], v[154:157], v[178:181], v[28:31]
	v_mfma_f32_16x16x32_bf16 v[20:23], v[146:149], v[186:189], v[20:23]
	v_mfma_f32_16x16x32_bf16 v[12:15], v[154:157], v[186:189], v[12:15]
	s_setprio 0
	s_barrier
	s_add_u32 s10, s16, 0xb0080
	s_addc_u32 s11, s17, 0
	s_add_i32 s16, s20, s61
	s_mov_b32 m0, s16
	v_lshl_add_u64 v[134:135], s[10:11], 0, v[144:145]
	global_load_lds_dwordx4 v[134:135], off
	s_add_i32 m0, s16, 0x2000
	v_lshl_add_u64 v[134:135], s[10:11], 0, v[128:129]
	global_load_lds_dwordx4 v[134:135], off
	s_waitcnt vmcnt(6)
	s_barrier
	s_setprio 1
	v_mfma_f32_16x16x32_bf16 v[48:51], v[196:199], v[158:161], v[48:51]
	v_mfma_f32_16x16x32_bf16 v[40:43], v[204:207], v[158:161], v[40:43]
	v_mfma_f32_16x16x32_bf16 v[32:35], v[196:199], v[166:169], v[32:35]
	v_mfma_f32_16x16x32_bf16 v[24:27], v[204:207], v[166:169], v[24:27]
	v_mfma_f32_16x16x32_bf16 v[16:19], v[196:199], v[174:177], v[16:19]
	v_mfma_f32_16x16x32_bf16 v[8:11], v[204:207], v[174:177], v[8:11]
	v_mfma_f32_16x16x32_bf16 v[4:7], v[196:199], v[182:185], v[4:7]
	v_mfma_f32_16x16x32_bf16 v[0:3], v[204:207], v[182:185], v[0:3]
	v_mfma_f32_16x16x32_bf16 v[48:51], v[200:203], v[162:165], v[48:51]
	v_mfma_f32_16x16x32_bf16 v[40:43], v[214:217], v[162:165], v[40:43]
	v_mfma_f32_16x16x32_bf16 v[32:35], v[200:203], v[170:173], v[32:35]
	v_mfma_f32_16x16x32_bf16 v[24:27], v[214:217], v[170:173], v[24:27]
	v_mfma_f32_16x16x32_bf16 v[16:19], v[200:203], v[178:181], v[16:19]
	v_mfma_f32_16x16x32_bf16 v[8:11], v[214:217], v[178:181], v[8:11]
	v_mfma_f32_16x16x32_bf16 v[4:7], v[200:203], v[186:189], v[4:7]
	v_mfma_f32_16x16x32_bf16 v[0:3], v[214:217], v[186:189], v[0:3]
	s_setprio 0
	s_add_i32 s78, s78, 2
	s_add_u32 s24, s24, 0x100
	s_addc_u32 s25, s25, 0
	s_cmp_gt_u32 s78, 41
	s_mov_b64 s[10:11], s[12:13]
	s_barrier
	s_cbranch_scc0 .LBB0_1462
; __device__ __forceinline__ unsigned pk2(float lo, float hi) { unsigned r; asm("v_cvt_pk_bf16_f32 %0, %1, %2" : "=v"(r) : "v"(lo), "v"(hi)); return r; }
;     __device__ __forceinline__ void operator()(const f32x4 (&acc)[2][2][4][2], const Unit& u, int wr, int wc, int fr, int fq) const {
;     ...
;         int c = col_t + 64 * wc + 16 * fq;
;         if (mode == 2) c = (c >> 6) * 96 + (c & 63);
; #pragma unroll
;         for (int ai = 0; ai < 2; ++ai)
; #pragma unroll
;             for (int m = 0; m < 4; ++m) {
;                 const int row = row_t + ai * HALF + wr * 64 + m * 16 + fr;
;                 bf16_t* rp = O + (size_t)row * ldc + c;
; #pragma unroll
;                 for (int bj = 0; bj < 2; ++bj) {
;                     const f32x4 v0 = acc[ai][bj][m][0], v1 = acc[ai][bj][m][1];
;                     u32x4 o; o.x = pk2(v0[0], v0[1]); o.y = pk2(v0[2], v0[3]); o.z = pk2(v1[0], v1[1]); o.w = pk2(v1[2], v1[3]);
;                     *(u32x4*)(rp + 8 * bj) = o;
;                 }
;             }
	v_lshl_add_u32 v134, s77, 8, v138
	v_cvt_pk_bf16_f32 v68, v68, v69
	v_cvt_pk_bf16_f32 v69, v70, v71
	v_cvt_pk_bf16_f32 v70, v64, v65
	v_add_u32_e32 v64, 0x80, v134
	v_lshl_or_b32 v136, s15, 8, v140
	v_ashrrev_i32_e32 v135, 31, v134
	v_cvt_pk_bf16_f32 v112, v112, v113
	v_cvt_pk_bf16_f32 v113, v114, v115
	v_cvt_pk_bf16_f32 v114, v104, v105
	v_or_b32_e32 v104, 16, v134
	v_ashrrev_i32_e32 v65, 31, v64
	v_cvt_pk_bf16_f32 v48, v48, v49
	v_cvt_pk_bf16_f32 v49, v50, v51
	v_cvt_pk_bf16_f32 v50, v40, v41
	v_add_u32_e32 v40, 0x90, v134
	v_ashrrev_i32_e32 v137, 31, v136
	v_lshlrev_b64 v[142:143], 11, v[134:135]
	v_ashrrev_i32_e32 v105, 31, v104
	v_cvt_pk_bf16_f32 v96, v96, v97
	v_cvt_pk_bf16_f32 v97, v98, v99
	v_cvt_pk_bf16_f32 v98, v88, v89
	v_or_b32_e32 v88, 32, v134
	v_lshlrev_b64 v[64:65], 11, v[64:65]
	v_ashrrev_i32_e32 v41, 31, v40
	v_cvt_pk_bf16_f32 v32, v32, v33
	v_cvt_pk_bf16_f32 v33, v34, v35
	v_cvt_pk_bf16_f32 v34, v24, v25
	v_add_u32_e32 v24, 0xa0, v134
	v_lshl_add_u64 v[142:143], s[8:9], 0, v[142:143]
	v_lshlrev_b64 v[136:137], 1, v[136:137]
	v_lshlrev_b64 v[104:105], 11, v[104:105]
	v_ashrrev_i32_e32 v89, 31, v88
	v_cvt_pk_bf16_f32 v80, v80, v81
	v_cvt_pk_bf16_f32 v81, v82, v83
	v_cvt_pk_bf16_f32 v82, v72, v73
	v_or_b32_e32 v72, 48, v134
	v_lshl_add_u64 v[64:65], s[8:9], 0, v[64:65]
	v_lshlrev_b64 v[40:41], 11, v[40:41]
	v_ashrrev_i32_e32 v25, 31, v24
	v_cvt_pk_bf16_f32 v16, v16, v17
	v_cvt_pk_bf16_f32 v17, v18, v19
	v_cvt_pk_bf16_f32 v18, v8, v9
	v_add_u32_e32 v8, 0xb0, v134
	v_lshl_add_u64 v[142:143], v[142:143], 0, v[136:137]
	v_lshl_add_u64 v[104:105], s[8:9], 0, v[104:105]
	v_lshlrev_b64 v[88:89], 11, v[88:89]
	v_ashrrev_i32_e32 v73, 31, v72
	v_lshl_add_u64 v[64:65], v[64:65], 0, v[136:137]
	v_lshl_add_u64 v[40:41], s[8:9], 0, v[40:41]
	v_lshlrev_b64 v[24:25], 11, v[24:25]
	v_ashrrev_i32_e32 v9, 31, v8
	v_cvt_pk_bf16_f32 v115, v106, v107
	global_store_dwordx4 v[142:143], v[112:115], off offset:16
	v_lshl_add_u64 v[88:89], s[8:9], 0, v[88:89]
	v_lshlrev_b64 v[72:73], 11, v[72:73]
	v_lshl_add_u64 v[112:113], v[104:105], 0, v[136:137]
	v_cvt_pk_bf16_f32 v51, v42, v43
	global_store_dwordx4 v[64:65], v[48:51], off offset:16
	v_lshl_add_u64 v[24:25], s[8:9], 0, v[24:25]
	v_lshlrev_b64 v[8:9], 11, v[8:9]
	v_lshl_add_u64 v[48:49], v[40:41], 0, v[136:137]
	v_cvt_pk_bf16_f32 v99, v90, v91
	global_store_dwordx4 v[112:113], v[96:99], off offset:16
	v_lshl_add_u64 v[72:73], s[8:9], 0, v[72:73]
	v_cvt_pk_bf16_f32 v35, v26, v27
	global_store_dwordx4 v[48:49], v[32:35], off offset:16
	v_lshl_add_u64 v[96:97], v[88:89], 0, v[136:137]
	v_lshl_add_u64 v[8:9], s[8:9], 0, v[8:9]
	v_lshl_add_u64 v[32:33], v[24:25], 0, v[136:137]
	v_cvt_pk_bf16_f32 v83, v74, v75
	global_store_dwordx4 v[96:97], v[80:83], off offset:16
	v_cvt_pk_bf16_f32 v19, v10, v11
	global_store_dwordx4 v[32:33], v[16:19], off offset:16
	s_and_b64 vcc, exec, s[0:1]
	v_lshl_add_u64 v[80:81], v[72:73], 0, v[136:137]
	v_lshl_add_u64 v[16:17], v[8:9], 0, v[136:137]
	s_mov_b32 s15, s72
	s_mov_b32 s77, s76
	s_mov_b64 s[12:13], s[6:7]
	s_mov_b64 s[10:11], s[4:5]
	v_cvt_pk_bf16_f32 v124, v124, v125
	v_cvt_pk_bf16_f32 v125, v126, v127
	v_cvt_pk_bf16_f32 v126, v120, v121
	v_cvt_pk_bf16_f32 v127, v122, v123
	global_store_dwordx4 v[142:143], v[124:127], off
	v_cvt_pk_bf16_f32 v104, v116, v117
	v_cvt_pk_bf16_f32 v105, v118, v119
	v_cvt_pk_bf16_f32 v106, v108, v109
	v_cvt_pk_bf16_f32 v107, v110, v111
	global_store_dwordx4 v[112:113], v[104:107], off
	v_cvt_pk_bf16_f32 v88, v100, v101
	v_cvt_pk_bf16_f32 v89, v102, v103
	v_cvt_pk_bf16_f32 v90, v92, v93
	v_cvt_pk_bf16_f32 v91, v94, v95
	global_store_dwordx4 v[96:97], v[88:91], off
	v_cvt_pk_bf16_f32 v72, v84, v85
	v_cvt_pk_bf16_f32 v73, v86, v87
	v_cvt_pk_bf16_f32 v74, v76, v77
	v_cvt_pk_bf16_f32 v75, v78, v79
	global_store_dwordx4 v[80:81], v[72:75], off
	v_cvt_pk_bf16_f32 v71, v66, v67
	global_store_dwordx4 v[80:81], v[68:71], off offset:16
	v_cvt_pk_bf16_f32 v60, v60, v61
	v_cvt_pk_bf16_f32 v61, v62, v63
	v_cvt_pk_bf16_f32 v62, v56, v57
	v_cvt_pk_bf16_f32 v63, v58, v59
	global_store_dwordx4 v[64:65], v[60:63], off
	v_cvt_pk_bf16_f32 v40, v52, v53
	v_cvt_pk_bf16_f32 v41, v54, v55
	v_cvt_pk_bf16_f32 v42, v44, v45
	v_cvt_pk_bf16_f32 v43, v46, v47
	global_store_dwordx4 v[48:49], v[40:43], off
	v_cvt_pk_bf16_f32 v24, v36, v37
	v_cvt_pk_bf16_f32 v25, v38, v39
	v_cvt_pk_bf16_f32 v26, v28, v29
	v_cvt_pk_bf16_f32 v27, v30, v31
	global_store_dwordx4 v[32:33], v[24:27], off
	v_cvt_pk_bf16_f32 v8, v20, v21
	v_cvt_pk_bf16_f32 v9, v22, v23
	v_cvt_pk_bf16_f32 v10, v12, v13
	v_cvt_pk_bf16_f32 v11, v14, v15
	global_store_dwordx4 v[16:17], v[8:11], off
	v_cvt_pk_bf16_f32 v4, v4, v5
	v_cvt_pk_bf16_f32 v5, v6, v7
	v_cvt_pk_bf16_f32 v6, v0, v1
	v_cvt_pk_bf16_f32 v7, v2, v3
	global_store_dwordx4 v[16:17], v[4:7], off offset:16
	s_cbranch_vccz .LBB0_1455
	s_waitcnt vmcnt(0)
	s_cmpk_gt_u32 s23, 0xff
	s_cbranch_scc1 .LBB0_1466
	s_barrier
